# batched wave-reduction permutes (one wait per hop) and pipelined pool MFMA fragment reads on top of v69
# speedup vs baseline: 1.0443x; 1.0031x over previous
.LBB0_208:
	s_or_b64 exec, exec, s[44:45]
	v_add_u32_e32 v58, s95, v83
	v_min_i32_e32 v58, 3, v58
	v_add_u32_e32 v58, 1, v58
	v_cvt_f32_i32_e32 v58, v58
	s_waitcnt vmcnt(26)
	v_cndmask_b32_e32 v9, 0, v9, vcc
	s_waitcnt vmcnt(8)
	v_cndmask_b32_e64 v0, 0, v52, s[38:39]
	v_cndmask_b32_e64 v10, 0, v10, s[0:1]
	v_lshlrev_b32_e32 v52, 16, v9
	v_and_b32_e32 v9, 0xffff0000, v9
	v_cndmask_b32_e64 v11, 0, v11, s[2:3]
	v_add_f32_e32 v53, 0, v52
	v_add_f32_e32 v54, 0, v9
	v_lshlrev_b32_e32 v55, 16, v10
	v_and_b32_e32 v10, 0xffff0000, v10
	v_rcp_iflag_f32_e32 v58, v58
	v_cndmask_b32_e64 v12, 0, v12, s[6:7]
	v_add_f32_e32 v53, v53, v55
	v_add_f32_e32 v54, v54, v10
	v_lshlrev_b32_e32 v56, 16, v11
	v_and_b32_e32 v11, 0xffff0000, v11
	v_add_f32_e32 v53, v53, v56
	v_add_f32_e32 v54, v54, v11
	v_lshlrev_b32_e32 v57, 16, v12
	v_and_b32_e32 v12, 0xffff0000, v12
	v_add_f32_e32 v53, v53, v57
	v_add_f32_e32 v54, v54, v12
	v_fma_f32 v59, v58, v53, -v57
	v_fma_f32 v58, v58, v54, -v12
	v_sub_f32_e32 v9, v54, v9
	v_add_u32_e32 v54, s95, v127
	v_min_i32_e32 v54, 3, v54
	v_add_u32_e32 v54, 1, v54
	v_cvt_f32_i32_e32 v54, v54
	v_cndmask_b32_e64 v13, v13, 0, s[8:9]
	v_sub_f32_e32 v52, v53, v52
	v_lshlrev_b32_e32 v53, 16, v13
	v_rcp_iflag_f32_e32 v54, v54
	v_and_b32_e32 v13, 0xffff0000, v13
	v_cvt_pk_bf16_f32 v58, v59, v58
	v_add_u32_e32 v116, 0, v145
	v_add_f32_e32 v52, v52, v53
	v_add_f32_e32 v9, v9, v13
	s_waitcnt lgkmcnt(0)
	s_barrier
	ds_write_b32 v116, v58 offset:34816
	v_fma_f32 v58, v54, v52, -v53
	v_fma_f32 v54, v54, v9, -v13
	v_cvt_pk_bf16_f32 v54, v58, v54
	v_add_u32_e32 v117, 0, v146
	ds_write_b32 v117, v54 offset:34816
	v_add_u32_e32 v54, s95, v128
	v_min_i32_e32 v54, 3, v54
	v_add_u32_e32 v54, 1, v54
	v_cvt_f32_i32_e32 v54, v54
	v_cndmask_b32_e64 v14, 0, v14, s[10:11]
	v_sub_f32_e32 v52, v52, v55
	v_sub_f32_e32 v9, v9, v10
	v_rcp_iflag_f32_e32 v54, v54
	v_lshlrev_b32_e32 v10, 16, v14
	v_and_b32_e32 v14, 0xffff0000, v14
	v_add_f32_e32 v52, v52, v10
	v_add_f32_e32 v9, v9, v14
	v_fma_f32 v55, v54, v52, -v10
	v_fma_f32 v54, v54, v9, -v14
	v_cvt_pk_bf16_f32 v54, v55, v54
	v_add_u32_e32 v168, 0, v147
	ds_write_b32 v168, v54 offset:34816
	v_add_u32_e32 v54, s95, v129
	v_min_i32_e32 v54, 3, v54
	v_add_u32_e32 v54, 1, v54
	v_cvt_f32_i32_e32 v54, v54
	v_cndmask_b32_e64 v15, 0, v15, s[12:13]
	v_sub_f32_e32 v52, v52, v56
	v_sub_f32_e32 v9, v9, v11
	v_rcp_iflag_f32_e32 v54, v54
	v_lshlrev_b32_e32 v11, 16, v15
	v_and_b32_e32 v15, 0xffff0000, v15
	v_add_f32_e32 v52, v52, v11
	v_add_f32_e32 v9, v9, v15
	v_fma_f32 v55, v54, v52, -v11
	v_fma_f32 v54, v54, v9, -v15
	v_cvt_pk_bf16_f32 v54, v55, v54
	v_add_u32_e32 v169, 0, v148
	ds_write_b32 v169, v54 offset:34816
	v_add_u32_e32 v54, s95, v130
	v_min_i32_e32 v54, 3, v54
	v_add_u32_e32 v54, 1, v54
	v_cvt_f32_i32_e32 v54, v54
	v_cndmask_b32_e64 v16, 0, v16, s[14:15]
	v_sub_f32_e32 v52, v52, v57
	v_sub_f32_e32 v9, v9, v12
	v_rcp_iflag_f32_e32 v54, v54
	v_lshlrev_b32_e32 v12, 16, v16
	v_add_f32_e32 v52, v52, v12
	v_and_b32_e32 v16, 0xffff0000, v16
	v_fma_f32 v55, v54, v52, -v12
	v_sub_f32_e32 v52, v52, v53
	v_add_u32_e32 v53, s95, v131
	v_min_i32_e32 v53, 3, v53
	v_add_u32_e32 v53, 1, v53
	v_cvt_f32_i32_e32 v53, v53
	v_cndmask_b32_e64 v17, 0, v17, s[16:17]
	v_add_f32_e32 v9, v9, v16
	v_fma_f32 v54, v54, v9, -v16
	v_rcp_iflag_f32_e32 v53, v53
	v_sub_f32_e32 v9, v9, v13
	v_lshlrev_b32_e32 v13, 16, v17
	v_cvt_pk_bf16_f32 v54, v55, v54
	v_add_u32_e32 v170, 0, v149
	v_add_f32_e32 v52, v52, v13
	ds_write_b32 v170, v54 offset:34816
	v_fma_f32 v54, v53, v52, -v13
	v_sub_f32_e32 v10, v52, v10
	v_add_u32_e32 v52, s95, v132
	v_min_i32_e32 v52, 3, v52
	v_add_u32_e32 v52, 1, v52
	v_cvt_f32_i32_e32 v52, v52
	v_and_b32_e32 v17, 0xffff0000, v17
	v_cndmask_b32_e64 v50, 0, v50, s[18:19]
	v_add_f32_e32 v9, v9, v17
	v_rcp_iflag_f32_e32 v52, v52
	v_fma_f32 v53, v53, v9, -v17
	v_sub_f32_e32 v9, v9, v14
	v_lshlrev_b32_e32 v14, 16, v50
	v_and_b32_e32 v50, 0xffff0000, v50
	v_cndmask_b32_e64 v51, 0, v51, s[20:21]
	v_cvt_pk_bf16_f32 v53, v54, v53
	v_add_u32_e32 v171, 0, v150
	v_add_f32_e32 v10, v10, v14
	v_add_f32_e32 v9, v9, v50
	ds_write_b32 v171, v53 offset:34816
	v_fma_f32 v53, v52, v10, -v14
	v_fma_f32 v52, v52, v9, -v50
	v_sub_f32_e32 v10, v10, v11
	v_sub_f32_e32 v9, v9, v15
	v_lshlrev_b32_e32 v11, 16, v51
	v_and_b32_e32 v15, 0xffff0000, v51
	v_add_u32_e32 v51, s95, v133
	v_min_i32_e32 v51, 3, v51
	v_add_u32_e32 v51, 1, v51
	v_cvt_f32_i32_e32 v51, v51
	v_cvt_pk_bf16_f32 v52, v53, v52
	v_add_u32_e32 v172, 0, v151
	v_add_f32_e32 v10, v10, v11
	v_rcp_iflag_f32_e32 v51, v51
	v_add_f32_e32 v9, v9, v15
	ds_write_b32 v172, v52 offset:34816
	v_cndmask_b32_e64 v8, 0, v8, s[22:23]
	v_fma_f32 v52, v51, v10, -v11
	v_fma_f32 v51, v51, v9, -v15
	v_sub_f32_e32 v9, v9, v16
	v_add_u32_e32 v16, s95, v134
	v_min_i32_e32 v16, 3, v16
	v_add_u32_e32 v16, 1, v16
	v_cvt_f32_i32_e32 v16, v16
	v_sub_f32_e32 v10, v10, v12
	v_lshlrev_b32_e32 v12, 16, v8
	v_and_b32_e32 v8, 0xffff0000, v8
	v_rcp_iflag_f32_e32 v16, v16
	v_cvt_pk_bf16_f32 v51, v52, v51
	v_add_u32_e32 v173, 0, v152
	v_add_f32_e32 v10, v10, v12
	v_add_f32_e32 v9, v9, v8
	ds_write_b32 v173, v51 offset:34816
	v_fma_f32 v51, v16, v10, -v12
	v_fma_f32 v16, v16, v9, -v8
	v_cvt_pk_bf16_f32 v16, v51, v16
	v_add_u32_e32 v174, 0, v153
	ds_write_b32 v174, v16 offset:34816
	v_add_u32_e32 v16, s95, v135
	v_min_i32_e32 v16, 3, v16
	v_add_u32_e32 v16, 1, v16
	v_cvt_f32_i32_e32 v16, v16
	v_cndmask_b32_e64 v7, 0, v7, s[24:25]
	v_sub_f32_e32 v10, v10, v13
	v_sub_f32_e32 v9, v9, v17
	v_rcp_iflag_f32_e32 v16, v16
	v_lshlrev_b32_e32 v13, 16, v7
	v_and_b32_e32 v7, 0xffff0000, v7
	v_add_f32_e32 v10, v10, v13
	v_add_f32_e32 v9, v9, v7
	v_fma_f32 v17, v16, v10, -v13
	v_fma_f32 v16, v16, v9, -v7
	v_cvt_pk_bf16_f32 v16, v17, v16
	v_add_u32_e32 v175, 0, v154
	ds_write_b32 v175, v16 offset:34816
	v_add_u32_e32 v16, s95, v136
	v_min_i32_e32 v16, 3, v16
	v_add_u32_e32 v16, 1, v16
	v_cvt_f32_i32_e32 v16, v16
	v_cndmask_b32_e64 v6, 0, v6, s[26:27]
	v_sub_f32_e32 v10, v10, v14
	v_sub_f32_e32 v9, v9, v50
	v_rcp_iflag_f32_e32 v16, v16
	v_lshlrev_b32_e32 v14, 16, v6
	v_and_b32_e32 v6, 0xffff0000, v6
	v_add_f32_e32 v10, v10, v14
	v_add_f32_e32 v9, v9, v6
	v_fma_f32 v17, v16, v10, -v14
	v_fma_f32 v16, v16, v9, -v6
	v_sub_f32_e32 v9, v9, v15
	v_add_u32_e32 v15, s95, v137
	v_min_i32_e32 v15, 3, v15
	v_add_u32_e32 v15, 1, v15
	v_cvt_f32_i32_e32 v15, v15
	v_cndmask_b32_e64 v5, 0, v5, s[28:29]
	v_sub_f32_e32 v10, v10, v11
	v_lshlrev_b32_e32 v11, 16, v5
	v_rcp_iflag_f32_e32 v15, v15
	v_cvt_pk_bf16_f32 v16, v17, v16
	v_add_u32_e32 v176, 0, v155
	v_add_f32_e32 v10, v10, v11
	ds_write_b32 v176, v16 offset:34816
	v_fma_f32 v16, v15, v10, -v11
	v_sub_f32_e32 v10, v10, v12
	v_add_u32_e32 v12, s95, v138
	v_min_i32_e32 v12, 3, v12
	v_add_u32_e32 v12, 1, v12
	v_cvt_f32_i32_e32 v12, v12
	v_and_b32_e32 v5, 0xffff0000, v5
	v_cndmask_b32_e64 v4, 0, v4, s[42:43]
	v_add_f32_e32 v9, v9, v5
	v_rcp_iflag_f32_e32 v12, v12
	v_fma_f32 v15, v15, v9, -v5
	v_sub_f32_e32 v8, v9, v8
	v_lshlrev_b32_e32 v9, 16, v4
	v_and_b32_e32 v4, 0xffff0000, v4
	v_add_f32_e32 v10, v10, v9
	v_add_f32_e32 v8, v8, v4
	v_fma_f32 v9, v12, v10, -v9
	v_fma_f32 v4, v12, v8, -v4
	v_cvt_pk_bf16_f32 v4, v9, v4
	v_add_u32_e32 v9, s95, v139
	v_min_i32_e32 v9, 3, v9
	v_add_u32_e32 v9, 1, v9
	v_cvt_f32_i32_e32 v9, v9
	v_cndmask_b32_e64 v3, 0, v3, s[34:35]
	v_add_u32_e32 v177, 0, v156
	v_add_u32_e32 v178, 0, v157
	v_rcp_iflag_f32_e32 v9, v9
	v_sub_f32_e32 v7, v8, v7
	v_lshlrev_b32_e32 v8, 16, v3
	v_and_b32_e32 v3, 0xffff0000, v3
	v_cvt_pk_bf16_f32 v15, v16, v15
	ds_write_b32 v177, v15 offset:34816
	ds_write_b32 v178, v4 offset:34816
	v_sub_f32_e32 v4, v10, v13
	v_add_f32_e32 v7, v7, v3
	v_add_f32_e32 v4, v4, v8
	v_fma_f32 v3, v9, v7, -v3
	v_fma_f32 v8, v9, v4, -v8
	v_cvt_pk_bf16_f32 v3, v8, v3
	v_add_u32_e32 v179, 0, v158
	ds_write_b32 v179, v3 offset:34816
	v_sub_f32_e32 v3, v4, v14
	v_sub_f32_e32 v4, v7, v6
	v_add_u32_e32 v7, s95, v140
	v_min_i32_e32 v7, 3, v7
	v_add_u32_e32 v7, 1, v7
	v_cvt_f32_i32_e32 v7, v7
	v_cndmask_b32_e64 v2, 0, v2, s[36:37]
	v_lshlrev_b32_e32 v6, 16, v2
	v_and_b32_e32 v2, 0xffff0000, v2
	v_rcp_iflag_f32_e32 v7, v7
	v_add_f32_e32 v4, v4, v2
	v_add_f32_e32 v3, v3, v6
	v_add_u32_e32 v180, 0, v159
	v_fma_f32 v2, v7, v4, -v2
	v_fma_f32 v6, v7, v3, -v6
	v_cvt_pk_bf16_f32 v2, v6, v2
	ds_write_b32 v180, v2 offset:34816
	v_sub_f32_e32 v2, v3, v11
	v_sub_f32_e32 v3, v4, v5
	v_add_u32_e32 v5, s95, v141
	v_min_i32_e32 v5, 3, v5
	v_add_u32_e32 v5, 1, v5
	v_cvt_f32_i32_e32 v5, v5
	s_or_b32 s0, s94, 0x80
	v_lshlrev_b32_e32 v4, 16, v0
	v_and_b32_e32 v0, 0xffff0000, v0
	v_rcp_iflag_f32_e32 v5, v5
	s_xor_b32 s1, s95, 0xffffff7f
	s_mul_i32 s2, s0, 0x1e00
	v_add_f32_e32 v2, v2, v4
	v_add_f32_e32 v3, v3, v0
	s_mul_hi_i32 s3, s0, 0x1e00
	s_add_u32 s2, s91, s2
	v_fma_f32 v2, v5, v2, -v4
	v_fma_f32 v0, v5, v3, -v0
	s_addc_u32 s3, s92, s3
	v_mov_b32_e32 v105, v1
	v_cvt_pk_bf16_f32 v0, v2, v0
	v_add_u32_e32 v181, 0, v160
	v_cmp_lt_i32_e32 vcc, s1, v141
	v_lshl_add_u64 v[2:3], s[2:3], 0, v[104:105]
	s_mov_b64 s[2:3], 0x1520
	ds_write_b32 v181, v0 offset:34816
	v_lshl_add_u64 v[2:3], v[2:3], 0, s[2:3]
	v_cndmask_b32_e32 v0, 0, v141, vcc
	s_movk_i32 s6, 0x1e00
	v_mad_i64_i32 v[4:5], s[2:3], v0, s6, v[2:3]
	global_load_dword v0, v[4:5], off
	v_add_u32_e32 v185, v144, v143
	v_add_u32_e32 v184, v144, v161
	v_lshlrev_b32_e32 v104, 1, v90
	v_mov_b32_e32 v103, v1
	v_add_u32_e32 v183, v144, v163
	v_lshlrev_b32_e32 v114, 1, v98
	v_mov_b32_e32 v115, v1
	s_waitcnt vmcnt(0)
	v_cndmask_b32_e32 v182, 0, v0, vcc
	v_cmp_lt_i32_e32 vcc, s1, v124
	v_mov_b32_e32 v211, 0
	s_nop 0
	v_cndmask_b32_e32 v0, 0, v124, vcc
	v_mad_i64_i32 v[4:5], s[2:3], v0, s6, v[2:3]
	s_and_saveexec_b64 s[98:99], vcc
	global_load_dword v211, v[4:5], off
	s_mov_b64 exec, s[98:99]
	v_cmp_lt_i32_e32 vcc, s1, v125
	v_mov_b32_e32 v212, 0
	s_nop 0
	v_cndmask_b32_e32 v0, 0, v125, vcc
	v_mad_i64_i32 v[4:5], s[2:3], v0, s6, v[2:3]
	s_and_saveexec_b64 s[98:99], vcc
	global_load_dword v212, v[4:5], off
	s_mov_b64 exec, s[98:99]
	v_cmp_lt_i32_e32 vcc, s1, v126
	v_mov_b32_e32 v213, 0
	s_nop 0
	v_cndmask_b32_e32 v0, 0, v126, vcc
	v_mad_i64_i32 v[4:5], s[2:3], v0, s6, v[2:3]
	s_and_saveexec_b64 s[98:99], vcc
	global_load_dword v213, v[4:5], off
	s_mov_b64 exec, s[98:99]
	v_cmp_lt_i32_e32 vcc, s1, v83
	v_mov_b32_e32 v214, 0
	s_nop 0
	v_cndmask_b32_e32 v0, 0, v83, vcc
	v_mad_i64_i32 v[4:5], s[2:3], v0, s6, v[2:3]
	s_and_saveexec_b64 s[98:99], vcc
	global_load_dword v214, v[4:5], off
	s_mov_b64 exec, s[98:99]
	v_cmp_gt_i32_e32 vcc, s1, v83
	s_nop 1
	v_cndmask_b32_e64 v0, v127, 0, vcc
	v_mad_i64_i32 v[4:5], s[2:3], v0, s6, v[2:3]
	global_load_dword v0, v[4:5], off
	s_waitcnt vmcnt(0)
	v_cndmask_b32_e64 v191, v0, 0, vcc
	v_cmp_lt_i32_e32 vcc, s1, v128
	v_mov_b32_e32 v210, 0
	s_nop 0
	v_cndmask_b32_e32 v0, 0, v128, vcc
	v_mad_i64_i32 v[4:5], s[2:3], v0, s6, v[2:3]
	s_and_saveexec_b64 s[98:99], vcc
	global_load_dword v210, v[4:5], off
	s_mov_b64 exec, s[98:99]
	v_cmp_lt_i32_e32 vcc, s1, v129
	v_mov_b32_e32 v209, 0
	s_nop 0
	v_cndmask_b32_e32 v0, 0, v129, vcc
	v_mad_i64_i32 v[4:5], s[2:3], v0, s6, v[2:3]
	s_and_saveexec_b64 s[98:99], vcc
	global_load_dword v209, v[4:5], off
	s_mov_b64 exec, s[98:99]
	v_cmp_lt_i32_e32 vcc, s1, v130
	v_mov_b32_e32 v208, 0
	s_nop 0
	v_cndmask_b32_e32 v0, 0, v130, vcc
	v_mad_i64_i32 v[4:5], s[2:3], v0, s6, v[2:3]
	s_and_saveexec_b64 s[98:99], vcc
	global_load_dword v208, v[4:5], off
	s_mov_b64 exec, s[98:99]
	v_cmp_lt_i32_e32 vcc, s1, v131
	v_mov_b32_e32 v207, 0
	s_nop 0
	v_cndmask_b32_e32 v0, 0, v131, vcc
	v_mad_i64_i32 v[4:5], s[2:3], v0, s6, v[2:3]
	s_and_saveexec_b64 s[98:99], vcc
	global_load_dword v207, v[4:5], off
	s_mov_b64 exec, s[98:99]
	v_cmp_lt_i32_e32 vcc, s1, v132
	v_mov_b32_e32 v206, 0
	s_nop 0
	v_cndmask_b32_e32 v0, 0, v132, vcc
	v_mad_i64_i32 v[4:5], s[2:3], v0, s6, v[2:3]
	s_and_saveexec_b64 s[98:99], vcc
	global_load_dword v206, v[4:5], off
	s_mov_b64 exec, s[98:99]
	v_cmp_lt_i32_e32 vcc, s1, v133
	v_mov_b32_e32 v205, 0
	s_nop 0
	v_cndmask_b32_e32 v0, 0, v133, vcc
	v_mad_i64_i32 v[4:5], s[2:3], v0, s6, v[2:3]
	s_and_saveexec_b64 s[98:99], vcc
	global_load_dword v205, v[4:5], off
	s_mov_b64 exec, s[98:99]
	v_cmp_lt_i32_e32 vcc, s1, v134
	v_mov_b32_e32 v204, 0
	s_nop 0
	v_cndmask_b32_e32 v0, 0, v134, vcc
	v_mad_i64_i32 v[4:5], s[2:3], v0, s6, v[2:3]
	s_and_saveexec_b64 s[98:99], vcc
	global_load_dword v204, v[4:5], off
	s_mov_b64 exec, s[98:99]
	v_cmp_lt_i32_e32 vcc, s1, v135
	v_mov_b32_e32 v192, 0
	s_nop 0
	v_cndmask_b32_e32 v0, 0, v135, vcc
	v_mad_i64_i32 v[4:5], s[2:3], v0, s6, v[2:3]
	s_and_saveexec_b64 s[98:99], vcc
	global_load_dword v192, v[4:5], off
	s_mov_b64 exec, s[98:99]
	v_cmp_lt_i32_e32 vcc, s1, v136
	v_mov_b32_e32 v190, 0
	s_nop 0
	v_cndmask_b32_e32 v0, 0, v136, vcc
	v_mad_i64_i32 v[4:5], s[2:3], v0, s6, v[2:3]
	s_and_saveexec_b64 s[98:99], vcc
	global_load_dword v190, v[4:5], off
	s_mov_b64 exec, s[98:99]
	v_cmp_lt_i32_e32 vcc, s1, v137
	v_mov_b32_e32 v189, 0
	s_nop 0
	v_cndmask_b32_e32 v0, 0, v137, vcc
	v_mad_i64_i32 v[4:5], s[2:3], v0, s6, v[2:3]
	s_and_saveexec_b64 s[98:99], vcc
	global_load_dword v189, v[4:5], off
	s_mov_b64 exec, s[98:99]
	v_cmp_lt_i32_e32 vcc, s1, v138
	v_mov_b32_e32 v188, 0
	s_nop 0
	v_cndmask_b32_e32 v0, 0, v138, vcc
	v_mad_i64_i32 v[4:5], s[2:3], v0, s6, v[2:3]
	s_and_saveexec_b64 s[98:99], vcc
	global_load_dword v188, v[4:5], off
	s_mov_b64 exec, s[98:99]
	v_cmp_lt_i32_e32 vcc, s1, v139
	v_mov_b32_e32 v187, 0
	s_nop 0
	v_cndmask_b32_e32 v0, 0, v139, vcc
	v_mad_i64_i32 v[4:5], s[2:3], v0, s6, v[2:3]
	s_and_saveexec_b64 s[98:99], vcc
	global_load_dword v187, v[4:5], off
	s_mov_b64 exec, s[98:99]
	v_cmp_lt_i32_e32 vcc, s1, v140
	s_and_b32 s1, s0, 0xf80
	s_nop 0
	v_cndmask_b32_e32 v0, 0, v140, vcc
	v_mad_i64_i32 v[2:3], s[2:3], v0, s6, v[2:3]
	global_load_dword v0, v[2:3], off
	v_add_u32_e32 v2, s94, v142
	v_ashrrev_i32_e32 v3, 31, v2
	v_lshlrev_b64 v[2:3], 12, v[2:3]
	s_waitcnt lgkmcnt(0)
	s_barrier
	v_lshl_add_u64 v[2:3], s[70:71], 0, v[2:3]
	s_mov_b64 s[2:3], 0x26000900
	ds_read_b128 v[74:77], v185 offset:34816
	ds_read_b128 v[78:81], v185 offset:34848
	ds_read_b128 v[70:73], v185 offset:34880
	ds_read_b128 v[66:69], v185 offset:34912
	ds_read_b128 v[62:65], v185 offset:34944
	ds_read_b128 v[58:61], v185 offset:34976
	ds_read_b128 v[54:57], v185 offset:35008
	ds_read_b128 v[50:53], v185 offset:35040
	v_lshl_add_u64 v[106:107], v[2:3], 0, s[2:3]
	ds_read_b128 v[2:5], v184
	ds_read_b128 v[108:111], v184 offset:32
	ds_read_b128 v[228:231], v184 offset:64
	ds_read_b128 v[242:245], v184 offset:96
	s_waitcnt lgkmcnt(3)
	v_mfma_f32_32x32x16_bf16 v[2:17], v[2:5], v[74:77], 0
	s_waitcnt vmcnt(0)
	v_cndmask_b32_e32 v186, 0, v0, vcc
	s_waitcnt lgkmcnt(2)
	v_mfma_f32_32x32x16_bf16 v[2:17], v[108:111], v[78:81], v[2:17]
	ds_read_b128 v[108:111], v184 offset:128
	s_waitcnt lgkmcnt(2)
	v_mfma_f32_32x32x16_bf16 v[2:17], v[228:231], v[70:73], v[2:17]
	ds_read_b128 v[228:231], v184 offset:160
	s_waitcnt lgkmcnt(2)
	v_mfma_f32_32x32x16_bf16 v[2:17], v[242:245], v[66:69], v[2:17]
	ds_read_b128 v[242:245], v184 offset:192
	s_waitcnt lgkmcnt(2)
	v_mfma_f32_32x32x16_bf16 v[2:17], v[108:111], v[62:65], v[2:17]
	ds_read_b128 v[108:111], v184 offset:224
	s_waitcnt lgkmcnt(2)
	v_mfma_f32_32x32x16_bf16 v[2:17], v[228:231], v[58:61], v[2:17]
	s_waitcnt lgkmcnt(1)
	v_mfma_f32_32x32x16_bf16 v[2:17], v[242:245], v[54:57], v[2:17]
	s_waitcnt lgkmcnt(0)
	v_mfma_f32_32x32x16_bf16 v[2:17], v[108:111], v[50:53], v[2:17]
	v_lshlrev_b32_e32 v108, 1, v92
	v_mov_b32_e32 v109, v1
	s_nop 9
	v_mul_f32_e32 v0, v46, v2
	v_mul_f32_e32 v2, v47, v3
	v_cvt_pk_bf16_f32 v2, v0, v2
	v_mul_f32_e32 v0, v48, v4
	v_mul_f32_e32 v3, v49, v5
	v_cvt_pk_bf16_f32 v3, v0, v3
	v_lshlrev_b32_e32 v0, 1, v88
	v_lshl_add_u64 v[4:5], v[106:107], 0, v[0:1]
	global_store_dwordx2 v[4:5], v[2:3], off
	v_mul_f32_e32 v2, v42, v6
	v_mul_f32_e32 v3, v43, v7
	v_cvt_pk_bf16_f32 v2, v2, v3
	v_mul_f32_e32 v3, v44, v8
	v_mul_f32_e32 v4, v45, v9
	v_cvt_pk_bf16_f32 v3, v3, v4
	v_lshl_add_u64 v[4:5], v[106:107], 0, v[104:105]
	global_store_dwordx2 v[4:5], v[2:3], off
	v_mul_f32_e32 v2, v38, v10
	v_mul_f32_e32 v3, v39, v11
	v_cvt_pk_bf16_f32 v2, v2, v3
	v_mul_f32_e32 v3, v40, v12
	v_mul_f32_e32 v4, v41, v13
	v_cvt_pk_bf16_f32 v3, v3, v4
	v_lshl_add_u64 v[4:5], v[106:107], 0, v[108:109]
	global_store_dwordx2 v[4:5], v[2:3], off
	v_mul_f32_e32 v2, v34, v14
	v_mul_f32_e32 v3, v35, v15
	v_cvt_pk_bf16_f32 v2, v2, v3
	v_mul_f32_e32 v3, v36, v16
	v_mul_f32_e32 v4, v37, v17
	v_cvt_pk_bf16_f32 v3, v3, v4
	v_lshl_add_u64 v[4:5], v[106:107], 0, v[102:103]
	global_store_dwordx2 v[4:5], v[2:3], off
	ds_read_b128 v[2:5], v183
	ds_read_b128 v[110:113], v183 offset:32
	s_waitcnt lgkmcnt(1)
	v_mfma_f32_32x32x16_bf16 v[2:17], v[2:5], v[74:77], 0
	ds_read_b128 v[74:77], v183 offset:64
	s_waitcnt lgkmcnt(1)
	v_mfma_f32_32x32x16_bf16 v[2:17], v[110:113], v[78:81], v[2:17]
	v_lshlrev_b32_e32 v110, 1, v94
	v_mov_b32_e32 v111, v1
	v_lshlrev_b32_e32 v112, 1, v96
	v_mov_b32_e32 v113, v1
	s_waitcnt lgkmcnt(0)
	v_mfma_f32_32x32x16_bf16 v[2:17], v[74:77], v[70:73], v[2:17]
	ds_read_b128 v[70:73], v183 offset:96
	s_waitcnt lgkmcnt(0)
	v_mfma_f32_32x32x16_bf16 v[2:17], v[70:73], v[66:69], v[2:17]
	ds_read_b128 v[66:69], v183 offset:128
	s_waitcnt lgkmcnt(0)
	v_mfma_f32_32x32x16_bf16 v[2:17], v[66:69], v[62:65], v[2:17]
	ds_read_b128 v[62:65], v183 offset:160
	s_waitcnt lgkmcnt(0)
	v_mfma_f32_32x32x16_bf16 v[2:17], v[62:65], v[58:61], v[2:17]
	ds_read_b128 v[58:61], v183 offset:192
	s_waitcnt lgkmcnt(0)
	v_mfma_f32_32x32x16_bf16 v[2:17], v[58:61], v[54:57], v[2:17]
	ds_read_b128 v[54:57], v183 offset:224
	s_waitcnt lgkmcnt(0)
	v_mfma_f32_32x32x16_bf16 v[2:17], v[54:57], v[50:53], v[2:17]
	s_nop 11
	v_mul_f32_e32 v2, v30, v2
	v_mul_f32_e32 v3, v31, v3
	v_cvt_pk_bf16_f32 v2, v2, v3
	v_mul_f32_e32 v3, v32, v4
	v_mul_f32_e32 v4, v33, v5
	v_cvt_pk_bf16_f32 v3, v3, v4
	v_lshl_add_u64 v[4:5], v[106:107], 0, v[110:111]
	global_store_dwordx2 v[4:5], v[2:3], off
	v_mul_f32_e32 v2, v26, v6
	v_mul_f32_e32 v3, v27, v7
	v_cvt_pk_bf16_f32 v2, v2, v3
	v_mul_f32_e32 v3, v28, v8
	v_mul_f32_e32 v4, v29, v9
	v_cvt_pk_bf16_f32 v3, v3, v4
	v_lshl_add_u64 v[4:5], v[106:107], 0, v[112:113]
	global_store_dwordx2 v[4:5], v[2:3], off
	v_mul_f32_e32 v2, v22, v10
	v_mul_f32_e32 v3, v23, v11
	v_cvt_pk_bf16_f32 v2, v2, v3
	v_mul_f32_e32 v3, v24, v12
	v_mul_f32_e32 v4, v25, v13
	v_add_u32_e32 v12, s1, v83
	v_cvt_pk_bf16_f32 v3, v3, v4
	v_lshl_add_u64 v[4:5], v[106:107], 0, v[114:115]
	v_min_i32_e32 v12, 3, v12
	global_store_dwordx2 v[4:5], v[2:3], off
	v_mul_f32_e32 v2, v18, v14
	v_mul_f32_e32 v3, v19, v15
	v_add_u32_e32 v12, 1, v12
	v_cvt_pk_bf16_f32 v2, v2, v3
	v_mul_f32_e32 v3, v20, v16
	v_mul_f32_e32 v4, v21, v17
	v_cvt_f32_i32_e32 v12, v12
	v_cvt_pk_bf16_f32 v3, v3, v4
	v_lshlrev_b32_e32 v4, 1, v100
	v_mov_b32_e32 v5, v1
	v_lshl_add_u64 v[4:5], v[106:107], 0, v[4:5]
	global_store_dwordx2 v[4:5], v[2:3], off
	v_lshlrev_b32_e32 v2, 16, v211
	v_and_b32_e32 v4, 0xffff0000, v211
	v_add_f32_e32 v3, 0, v2
	v_add_f32_e32 v5, 0, v4
	v_lshlrev_b32_e32 v6, 16, v212
	v_and_b32_e32 v7, 0xffff0000, v212
	v_rcp_iflag_f32_e32 v12, v12
	v_add_f32_e32 v3, v3, v6
	v_add_f32_e32 v5, v5, v7
	v_lshlrev_b32_e32 v8, 16, v213
	v_and_b32_e32 v9, 0xffff0000, v213
	v_add_f32_e32 v3, v3, v8
	v_add_f32_e32 v5, v5, v9
	v_lshlrev_b32_e32 v10, 16, v214
	v_and_b32_e32 v11, 0xffff0000, v214
	v_add_f32_e32 v3, v3, v10
	v_add_f32_e32 v5, v5, v11
	v_fma_f32 v13, v12, v3, -v10
	v_fma_f32 v12, v12, v5, -v11
	v_cvt_pk_bf16_f32 v12, v13, v12
	s_waitcnt lgkmcnt(0)
	s_barrier
	ds_write_b32 v116, v12 offset:34816
	v_add_u32_e32 v12, s1, v127
	v_min_i32_e32 v12, 3, v12
	v_add_u32_e32 v12, 1, v12
	v_cvt_f32_i32_e32 v12, v12
	v_sub_f32_e32 v2, v3, v2
	v_sub_f32_e32 v3, v5, v4
	v_lshlrev_b32_e32 v4, 16, v191
	v_rcp_iflag_f32_e32 v12, v12
	v_and_b32_e32 v5, 0xffff0000, v191
	v_add_f32_e32 v2, v2, v4
	v_add_f32_e32 v3, v3, v5
	v_fma_f32 v13, v12, v2, -v4
	v_fma_f32 v12, v12, v3, -v5
	v_cvt_pk_bf16_f32 v12, v13, v12
	ds_write_b32 v117, v12 offset:34816
	v_add_u32_e32 v12, s1, v128
	v_min_i32_e32 v12, 3, v12
	v_add_u32_e32 v12, 1, v12
	v_cvt_f32_i32_e32 v12, v12
	v_sub_f32_e32 v2, v2, v6
	v_sub_f32_e32 v3, v3, v7
	v_lshlrev_b32_e32 v6, 16, v210
	v_rcp_iflag_f32_e32 v12, v12
	v_and_b32_e32 v7, 0xffff0000, v210
	v_add_f32_e32 v2, v2, v6
	v_add_f32_e32 v3, v3, v7
	v_fma_f32 v13, v12, v2, -v6
	v_fma_f32 v12, v12, v3, -v7
	v_cvt_pk_bf16_f32 v12, v13, v12
	ds_write_b32 v168, v12 offset:34816
	v_add_u32_e32 v12, s1, v129
	v_min_i32_e32 v12, 3, v12
	v_add_u32_e32 v12, 1, v12
	v_cvt_f32_i32_e32 v12, v12
	v_sub_f32_e32 v2, v2, v8
	v_sub_f32_e32 v3, v3, v9
	v_lshlrev_b32_e32 v8, 16, v209
	v_rcp_iflag_f32_e32 v12, v12
	v_and_b32_e32 v9, 0xffff0000, v209
	v_add_f32_e32 v2, v2, v8
	v_add_f32_e32 v3, v3, v9
	v_fma_f32 v13, v12, v2, -v8
	v_fma_f32 v12, v12, v3, -v9
	v_cvt_pk_bf16_f32 v12, v13, v12
	ds_write_b32 v169, v12 offset:34816
	v_add_u32_e32 v12, s1, v130
	v_min_i32_e32 v12, 3, v12
	v_add_u32_e32 v12, 1, v12
	v_cvt_f32_i32_e32 v12, v12
	v_sub_f32_e32 v2, v2, v10
	v_sub_f32_e32 v3, v3, v11
	v_lshlrev_b32_e32 v10, 16, v208
	v_rcp_iflag_f32_e32 v12, v12
	v_and_b32_e32 v11, 0xffff0000, v208
	v_add_f32_e32 v2, v2, v10
	v_add_f32_e32 v3, v3, v11
	v_fma_f32 v13, v12, v2, -v10
	v_fma_f32 v12, v12, v3, -v11
	v_cvt_pk_bf16_f32 v12, v13, v12
	ds_write_b32 v170, v12 offset:34816
	v_add_u32_e32 v12, s1, v131
	v_min_i32_e32 v12, 3, v12
	v_add_u32_e32 v12, 1, v12
	v_cvt_f32_i32_e32 v12, v12
	v_sub_f32_e32 v2, v2, v4
	v_sub_f32_e32 v3, v3, v5
	v_lshlrev_b32_e32 v4, 16, v207
	v_rcp_iflag_f32_e32 v12, v12
	v_and_b32_e32 v5, 0xffff0000, v207
	v_add_f32_e32 v2, v2, v4
	v_add_f32_e32 v3, v3, v5
	v_fma_f32 v13, v12, v2, -v4
	v_fma_f32 v12, v12, v3, -v5
	v_cvt_pk_bf16_f32 v12, v13, v12
	ds_write_b32 v171, v12 offset:34816
	v_add_u32_e32 v12, s1, v132
	v_min_i32_e32 v12, 3, v12
	v_add_u32_e32 v12, 1, v12
	v_cvt_f32_i32_e32 v12, v12
	v_sub_f32_e32 v2, v2, v6
	v_sub_f32_e32 v3, v3, v7
	v_lshlrev_b32_e32 v6, 16, v206
	v_rcp_iflag_f32_e32 v12, v12
	v_and_b32_e32 v7, 0xffff0000, v206
	v_add_f32_e32 v2, v2, v6
	v_add_f32_e32 v3, v3, v7
	v_fma_f32 v13, v12, v2, -v6
	v_fma_f32 v12, v12, v3, -v7
	v_cvt_pk_bf16_f32 v12, v13, v12
	ds_write_b32 v172, v12 offset:34816
	v_add_u32_e32 v12, s1, v133
	v_min_i32_e32 v12, 3, v12
	v_add_u32_e32 v12, 1, v12
	v_cvt_f32_i32_e32 v12, v12
	v_sub_f32_e32 v2, v2, v8
	v_sub_f32_e32 v3, v3, v9
	v_lshlrev_b32_e32 v8, 16, v205
	v_rcp_iflag_f32_e32 v12, v12
	v_and_b32_e32 v9, 0xffff0000, v205
	v_add_f32_e32 v2, v2, v8
	v_add_f32_e32 v3, v3, v9
	v_fma_f32 v13, v12, v2, -v8
	v_fma_f32 v12, v12, v3, -v9
	v_cvt_pk_bf16_f32 v12, v13, v12
	ds_write_b32 v173, v12 offset:34816
	v_add_u32_e32 v12, s1, v134
	v_min_i32_e32 v12, 3, v12
	v_add_u32_e32 v12, 1, v12
	v_cvt_f32_i32_e32 v12, v12
	v_sub_f32_e32 v2, v2, v10
	v_sub_f32_e32 v3, v3, v11
	v_lshlrev_b32_e32 v10, 16, v204
	v_rcp_iflag_f32_e32 v12, v12
	v_and_b32_e32 v11, 0xffff0000, v204
	v_add_f32_e32 v2, v2, v10
	v_add_f32_e32 v3, v3, v11
	v_fma_f32 v13, v12, v2, -v10
	v_fma_f32 v12, v12, v3, -v11
	v_cvt_pk_bf16_f32 v12, v13, v12
	ds_write_b32 v174, v12 offset:34816
	v_add_u32_e32 v12, s1, v135
	v_min_i32_e32 v12, 3, v12
	v_add_u32_e32 v12, 1, v12
	v_cvt_f32_i32_e32 v12, v12
	v_sub_f32_e32 v2, v2, v4
	v_sub_f32_e32 v3, v3, v5
	v_lshlrev_b32_e32 v4, 16, v192
	v_rcp_iflag_f32_e32 v12, v12
	v_and_b32_e32 v5, 0xffff0000, v192
	v_add_f32_e32 v2, v2, v4
	v_add_f32_e32 v3, v3, v5
	v_fma_f32 v13, v12, v2, -v4
	v_fma_f32 v12, v12, v3, -v5
	v_cvt_pk_bf16_f32 v12, v13, v12
	ds_write_b32 v175, v12 offset:34816
	v_add_u32_e32 v12, s1, v136
	v_min_i32_e32 v12, 3, v12
	v_add_u32_e32 v12, 1, v12
	v_cvt_f32_i32_e32 v12, v12
	v_sub_f32_e32 v2, v2, v6
	v_sub_f32_e32 v3, v3, v7
	v_lshlrev_b32_e32 v6, 16, v190
	v_rcp_iflag_f32_e32 v12, v12
	v_and_b32_e32 v7, 0xffff0000, v190
	v_add_f32_e32 v2, v2, v6
	v_add_f32_e32 v3, v3, v7
	v_fma_f32 v13, v12, v2, -v6
	v_fma_f32 v12, v12, v3, -v7
	v_cvt_pk_bf16_f32 v12, v13, v12
	ds_write_b32 v176, v12 offset:34816
	v_add_u32_e32 v12, s1, v137
	v_min_i32_e32 v12, 3, v12
	v_add_u32_e32 v12, 1, v12
	v_cvt_f32_i32_e32 v12, v12
	v_sub_f32_e32 v2, v2, v8
	v_sub_f32_e32 v3, v3, v9
	v_lshlrev_b32_e32 v8, 16, v189
	v_rcp_iflag_f32_e32 v12, v12
	v_and_b32_e32 v9, 0xffff0000, v189
	v_add_f32_e32 v2, v2, v8
	v_add_f32_e32 v3, v3, v9
	v_fma_f32 v13, v12, v2, -v8
	v_fma_f32 v12, v12, v3, -v9
	v_cvt_pk_bf16_f32 v12, v13, v12
	ds_write_b32 v177, v12 offset:34816
	v_add_u32_e32 v12, s1, v138
	v_min_i32_e32 v12, 3, v12
	v_add_u32_e32 v12, 1, v12
	v_cvt_f32_i32_e32 v12, v12
	v_sub_f32_e32 v2, v2, v10
	v_lshlrev_b32_e32 v10, 16, v188
	v_sub_f32_e32 v3, v3, v11
	v_rcp_iflag_f32_e32 v12, v12
	v_and_b32_e32 v11, 0xffff0000, v188
	v_add_f32_e32 v2, v2, v10
	v_add_f32_e32 v3, v3, v11
	v_fma_f32 v10, v12, v2, -v10
	v_fma_f32 v11, v12, v3, -v11
	v_cvt_pk_bf16_f32 v10, v10, v11
	ds_write_b32 v178, v10 offset:34816
	v_add_u32_e32 v10, s1, v139
	v_min_i32_e32 v10, 3, v10
	v_add_u32_e32 v10, 1, v10
	v_cvt_f32_i32_e32 v10, v10
	v_sub_f32_e32 v2, v2, v4
	v_lshlrev_b32_e32 v4, 16, v187
	v_add_f32_e32 v2, v2, v4
	v_rcp_iflag_f32_e32 v10, v10
	v_sub_f32_e32 v3, v3, v5
	v_and_b32_e32 v5, 0xffff0000, v187
	v_add_f32_e32 v3, v3, v5
	v_fma_f32 v4, v10, v2, -v4
	v_sub_f32_e32 v2, v2, v6
	v_add_u32_e32 v6, s1, v140
	v_min_i32_e32 v6, 3, v6
	v_add_u32_e32 v6, 1, v6
	v_cvt_f32_i32_e32 v6, v6
	v_fma_f32 v5, v10, v3, -v5
	v_cvt_pk_bf16_f32 v4, v4, v5
	ds_write_b32 v179, v4 offset:34816
	v_rcp_iflag_f32_e32 v6, v6
	v_sub_f32_e32 v3, v3, v7
	v_lshlrev_b32_e32 v4, 16, v186
	v_and_b32_e32 v5, 0xffff0000, v186
	v_add_f32_e32 v2, v2, v4
	v_add_f32_e32 v3, v3, v5
	v_fma_f32 v4, v6, v2, -v4
	v_fma_f32 v5, v6, v3, -v5
	v_add_u32_e32 v6, s1, v141
	v_min_i32_e32 v6, 3, v6
	v_add_u32_e32 v6, 1, v6
	v_cvt_f32_i32_e32 v6, v6
	v_cvt_pk_bf16_f32 v4, v4, v5
	ds_write_b32 v180, v4 offset:34816
	v_sub_f32_e32 v2, v2, v8
	v_rcp_iflag_f32_e32 v6, v6
	v_lshlrev_b32_e32 v4, 16, v182
	v_sub_f32_e32 v3, v3, v9
	v_and_b32_e32 v5, 0xffff0000, v182
	v_add_f32_e32 v2, v2, v4
	v_add_f32_e32 v3, v3, v5
	v_fma_f32 v2, v6, v2, -v4
	v_fma_f32 v3, v6, v3, -v5
	v_cvt_pk_bf16_f32 v2, v2, v3
	ds_write_b32 v181, v2 offset:34816
	v_add_u32_e32 v2, s0, v142
	v_ashrrev_i32_e32 v3, 31, v2
	v_lshlrev_b64 v[2:3], 12, v[2:3]
	s_waitcnt lgkmcnt(0)
	s_barrier
	v_lshl_add_u64 v[2:3], s[70:71], 0, v[2:3]
	ds_read_b128 v[74:77], v185 offset:34816
	ds_read_b128 v[78:81], v185 offset:34848
	ds_read_b128 v[70:73], v185 offset:34880
	ds_read_b128 v[66:69], v185 offset:34912
	ds_read_b128 v[62:65], v185 offset:34944
	ds_read_b128 v[58:61], v185 offset:34976
	ds_read_b128 v[54:57], v185 offset:35008
	ds_read_b128 v[50:53], v185 offset:35040
	v_lshl_add_u64 v[106:107], v[2:3], 0, s[2:3]
	ds_read_b128 v[2:5], v184
	ds_read_b128 v[168:171], v184 offset:32
	ds_read_b128 v[228:231], v184 offset:64
	ds_read_b128 v[242:245], v184 offset:96
	s_waitcnt lgkmcnt(3)
	v_mfma_f32_32x32x16_bf16 v[2:17], v[2:5], v[74:77], 0
	s_waitcnt lgkmcnt(2)
	v_mfma_f32_32x32x16_bf16 v[2:17], v[168:171], v[78:81], v[2:17]
	ds_read_b128 v[168:171], v184 offset:128
	s_waitcnt lgkmcnt(2)
	v_mfma_f32_32x32x16_bf16 v[2:17], v[228:231], v[70:73], v[2:17]
	ds_read_b128 v[228:231], v184 offset:160
	s_waitcnt lgkmcnt(2)
	v_mfma_f32_32x32x16_bf16 v[2:17], v[242:245], v[66:69], v[2:17]
	ds_read_b128 v[242:245], v184 offset:192
	s_waitcnt lgkmcnt(2)
	v_mfma_f32_32x32x16_bf16 v[2:17], v[168:171], v[62:65], v[2:17]
	ds_read_b128 v[168:171], v184 offset:224
	s_waitcnt lgkmcnt(2)
	v_mfma_f32_32x32x16_bf16 v[2:17], v[228:231], v[58:61], v[2:17]
	s_waitcnt lgkmcnt(1)
	v_mfma_f32_32x32x16_bf16 v[2:17], v[242:245], v[54:57], v[2:17]
	s_waitcnt lgkmcnt(0)
	v_mfma_f32_32x32x16_bf16 v[2:17], v[168:171], v[50:53], v[2:17]
	s_nop 11
	v_mul_f32_e32 v2, v46, v2
	v_mul_f32_e32 v3, v47, v3
	v_cvt_pk_bf16_f32 v2, v2, v3
	v_mul_f32_e32 v3, v48, v4
	v_mul_f32_e32 v4, v49, v5
	v_cvt_pk_bf16_f32 v3, v3, v4
	v_lshl_add_u64 v[4:5], v[106:107], 0, v[0:1]
	global_store_dwordx2 v[4:5], v[2:3], off
	v_mul_f32_e32 v0, v42, v6
	v_mul_f32_e32 v2, v43, v7
	v_mul_f32_e32 v3, v45, v9
	v_cvt_pk_bf16_f32 v2, v0, v2
	v_mul_f32_e32 v0, v44, v8
	v_cvt_pk_bf16_f32 v3, v0, v3
	v_lshl_add_u64 v[4:5], v[106:107], 0, v[104:105]
	global_store_dwordx2 v[4:5], v[2:3], off
	v_mul_f32_e32 v0, v38, v10
	v_mul_f32_e32 v2, v39, v11
	v_mul_f32_e32 v3, v41, v13
	v_cvt_pk_bf16_f32 v2, v0, v2
	v_mul_f32_e32 v0, v40, v12
	v_cvt_pk_bf16_f32 v3, v0, v3
	v_lshl_add_u64 v[4:5], v[106:107], 0, v[108:109]
	global_store_dwordx2 v[4:5], v[2:3], off
	v_mul_f32_e32 v0, v34, v14
	v_mul_f32_e32 v2, v35, v15
	v_mul_f32_e32 v3, v37, v17
	v_lshl_add_u64 v[4:5], v[106:107], 0, v[102:103]
	v_cvt_pk_bf16_f32 v2, v0, v2
	v_mul_f32_e32 v0, v36, v16
	v_cvt_pk_bf16_f32 v3, v0, v3
	global_store_dwordx2 v[4:5], v[2:3], off
	ds_read_b128 v[2:5], v183
	ds_read_b128 v[34:37], v183 offset:32
	ds_read_b128 v[228:231], v183 offset:64
	ds_read_b128 v[242:245], v183 offset:96
	s_waitcnt lgkmcnt(3)
	v_mfma_f32_32x32x16_bf16 v[2:17], v[2:5], v[74:77], 0
	s_waitcnt lgkmcnt(2)
	v_mfma_f32_32x32x16_bf16 v[2:17], v[34:37], v[78:81], v[2:17]
	ds_read_b128 v[34:37], v183 offset:128
	s_waitcnt lgkmcnt(2)
	v_mfma_f32_32x32x16_bf16 v[2:17], v[228:231], v[70:73], v[2:17]
	ds_read_b128 v[228:231], v183 offset:160
	s_waitcnt lgkmcnt(2)
	v_mfma_f32_32x32x16_bf16 v[2:17], v[242:245], v[66:69], v[2:17]
	ds_read_b128 v[242:245], v183 offset:192
	s_waitcnt lgkmcnt(2)
	v_mfma_f32_32x32x16_bf16 v[2:17], v[34:37], v[62:65], v[2:17]
	ds_read_b128 v[34:37], v183 offset:224
	s_waitcnt lgkmcnt(2)
	v_mfma_f32_32x32x16_bf16 v[2:17], v[228:231], v[58:61], v[2:17]
	s_waitcnt lgkmcnt(1)
	v_mfma_f32_32x32x16_bf16 v[2:17], v[242:245], v[54:57], v[2:17]
	s_waitcnt lgkmcnt(0)
	v_mfma_f32_32x32x16_bf16 v[2:17], v[34:37], v[50:53], v[2:17]
	s_nop 11
	v_mul_f32_e32 v0, v30, v2
	v_mul_f32_e32 v2, v31, v3
	v_mul_f32_e32 v3, v33, v5
	v_cvt_pk_bf16_f32 v2, v0, v2
	v_mul_f32_e32 v0, v32, v4
	v_cvt_pk_bf16_f32 v3, v0, v3
	v_lshl_add_u64 v[4:5], v[106:107], 0, v[110:111]
	global_store_dwordx2 v[4:5], v[2:3], off
	v_mul_f32_e32 v0, v26, v6
	v_mul_f32_e32 v2, v27, v7
	v_mul_f32_e32 v3, v29, v9
	v_cvt_pk_bf16_f32 v2, v0, v2
	v_mul_f32_e32 v0, v28, v8
	v_cvt_pk_bf16_f32 v3, v0, v3
	v_lshl_add_u64 v[4:5], v[106:107], 0, v[112:113]
	global_store_dwordx2 v[4:5], v[2:3], off
	v_mul_f32_e32 v0, v22, v10
	v_mul_f32_e32 v2, v23, v11
	v_mul_f32_e32 v3, v25, v13
	v_cvt_pk_bf16_f32 v2, v0, v2
	v_mul_f32_e32 v0, v24, v12
	v_cvt_pk_bf16_f32 v3, v0, v3
	v_lshl_add_u64 v[4:5], v[106:107], 0, v[114:115]
	global_store_dwordx2 v[4:5], v[2:3], off
	v_mul_f32_e32 v0, v18, v14
	v_mul_f32_e32 v2, v19, v15
	v_mul_f32_e32 v3, v21, v17
	v_cvt_pk_bf16_f32 v2, v0, v2
	v_mul_f32_e32 v0, v20, v16
	v_cvt_pk_bf16_f32 v3, v0, v3

.LBB0_215:
	s_or_b64 exec, exec, s[84:85]
	s_waitcnt vmcnt(38)
	v_cndmask_b32_e64 v4, 0, v4, s[8:9]
	s_waitcnt vmcnt(37)
	v_cndmask_b32_e64 v5, 0, v5, s[10:11]
	v_lshlrev_b32_e32 v71, 16, v4
	v_and_b32_e32 v72, 0xffff0000, v4
	s_waitcnt vmcnt(28)
	v_cndmask_b32_e64 v70, 0, v51, s[2:3]
	v_cndmask_b32_e64 v7, 0, v7, s[12:13]
	v_add_f32_e32 v51, 0, v71
	v_add_f32_e32 v4, 0, v72
	v_lshlrev_b32_e32 v73, 16, v5
	v_and_b32_e32 v74, 0xffff0000, v5
	v_cndmask_b32_e64 v8, 0, v8, s[14:15]
	v_add_f32_e32 v51, v51, v73
	v_add_f32_e32 v4, v4, v74
	v_lshlrev_b32_e32 v75, 16, v7
	v_and_b32_e32 v76, 0xffff0000, v7
	v_cndmask_b32_e64 v10, 0, v10, s[16:17]
	v_add_f32_e32 v5, v51, v75
	v_add_f32_e32 v4, v4, v76
	v_lshlrev_b32_e32 v77, 16, v8
	v_and_b32_e32 v78, 0xffff0000, v8
	v_cndmask_b32_e64 v11, 0, v11, s[18:19]
	v_add_f32_e32 v5, v5, v77
	v_add_f32_e32 v4, v4, v78
	v_lshlrev_b32_e32 v79, 16, v10
	v_and_b32_e32 v80, 0xffff0000, v10
	v_cndmask_b32_e64 v13, 0, v13, s[20:21]
	v_add_f32_e32 v5, v5, v79
	v_add_f32_e32 v4, v4, v80
	v_lshlrev_b32_e32 v81, 16, v11
	v_and_b32_e32 v103, 0xffff0000, v11
	s_waitcnt vmcnt(27)
	v_cndmask_b32_e64 v69, 0, v52, s[6:7]
	v_cndmask_b32_e64 v14, 0, v14, s[22:23]
	v_add_f32_e32 v5, v5, v81
	v_add_f32_e32 v4, v4, v103
	v_lshlrev_b32_e32 v104, 16, v13
	v_and_b32_e32 v105, 0xffff0000, v13
	s_waitcnt vmcnt(8)
	v_cndmask_b32_e64 v0, 0, v65, s[62:63]
	v_cndmask_b32_e64 v65, 0, v57, s[68:69]
	v_cndmask_b32_e64 v66, 0, v56, s[28:29]
	v_cndmask_b32_e32 v16, 0, v16, vcc
	v_add_f32_e32 v5, v5, v104
	v_add_f32_e32 v4, v4, v105
	v_lshlrev_b32_e32 v56, 16, v14
	v_and_b32_e32 v57, 0xffff0000, v14
	v_lshlrev_b32_e32 v13, 16, v69
	v_and_b32_e32 v14, 0xffff0000, v69
	v_add_u32_e32 v69, s95, v83
	v_cndmask_b32_e64 v67, 0, v54, s[26:27]
	v_cndmask_b32_e64 v68, 0, v53, s[24:25]
	v_cndmask_b32_e64 v17, 0, v17, s[0:1]
	v_add_f32_e32 v5, v5, v56
	v_add_f32_e32 v4, v4, v57
	v_lshlrev_b32_e32 v53, 16, v16
	v_and_b32_e32 v54, 0xffff0000, v16
	v_min_i32_e32 v69, 15, v69
	v_add_f32_e32 v5, v5, v53
	v_add_f32_e32 v4, v4, v54
	v_lshlrev_b32_e32 v51, 16, v17
	v_and_b32_e32 v52, 0xffff0000, v17
	v_add_u32_e32 v69, 1, v69
	v_add_f32_e32 v5, v5, v51
	v_add_f32_e32 v4, v4, v52
	v_lshlrev_b32_e32 v16, 16, v70
	v_and_b32_e32 v17, 0xffff0000, v70
	v_cvt_f32_i32_e32 v69, v69
	v_add_f32_e32 v5, v5, v16
	v_add_f32_e32 v4, v4, v17
	v_add_f32_e32 v5, v5, v13
	v_add_f32_e32 v4, v4, v14
	v_lshlrev_b32_e32 v10, 16, v68
	v_and_b32_e32 v11, 0xffff0000, v68
	v_add_f32_e32 v5, v5, v10
	v_add_f32_e32 v4, v4, v11
	v_lshlrev_b32_e32 v7, 16, v67
	v_and_b32_e32 v8, 0xffff0000, v67
	v_add_f32_e32 v5, v5, v7
	v_add_f32_e32 v67, v4, v8
	v_lshlrev_b32_e32 v4, 16, v66
	v_rcp_iflag_f32_e32 v69, v69
	v_add_f32_e32 v68, v5, v4
	v_and_b32_e32 v5, 0xffff0000, v66
	v_add_f32_e32 v66, v67, v5
	v_lshlrev_b32_e32 v67, 16, v65
	v_and_b32_e32 v65, 0xffff0000, v65
	v_add_f32_e32 v66, v66, v65
	v_add_f32_e32 v68, v68, v67
	v_fma_f32 v65, v69, v66, -v65
	v_fma_f32 v67, v69, v68, -v67
	v_cvt_pk_bf16_f32 v65, v67, v65
	v_add_u32_e32 v116, 0, v145
	s_waitcnt lgkmcnt(0)
	s_barrier
	ds_write_b32 v116, v65 offset:34816
	v_sub_f32_e32 v65, v68, v71
	v_add_u32_e32 v68, s95, v127
	v_min_i32_e32 v68, 15, v68
	v_add_u32_e32 v68, 1, v68
	v_cvt_f32_i32_e32 v68, v68
	v_cndmask_b32_e64 v59, v59, 0, s[34:35]
	v_sub_f32_e32 v66, v66, v72
	v_lshlrev_b32_e32 v67, 16, v59
	v_rcp_iflag_f32_e32 v68, v68
	v_and_b32_e32 v59, 0xffff0000, v59
	v_add_f32_e32 v65, v65, v67
	v_add_f32_e32 v66, v66, v59
	v_fma_f32 v67, v68, v65, -v67
	v_fma_f32 v59, v68, v66, -v59
	v_cvt_pk_bf16_f32 v59, v67, v59
	v_add_u32_e32 v67, s95, v128
	v_min_i32_e32 v67, 15, v67
	v_add_u32_e32 v67, 1, v67
	v_cvt_f32_i32_e32 v67, v67
	v_cndmask_b32_e64 v60, 0, v60, s[36:37]
	v_add_u32_e32 v117, 0, v146
	ds_write_b32 v117, v59 offset:34816
	v_rcp_iflag_f32_e32 v67, v67
	v_sub_f32_e32 v59, v65, v73
	v_sub_f32_e32 v65, v66, v74
	v_lshlrev_b32_e32 v66, 16, v60
	v_and_b32_e32 v60, 0xffff0000, v60
	v_add_f32_e32 v59, v59, v66
	v_add_f32_e32 v65, v65, v60
	v_fma_f32 v66, v67, v59, -v66
	v_fma_f32 v60, v67, v65, -v60
	v_cvt_pk_bf16_f32 v60, v66, v60
	v_add_u32_e32 v66, s95, v129
	v_min_i32_e32 v66, 15, v66
	v_add_u32_e32 v66, 1, v66
	v_cvt_f32_i32_e32 v66, v66
	v_cndmask_b32_e64 v61, 0, v61, s[38:39]
	v_add_u32_e32 v168, 0, v147
	ds_write_b32 v168, v60 offset:34816
	v_rcp_iflag_f32_e32 v66, v66
	v_sub_f32_e32 v59, v59, v75
	v_sub_f32_e32 v60, v65, v76
	v_lshlrev_b32_e32 v65, 16, v61
	v_and_b32_e32 v61, 0xffff0000, v61
	v_add_f32_e32 v59, v59, v65
	v_add_f32_e32 v60, v60, v61
	v_fma_f32 v65, v66, v59, -v65
	v_fma_f32 v61, v66, v60, -v61
	v_cvt_pk_bf16_f32 v61, v65, v61
	v_add_u32_e32 v65, s95, v130
	v_min_i32_e32 v65, 15, v65
	v_add_u32_e32 v65, 1, v65
	v_cvt_f32_i32_e32 v65, v65
	v_cndmask_b32_e64 v62, 0, v62, s[40:41]
	v_add_u32_e32 v169, 0, v148
	ds_write_b32 v169, v61 offset:34816
	v_rcp_iflag_f32_e32 v65, v65
	v_sub_f32_e32 v59, v59, v77
	v_lshlrev_b32_e32 v61, 16, v62
	v_sub_f32_e32 v60, v60, v78
	v_and_b32_e32 v62, 0xffff0000, v62
	v_add_f32_e32 v59, v59, v61
	v_add_f32_e32 v60, v60, v62
	v_fma_f32 v61, v65, v59, -v61
	v_cndmask_b32_e64 v63, 0, v63, s[42:43]
	v_fma_f32 v62, v65, v60, -v62
	v_cvt_pk_bf16_f32 v61, v61, v62
	v_add_u32_e32 v170, 0, v149
	ds_write_b32 v170, v61 offset:34816
	v_lshlrev_b32_e32 v61, 16, v63
	v_and_b32_e32 v62, 0xffff0000, v63
	v_add_u32_e32 v63, s95, v131
	v_min_i32_e32 v63, 15, v63
	v_add_u32_e32 v63, 1, v63
	v_cvt_f32_i32_e32 v63, v63
	v_sub_f32_e32 v59, v59, v79
	v_sub_f32_e32 v60, v60, v80
	v_add_f32_e32 v59, v59, v61
	v_rcp_iflag_f32_e32 v63, v63
	v_add_f32_e32 v60, v60, v62
	v_cndmask_b32_e64 v64, 0, v64, s[44:45]
	v_add_u32_e32 v171, 0, v150
	v_fma_f32 v61, v63, v59, -v61
	v_fma_f32 v62, v63, v60, -v62
	v_add_u32_e32 v63, s95, v132
	v_min_i32_e32 v63, 15, v63
	v_add_u32_e32 v63, 1, v63
	v_cvt_f32_i32_e32 v63, v63
	v_cvt_pk_bf16_f32 v61, v61, v62
	ds_write_b32 v171, v61 offset:34816
	v_sub_f32_e32 v59, v59, v81
	v_rcp_iflag_f32_e32 v63, v63
	v_sub_f32_e32 v60, v60, v103
	v_lshlrev_b32_e32 v61, 16, v64
	v_and_b32_e32 v62, 0xffff0000, v64
	v_add_f32_e32 v59, v59, v61
	v_add_f32_e32 v60, v60, v62
	v_fma_f32 v61, v63, v59, -v61
	v_fma_f32 v62, v63, v60, -v62
	v_cvt_pk_bf16_f32 v61, v61, v62
	v_add_u32_e32 v62, s95, v133
	v_min_i32_e32 v62, 15, v62
	v_add_u32_e32 v62, 1, v62
	v_cvt_f32_i32_e32 v62, v62
	v_cndmask_b32_e64 v58, 0, v58, s[46:47]
	v_add_u32_e32 v172, 0, v151
	ds_write_b32 v172, v61 offset:34816
	v_rcp_iflag_f32_e32 v62, v62
	v_sub_f32_e32 v59, v59, v104
	v_lshlrev_b32_e32 v61, 16, v58
	v_add_f32_e32 v59, v59, v61
	v_fma_f32 v61, v62, v59, -v61
	v_sub_f32_e32 v56, v59, v56
	v_add_u32_e32 v59, s95, v134
	v_min_i32_e32 v59, 15, v59
	v_add_u32_e32 v59, 1, v59
	v_cvt_f32_i32_e32 v59, v59
	v_sub_f32_e32 v60, v60, v105
	v_and_b32_e32 v58, 0xffff0000, v58
	v_add_f32_e32 v60, v60, v58
	v_fma_f32 v58, v62, v60, -v58
	v_rcp_iflag_f32_e32 v59, v59
	v_cndmask_b32_e64 v55, 0, v55, s[48:49]
	v_cvt_pk_bf16_f32 v58, v61, v58
	v_add_u32_e32 v173, 0, v152
	ds_write_b32 v173, v58 offset:34816
	v_lshlrev_b32_e32 v58, 16, v55
	v_add_f32_e32 v56, v56, v58
	v_fma_f32 v58, v59, v56, -v58
	v_sub_f32_e32 v53, v56, v53
	v_add_u32_e32 v56, s95, v135
	v_min_i32_e32 v56, 15, v56
	v_add_u32_e32 v56, 1, v56
	v_cvt_f32_i32_e32 v56, v56
	v_sub_f32_e32 v57, v60, v57
	v_and_b32_e32 v55, 0xffff0000, v55
	v_add_f32_e32 v57, v57, v55
	v_fma_f32 v55, v59, v57, -v55
	v_rcp_iflag_f32_e32 v56, v56
	v_cndmask_b32_e64 v50, 0, v50, s[50:51]
	v_cvt_pk_bf16_f32 v55, v58, v55
	v_add_u32_e32 v174, 0, v153
	ds_write_b32 v174, v55 offset:34816
	v_sub_f32_e32 v54, v57, v54
	v_lshlrev_b32_e32 v55, 16, v50
	v_and_b32_e32 v50, 0xffff0000, v50
	v_add_f32_e32 v54, v54, v50
	v_add_f32_e32 v53, v53, v55
	v_fma_f32 v50, v56, v54, -v50
	v_fma_f32 v55, v56, v53, -v55
	v_cvt_pk_bf16_f32 v50, v55, v50
	v_add_u32_e32 v175, 0, v154
	ds_write_b32 v175, v50 offset:34816
	v_sub_f32_e32 v50, v53, v51
	v_add_u32_e32 v53, s95, v136
	v_min_i32_e32 v53, 15, v53
	v_add_u32_e32 v53, 1, v53
	v_cvt_f32_i32_e32 v53, v53
	v_cndmask_b32_e64 v15, 0, v15, s[52:53]
	v_sub_f32_e32 v51, v54, v52
	v_lshlrev_b32_e32 v52, 16, v15
	v_rcp_iflag_f32_e32 v53, v53
	v_and_b32_e32 v15, 0xffff0000, v15
	v_add_f32_e32 v51, v51, v15
	v_add_f32_e32 v50, v50, v52
	v_fma_f32 v15, v53, v51, -v15
	v_fma_f32 v52, v53, v50, -v52
	v_cvt_pk_bf16_f32 v15, v52, v15
	v_add_u32_e32 v176, 0, v155
	ds_write_b32 v176, v15 offset:34816
	v_sub_f32_e32 v15, v50, v16
	v_add_u32_e32 v50, s95, v137
	v_min_i32_e32 v50, 15, v50
	v_add_u32_e32 v50, 1, v50
	v_cvt_f32_i32_e32 v50, v50
	v_cndmask_b32_e64 v12, 0, v12, s[54:55]
	v_sub_f32_e32 v16, v51, v17
	v_lshlrev_b32_e32 v17, 16, v12
	v_rcp_iflag_f32_e32 v50, v50
	v_and_b32_e32 v12, 0xffff0000, v12
	v_add_f32_e32 v16, v16, v12
	v_add_f32_e32 v15, v15, v17
	v_fma_f32 v12, v50, v16, -v12
	v_fma_f32 v17, v50, v15, -v17
	v_cvt_pk_bf16_f32 v12, v17, v12
	v_add_u32_e32 v177, 0, v156
	ds_write_b32 v177, v12 offset:34816
	v_sub_f32_e32 v12, v15, v13
	v_add_u32_e32 v15, s95, v138
	v_min_i32_e32 v15, 15, v15
	v_add_u32_e32 v15, 1, v15
	v_cvt_f32_i32_e32 v15, v15
	v_cndmask_b32_e64 v9, 0, v9, s[56:57]
	v_sub_f32_e32 v13, v16, v14
	v_lshlrev_b32_e32 v14, 16, v9
	v_rcp_iflag_f32_e32 v15, v15
	v_and_b32_e32 v9, 0xffff0000, v9
	v_add_f32_e32 v13, v13, v9
	v_add_f32_e32 v12, v12, v14
	v_fma_f32 v9, v15, v13, -v9
	v_fma_f32 v14, v15, v12, -v14
	v_cvt_pk_bf16_f32 v9, v14, v9
	v_add_u32_e32 v178, 0, v157
	ds_write_b32 v178, v9 offset:34816
	v_sub_f32_e32 v9, v12, v10
	v_add_u32_e32 v12, s95, v139
	v_min_i32_e32 v12, 15, v12
	v_add_u32_e32 v12, 1, v12
	v_cvt_f32_i32_e32 v12, v12
	v_cndmask_b32_e64 v6, 0, v6, s[58:59]
	v_sub_f32_e32 v10, v13, v11
	v_lshlrev_b32_e32 v11, 16, v6
	v_rcp_iflag_f32_e32 v12, v12
	v_and_b32_e32 v6, 0xffff0000, v6
	v_add_f32_e32 v10, v10, v6
	v_add_f32_e32 v9, v9, v11
	v_fma_f32 v6, v12, v10, -v6
	v_fma_f32 v11, v12, v9, -v11
	v_cvt_pk_bf16_f32 v6, v11, v6
	v_add_u32_e32 v179, 0, v158
	ds_write_b32 v179, v6 offset:34816
	v_sub_f32_e32 v6, v9, v7
	v_add_u32_e32 v9, s95, v140
	v_min_i32_e32 v9, 15, v9
	v_add_u32_e32 v9, 1, v9
	v_cvt_f32_i32_e32 v9, v9
	v_cndmask_b32_e64 v3, 0, v3, s[60:61]
	v_sub_f32_e32 v7, v10, v8
	v_lshlrev_b32_e32 v8, 16, v3
	v_rcp_iflag_f32_e32 v9, v9
	v_and_b32_e32 v3, 0xffff0000, v3
	v_add_f32_e32 v7, v7, v3
	v_add_f32_e32 v6, v6, v8
	v_fma_f32 v3, v9, v7, -v3
	v_fma_f32 v8, v9, v6, -v8
	v_cvt_pk_bf16_f32 v3, v8, v3
	v_add_u32_e32 v180, 0, v159
	ds_write_b32 v180, v3 offset:34816
	v_sub_f32_e32 v3, v6, v4
	v_add_u32_e32 v6, s95, v141
	v_min_i32_e32 v6, 15, v6
	v_add_u32_e32 v6, 1, v6
	v_cvt_f32_i32_e32 v6, v6
	v_sub_f32_e32 v4, v7, v5
	v_lshlrev_b32_e32 v5, 16, v0
	v_and_b32_e32 v0, 0xffff0000, v0
	v_rcp_iflag_f32_e32 v6, v6
	s_or_b32 s0, s94, 0x80
	v_add_f32_e32 v3, v3, v5
	v_add_f32_e32 v4, v4, v0
	s_xor_b32 s1, s95, 0xffffff7f
	s_mul_i32 s2, s0, 0x1e00
	v_fma_f32 v3, v6, v3, -v5
	v_fma_f32 v0, v6, v4, -v0
	s_mul_hi_i32 s3, s0, 0x1e00
	s_add_u32 s2, s91, s2
	v_cvt_pk_bf16_f32 v0, v3, v0
	s_addc_u32 s3, s92, s3
	v_mov_b32_e32 v3, v1
	v_add_u32_e32 v181, 0, v160
	v_cmp_lt_i32_e32 vcc, s1, v141
	v_lshl_add_u64 v[2:3], s[2:3], 0, v[2:3]
	s_mov_b64 s[2:3], 0x1720
	ds_write_b32 v181, v0 offset:34816
	v_lshl_add_u64 v[2:3], v[2:3], 0, s[2:3]
	v_cndmask_b32_e32 v0, 0, v141, vcc
	s_movk_i32 s6, 0x1e00
	v_mad_i64_i32 v[4:5], s[2:3], v0, s6, v[2:3]
	global_load_dword v0, v[4:5], off
	v_add_u32_e32 v185, v144, v143
	v_add_u32_e32 v183, v144, v161
	v_lshlrev_b32_e32 v104, 1, v90
	v_mov_b32_e32 v105, v1
	v_mov_b32_e32 v103, v1
	v_add_u32_e32 v184, v144, v163
	v_lshlrev_b32_e32 v114, 1, v98
	v_mov_b32_e32 v115, v1
	v_readlane_b32 s56, v253, 1
	s_mov_b64 s[8:9], 0
	v_readlane_b32 s58, v253, 3
	s_movk_i32 s56, 0x5ff
	s_mov_b32 s61, 0xf800000
	v_readlane_b32 s57, v253, 2
	v_readlane_b32 s59, v253, 4
	s_waitcnt vmcnt(0)
	v_cndmask_b32_e32 v182, 0, v0, vcc
	v_cmp_lt_i32_e32 vcc, s1, v85
	v_mov_b32_e32 v209, 0
	s_nop 0
	v_cndmask_b32_e32 v0, 0, v85, vcc
	v_mad_i64_i32 v[4:5], s[2:3], v0, s6, v[2:3]
	s_and_saveexec_b64 s[98:99], vcc
	global_load_dword v209, v[4:5], off
	s_mov_b64 exec, s[98:99]
	v_cmp_lt_i32_e32 vcc, s1, v91
	v_mov_b32_e32 v211, 0
	s_nop 0
	v_cndmask_b32_e32 v0, 0, v91, vcc
	v_mad_i64_i32 v[4:5], s[2:3], v0, s6, v[2:3]
	s_and_saveexec_b64 s[98:99], vcc
	global_load_dword v211, v[4:5], off
	s_mov_b64 exec, s[98:99]
	v_cmp_lt_i32_e32 vcc, s1, v93
	v_mov_b32_e32 v212, 0
	s_nop 0
	v_cndmask_b32_e32 v0, 0, v93, vcc
	v_mad_i64_i32 v[4:5], s[2:3], v0, s6, v[2:3]
	s_and_saveexec_b64 s[98:99], vcc
	global_load_dword v212, v[4:5], off
	s_mov_b64 exec, s[98:99]
	v_cmp_lt_i32_e32 vcc, s1, v95
	v_mov_b32_e32 v213, 0
	s_nop 0
	v_cndmask_b32_e32 v0, 0, v95, vcc
	v_mad_i64_i32 v[4:5], s[2:3], v0, s6, v[2:3]
	s_and_saveexec_b64 s[98:99], vcc
	global_load_dword v213, v[4:5], off
	s_mov_b64 exec, s[98:99]
	v_cmp_lt_i32_e32 vcc, s1, v97
	v_mov_b32_e32 v214, 0
	s_nop 0
	v_cndmask_b32_e32 v0, 0, v97, vcc
	v_mad_i64_i32 v[4:5], s[2:3], v0, s6, v[2:3]
	s_and_saveexec_b64 s[98:99], vcc
	global_load_dword v214, v[4:5], off
	s_mov_b64 exec, s[98:99]
	v_cmp_lt_i32_e32 vcc, s1, v99
	v_mov_b32_e32 v215, 0
	s_nop 0
	v_cndmask_b32_e32 v0, 0, v99, vcc
	v_mad_i64_i32 v[4:5], s[2:3], v0, s6, v[2:3]
	s_and_saveexec_b64 s[98:99], vcc
	global_load_dword v215, v[4:5], off
	s_mov_b64 exec, s[98:99]
	v_cmp_lt_i32_e32 vcc, s1, v101
	v_mov_b32_e32 v217, 0
	s_nop 0
	v_cndmask_b32_e32 v0, 0, v101, vcc
	v_mad_i64_i32 v[4:5], s[2:3], v0, s6, v[2:3]
	s_and_saveexec_b64 s[98:99], vcc
	global_load_dword v217, v[4:5], off
	s_mov_b64 exec, s[98:99]
	v_cmp_lt_i32_e32 vcc, s1, v119
	v_mov_b32_e32 v218, 0
	s_nop 0
	v_cndmask_b32_e32 v0, 0, v119, vcc
	v_mad_i64_i32 v[4:5], s[2:3], v0, s6, v[2:3]
	s_and_saveexec_b64 s[98:99], vcc
	global_load_dword v218, v[4:5], off
	s_mov_b64 exec, s[98:99]
	v_cmp_lt_i32_e32 vcc, s1, v120
	v_mov_b32_e32 v219, 0
	s_nop 0
	v_cndmask_b32_e32 v0, 0, v120, vcc
	v_mad_i64_i32 v[4:5], s[2:3], v0, s6, v[2:3]
	s_and_saveexec_b64 s[98:99], vcc
	global_load_dword v219, v[4:5], off
	s_mov_b64 exec, s[98:99]
	v_cmp_lt_i32_e32 vcc, s1, v121
	v_mov_b32_e32 v220, 0
	s_nop 0
	v_cndmask_b32_e32 v0, 0, v121, vcc
	v_mad_i64_i32 v[4:5], s[2:3], v0, s6, v[2:3]
	s_and_saveexec_b64 s[98:99], vcc
	global_load_dword v220, v[4:5], off
	s_mov_b64 exec, s[98:99]
	v_cmp_lt_i32_e32 vcc, s1, v122
	v_mov_b32_e32 v221, 0
	s_nop 0
	v_cndmask_b32_e32 v0, 0, v122, vcc
	v_mad_i64_i32 v[4:5], s[2:3], v0, s6, v[2:3]
	s_and_saveexec_b64 s[98:99], vcc
	global_load_dword v221, v[4:5], off
	s_mov_b64 exec, s[98:99]
	v_cmp_lt_i32_e32 vcc, s1, v123
	v_mov_b32_e32 v223, 0
	s_nop 0
	v_cndmask_b32_e32 v0, 0, v123, vcc
	v_mad_i64_i32 v[4:5], s[2:3], v0, s6, v[2:3]
	s_and_saveexec_b64 s[98:99], vcc
	global_load_dword v223, v[4:5], off
	s_mov_b64 exec, s[98:99]
	v_cmp_lt_i32_e32 vcc, s1, v124
	v_mov_b32_e32 v224, 0
	s_nop 0
	v_cndmask_b32_e32 v0, 0, v124, vcc
	v_mad_i64_i32 v[4:5], s[2:3], v0, s6, v[2:3]
	s_and_saveexec_b64 s[98:99], vcc
	global_load_dword v224, v[4:5], off
	s_mov_b64 exec, s[98:99]
	v_cmp_lt_i32_e32 vcc, s1, v125
	v_mov_b32_e32 v225, 0
	s_nop 0
	v_cndmask_b32_e32 v0, 0, v125, vcc
	v_mad_i64_i32 v[4:5], s[2:3], v0, s6, v[2:3]
	s_and_saveexec_b64 s[98:99], vcc
	global_load_dword v225, v[4:5], off
	s_mov_b64 exec, s[98:99]
	v_cmp_lt_i32_e32 vcc, s1, v126
	v_mov_b32_e32 v227, 0
	s_nop 0
	v_cndmask_b32_e32 v0, 0, v126, vcc
	v_mad_i64_i32 v[4:5], s[2:3], v0, s6, v[2:3]
	s_and_saveexec_b64 s[98:99], vcc
	global_load_dword v227, v[4:5], off
	s_mov_b64 exec, s[98:99]
	v_cmp_lt_i32_e32 vcc, s1, v83
	v_mov_b32_e32 v226, 0
	s_nop 0
	v_cndmask_b32_e32 v0, 0, v83, vcc
	v_mad_i64_i32 v[4:5], s[2:3], v0, s6, v[2:3]
	s_and_saveexec_b64 s[98:99], vcc
	global_load_dword v226, v[4:5], off
	s_mov_b64 exec, s[98:99]
	v_cmp_gt_i32_e32 vcc, s1, v83
	s_nop 1
	v_cndmask_b32_e64 v0, v127, 0, vcc
	v_mad_i64_i32 v[4:5], s[2:3], v0, s6, v[2:3]
	global_load_dword v0, v[4:5], off
	s_waitcnt vmcnt(0)
	v_cndmask_b32_e64 v222, v0, 0, vcc
	v_cmp_lt_i32_e32 vcc, s1, v128
	v_mov_b32_e32 v216, 0
	s_nop 0
	v_cndmask_b32_e32 v0, 0, v128, vcc
	v_mad_i64_i32 v[4:5], s[2:3], v0, s6, v[2:3]
	s_and_saveexec_b64 s[98:99], vcc
	global_load_dword v216, v[4:5], off
	s_mov_b64 exec, s[98:99]
	v_cmp_lt_i32_e32 vcc, s1, v129
	v_mov_b32_e32 v210, 0
	s_nop 0
	v_cndmask_b32_e32 v0, 0, v129, vcc
	v_mad_i64_i32 v[4:5], s[2:3], v0, s6, v[2:3]
	s_and_saveexec_b64 s[98:99], vcc
	global_load_dword v210, v[4:5], off
	s_mov_b64 exec, s[98:99]
	v_cmp_lt_i32_e32 vcc, s1, v130
	v_mov_b32_e32 v208, 0
	s_nop 0
	v_cndmask_b32_e32 v0, 0, v130, vcc
	v_mad_i64_i32 v[4:5], s[2:3], v0, s6, v[2:3]
	s_and_saveexec_b64 s[98:99], vcc
	global_load_dword v208, v[4:5], off
	s_mov_b64 exec, s[98:99]
	v_cmp_lt_i32_e32 vcc, s1, v131
	v_mov_b32_e32 v207, 0
	s_nop 0
	v_cndmask_b32_e32 v0, 0, v131, vcc
	v_mad_i64_i32 v[4:5], s[2:3], v0, s6, v[2:3]
	s_and_saveexec_b64 s[98:99], vcc
	global_load_dword v207, v[4:5], off
	s_mov_b64 exec, s[98:99]
	v_cmp_lt_i32_e32 vcc, s1, v132
	v_mov_b32_e32 v206, 0
	s_nop 0
	v_cndmask_b32_e32 v0, 0, v132, vcc
	v_mad_i64_i32 v[4:5], s[2:3], v0, s6, v[2:3]
	s_and_saveexec_b64 s[98:99], vcc
	global_load_dword v206, v[4:5], off
	s_mov_b64 exec, s[98:99]
	v_cmp_lt_i32_e32 vcc, s1, v133
	v_mov_b32_e32 v205, 0
	s_nop 0
	v_cndmask_b32_e32 v0, 0, v133, vcc
	v_mad_i64_i32 v[4:5], s[2:3], v0, s6, v[2:3]
	s_and_saveexec_b64 s[98:99], vcc
	global_load_dword v205, v[4:5], off
	s_mov_b64 exec, s[98:99]
	v_cmp_lt_i32_e32 vcc, s1, v134
	v_mov_b32_e32 v204, 0
	s_nop 0
	v_cndmask_b32_e32 v0, 0, v134, vcc
	v_mad_i64_i32 v[4:5], s[2:3], v0, s6, v[2:3]
	s_and_saveexec_b64 s[98:99], vcc
	global_load_dword v204, v[4:5], off
	s_mov_b64 exec, s[98:99]
	v_cmp_lt_i32_e32 vcc, s1, v135
	v_mov_b32_e32 v192, 0
	s_nop 0
	v_cndmask_b32_e32 v0, 0, v135, vcc
	v_mad_i64_i32 v[4:5], s[2:3], v0, s6, v[2:3]
	s_and_saveexec_b64 s[98:99], vcc
	global_load_dword v192, v[4:5], off
	s_mov_b64 exec, s[98:99]
	v_cmp_lt_i32_e32 vcc, s1, v136
	v_mov_b32_e32 v190, 0
	s_nop 0
	v_cndmask_b32_e32 v0, 0, v136, vcc
	v_mad_i64_i32 v[4:5], s[2:3], v0, s6, v[2:3]
	s_and_saveexec_b64 s[98:99], vcc
	global_load_dword v190, v[4:5], off
	s_mov_b64 exec, s[98:99]
	v_cmp_lt_i32_e32 vcc, s1, v137
	v_mov_b32_e32 v189, 0
	s_nop 0
	v_cndmask_b32_e32 v0, 0, v137, vcc
	v_mad_i64_i32 v[4:5], s[2:3], v0, s6, v[2:3]
	s_and_saveexec_b64 s[98:99], vcc
	global_load_dword v189, v[4:5], off
	s_mov_b64 exec, s[98:99]
	v_cmp_lt_i32_e32 vcc, s1, v138
	v_mov_b32_e32 v188, 0
	s_nop 0
	v_cndmask_b32_e32 v0, 0, v138, vcc
	v_mad_i64_i32 v[4:5], s[2:3], v0, s6, v[2:3]
	s_and_saveexec_b64 s[98:99], vcc
	global_load_dword v188, v[4:5], off
	s_mov_b64 exec, s[98:99]
	v_cmp_lt_i32_e32 vcc, s1, v139
	v_mov_b32_e32 v187, 0
	s_nop 0
	v_cndmask_b32_e32 v0, 0, v139, vcc
	v_mad_i64_i32 v[4:5], s[2:3], v0, s6, v[2:3]
	s_and_saveexec_b64 s[98:99], vcc
	global_load_dword v187, v[4:5], off
	s_mov_b64 exec, s[98:99]
	v_cmp_lt_i32_e32 vcc, s1, v140
	s_and_b32 s1, s0, 0xf80
	s_nop 0
	v_cndmask_b32_e32 v0, 0, v140, vcc
	v_mad_i64_i32 v[2:3], s[2:3], v0, s6, v[2:3]
	global_load_dword v0, v[2:3], off
	v_add_u32_e32 v2, s94, v142
	v_ashrrev_i32_e32 v3, 31, v2
	v_lshlrev_b64 v[2:3], 12, v[2:3]
	s_waitcnt lgkmcnt(0)
	s_barrier
	v_lshl_add_u64 v[2:3], s[70:71], 0, v[2:3]
	s_mov_b64 s[2:3], 0x26000b00
	ds_read_b128 v[74:77], v185 offset:34816
	ds_read_b128 v[78:81], v185 offset:34848
	ds_read_b128 v[70:73], v185 offset:34880
	ds_read_b128 v[66:69], v185 offset:34912
	ds_read_b128 v[62:65], v185 offset:34944
	ds_read_b128 v[58:61], v185 offset:34976
	ds_read_b128 v[54:57], v185 offset:35008
	ds_read_b128 v[50:53], v185 offset:35040
	v_lshl_add_u64 v[106:107], v[2:3], 0, s[2:3]
	ds_read_b128 v[2:5], v183
	ds_read_b128 v[108:111], v183 offset:32
	ds_read_b128 v[228:231], v183 offset:64
	ds_read_b128 v[242:245], v183 offset:96
	s_waitcnt lgkmcnt(3)
	v_mfma_f32_32x32x16_bf16 v[2:17], v[2:5], v[74:77], 0
	s_waitcnt vmcnt(0)
	v_cndmask_b32_e32 v186, 0, v0, vcc
	s_waitcnt lgkmcnt(2)
	v_mfma_f32_32x32x16_bf16 v[2:17], v[108:111], v[78:81], v[2:17]
	ds_read_b128 v[108:111], v183 offset:128
	s_waitcnt lgkmcnt(2)
	v_mfma_f32_32x32x16_bf16 v[2:17], v[228:231], v[70:73], v[2:17]
	ds_read_b128 v[228:231], v183 offset:160
	s_waitcnt lgkmcnt(2)
	v_mfma_f32_32x32x16_bf16 v[2:17], v[242:245], v[66:69], v[2:17]
	ds_read_b128 v[242:245], v183 offset:192
	s_waitcnt lgkmcnt(2)
	v_mfma_f32_32x32x16_bf16 v[2:17], v[108:111], v[62:65], v[2:17]
	ds_read_b128 v[108:111], v183 offset:224
	s_waitcnt lgkmcnt(2)
	v_mfma_f32_32x32x16_bf16 v[2:17], v[228:231], v[58:61], v[2:17]
	s_waitcnt lgkmcnt(1)
	v_mfma_f32_32x32x16_bf16 v[2:17], v[242:245], v[54:57], v[2:17]
	s_waitcnt lgkmcnt(0)
	v_mfma_f32_32x32x16_bf16 v[2:17], v[108:111], v[50:53], v[2:17]
	v_lshlrev_b32_e32 v108, 1, v92
	v_mov_b32_e32 v109, v1
	s_nop 9
	v_mul_f32_e32 v0, v46, v2
	v_mul_f32_e32 v2, v47, v3
	v_cvt_pk_bf16_f32 v2, v0, v2
	v_mul_f32_e32 v0, v48, v4
	v_mul_f32_e32 v3, v49, v5
	v_cvt_pk_bf16_f32 v3, v0, v3
	v_lshlrev_b32_e32 v0, 1, v88
	v_lshl_add_u64 v[4:5], v[106:107], 0, v[0:1]
	global_store_dwordx2 v[4:5], v[2:3], off
	v_mul_f32_e32 v2, v42, v6
	v_mul_f32_e32 v3, v43, v7
	v_cvt_pk_bf16_f32 v2, v2, v3
	v_mul_f32_e32 v3, v44, v8
	v_mul_f32_e32 v4, v45, v9
	v_cvt_pk_bf16_f32 v3, v3, v4
	v_lshl_add_u64 v[4:5], v[106:107], 0, v[104:105]
	global_store_dwordx2 v[4:5], v[2:3], off
	v_mul_f32_e32 v2, v38, v10
	v_mul_f32_e32 v3, v39, v11
	v_cvt_pk_bf16_f32 v2, v2, v3
	v_mul_f32_e32 v3, v40, v12
	v_mul_f32_e32 v4, v41, v13
	v_cvt_pk_bf16_f32 v3, v3, v4
	v_lshl_add_u64 v[4:5], v[106:107], 0, v[108:109]
	global_store_dwordx2 v[4:5], v[2:3], off
	v_mul_f32_e32 v2, v34, v14
	v_mul_f32_e32 v3, v35, v15
	v_cvt_pk_bf16_f32 v2, v2, v3
	v_mul_f32_e32 v3, v36, v16
	v_mul_f32_e32 v4, v37, v17
	v_cvt_pk_bf16_f32 v3, v3, v4
	v_lshl_add_u64 v[4:5], v[106:107], 0, v[102:103]
	global_store_dwordx2 v[4:5], v[2:3], off
	ds_read_b128 v[2:5], v184
	ds_read_b128 v[110:113], v184 offset:32
	s_waitcnt lgkmcnt(1)
	v_mfma_f32_32x32x16_bf16 v[2:17], v[2:5], v[74:77], 0
	ds_read_b128 v[74:77], v184 offset:64
	s_waitcnt lgkmcnt(1)
	v_mfma_f32_32x32x16_bf16 v[2:17], v[110:113], v[78:81], v[2:17]
	v_lshlrev_b32_e32 v110, 1, v94
	v_mov_b32_e32 v111, v1
	v_lshlrev_b32_e32 v112, 1, v96
	v_mov_b32_e32 v113, v1
	s_waitcnt lgkmcnt(0)
	v_mfma_f32_32x32x16_bf16 v[2:17], v[74:77], v[70:73], v[2:17]
	ds_read_b128 v[70:73], v184 offset:96
	s_waitcnt lgkmcnt(0)
	v_mfma_f32_32x32x16_bf16 v[2:17], v[70:73], v[66:69], v[2:17]
	ds_read_b128 v[66:69], v184 offset:128
	s_waitcnt lgkmcnt(0)
	v_mfma_f32_32x32x16_bf16 v[2:17], v[66:69], v[62:65], v[2:17]
	ds_read_b128 v[62:65], v184 offset:160
	v_add_u32_e32 v68, s1, v83
	v_min_i32_e32 v68, 15, v68
	v_add_u32_e32 v68, 1, v68
	v_cvt_f32_i32_e32 v68, v68
	v_lshlrev_b32_e32 v66, 16, v226
	v_and_b32_e32 v67, 0xffff0000, v226
	s_waitcnt lgkmcnt(0)
	v_mfma_f32_32x32x16_bf16 v[2:17], v[62:65], v[58:61], v[2:17]
	ds_read_b128 v[58:61], v184 offset:192
	v_lshlrev_b32_e32 v62, 16, v217
	v_and_b32_e32 v63, 0xffff0000, v217
	v_rcp_iflag_f32_e32 v68, v68
	s_waitcnt lgkmcnt(0)
	v_mfma_f32_32x32x16_bf16 v[2:17], v[58:61], v[54:57], v[2:17]
	ds_read_b128 v[54:57], v184 offset:224
	v_lshlrev_b32_e32 v58, 16, v214
	v_and_b32_e32 v59, 0xffff0000, v214
	v_lshlrev_b32_e32 v60, 16, v215
	v_and_b32_e32 v61, 0xffff0000, v215
	s_waitcnt lgkmcnt(0)
	v_mfma_f32_32x32x16_bf16 v[2:17], v[54:57], v[50:53], v[2:17]
	v_lshlrev_b32_e32 v50, 16, v209
	v_and_b32_e32 v51, 0xffff0000, v209
	v_lshlrev_b32_e32 v52, 16, v211
	v_and_b32_e32 v53, 0xffff0000, v211
	v_lshlrev_b32_e32 v54, 16, v212
	v_and_b32_e32 v55, 0xffff0000, v212
	v_lshlrev_b32_e32 v56, 16, v213
	s_nop 4
	v_mul_f32_e32 v2, v30, v2
	v_mul_f32_e32 v3, v31, v3
	v_cvt_pk_bf16_f32 v2, v2, v3
	v_mul_f32_e32 v3, v32, v4
	v_mul_f32_e32 v4, v33, v5
	v_cvt_pk_bf16_f32 v3, v3, v4
	v_lshl_add_u64 v[4:5], v[106:107], 0, v[110:111]
	global_store_dwordx2 v[4:5], v[2:3], off
	v_mul_f32_e32 v2, v26, v6
	v_mul_f32_e32 v3, v27, v7
	v_cvt_pk_bf16_f32 v2, v2, v3
	v_mul_f32_e32 v3, v28, v8
	v_mul_f32_e32 v4, v29, v9
	v_cvt_pk_bf16_f32 v3, v3, v4
	v_lshl_add_u64 v[4:5], v[106:107], 0, v[112:113]
	global_store_dwordx2 v[4:5], v[2:3], off
	v_mul_f32_e32 v2, v22, v10
	v_mul_f32_e32 v3, v23, v11
	v_cvt_pk_bf16_f32 v2, v2, v3
	v_mul_f32_e32 v3, v24, v12
	v_mul_f32_e32 v4, v25, v13
	v_cvt_pk_bf16_f32 v3, v3, v4
	v_lshl_add_u64 v[4:5], v[106:107], 0, v[114:115]
	global_store_dwordx2 v[4:5], v[2:3], off
	v_mul_f32_e32 v2, v18, v14
	v_mul_f32_e32 v3, v19, v15
	v_cvt_pk_bf16_f32 v2, v2, v3
	v_mul_f32_e32 v3, v20, v16
	v_mul_f32_e32 v4, v21, v17
	v_cvt_pk_bf16_f32 v3, v3, v4
	v_lshlrev_b32_e32 v4, 1, v100
	v_mov_b32_e32 v5, v1
	v_lshl_add_u64 v[4:5], v[106:107], 0, v[4:5]
	global_store_dwordx2 v[4:5], v[2:3], off
	v_add_f32_e32 v2, 0, v50
	v_add_f32_e32 v3, 0, v51
	v_add_f32_e32 v2, v2, v52
	v_add_f32_e32 v3, v3, v53
	v_add_f32_e32 v2, v2, v54
	v_add_f32_e32 v3, v3, v55
	v_add_f32_e32 v2, v2, v56
	v_and_b32_e32 v57, 0xffff0000, v213
	v_add_f32_e32 v3, v3, v57
	v_add_f32_e32 v2, v2, v58
	v_add_f32_e32 v3, v3, v59
	v_add_f32_e32 v2, v2, v60
	v_add_f32_e32 v3, v3, v61
	v_add_f32_e32 v2, v2, v62
	v_lshlrev_b32_e32 v16, 16, v218
	v_add_f32_e32 v3, v3, v63
	v_add_f32_e32 v2, v2, v16
	v_and_b32_e32 v17, 0xffff0000, v218
	v_lshlrev_b32_e32 v14, 16, v219
	v_add_f32_e32 v3, v3, v17
	v_add_f32_e32 v2, v2, v14
	v_and_b32_e32 v15, 0xffff0000, v219
	v_lshlrev_b32_e32 v12, 16, v220
	v_add_f32_e32 v3, v3, v15
	v_add_f32_e32 v2, v2, v12
	v_and_b32_e32 v13, 0xffff0000, v220
	v_lshlrev_b32_e32 v10, 16, v221
	v_add_f32_e32 v3, v3, v13
	v_add_f32_e32 v2, v2, v10
	v_and_b32_e32 v11, 0xffff0000, v221
	v_lshlrev_b32_e32 v8, 16, v223
	v_add_f32_e32 v3, v3, v11
	v_add_f32_e32 v2, v2, v8
	v_and_b32_e32 v9, 0xffff0000, v223
	v_lshlrev_b32_e32 v6, 16, v224
	v_add_f32_e32 v3, v3, v9
	v_add_f32_e32 v2, v2, v6
	v_and_b32_e32 v7, 0xffff0000, v224
	v_lshlrev_b32_e32 v4, 16, v225
	v_add_f32_e32 v3, v3, v7
	v_add_f32_e32 v64, v2, v4
	v_and_b32_e32 v5, 0xffff0000, v225
	v_lshlrev_b32_e32 v2, 16, v227
	v_add_f32_e32 v65, v3, v5
	v_add_f32_e32 v64, v64, v2
	v_and_b32_e32 v3, 0xffff0000, v227
	v_add_f32_e32 v65, v65, v3
	v_add_f32_e32 v64, v64, v66
	v_add_f32_e32 v65, v65, v67
	v_fma_f32 v66, v68, v64, -v66
	v_fma_f32 v67, v68, v65, -v67
	v_cvt_pk_bf16_f32 v66, v66, v67
	s_waitcnt lgkmcnt(0)
	s_barrier
	ds_write_b32 v116, v66 offset:34816
	v_add_u32_e32 v66, s1, v127
	v_min_i32_e32 v66, 15, v66
	v_add_u32_e32 v66, 1, v66
	v_cvt_f32_i32_e32 v66, v66
	v_sub_f32_e32 v50, v64, v50
	v_lshlrev_b32_e32 v64, 16, v222
	v_sub_f32_e32 v51, v65, v51
	v_rcp_iflag_f32_e32 v66, v66
	v_and_b32_e32 v65, 0xffff0000, v222
	v_add_f32_e32 v50, v50, v64
	v_add_f32_e32 v51, v51, v65
	v_fma_f32 v64, v66, v50, -v64
	v_fma_f32 v65, v66, v51, -v65
	v_cvt_pk_bf16_f32 v64, v64, v65
	ds_write_b32 v117, v64 offset:34816
	v_add_u32_e32 v64, s1, v128
	v_min_i32_e32 v64, 15, v64
	v_add_u32_e32 v64, 1, v64
	v_cvt_f32_i32_e32 v64, v64
	v_sub_f32_e32 v50, v50, v52
	v_lshlrev_b32_e32 v52, 16, v216
	v_add_f32_e32 v50, v50, v52
	v_rcp_iflag_f32_e32 v64, v64
	v_sub_f32_e32 v51, v51, v53
	v_and_b32_e32 v53, 0xffff0000, v216
	v_add_f32_e32 v51, v51, v53
	v_fma_f32 v52, v64, v50, -v52
	v_sub_f32_e32 v50, v50, v54
	v_add_u32_e32 v54, s1, v129
	v_min_i32_e32 v54, 15, v54
	v_add_u32_e32 v54, 1, v54
	v_cvt_f32_i32_e32 v54, v54
	v_fma_f32 v53, v64, v51, -v53
	v_cvt_pk_bf16_f32 v52, v52, v53
	ds_write_b32 v168, v52 offset:34816
	v_rcp_iflag_f32_e32 v54, v54
	v_sub_f32_e32 v51, v51, v55
	v_lshlrev_b32_e32 v52, 16, v210
	v_and_b32_e32 v53, 0xffff0000, v210
	v_add_f32_e32 v50, v50, v52
	v_add_f32_e32 v51, v51, v53
	v_fma_f32 v52, v54, v50, -v52
	v_fma_f32 v53, v54, v51, -v53
	v_add_u32_e32 v54, s1, v130
	v_min_i32_e32 v54, 15, v54
	v_add_u32_e32 v54, 1, v54
	v_cvt_f32_i32_e32 v54, v54
	v_cvt_pk_bf16_f32 v52, v52, v53
	ds_write_b32 v169, v52 offset:34816
	v_sub_f32_e32 v50, v50, v56
	v_rcp_iflag_f32_e32 v54, v54
	v_sub_f32_e32 v51, v51, v57
	v_lshlrev_b32_e32 v52, 16, v208
	v_and_b32_e32 v53, 0xffff0000, v208
	v_add_f32_e32 v50, v50, v52
	v_add_f32_e32 v51, v51, v53
	v_fma_f32 v52, v54, v50, -v52
	v_fma_f32 v53, v54, v51, -v53
	v_add_u32_e32 v54, s1, v131
	v_min_i32_e32 v54, 15, v54
	v_add_u32_e32 v54, 1, v54
	v_cvt_f32_i32_e32 v54, v54
	v_cvt_pk_bf16_f32 v52, v52, v53
	ds_write_b32 v170, v52 offset:34816
	v_sub_f32_e32 v50, v50, v58
	v_rcp_iflag_f32_e32 v54, v54
	v_sub_f32_e32 v51, v51, v59
	v_lshlrev_b32_e32 v52, 16, v207
	v_and_b32_e32 v53, 0xffff0000, v207
	v_add_f32_e32 v50, v50, v52
	v_add_f32_e32 v51, v51, v53
	v_fma_f32 v52, v54, v50, -v52
	v_fma_f32 v53, v54, v51, -v53
	v_add_u32_e32 v54, s1, v132
	v_min_i32_e32 v54, 15, v54
	v_add_u32_e32 v54, 1, v54
	v_cvt_f32_i32_e32 v54, v54
	v_cvt_pk_bf16_f32 v52, v52, v53
	ds_write_b32 v171, v52 offset:34816
	v_sub_f32_e32 v50, v50, v60
	v_rcp_iflag_f32_e32 v54, v54
	v_sub_f32_e32 v51, v51, v61
	v_lshlrev_b32_e32 v52, 16, v206
	v_and_b32_e32 v53, 0xffff0000, v206
	v_add_f32_e32 v50, v50, v52
	v_add_f32_e32 v51, v51, v53
	v_fma_f32 v52, v54, v50, -v52
	v_fma_f32 v53, v54, v51, -v53
	v_add_u32_e32 v54, s1, v133
	v_min_i32_e32 v54, 15, v54
	v_add_u32_e32 v54, 1, v54
	v_cvt_f32_i32_e32 v54, v54
	v_cvt_pk_bf16_f32 v52, v52, v53
	ds_write_b32 v172, v52 offset:34816
	v_sub_f32_e32 v50, v50, v62
	v_rcp_iflag_f32_e32 v54, v54
	v_lshlrev_b32_e32 v52, 16, v205
	v_sub_f32_e32 v51, v51, v63
	v_and_b32_e32 v53, 0xffff0000, v205
	v_add_f32_e32 v50, v50, v52
	v_add_f32_e32 v51, v51, v53
	v_fma_f32 v52, v54, v50, -v52
	v_fma_f32 v53, v54, v51, -v53
	v_cvt_pk_bf16_f32 v52, v52, v53
	ds_write_b32 v173, v52 offset:34816
	v_add_u32_e32 v52, s1, v134
	v_min_i32_e32 v52, 15, v52
	v_add_u32_e32 v52, 1, v52
	v_cvt_f32_i32_e32 v52, v52
	v_sub_f32_e32 v16, v50, v16
	v_lshlrev_b32_e32 v50, 16, v204
	v_sub_f32_e32 v17, v51, v17
	v_rcp_iflag_f32_e32 v52, v52
	v_and_b32_e32 v51, 0xffff0000, v204
	v_add_f32_e32 v16, v16, v50
	v_add_f32_e32 v17, v17, v51
	v_fma_f32 v50, v52, v16, -v50
	v_fma_f32 v51, v52, v17, -v51
	v_cvt_pk_bf16_f32 v50, v50, v51
	ds_write_b32 v174, v50 offset:34816
	v_add_u32_e32 v50, s1, v135
	v_min_i32_e32 v50, 15, v50
	v_add_u32_e32 v50, 1, v50
	v_cvt_f32_i32_e32 v50, v50
	v_sub_f32_e32 v14, v16, v14
	v_lshlrev_b32_e32 v16, 16, v192
	v_sub_f32_e32 v15, v17, v15
	v_rcp_iflag_f32_e32 v50, v50
	v_and_b32_e32 v17, 0xffff0000, v192
	v_add_f32_e32 v14, v14, v16
	v_add_f32_e32 v15, v15, v17
	v_fma_f32 v16, v50, v14, -v16
	v_fma_f32 v17, v50, v15, -v17
	v_cvt_pk_bf16_f32 v16, v16, v17
	ds_write_b32 v175, v16 offset:34816
	v_add_u32_e32 v16, s1, v136
	v_min_i32_e32 v16, 15, v16
	v_add_u32_e32 v16, 1, v16
	v_cvt_f32_i32_e32 v16, v16
	v_sub_f32_e32 v12, v14, v12
	v_lshlrev_b32_e32 v14, 16, v190
	v_sub_f32_e32 v13, v15, v13
	v_rcp_iflag_f32_e32 v16, v16
	v_and_b32_e32 v15, 0xffff0000, v190
	v_add_f32_e32 v12, v12, v14
	v_add_f32_e32 v13, v13, v15
	v_fma_f32 v14, v16, v12, -v14
	v_fma_f32 v15, v16, v13, -v15
	v_cvt_pk_bf16_f32 v14, v14, v15
	ds_write_b32 v176, v14 offset:34816
	v_add_u32_e32 v14, s1, v137
	v_min_i32_e32 v14, 15, v14
	v_add_u32_e32 v14, 1, v14
	v_cvt_f32_i32_e32 v14, v14
	v_sub_f32_e32 v10, v12, v10
	v_lshlrev_b32_e32 v12, 16, v189
	v_sub_f32_e32 v11, v13, v11
	v_rcp_iflag_f32_e32 v14, v14
	v_and_b32_e32 v13, 0xffff0000, v189
	v_add_f32_e32 v10, v10, v12
	v_add_f32_e32 v11, v11, v13
	v_fma_f32 v12, v14, v10, -v12
	v_fma_f32 v13, v14, v11, -v13
	v_cvt_pk_bf16_f32 v12, v12, v13
	ds_write_b32 v177, v12 offset:34816
	v_add_u32_e32 v12, s1, v138
	v_min_i32_e32 v12, 15, v12
	v_add_u32_e32 v12, 1, v12
	v_cvt_f32_i32_e32 v12, v12
	v_sub_f32_e32 v8, v10, v8
	v_lshlrev_b32_e32 v10, 16, v188
	v_sub_f32_e32 v9, v11, v9
	v_rcp_iflag_f32_e32 v12, v12
	v_and_b32_e32 v11, 0xffff0000, v188
	v_add_f32_e32 v8, v8, v10
	v_add_f32_e32 v9, v9, v11
	v_fma_f32 v10, v12, v8, -v10
	v_fma_f32 v11, v12, v9, -v11
	v_cvt_pk_bf16_f32 v10, v10, v11
	ds_write_b32 v178, v10 offset:34816
	v_add_u32_e32 v10, s1, v139
	v_min_i32_e32 v10, 15, v10
	v_add_u32_e32 v10, 1, v10
	v_cvt_f32_i32_e32 v10, v10
	v_sub_f32_e32 v6, v8, v6
	v_lshlrev_b32_e32 v8, 16, v187
	v_sub_f32_e32 v7, v9, v7
	v_rcp_iflag_f32_e32 v10, v10
	v_and_b32_e32 v9, 0xffff0000, v187
	v_add_f32_e32 v6, v6, v8
	v_add_f32_e32 v7, v7, v9
	v_fma_f32 v8, v10, v6, -v8
	v_fma_f32 v9, v10, v7, -v9
	v_cvt_pk_bf16_f32 v8, v8, v9
	ds_write_b32 v179, v8 offset:34816
	v_add_u32_e32 v8, s1, v140
	v_min_i32_e32 v8, 15, v8
	v_add_u32_e32 v8, 1, v8
	v_cvt_f32_i32_e32 v8, v8
	v_sub_f32_e32 v4, v6, v4
	v_lshlrev_b32_e32 v6, 16, v186
	v_sub_f32_e32 v5, v7, v5
	v_rcp_iflag_f32_e32 v8, v8
	v_and_b32_e32 v7, 0xffff0000, v186
	v_add_f32_e32 v4, v4, v6
	v_add_f32_e32 v5, v5, v7
	v_fma_f32 v6, v8, v4, -v6
	v_fma_f32 v7, v8, v5, -v7
	v_cvt_pk_bf16_f32 v6, v6, v7
	ds_write_b32 v180, v6 offset:34816
	v_add_u32_e32 v6, s1, v141
	v_min_i32_e32 v6, 15, v6
	v_add_u32_e32 v6, 1, v6
	v_cvt_f32_i32_e32 v6, v6
	v_sub_f32_e32 v2, v4, v2
	v_lshlrev_b32_e32 v4, 16, v182
	v_sub_f32_e32 v3, v5, v3
	v_rcp_iflag_f32_e32 v6, v6
	v_and_b32_e32 v5, 0xffff0000, v182
	v_add_f32_e32 v2, v2, v4
	v_add_f32_e32 v3, v3, v5
	v_fma_f32 v2, v6, v2, -v4
	v_fma_f32 v3, v6, v3, -v5
	v_cvt_pk_bf16_f32 v2, v2, v3
	ds_write_b32 v181, v2 offset:34816
	v_add_u32_e32 v2, s0, v142
	v_ashrrev_i32_e32 v3, 31, v2
	v_lshlrev_b64 v[2:3], 12, v[2:3]
	s_waitcnt lgkmcnt(0)
	s_barrier
	v_lshl_add_u64 v[2:3], s[70:71], 0, v[2:3]
	ds_read_b128 v[74:77], v185 offset:34816
	ds_read_b128 v[78:81], v185 offset:34848
	ds_read_b128 v[70:73], v185 offset:34880
	ds_read_b128 v[66:69], v185 offset:34912
	ds_read_b128 v[62:65], v185 offset:34944
	ds_read_b128 v[58:61], v185 offset:34976
	ds_read_b128 v[54:57], v185 offset:35008
	ds_read_b128 v[50:53], v185 offset:35040
	v_lshl_add_u64 v[106:107], v[2:3], 0, s[2:3]
	ds_read_b128 v[2:5], v183
	ds_read_b128 v[168:171], v183 offset:32
	ds_read_b128 v[228:231], v183 offset:64
	ds_read_b128 v[242:245], v183 offset:96
	s_waitcnt lgkmcnt(3)
	v_mfma_f32_32x32x16_bf16 v[2:17], v[2:5], v[74:77], 0
	s_waitcnt lgkmcnt(2)
	v_mfma_f32_32x32x16_bf16 v[2:17], v[168:171], v[78:81], v[2:17]
	ds_read_b128 v[168:171], v183 offset:128
	s_waitcnt lgkmcnt(2)
	v_mfma_f32_32x32x16_bf16 v[2:17], v[228:231], v[70:73], v[2:17]
	ds_read_b128 v[228:231], v183 offset:160
	s_waitcnt lgkmcnt(2)
	v_mfma_f32_32x32x16_bf16 v[2:17], v[242:245], v[66:69], v[2:17]
	ds_read_b128 v[242:245], v183 offset:192
	s_waitcnt lgkmcnt(2)
	v_mfma_f32_32x32x16_bf16 v[2:17], v[168:171], v[62:65], v[2:17]
	ds_read_b128 v[168:171], v183 offset:224
	s_waitcnt lgkmcnt(2)
	v_mfma_f32_32x32x16_bf16 v[2:17], v[228:231], v[58:61], v[2:17]
	s_waitcnt lgkmcnt(1)
	v_mfma_f32_32x32x16_bf16 v[2:17], v[242:245], v[54:57], v[2:17]
	s_waitcnt lgkmcnt(0)
	v_mfma_f32_32x32x16_bf16 v[2:17], v[168:171], v[50:53], v[2:17]
	s_nop 11
	v_mul_f32_e32 v2, v46, v2
	v_mul_f32_e32 v3, v47, v3
	v_cvt_pk_bf16_f32 v2, v2, v3
	v_mul_f32_e32 v3, v48, v4
	v_mul_f32_e32 v4, v49, v5
	v_cvt_pk_bf16_f32 v3, v3, v4
	v_lshl_add_u64 v[4:5], v[106:107], 0, v[0:1]
	global_store_dwordx2 v[4:5], v[2:3], off
	v_mul_f32_e32 v0, v42, v6
	v_mul_f32_e32 v2, v43, v7
	v_mul_f32_e32 v3, v45, v9
	v_cvt_pk_bf16_f32 v2, v0, v2
	v_mul_f32_e32 v0, v44, v8
	v_cvt_pk_bf16_f32 v3, v0, v3
	v_lshl_add_u64 v[4:5], v[106:107], 0, v[104:105]
	global_store_dwordx2 v[4:5], v[2:3], off
	v_mul_f32_e32 v0, v38, v10
	v_mul_f32_e32 v2, v39, v11
	v_mul_f32_e32 v3, v41, v13
	v_cvt_pk_bf16_f32 v2, v0, v2
	v_mul_f32_e32 v0, v40, v12
	v_cvt_pk_bf16_f32 v3, v0, v3
	v_lshl_add_u64 v[4:5], v[106:107], 0, v[108:109]
	global_store_dwordx2 v[4:5], v[2:3], off
	v_mul_f32_e32 v0, v34, v14
	v_mul_f32_e32 v2, v35, v15
	v_mul_f32_e32 v3, v37, v17
	v_lshl_add_u64 v[4:5], v[106:107], 0, v[102:103]
	v_cvt_pk_bf16_f32 v2, v0, v2
	v_mul_f32_e32 v0, v36, v16
	v_cvt_pk_bf16_f32 v3, v0, v3
	global_store_dwordx2 v[4:5], v[2:3], off
	ds_read_b128 v[2:5], v184
	ds_read_b128 v[34:37], v184 offset:32
	ds_read_b128 v[228:231], v184 offset:64
	ds_read_b128 v[242:245], v184 offset:96
	s_waitcnt lgkmcnt(3)
	v_mfma_f32_32x32x16_bf16 v[2:17], v[2:5], v[74:77], 0
	s_waitcnt lgkmcnt(2)
	v_mfma_f32_32x32x16_bf16 v[2:17], v[34:37], v[78:81], v[2:17]
	ds_read_b128 v[34:37], v184 offset:128
	s_waitcnt lgkmcnt(2)
	v_mfma_f32_32x32x16_bf16 v[2:17], v[228:231], v[70:73], v[2:17]
	ds_read_b128 v[228:231], v184 offset:160
	s_waitcnt lgkmcnt(2)
	v_mfma_f32_32x32x16_bf16 v[2:17], v[242:245], v[66:69], v[2:17]
	ds_read_b128 v[242:245], v184 offset:192
	s_waitcnt lgkmcnt(2)
	v_mfma_f32_32x32x16_bf16 v[2:17], v[34:37], v[62:65], v[2:17]
	ds_read_b128 v[34:37], v184 offset:224
	s_waitcnt lgkmcnt(2)
	v_mfma_f32_32x32x16_bf16 v[2:17], v[228:231], v[58:61], v[2:17]
	s_waitcnt lgkmcnt(1)
	v_mfma_f32_32x32x16_bf16 v[2:17], v[242:245], v[54:57], v[2:17]
	s_waitcnt lgkmcnt(0)
	v_mfma_f32_32x32x16_bf16 v[2:17], v[34:37], v[50:53], v[2:17]
	s_nop 11
	v_mul_f32_e32 v0, v30, v2
	v_mul_f32_e32 v2, v31, v3
	v_mul_f32_e32 v3, v33, v5
	v_cvt_pk_bf16_f32 v2, v0, v2
	v_mul_f32_e32 v0, v32, v4
	v_cvt_pk_bf16_f32 v3, v0, v3
	v_lshl_add_u64 v[4:5], v[106:107], 0, v[110:111]
	global_store_dwordx2 v[4:5], v[2:3], off
	v_mul_f32_e32 v0, v26, v6
	v_mul_f32_e32 v2, v27, v7
	v_mul_f32_e32 v3, v29, v9
	v_cvt_pk_bf16_f32 v2, v0, v2
	v_mul_f32_e32 v0, v28, v8
	v_cvt_pk_bf16_f32 v3, v0, v3
	v_lshl_add_u64 v[4:5], v[106:107], 0, v[112:113]
	global_store_dwordx2 v[4:5], v[2:3], off
	v_mul_f32_e32 v0, v22, v10
	v_mul_f32_e32 v2, v23, v11
	v_mul_f32_e32 v3, v25, v13
	v_cvt_pk_bf16_f32 v2, v0, v2
	v_mul_f32_e32 v0, v24, v12
	v_cvt_pk_bf16_f32 v3, v0, v3
	v_lshl_add_u64 v[4:5], v[106:107], 0, v[114:115]
	global_store_dwordx2 v[4:5], v[2:3], off
	v_mul_f32_e32 v0, v18, v14
	v_mul_f32_e32 v2, v19, v15
	v_mul_f32_e32 v3, v21, v17
	v_cvt_pk_bf16_f32 v2, v0, v2
	v_mul_f32_e32 v0, v20, v16
	v_cvt_pk_bf16_f32 v3, v0, v3

.LBB0_220:
	s_or_b64 exec, exec, s[52:53]
	s_waitcnt vmcnt(26)
	v_cndmask_b32_e64 v14, 0, v14, s[8:9]
	v_cndmask_b32_e32 v10, 0, v10, vcc
	v_lshlrev_b32_e32 v65, 16, v14
	v_and_b32_e32 v66, 0xffff0000, v14
	v_add_u32_e32 v14, s95, v83
	s_waitcnt vmcnt(8)
	v_cndmask_b32_e64 v0, 0, v57, s[46:47]
	v_cndmask_b32_e64 v57, 0, v56, s[28:29]
	v_cndmask_b32_e64 v11, 0, v11, s[0:1]
	v_lshlrev_b32_e32 v56, 16, v10
	v_min_i32_e32 v14, 7, v14
	v_cndmask_b32_e64 v12, 0, v12, s[2:3]
	v_add_f32_e32 v58, 0, v56
	v_and_b32_e32 v59, 0xffff0000, v10
	v_lshlrev_b32_e32 v60, 16, v11
	v_add_u32_e32 v14, 1, v14
	v_add_f32_e32 v10, 0, v59
	v_add_f32_e32 v58, v58, v60
	v_and_b32_e32 v61, 0xffff0000, v11
	v_lshlrev_b32_e32 v62, 16, v12
	v_cvt_f32_i32_e32 v14, v14
	v_cndmask_b32_e64 v13, 0, v13, s[6:7]
	v_add_f32_e32 v10, v10, v61
	v_add_f32_e32 v11, v58, v62
	v_and_b32_e32 v58, 0xffff0000, v12
	v_add_f32_e32 v10, v10, v58
	v_lshlrev_b32_e32 v63, 16, v13
	v_and_b32_e32 v64, 0xffff0000, v13
	v_cndmask_b32_e64 v15, 0, v15, s[10:11]
	v_add_f32_e32 v11, v11, v63
	v_add_f32_e32 v10, v10, v64
	v_cndmask_b32_e64 v16, 0, v16, s[12:13]
	v_add_f32_e32 v11, v11, v65
	v_add_f32_e32 v10, v10, v66
	v_lshlrev_b32_e32 v67, 16, v15
	v_and_b32_e32 v68, 0xffff0000, v15
	v_rcp_iflag_f32_e32 v14, v14
	v_cndmask_b32_e64 v17, 0, v17, s[14:15]
	v_add_f32_e32 v11, v11, v67
	v_add_f32_e32 v10, v10, v68
	v_lshlrev_b32_e32 v69, 16, v16
	v_and_b32_e32 v70, 0xffff0000, v16
	v_add_f32_e32 v12, v11, v69
	v_add_f32_e32 v13, v10, v70
	v_lshlrev_b32_e32 v10, 16, v17
	v_and_b32_e32 v11, 0xffff0000, v17
	v_add_u32_e32 v16, s95, v127
	v_add_f32_e32 v12, v12, v10
	v_add_f32_e32 v13, v13, v11
	v_min_i32_e32 v16, 7, v16
	v_fma_f32 v15, v14, v12, -v10
	v_fma_f32 v14, v14, v13, -v11
	v_add_u32_e32 v16, 1, v16
	v_cndmask_b32_e64 v50, v50, 0, s[16:17]
	v_cvt_pk_bf16_f32 v14, v15, v14
	v_add_u32_e32 v116, 0, v145
	v_cvt_f32_i32_e32 v16, v16
	s_waitcnt lgkmcnt(0)
	s_barrier
	ds_write_b32 v116, v14 offset:34816
	v_sub_f32_e32 v14, v12, v56
	v_sub_f32_e32 v15, v13, v59
	v_lshlrev_b32_e32 v12, 16, v50
	v_and_b32_e32 v13, 0xffff0000, v50
	v_add_u32_e32 v50, s95, v128
	v_min_i32_e32 v50, 7, v50
	v_add_u32_e32 v50, 1, v50
	v_rcp_iflag_f32_e32 v16, v16
	v_cvt_f32_i32_e32 v50, v50
	v_add_f32_e32 v14, v14, v12
	v_add_f32_e32 v15, v15, v13
	v_fma_f32 v17, v16, v14, -v12
	v_fma_f32 v16, v16, v15, -v13
	v_rcp_iflag_f32_e32 v50, v50
	v_cndmask_b32_e64 v51, 0, v51, s[18:19]
	v_cvt_pk_bf16_f32 v16, v17, v16
	v_add_u32_e32 v117, 0, v146
	ds_write_b32 v117, v16 offset:34816
	v_sub_f32_e32 v16, v14, v60
	v_sub_f32_e32 v17, v15, v61
	v_lshlrev_b32_e32 v14, 16, v51
	v_and_b32_e32 v15, 0xffff0000, v51
	v_add_f32_e32 v16, v16, v14
	v_add_f32_e32 v17, v17, v15
	v_fma_f32 v51, v50, v16, -v14
	v_fma_f32 v50, v50, v17, -v15
	v_cndmask_b32_e64 v52, 0, v52, s[20:21]
	v_cvt_pk_bf16_f32 v50, v51, v50
	v_add_u32_e32 v168, 0, v147
	ds_write_b32 v168, v50 offset:34816
	v_sub_f32_e32 v50, v16, v62
	v_sub_f32_e32 v51, v17, v58
	v_lshlrev_b32_e32 v16, 16, v52
	v_and_b32_e32 v17, 0xffff0000, v52
	v_add_u32_e32 v52, s95, v129
	v_min_i32_e32 v52, 7, v52
	v_add_u32_e32 v52, 1, v52
	v_cvt_f32_i32_e32 v52, v52
	v_add_f32_e32 v50, v50, v16
	v_add_f32_e32 v51, v51, v17
	v_cndmask_b32_e64 v53, 0, v53, s[22:23]
	v_rcp_iflag_f32_e32 v52, v52
	v_add_u32_e32 v169, 0, v148
	v_cndmask_b32_e64 v54, 0, v54, s[24:25]
	v_add_u32_e32 v170, 0, v149
	v_fma_f32 v56, v52, v50, -v16
	v_fma_f32 v52, v52, v51, -v17
	v_cvt_pk_bf16_f32 v52, v56, v52
	v_sub_f32_e32 v56, v51, v64
	v_and_b32_e32 v51, 0xffff0000, v53
	ds_write_b32 v169, v52 offset:34816
	v_sub_f32_e32 v52, v50, v63
	v_lshlrev_b32_e32 v50, 16, v53
	v_add_f32_e32 v53, v56, v51
	v_add_u32_e32 v56, s95, v130
	v_min_i32_e32 v56, 7, v56
	v_add_u32_e32 v56, 1, v56
	v_cvt_f32_i32_e32 v56, v56
	v_add_f32_e32 v52, v52, v50
	v_cndmask_b32_e64 v55, 0, v55, s[26:27]
	v_add_u32_e32 v171, 0, v150
	v_rcp_iflag_f32_e32 v56, v56
	v_add_u32_e32 v172, 0, v151
	v_cndmask_b32_e64 v9, 0, v9, s[50:51]
	v_add_u32_e32 v173, 0, v152
	v_fma_f32 v58, v56, v52, -v50
	v_fma_f32 v56, v56, v53, -v51
	v_cvt_pk_bf16_f32 v56, v58, v56
	ds_write_b32 v170, v56 offset:34816
	v_sub_f32_e32 v56, v52, v65
	v_sub_f32_e32 v58, v53, v66
	v_lshlrev_b32_e32 v52, 16, v54
	v_and_b32_e32 v53, 0xffff0000, v54
	v_add_f32_e32 v54, v56, v52
	v_add_f32_e32 v56, v58, v53
	v_add_u32_e32 v58, s95, v131
	v_min_i32_e32 v58, 7, v58
	v_add_u32_e32 v58, 1, v58
	v_cvt_f32_i32_e32 v58, v58
	v_add_u32_e32 v174, 0, v153
	v_cndmask_b32_e64 v8, 0, v8, s[34:35]
	v_cndmask_b32_e64 v7, 0, v7, s[36:37]
	v_rcp_iflag_f32_e32 v58, v58
	v_add_u32_e32 v175, 0, v154
	v_cndmask_b32_e64 v6, 0, v6, s[38:39]
	v_add_u32_e32 v176, 0, v155
	v_fma_f32 v59, v58, v54, -v52
	v_fma_f32 v58, v58, v56, -v53
	v_cvt_pk_bf16_f32 v58, v59, v58
	v_add_u32_e32 v59, s95, v132
	v_min_i32_e32 v59, 7, v59
	v_add_u32_e32 v59, 1, v59
	v_cvt_f32_i32_e32 v59, v59
	ds_write_b32 v171, v58 offset:34816
	v_sub_f32_e32 v58, v54, v67
	v_sub_f32_e32 v56, v56, v68
	v_rcp_iflag_f32_e32 v59, v59
	v_lshlrev_b32_e32 v54, 16, v55
	v_and_b32_e32 v55, 0xffff0000, v55
	v_add_f32_e32 v58, v58, v54
	v_add_f32_e32 v56, v56, v55
	v_fma_f32 v60, v59, v58, -v54
	v_fma_f32 v59, v59, v56, -v55
	v_cvt_pk_bf16_f32 v59, v60, v59
	v_add_u32_e32 v60, s95, v133
	v_min_i32_e32 v60, 7, v60
	v_add_u32_e32 v60, 1, v60
	v_cvt_f32_i32_e32 v60, v60
	ds_write_b32 v172, v59 offset:34816
	v_sub_f32_e32 v58, v58, v69
	v_sub_f32_e32 v59, v56, v70
	v_rcp_iflag_f32_e32 v60, v60
	v_lshlrev_b32_e32 v56, 16, v57
	v_and_b32_e32 v57, 0xffff0000, v57
	v_add_f32_e32 v58, v58, v56
	v_add_f32_e32 v59, v59, v57
	v_fma_f32 v61, v60, v58, -v56
	v_fma_f32 v60, v60, v59, -v57
	v_sub_f32_e32 v11, v59, v11
	v_add_u32_e32 v59, s95, v134
	v_min_i32_e32 v59, 7, v59
	v_add_u32_e32 v59, 1, v59
	v_cvt_f32_i32_e32 v59, v59
	v_sub_f32_e32 v10, v58, v10
	v_lshlrev_b32_e32 v58, 16, v9
	v_and_b32_e32 v9, 0xffff0000, v9
	v_rcp_iflag_f32_e32 v59, v59
	v_add_f32_e32 v11, v11, v9
	v_add_f32_e32 v10, v10, v58
	v_cvt_pk_bf16_f32 v60, v61, v60
	v_fma_f32 v9, v59, v11, -v9
	v_fma_f32 v58, v59, v10, -v58
	v_cvt_pk_bf16_f32 v9, v58, v9
	ds_write_b32 v173, v60 offset:34816
	ds_write_b32 v174, v9 offset:34816
	v_sub_f32_e32 v9, v10, v12
	v_add_u32_e32 v12, s95, v135
	v_min_i32_e32 v12, 7, v12
	v_add_u32_e32 v12, 1, v12
	v_cvt_f32_i32_e32 v12, v12
	v_sub_f32_e32 v10, v11, v13
	v_lshlrev_b32_e32 v11, 16, v8
	v_and_b32_e32 v8, 0xffff0000, v8
	v_rcp_iflag_f32_e32 v12, v12
	v_add_f32_e32 v9, v9, v11
	v_add_f32_e32 v10, v10, v8
	v_cndmask_b32_e64 v5, 0, v5, s[40:41]
	v_fma_f32 v11, v12, v9, -v11
	v_fma_f32 v8, v12, v10, -v8
	v_cvt_pk_bf16_f32 v8, v11, v8
	v_add_u32_e32 v11, s95, v136
	v_min_i32_e32 v11, 7, v11
	v_add_u32_e32 v11, 1, v11
	v_cvt_f32_i32_e32 v11, v11
	ds_write_b32 v175, v8 offset:34816
	v_sub_f32_e32 v8, v9, v14
	v_sub_f32_e32 v9, v10, v15
	v_rcp_iflag_f32_e32 v11, v11
	v_lshlrev_b32_e32 v10, 16, v7
	v_and_b32_e32 v7, 0xffff0000, v7
	v_add_f32_e32 v8, v8, v10
	v_add_f32_e32 v9, v9, v7
	v_fma_f32 v10, v11, v8, -v10
	v_fma_f32 v7, v11, v9, -v7
	v_cvt_pk_bf16_f32 v7, v10, v7
	v_add_u32_e32 v10, s95, v137
	v_min_i32_e32 v10, 7, v10
	v_add_u32_e32 v10, 1, v10
	v_cvt_f32_i32_e32 v10, v10
	ds_write_b32 v176, v7 offset:34816
	v_sub_f32_e32 v7, v8, v16
	v_sub_f32_e32 v8, v9, v17
	v_rcp_iflag_f32_e32 v10, v10
	v_lshlrev_b32_e32 v9, 16, v6
	v_and_b32_e32 v6, 0xffff0000, v6
	v_add_f32_e32 v7, v7, v9
	v_add_f32_e32 v8, v8, v6
	v_fma_f32 v9, v10, v7, -v9
	v_fma_f32 v6, v10, v8, -v6
	v_cvt_pk_bf16_f32 v6, v9, v6
	v_add_u32_e32 v9, s95, v138
	v_min_i32_e32 v9, 7, v9
	v_add_u32_e32 v9, 1, v9
	v_cvt_f32_i32_e32 v9, v9
	v_add_u32_e32 v177, 0, v156
	ds_write_b32 v177, v6 offset:34816
	v_sub_f32_e32 v6, v7, v50
	v_rcp_iflag_f32_e32 v9, v9
	v_sub_f32_e32 v7, v8, v51
	v_lshlrev_b32_e32 v8, 16, v5
	v_and_b32_e32 v5, 0xffff0000, v5
	v_add_f32_e32 v6, v6, v8
	v_add_f32_e32 v7, v7, v5
	v_fma_f32 v8, v9, v6, -v8
	v_fma_f32 v5, v9, v7, -v5
	v_cvt_pk_bf16_f32 v5, v8, v5
	v_add_u32_e32 v8, s95, v139
	v_min_i32_e32 v8, 7, v8
	v_add_u32_e32 v8, 1, v8
	v_cvt_f32_i32_e32 v8, v8
	v_cndmask_b32_e64 v4, 0, v4, s[42:43]
	v_add_u32_e32 v178, 0, v157
	ds_write_b32 v178, v5 offset:34816
	v_rcp_iflag_f32_e32 v8, v8
	v_sub_f32_e32 v5, v6, v52
	v_sub_f32_e32 v6, v7, v53
	v_lshlrev_b32_e32 v7, 16, v4
	v_and_b32_e32 v4, 0xffff0000, v4
	v_add_f32_e32 v5, v5, v7
	v_add_f32_e32 v6, v6, v4
	v_fma_f32 v7, v8, v5, -v7
	v_fma_f32 v4, v8, v6, -v4
	v_cvt_pk_bf16_f32 v4, v7, v4
	v_add_u32_e32 v7, s95, v140
	v_min_i32_e32 v7, 7, v7
	v_add_u32_e32 v7, 1, v7
	v_cvt_f32_i32_e32 v7, v7
	v_cndmask_b32_e64 v3, 0, v3, s[44:45]
	v_add_u32_e32 v179, 0, v158
	ds_write_b32 v179, v4 offset:34816
	v_rcp_iflag_f32_e32 v7, v7
	v_sub_f32_e32 v4, v5, v54
	v_sub_f32_e32 v5, v6, v55
	v_lshlrev_b32_e32 v6, 16, v3
	v_and_b32_e32 v3, 0xffff0000, v3
	v_add_f32_e32 v4, v4, v6
	v_add_f32_e32 v5, v5, v3
	v_fma_f32 v6, v7, v4, -v6
	v_fma_f32 v3, v7, v5, -v3
	v_cvt_pk_bf16_f32 v3, v6, v3
	v_add_u32_e32 v6, s95, v141
	v_min_i32_e32 v6, 7, v6
	v_add_u32_e32 v6, 1, v6
	v_cvt_f32_i32_e32 v6, v6
	v_add_u32_e32 v180, 0, v159
	ds_write_b32 v180, v3 offset:34816
	v_sub_f32_e32 v3, v4, v56
	v_rcp_iflag_f32_e32 v6, v6
	v_sub_f32_e32 v4, v5, v57
	v_lshlrev_b32_e32 v5, 16, v0
	v_and_b32_e32 v0, 0xffff0000, v0
	s_or_b32 s0, s94, 0x80
	v_add_f32_e32 v3, v3, v5
	v_add_f32_e32 v4, v4, v0
	s_xor_b32 s1, s95, 0xffffff7f
	s_mul_i32 s2, s0, 0x1e00
	v_fma_f32 v3, v6, v3, -v5
	v_fma_f32 v0, v6, v4, -v0
	s_mul_hi_i32 s3, s0, 0x1e00
	s_add_u32 s2, s91, s2
	v_cvt_pk_bf16_f32 v0, v3, v0
	s_addc_u32 s3, s92, s3
	v_mov_b32_e32 v3, v1
	v_add_u32_e32 v181, 0, v160
	v_cmp_lt_i32_e32 vcc, s1, v141
	v_lshl_add_u64 v[2:3], s[2:3], 0, v[2:3]
	s_mov_b64 s[2:3], 0x1620
	ds_write_b32 v181, v0 offset:34816
	v_lshl_add_u64 v[2:3], v[2:3], 0, s[2:3]
	v_cndmask_b32_e32 v0, 0, v141, vcc
	s_movk_i32 s6, 0x1e00
	v_mad_i64_i32 v[4:5], s[2:3], v0, s6, v[2:3]
	global_load_dword v0, v[4:5], off
	v_add_u32_e32 v185, v144, v143
	v_add_u32_e32 v183, v144, v161
	v_lshlrev_b32_e32 v104, 1, v90
	v_mov_b32_e32 v105, v1
	v_mov_b32_e32 v103, v1
	v_add_u32_e32 v184, v144, v163
	v_lshlrev_b32_e32 v114, 1, v98
	v_mov_b32_e32 v115, v1
	s_waitcnt vmcnt(0)
	v_cndmask_b32_e32 v182, 0, v0, vcc
	v_cmp_lt_i32_e32 vcc, s1, v120
	v_mov_b32_e32 v211, 0
	s_nop 0
	v_cndmask_b32_e32 v0, 0, v120, vcc
	v_mad_i64_i32 v[4:5], s[2:3], v0, s6, v[2:3]
	s_and_saveexec_b64 s[98:99], vcc
	global_load_dword v211, v[4:5], off
	s_mov_b64 exec, s[98:99]
	v_cmp_lt_i32_e32 vcc, s1, v121
	v_mov_b32_e32 v212, 0
	s_nop 0
	v_cndmask_b32_e32 v0, 0, v121, vcc
	v_mad_i64_i32 v[4:5], s[2:3], v0, s6, v[2:3]
	s_and_saveexec_b64 s[98:99], vcc
	global_load_dword v212, v[4:5], off
	s_mov_b64 exec, s[98:99]
	v_cmp_lt_i32_e32 vcc, s1, v122
	v_mov_b32_e32 v213, 0
	s_nop 0
	v_cndmask_b32_e32 v0, 0, v122, vcc
	v_mad_i64_i32 v[4:5], s[2:3], v0, s6, v[2:3]
	s_and_saveexec_b64 s[98:99], vcc
	global_load_dword v213, v[4:5], off
	s_mov_b64 exec, s[98:99]
	v_cmp_lt_i32_e32 vcc, s1, v123
	v_mov_b32_e32 v214, 0
	s_nop 0
	v_cndmask_b32_e32 v0, 0, v123, vcc
	v_mad_i64_i32 v[4:5], s[2:3], v0, s6, v[2:3]
	s_and_saveexec_b64 s[98:99], vcc
	global_load_dword v214, v[4:5], off
	s_mov_b64 exec, s[98:99]
	v_cmp_lt_i32_e32 vcc, s1, v124
	v_mov_b32_e32 v215, 0
	s_nop 0
	v_cndmask_b32_e32 v0, 0, v124, vcc
	v_mad_i64_i32 v[4:5], s[2:3], v0, s6, v[2:3]
	s_and_saveexec_b64 s[98:99], vcc
	global_load_dword v215, v[4:5], off
	s_mov_b64 exec, s[98:99]
	v_cmp_lt_i32_e32 vcc, s1, v125
	v_mov_b32_e32 v216, 0
	s_nop 0
	v_cndmask_b32_e32 v0, 0, v125, vcc
	v_mad_i64_i32 v[4:5], s[2:3], v0, s6, v[2:3]
	s_and_saveexec_b64 s[98:99], vcc
	global_load_dword v216, v[4:5], off
	s_mov_b64 exec, s[98:99]
	v_cmp_lt_i32_e32 vcc, s1, v126
	v_mov_b32_e32 v218, 0
	s_nop 0
	v_cndmask_b32_e32 v0, 0, v126, vcc
	v_mad_i64_i32 v[4:5], s[2:3], v0, s6, v[2:3]
	s_and_saveexec_b64 s[98:99], vcc
	global_load_dword v218, v[4:5], off
	s_mov_b64 exec, s[98:99]
	v_cmp_lt_i32_e32 vcc, s1, v83
	v_mov_b32_e32 v217, 0
	s_nop 0
	v_cndmask_b32_e32 v0, 0, v83, vcc
	v_mad_i64_i32 v[4:5], s[2:3], v0, s6, v[2:3]
	s_and_saveexec_b64 s[98:99], vcc
	global_load_dword v217, v[4:5], off
	s_mov_b64 exec, s[98:99]
	v_cmp_gt_i32_e32 vcc, s1, v83
	s_nop 1
	v_cndmask_b32_e64 v0, v127, 0, vcc
	v_mad_i64_i32 v[4:5], s[2:3], v0, s6, v[2:3]
	global_load_dword v0, v[4:5], off
	s_waitcnt vmcnt(0)
	v_cndmask_b32_e64 v191, v0, 0, vcc
	v_cmp_lt_i32_e32 vcc, s1, v128
	v_mov_b32_e32 v210, 0
	s_nop 0
	v_cndmask_b32_e32 v0, 0, v128, vcc
	v_mad_i64_i32 v[4:5], s[2:3], v0, s6, v[2:3]
	s_and_saveexec_b64 s[98:99], vcc
	global_load_dword v210, v[4:5], off
	s_mov_b64 exec, s[98:99]
	v_cmp_lt_i32_e32 vcc, s1, v129
	v_mov_b32_e32 v209, 0
	s_nop 0
	v_cndmask_b32_e32 v0, 0, v129, vcc
	v_mad_i64_i32 v[4:5], s[2:3], v0, s6, v[2:3]
	s_and_saveexec_b64 s[98:99], vcc
	global_load_dword v209, v[4:5], off
	s_mov_b64 exec, s[98:99]
	v_cmp_lt_i32_e32 vcc, s1, v130
	v_mov_b32_e32 v208, 0
	s_nop 0
	v_cndmask_b32_e32 v0, 0, v130, vcc
	v_mad_i64_i32 v[4:5], s[2:3], v0, s6, v[2:3]
	s_and_saveexec_b64 s[98:99], vcc
	global_load_dword v208, v[4:5], off
	s_mov_b64 exec, s[98:99]
	v_cmp_lt_i32_e32 vcc, s1, v131
	v_mov_b32_e32 v207, 0
	s_nop 0
	v_cndmask_b32_e32 v0, 0, v131, vcc
	v_mad_i64_i32 v[4:5], s[2:3], v0, s6, v[2:3]
	s_and_saveexec_b64 s[98:99], vcc
	global_load_dword v207, v[4:5], off
	s_mov_b64 exec, s[98:99]
	v_cmp_lt_i32_e32 vcc, s1, v132
	v_mov_b32_e32 v206, 0
	s_nop 0
	v_cndmask_b32_e32 v0, 0, v132, vcc
	v_mad_i64_i32 v[4:5], s[2:3], v0, s6, v[2:3]
	s_and_saveexec_b64 s[98:99], vcc
	global_load_dword v206, v[4:5], off
	s_mov_b64 exec, s[98:99]
	v_cmp_lt_i32_e32 vcc, s1, v133
	v_mov_b32_e32 v205, 0
	s_nop 0
	v_cndmask_b32_e32 v0, 0, v133, vcc
	v_mad_i64_i32 v[4:5], s[2:3], v0, s6, v[2:3]
	s_and_saveexec_b64 s[98:99], vcc
	global_load_dword v205, v[4:5], off
	s_mov_b64 exec, s[98:99]
	v_cmp_lt_i32_e32 vcc, s1, v134
	v_mov_b32_e32 v204, 0
	s_nop 0
	v_cndmask_b32_e32 v0, 0, v134, vcc
	v_mad_i64_i32 v[4:5], s[2:3], v0, s6, v[2:3]
	s_and_saveexec_b64 s[98:99], vcc
	global_load_dword v204, v[4:5], off
	s_mov_b64 exec, s[98:99]
	v_cmp_lt_i32_e32 vcc, s1, v135
	v_mov_b32_e32 v192, 0
	s_nop 0
	v_cndmask_b32_e32 v0, 0, v135, vcc
	v_mad_i64_i32 v[4:5], s[2:3], v0, s6, v[2:3]
	s_and_saveexec_b64 s[98:99], vcc
	global_load_dword v192, v[4:5], off
	s_mov_b64 exec, s[98:99]
	v_cmp_lt_i32_e32 vcc, s1, v136
	v_mov_b32_e32 v190, 0
	s_nop 0
	v_cndmask_b32_e32 v0, 0, v136, vcc
	v_mad_i64_i32 v[4:5], s[2:3], v0, s6, v[2:3]
	s_and_saveexec_b64 s[98:99], vcc
	global_load_dword v190, v[4:5], off
	s_mov_b64 exec, s[98:99]
	v_cmp_lt_i32_e32 vcc, s1, v137
	v_mov_b32_e32 v189, 0
	s_nop 0
	v_cndmask_b32_e32 v0, 0, v137, vcc
	v_mad_i64_i32 v[4:5], s[2:3], v0, s6, v[2:3]
	s_and_saveexec_b64 s[98:99], vcc
	global_load_dword v189, v[4:5], off
	s_mov_b64 exec, s[98:99]
	v_cmp_lt_i32_e32 vcc, s1, v138
	v_mov_b32_e32 v188, 0
	s_nop 0
	v_cndmask_b32_e32 v0, 0, v138, vcc
	v_mad_i64_i32 v[4:5], s[2:3], v0, s6, v[2:3]
	s_and_saveexec_b64 s[98:99], vcc
	global_load_dword v188, v[4:5], off
	s_mov_b64 exec, s[98:99]
	v_cmp_lt_i32_e32 vcc, s1, v139
	v_mov_b32_e32 v187, 0
	s_nop 0
	v_cndmask_b32_e32 v0, 0, v139, vcc
	v_mad_i64_i32 v[4:5], s[2:3], v0, s6, v[2:3]
	s_and_saveexec_b64 s[98:99], vcc
	global_load_dword v187, v[4:5], off
	s_mov_b64 exec, s[98:99]
	v_cmp_lt_i32_e32 vcc, s1, v140
	s_and_b32 s1, s0, 0xf80
	s_nop 0
	v_cndmask_b32_e32 v0, 0, v140, vcc
	v_mad_i64_i32 v[2:3], s[2:3], v0, s6, v[2:3]
	global_load_dword v0, v[2:3], off
	v_add_u32_e32 v2, s94, v142
	v_ashrrev_i32_e32 v3, 31, v2
	v_lshlrev_b64 v[2:3], 12, v[2:3]
	s_waitcnt lgkmcnt(0)
	s_barrier
	v_lshl_add_u64 v[2:3], s[70:71], 0, v[2:3]
	s_mov_b64 s[2:3], 0x26000a00
	ds_read_b128 v[74:77], v185 offset:34816
	ds_read_b128 v[78:81], v185 offset:34848
	ds_read_b128 v[70:73], v185 offset:34880
	ds_read_b128 v[66:69], v185 offset:34912
	ds_read_b128 v[62:65], v185 offset:34944
	ds_read_b128 v[58:61], v185 offset:34976
	ds_read_b128 v[54:57], v185 offset:35008
	ds_read_b128 v[50:53], v185 offset:35040
	v_lshl_add_u64 v[106:107], v[2:3], 0, s[2:3]
	ds_read_b128 v[2:5], v183
	ds_read_b128 v[108:111], v183 offset:32
	ds_read_b128 v[228:231], v183 offset:64
	ds_read_b128 v[242:245], v183 offset:96
	s_waitcnt lgkmcnt(3)
	v_mfma_f32_32x32x16_bf16 v[2:17], v[2:5], v[74:77], 0
	s_waitcnt vmcnt(0)
	v_cndmask_b32_e32 v186, 0, v0, vcc
	s_waitcnt lgkmcnt(2)
	v_mfma_f32_32x32x16_bf16 v[2:17], v[108:111], v[78:81], v[2:17]
	ds_read_b128 v[108:111], v183 offset:128
	s_waitcnt lgkmcnt(2)
	v_mfma_f32_32x32x16_bf16 v[2:17], v[228:231], v[70:73], v[2:17]
	ds_read_b128 v[228:231], v183 offset:160
	s_waitcnt lgkmcnt(2)
	v_mfma_f32_32x32x16_bf16 v[2:17], v[242:245], v[66:69], v[2:17]
	ds_read_b128 v[242:245], v183 offset:192
	s_waitcnt lgkmcnt(2)
	v_mfma_f32_32x32x16_bf16 v[2:17], v[108:111], v[62:65], v[2:17]
	ds_read_b128 v[108:111], v183 offset:224
	s_waitcnt lgkmcnt(2)
	v_mfma_f32_32x32x16_bf16 v[2:17], v[228:231], v[58:61], v[2:17]
	s_waitcnt lgkmcnt(1)
	v_mfma_f32_32x32x16_bf16 v[2:17], v[242:245], v[54:57], v[2:17]
	s_waitcnt lgkmcnt(0)
	v_mfma_f32_32x32x16_bf16 v[2:17], v[108:111], v[50:53], v[2:17]
	v_lshlrev_b32_e32 v108, 1, v92
	v_mov_b32_e32 v109, v1
	s_nop 9
	v_mul_f32_e32 v0, v46, v2
	v_mul_f32_e32 v2, v47, v3
	v_cvt_pk_bf16_f32 v2, v0, v2
	v_mul_f32_e32 v0, v48, v4
	v_mul_f32_e32 v3, v49, v5
	v_cvt_pk_bf16_f32 v3, v0, v3
	v_lshlrev_b32_e32 v0, 1, v88
	v_lshl_add_u64 v[4:5], v[106:107], 0, v[0:1]
	global_store_dwordx2 v[4:5], v[2:3], off
	v_mul_f32_e32 v2, v42, v6
	v_mul_f32_e32 v3, v43, v7
	v_cvt_pk_bf16_f32 v2, v2, v3
	v_mul_f32_e32 v3, v44, v8
	v_mul_f32_e32 v4, v45, v9
	v_cvt_pk_bf16_f32 v3, v3, v4
	v_lshl_add_u64 v[4:5], v[106:107], 0, v[104:105]
	global_store_dwordx2 v[4:5], v[2:3], off
	v_mul_f32_e32 v2, v38, v10
	v_mul_f32_e32 v3, v39, v11
	v_cvt_pk_bf16_f32 v2, v2, v3
	v_mul_f32_e32 v3, v40, v12
	v_mul_f32_e32 v4, v41, v13
	v_cvt_pk_bf16_f32 v3, v3, v4
	v_lshl_add_u64 v[4:5], v[106:107], 0, v[108:109]
	global_store_dwordx2 v[4:5], v[2:3], off
	v_mul_f32_e32 v2, v34, v14
	v_mul_f32_e32 v3, v35, v15
	v_cvt_pk_bf16_f32 v2, v2, v3
	v_mul_f32_e32 v3, v36, v16
	v_mul_f32_e32 v4, v37, v17
	v_cvt_pk_bf16_f32 v3, v3, v4
	v_lshl_add_u64 v[4:5], v[106:107], 0, v[102:103]
	global_store_dwordx2 v[4:5], v[2:3], off
	ds_read_b128 v[2:5], v184
	ds_read_b128 v[110:113], v184 offset:32
	s_waitcnt lgkmcnt(1)
	v_mfma_f32_32x32x16_bf16 v[2:17], v[2:5], v[74:77], 0
	ds_read_b128 v[74:77], v184 offset:64
	s_waitcnt lgkmcnt(1)
	v_mfma_f32_32x32x16_bf16 v[2:17], v[110:113], v[78:81], v[2:17]
	v_lshlrev_b32_e32 v110, 1, v94
	v_mov_b32_e32 v111, v1
	v_lshlrev_b32_e32 v112, 1, v96
	v_mov_b32_e32 v113, v1
	s_waitcnt lgkmcnt(0)
	v_mfma_f32_32x32x16_bf16 v[2:17], v[74:77], v[70:73], v[2:17]
	ds_read_b128 v[70:73], v184 offset:96
	s_waitcnt lgkmcnt(0)
	v_mfma_f32_32x32x16_bf16 v[2:17], v[70:73], v[66:69], v[2:17]
	ds_read_b128 v[66:69], v184 offset:128
	s_waitcnt lgkmcnt(0)
	v_mfma_f32_32x32x16_bf16 v[2:17], v[66:69], v[62:65], v[2:17]
	ds_read_b128 v[62:65], v184 offset:160
	s_waitcnt lgkmcnt(0)
	v_mfma_f32_32x32x16_bf16 v[2:17], v[62:65], v[58:61], v[2:17]
	ds_read_b128 v[58:61], v184 offset:192
	s_waitcnt lgkmcnt(0)
	v_mfma_f32_32x32x16_bf16 v[2:17], v[58:61], v[54:57], v[2:17]
	ds_read_b128 v[54:57], v184 offset:224
	s_waitcnt lgkmcnt(0)
	v_mfma_f32_32x32x16_bf16 v[2:17], v[54:57], v[50:53], v[2:17]
	v_add_u32_e32 v52, s1, v83
	v_min_i32_e32 v52, 7, v52
	v_add_u32_e32 v52, 1, v52
	v_cvt_f32_i32_e32 v52, v52
	v_lshlrev_b32_e32 v50, 16, v217
	v_and_b32_e32 v51, 0xffff0000, v217
	s_nop 5
	v_mul_f32_e32 v2, v30, v2
	v_mul_f32_e32 v3, v31, v3
	v_cvt_pk_bf16_f32 v2, v2, v3
	v_mul_f32_e32 v3, v32, v4
	v_mul_f32_e32 v4, v33, v5
	v_cvt_pk_bf16_f32 v3, v3, v4
	v_lshl_add_u64 v[4:5], v[106:107], 0, v[110:111]
	global_store_dwordx2 v[4:5], v[2:3], off
	v_mul_f32_e32 v2, v26, v6
	v_mul_f32_e32 v3, v27, v7
	v_cvt_pk_bf16_f32 v2, v2, v3
	v_mul_f32_e32 v3, v28, v8
	v_mul_f32_e32 v4, v29, v9
	v_cvt_pk_bf16_f32 v3, v3, v4
	v_lshl_add_u64 v[4:5], v[106:107], 0, v[112:113]
	global_store_dwordx2 v[4:5], v[2:3], off
	v_mul_f32_e32 v2, v22, v10
	v_mul_f32_e32 v3, v23, v11
	v_cvt_pk_bf16_f32 v2, v2, v3
	v_mul_f32_e32 v3, v24, v12
	v_mul_f32_e32 v4, v25, v13
	v_cvt_pk_bf16_f32 v3, v3, v4
	v_lshl_add_u64 v[4:5], v[106:107], 0, v[114:115]
	global_store_dwordx2 v[4:5], v[2:3], off
	v_mul_f32_e32 v2, v18, v14
	v_mul_f32_e32 v3, v19, v15
	v_cvt_pk_bf16_f32 v2, v2, v3
	v_mul_f32_e32 v3, v20, v16
	v_mul_f32_e32 v4, v21, v17
	v_cvt_pk_bf16_f32 v3, v3, v4
	v_lshlrev_b32_e32 v4, 1, v100
	v_mov_b32_e32 v5, v1
	v_lshl_add_u64 v[4:5], v[106:107], 0, v[4:5]
	global_store_dwordx2 v[4:5], v[2:3], off
	v_lshlrev_b32_e32 v2, 16, v211
	v_and_b32_e32 v4, 0xffff0000, v211
	v_add_f32_e32 v3, 0, v2
	v_add_f32_e32 v5, 0, v4
	v_lshlrev_b32_e32 v6, 16, v212
	v_and_b32_e32 v7, 0xffff0000, v212
	v_add_f32_e32 v3, v3, v6
	v_add_f32_e32 v5, v5, v7
	v_lshlrev_b32_e32 v8, 16, v213
	v_and_b32_e32 v9, 0xffff0000, v213
	v_add_f32_e32 v3, v3, v8
	v_add_f32_e32 v5, v5, v9
	v_lshlrev_b32_e32 v10, 16, v214
	v_and_b32_e32 v11, 0xffff0000, v214
	v_add_f32_e32 v3, v3, v10
	v_add_f32_e32 v5, v5, v11
	v_lshlrev_b32_e32 v12, 16, v215
	v_and_b32_e32 v13, 0xffff0000, v215
	v_add_f32_e32 v3, v3, v12
	v_add_f32_e32 v5, v5, v13
	v_lshlrev_b32_e32 v14, 16, v216
	v_and_b32_e32 v15, 0xffff0000, v216
	v_rcp_iflag_f32_e32 v52, v52
	v_add_f32_e32 v3, v3, v14
	v_add_f32_e32 v5, v5, v15
	v_lshlrev_b32_e32 v16, 16, v218
	v_and_b32_e32 v17, 0xffff0000, v218
	v_add_f32_e32 v3, v3, v16
	v_add_f32_e32 v5, v5, v17
	v_add_f32_e32 v3, v3, v50
	v_add_f32_e32 v5, v5, v51
	v_fma_f32 v53, v52, v3, -v50
	v_fma_f32 v52, v52, v5, -v51
	v_cvt_pk_bf16_f32 v52, v53, v52
	s_waitcnt lgkmcnt(0)
	s_barrier
	ds_write_b32 v116, v52 offset:34816
	v_add_u32_e32 v52, s1, v127
	v_min_i32_e32 v52, 7, v52
	v_add_u32_e32 v52, 1, v52
	v_cvt_f32_i32_e32 v52, v52
	v_sub_f32_e32 v2, v3, v2
	v_sub_f32_e32 v3, v5, v4
	v_lshlrev_b32_e32 v4, 16, v191
	v_rcp_iflag_f32_e32 v52, v52
	v_and_b32_e32 v5, 0xffff0000, v191
	v_add_f32_e32 v2, v2, v4
	v_add_f32_e32 v3, v3, v5
	v_fma_f32 v53, v52, v2, -v4
	v_fma_f32 v52, v52, v3, -v5
	v_cvt_pk_bf16_f32 v52, v53, v52
	ds_write_b32 v117, v52 offset:34816
	v_add_u32_e32 v52, s1, v128
	v_min_i32_e32 v52, 7, v52
	v_add_u32_e32 v52, 1, v52
	v_cvt_f32_i32_e32 v52, v52
	v_sub_f32_e32 v2, v2, v6
	v_sub_f32_e32 v3, v3, v7
	v_lshlrev_b32_e32 v6, 16, v210
	v_rcp_iflag_f32_e32 v52, v52
	v_and_b32_e32 v7, 0xffff0000, v210
	v_add_f32_e32 v2, v2, v6
	v_add_f32_e32 v3, v3, v7
	v_fma_f32 v53, v52, v2, -v6
	v_fma_f32 v52, v52, v3, -v7
	v_cvt_pk_bf16_f32 v52, v53, v52
	ds_write_b32 v168, v52 offset:34816
	v_add_u32_e32 v52, s1, v129
	v_min_i32_e32 v52, 7, v52
	v_add_u32_e32 v52, 1, v52
	v_cvt_f32_i32_e32 v52, v52
	v_sub_f32_e32 v2, v2, v8
	v_sub_f32_e32 v3, v3, v9
	v_lshlrev_b32_e32 v8, 16, v209
	v_rcp_iflag_f32_e32 v52, v52
	v_and_b32_e32 v9, 0xffff0000, v209
	v_add_f32_e32 v2, v2, v8
	v_add_f32_e32 v3, v3, v9
	v_fma_f32 v53, v52, v2, -v8
	v_fma_f32 v52, v52, v3, -v9
	v_cvt_pk_bf16_f32 v52, v53, v52
	ds_write_b32 v169, v52 offset:34816
	v_add_u32_e32 v52, s1, v130
	v_min_i32_e32 v52, 7, v52
	v_add_u32_e32 v52, 1, v52
	v_cvt_f32_i32_e32 v52, v52
	v_sub_f32_e32 v2, v2, v10
	v_sub_f32_e32 v3, v3, v11
	v_lshlrev_b32_e32 v10, 16, v208
	v_rcp_iflag_f32_e32 v52, v52
	v_and_b32_e32 v11, 0xffff0000, v208
	v_add_f32_e32 v2, v2, v10
	v_add_f32_e32 v3, v3, v11
	v_fma_f32 v53, v52, v2, -v10
	v_fma_f32 v52, v52, v3, -v11
	v_cvt_pk_bf16_f32 v52, v53, v52
	ds_write_b32 v170, v52 offset:34816
	v_add_u32_e32 v52, s1, v131
	v_min_i32_e32 v52, 7, v52
	v_add_u32_e32 v52, 1, v52
	v_cvt_f32_i32_e32 v52, v52
	v_sub_f32_e32 v2, v2, v12
	v_sub_f32_e32 v3, v3, v13
	v_lshlrev_b32_e32 v12, 16, v207
	v_rcp_iflag_f32_e32 v52, v52
	v_and_b32_e32 v13, 0xffff0000, v207
	v_add_f32_e32 v2, v2, v12
	v_add_f32_e32 v3, v3, v13
	v_fma_f32 v53, v52, v2, -v12
	v_fma_f32 v52, v52, v3, -v13
	v_cvt_pk_bf16_f32 v52, v53, v52
	ds_write_b32 v171, v52 offset:34816
	v_add_u32_e32 v52, s1, v132
	v_min_i32_e32 v52, 7, v52
	v_add_u32_e32 v52, 1, v52
	v_cvt_f32_i32_e32 v52, v52
	v_sub_f32_e32 v2, v2, v14
	v_sub_f32_e32 v3, v3, v15
	v_lshlrev_b32_e32 v14, 16, v206
	v_rcp_iflag_f32_e32 v52, v52
	v_and_b32_e32 v15, 0xffff0000, v206
	v_add_f32_e32 v2, v2, v14
	v_add_f32_e32 v3, v3, v15
	v_fma_f32 v53, v52, v2, -v14
	v_fma_f32 v52, v52, v3, -v15
	v_cvt_pk_bf16_f32 v52, v53, v52
	ds_write_b32 v172, v52 offset:34816
	v_add_u32_e32 v52, s1, v133
	v_min_i32_e32 v52, 7, v52
	v_add_u32_e32 v52, 1, v52
	v_cvt_f32_i32_e32 v52, v52
	v_sub_f32_e32 v2, v2, v16
	v_sub_f32_e32 v3, v3, v17
	v_lshlrev_b32_e32 v16, 16, v205
	v_rcp_iflag_f32_e32 v52, v52
	v_and_b32_e32 v17, 0xffff0000, v205
	v_add_f32_e32 v2, v2, v16
	v_add_f32_e32 v3, v3, v17
	v_fma_f32 v53, v52, v2, -v16
	v_fma_f32 v52, v52, v3, -v17
	v_cvt_pk_bf16_f32 v52, v53, v52
	ds_write_b32 v173, v52 offset:34816
	v_add_u32_e32 v52, s1, v134
	v_min_i32_e32 v52, 7, v52
	v_add_u32_e32 v52, 1, v52
	v_cvt_f32_i32_e32 v52, v52
	v_sub_f32_e32 v2, v2, v50
	v_lshlrev_b32_e32 v50, 16, v204
	v_sub_f32_e32 v3, v3, v51
	v_rcp_iflag_f32_e32 v52, v52
	v_and_b32_e32 v51, 0xffff0000, v204
	v_add_f32_e32 v2, v2, v50
	v_add_f32_e32 v3, v3, v51
	v_fma_f32 v50, v52, v2, -v50
	v_fma_f32 v51, v52, v3, -v51
	v_cvt_pk_bf16_f32 v50, v50, v51
	ds_write_b32 v174, v50 offset:34816
	v_add_u32_e32 v50, s1, v135
	v_min_i32_e32 v50, 7, v50
	v_add_u32_e32 v50, 1, v50
	v_cvt_f32_i32_e32 v50, v50
	v_sub_f32_e32 v2, v2, v4
	v_lshlrev_b32_e32 v4, 16, v192
	v_add_f32_e32 v2, v2, v4
	v_rcp_iflag_f32_e32 v50, v50
	v_sub_f32_e32 v3, v3, v5
	v_and_b32_e32 v5, 0xffff0000, v192
	v_add_f32_e32 v3, v3, v5
	v_fma_f32 v4, v50, v2, -v4
	v_sub_f32_e32 v2, v2, v6
	v_add_u32_e32 v6, s1, v136
	v_min_i32_e32 v6, 7, v6
	v_add_u32_e32 v6, 1, v6
	v_cvt_f32_i32_e32 v6, v6
	v_fma_f32 v5, v50, v3, -v5
	v_cvt_pk_bf16_f32 v4, v4, v5
	ds_write_b32 v175, v4 offset:34816
	v_rcp_iflag_f32_e32 v6, v6
	v_sub_f32_e32 v3, v3, v7
	v_lshlrev_b32_e32 v4, 16, v190
	v_and_b32_e32 v5, 0xffff0000, v190
	v_add_f32_e32 v2, v2, v4
	v_add_f32_e32 v3, v3, v5
	v_fma_f32 v4, v6, v2, -v4
	v_fma_f32 v5, v6, v3, -v5
	v_add_u32_e32 v6, s1, v137
	v_min_i32_e32 v6, 7, v6
	v_add_u32_e32 v6, 1, v6
	v_cvt_f32_i32_e32 v6, v6
	v_cvt_pk_bf16_f32 v4, v4, v5
	ds_write_b32 v176, v4 offset:34816
	v_sub_f32_e32 v2, v2, v8
	v_rcp_iflag_f32_e32 v6, v6
	v_sub_f32_e32 v3, v3, v9
	v_lshlrev_b32_e32 v4, 16, v189
	v_and_b32_e32 v5, 0xffff0000, v189
	v_add_f32_e32 v2, v2, v4
	v_add_f32_e32 v3, v3, v5
	v_fma_f32 v4, v6, v2, -v4
	v_fma_f32 v5, v6, v3, -v5
	v_add_u32_e32 v6, s1, v138
	v_min_i32_e32 v6, 7, v6
	v_add_u32_e32 v6, 1, v6
	v_cvt_f32_i32_e32 v6, v6
	v_cvt_pk_bf16_f32 v4, v4, v5
	ds_write_b32 v177, v4 offset:34816
	v_sub_f32_e32 v2, v2, v10
	v_rcp_iflag_f32_e32 v6, v6
	v_sub_f32_e32 v3, v3, v11
	v_lshlrev_b32_e32 v4, 16, v188
	v_and_b32_e32 v5, 0xffff0000, v188
	v_add_f32_e32 v2, v2, v4
	v_add_f32_e32 v3, v3, v5
	v_fma_f32 v4, v6, v2, -v4
	v_fma_f32 v5, v6, v3, -v5
	v_add_u32_e32 v6, s1, v139
	v_min_i32_e32 v6, 7, v6
	v_add_u32_e32 v6, 1, v6
	v_cvt_f32_i32_e32 v6, v6
	v_cvt_pk_bf16_f32 v4, v4, v5
	ds_write_b32 v178, v4 offset:34816
	v_sub_f32_e32 v2, v2, v12
	v_rcp_iflag_f32_e32 v6, v6
	v_sub_f32_e32 v3, v3, v13
	v_lshlrev_b32_e32 v4, 16, v187
	v_and_b32_e32 v5, 0xffff0000, v187
	v_add_f32_e32 v2, v2, v4
	v_add_f32_e32 v3, v3, v5
	v_fma_f32 v4, v6, v2, -v4
	v_fma_f32 v5, v6, v3, -v5
	v_add_u32_e32 v6, s1, v140
	v_min_i32_e32 v6, 7, v6
	v_add_u32_e32 v6, 1, v6
	v_cvt_f32_i32_e32 v6, v6
	v_cvt_pk_bf16_f32 v4, v4, v5
	ds_write_b32 v179, v4 offset:34816
	v_sub_f32_e32 v2, v2, v14
	v_rcp_iflag_f32_e32 v6, v6
	v_sub_f32_e32 v3, v3, v15
	v_lshlrev_b32_e32 v4, 16, v186
	v_and_b32_e32 v5, 0xffff0000, v186
	v_add_f32_e32 v2, v2, v4
	v_add_f32_e32 v3, v3, v5
	v_fma_f32 v4, v6, v2, -v4
	v_fma_f32 v5, v6, v3, -v5
	v_add_u32_e32 v6, s1, v141
	v_min_i32_e32 v6, 7, v6
	v_add_u32_e32 v6, 1, v6
	v_cvt_f32_i32_e32 v6, v6
	v_cvt_pk_bf16_f32 v4, v4, v5
	ds_write_b32 v180, v4 offset:34816
	v_sub_f32_e32 v2, v2, v16
	v_rcp_iflag_f32_e32 v6, v6
	v_lshlrev_b32_e32 v4, 16, v182
	v_sub_f32_e32 v3, v3, v17
	v_and_b32_e32 v5, 0xffff0000, v182
	v_add_f32_e32 v2, v2, v4
	v_add_f32_e32 v3, v3, v5
	v_fma_f32 v2, v6, v2, -v4
	v_fma_f32 v3, v6, v3, -v5
	v_cvt_pk_bf16_f32 v2, v2, v3
	ds_write_b32 v181, v2 offset:34816
	v_add_u32_e32 v2, s0, v142
	v_ashrrev_i32_e32 v3, 31, v2
	v_lshlrev_b64 v[2:3], 12, v[2:3]
	s_waitcnt lgkmcnt(0)
	s_barrier
	v_lshl_add_u64 v[2:3], s[70:71], 0, v[2:3]
	ds_read_b128 v[74:77], v185 offset:34816
	ds_read_b128 v[78:81], v185 offset:34848
	ds_read_b128 v[70:73], v185 offset:34880
	ds_read_b128 v[66:69], v185 offset:34912
	ds_read_b128 v[62:65], v185 offset:34944
	ds_read_b128 v[58:61], v185 offset:34976
	ds_read_b128 v[54:57], v185 offset:35008
	ds_read_b128 v[50:53], v185 offset:35040
	v_lshl_add_u64 v[106:107], v[2:3], 0, s[2:3]
	ds_read_b128 v[2:5], v183
	ds_read_b128 v[168:171], v183 offset:32
	ds_read_b128 v[228:231], v183 offset:64
	ds_read_b128 v[242:245], v183 offset:96
	s_waitcnt lgkmcnt(3)
	v_mfma_f32_32x32x16_bf16 v[2:17], v[2:5], v[74:77], 0
	s_waitcnt lgkmcnt(2)
	v_mfma_f32_32x32x16_bf16 v[2:17], v[168:171], v[78:81], v[2:17]
	ds_read_b128 v[168:171], v183 offset:128
	s_waitcnt lgkmcnt(2)
	v_mfma_f32_32x32x16_bf16 v[2:17], v[228:231], v[70:73], v[2:17]
	ds_read_b128 v[228:231], v183 offset:160
	s_waitcnt lgkmcnt(2)
	v_mfma_f32_32x32x16_bf16 v[2:17], v[242:245], v[66:69], v[2:17]
	ds_read_b128 v[242:245], v183 offset:192
	s_waitcnt lgkmcnt(2)
	v_mfma_f32_32x32x16_bf16 v[2:17], v[168:171], v[62:65], v[2:17]
	ds_read_b128 v[168:171], v183 offset:224
	s_waitcnt lgkmcnt(2)
	v_mfma_f32_32x32x16_bf16 v[2:17], v[228:231], v[58:61], v[2:17]
	s_waitcnt lgkmcnt(1)
	v_mfma_f32_32x32x16_bf16 v[2:17], v[242:245], v[54:57], v[2:17]
	s_waitcnt lgkmcnt(0)
	v_mfma_f32_32x32x16_bf16 v[2:17], v[168:171], v[50:53], v[2:17]
	s_nop 11
	v_mul_f32_e32 v2, v46, v2
	v_mul_f32_e32 v3, v47, v3
	v_cvt_pk_bf16_f32 v2, v2, v3
	v_mul_f32_e32 v3, v48, v4
	v_mul_f32_e32 v4, v49, v5
	v_cvt_pk_bf16_f32 v3, v3, v4
	v_lshl_add_u64 v[4:5], v[106:107], 0, v[0:1]
	global_store_dwordx2 v[4:5], v[2:3], off
	v_mul_f32_e32 v0, v42, v6
	v_mul_f32_e32 v2, v43, v7
	v_mul_f32_e32 v3, v45, v9
	v_cvt_pk_bf16_f32 v2, v0, v2
	v_mul_f32_e32 v0, v44, v8
	v_cvt_pk_bf16_f32 v3, v0, v3
	v_lshl_add_u64 v[4:5], v[106:107], 0, v[104:105]
	global_store_dwordx2 v[4:5], v[2:3], off
	v_mul_f32_e32 v0, v38, v10
	v_mul_f32_e32 v2, v39, v11
	v_mul_f32_e32 v3, v41, v13
	v_cvt_pk_bf16_f32 v2, v0, v2
	v_mul_f32_e32 v0, v40, v12
	v_cvt_pk_bf16_f32 v3, v0, v3
	v_lshl_add_u64 v[4:5], v[106:107], 0, v[108:109]
	global_store_dwordx2 v[4:5], v[2:3], off
	v_mul_f32_e32 v0, v34, v14
	v_mul_f32_e32 v2, v35, v15
	v_mul_f32_e32 v3, v37, v17
	v_lshl_add_u64 v[4:5], v[106:107], 0, v[102:103]
	v_cvt_pk_bf16_f32 v2, v0, v2
	v_mul_f32_e32 v0, v36, v16
	v_cvt_pk_bf16_f32 v3, v0, v3
	global_store_dwordx2 v[4:5], v[2:3], off
	ds_read_b128 v[2:5], v184
	ds_read_b128 v[34:37], v184 offset:32
	ds_read_b128 v[228:231], v184 offset:64
	ds_read_b128 v[242:245], v184 offset:96
	s_waitcnt lgkmcnt(3)
	v_mfma_f32_32x32x16_bf16 v[2:17], v[2:5], v[74:77], 0
	s_waitcnt lgkmcnt(2)
	v_mfma_f32_32x32x16_bf16 v[2:17], v[34:37], v[78:81], v[2:17]
	ds_read_b128 v[34:37], v184 offset:128
	s_waitcnt lgkmcnt(2)
	v_mfma_f32_32x32x16_bf16 v[2:17], v[228:231], v[70:73], v[2:17]
	ds_read_b128 v[228:231], v184 offset:160
	s_waitcnt lgkmcnt(2)
	v_mfma_f32_32x32x16_bf16 v[2:17], v[242:245], v[66:69], v[2:17]
	ds_read_b128 v[242:245], v184 offset:192
	s_waitcnt lgkmcnt(2)
	v_mfma_f32_32x32x16_bf16 v[2:17], v[34:37], v[62:65], v[2:17]
	ds_read_b128 v[34:37], v184 offset:224
	s_waitcnt lgkmcnt(2)
	v_mfma_f32_32x32x16_bf16 v[2:17], v[228:231], v[58:61], v[2:17]
	s_waitcnt lgkmcnt(1)
	v_mfma_f32_32x32x16_bf16 v[2:17], v[242:245], v[54:57], v[2:17]
	s_waitcnt lgkmcnt(0)
	v_mfma_f32_32x32x16_bf16 v[2:17], v[34:37], v[50:53], v[2:17]
	s_nop 11
	v_mul_f32_e32 v0, v30, v2
	v_mul_f32_e32 v2, v31, v3
	v_mul_f32_e32 v3, v33, v5
	v_cvt_pk_bf16_f32 v2, v0, v2
	v_mul_f32_e32 v0, v32, v4
	v_cvt_pk_bf16_f32 v3, v0, v3
	v_lshl_add_u64 v[4:5], v[106:107], 0, v[110:111]
	global_store_dwordx2 v[4:5], v[2:3], off
	v_mul_f32_e32 v0, v26, v6
	v_mul_f32_e32 v2, v27, v7
	v_mul_f32_e32 v3, v29, v9
	v_cvt_pk_bf16_f32 v2, v0, v2
	v_mul_f32_e32 v0, v28, v8
	v_cvt_pk_bf16_f32 v3, v0, v3
	v_lshl_add_u64 v[4:5], v[106:107], 0, v[112:113]
	global_store_dwordx2 v[4:5], v[2:3], off
	v_mul_f32_e32 v0, v22, v10
	v_mul_f32_e32 v2, v23, v11
	v_mul_f32_e32 v3, v25, v13
	v_cvt_pk_bf16_f32 v2, v0, v2
	v_mul_f32_e32 v0, v24, v12
	v_cvt_pk_bf16_f32 v3, v0, v3
	v_lshl_add_u64 v[4:5], v[106:107], 0, v[114:115]
	global_store_dwordx2 v[4:5], v[2:3], off
	v_mul_f32_e32 v0, v18, v14
	v_mul_f32_e32 v2, v19, v15
	v_mul_f32_e32 v3, v21, v17
	v_cvt_pk_bf16_f32 v2, v0, v2
	v_mul_f32_e32 v0, v20, v16
	v_cvt_pk_bf16_f32 v3, v0, v3

.LBB0_227:
	s_or_b64 exec, exec, s[40:41]
	v_add_u32_e32 v54, s95, v83
	v_min_i32_e32 v54, 1, v54
	v_add_u32_e32 v54, 1, v54
	v_cvt_f32_i32_e32 v54, v54
	s_waitcnt vmcnt(24)
	v_cndmask_b32_e32 v9, 0, v9, vcc
	s_waitcnt vmcnt(8)
	v_cndmask_b32_e64 v0, 0, v50, s[34:35]
	v_cndmask_b32_e64 v10, 0, v10, s[0:1]
	v_rcp_iflag_f32_e32 v54, v54
	v_lshlrev_b32_e32 v50, 16, v9
	v_and_b32_e32 v9, 0xffff0000, v9
	v_add_f32_e32 v51, 0, v50
	v_add_f32_e32 v52, 0, v9
	v_lshlrev_b32_e32 v53, 16, v10
	v_and_b32_e32 v10, 0xffff0000, v10
	v_add_f32_e32 v51, v51, v53
	v_add_f32_e32 v52, v52, v10
	v_fma_f32 v55, v54, v51, -v53
	v_fma_f32 v54, v54, v52, -v10
	v_sub_f32_e32 v9, v52, v9
	v_add_u32_e32 v52, s95, v127
	v_min_i32_e32 v52, 1, v52
	v_add_u32_e32 v52, 1, v52
	v_cvt_f32_i32_e32 v52, v52
	v_cndmask_b32_e64 v11, v11, 0, s[2:3]
	v_sub_f32_e32 v50, v51, v50
	v_lshlrev_b32_e32 v51, 16, v11
	v_rcp_iflag_f32_e32 v52, v52
	v_and_b32_e32 v11, 0xffff0000, v11
	v_cvt_pk_bf16_f32 v54, v55, v54
	v_add_u32_e32 v168, 0, v145
	v_add_f32_e32 v50, v50, v51
	v_add_f32_e32 v9, v9, v11
	s_waitcnt lgkmcnt(0)
	s_barrier
	ds_write_b32 v168, v54 offset:34816
	v_fma_f32 v54, v52, v50, -v51
	v_fma_f32 v52, v52, v9, -v11
	v_cvt_pk_bf16_f32 v52, v54, v52
	v_add_u32_e32 v169, 0, v146
	ds_write_b32 v169, v52 offset:34816
	v_add_u32_e32 v52, s95, v128
	v_min_i32_e32 v52, 1, v52
	v_add_u32_e32 v52, 1, v52
	v_cvt_f32_i32_e32 v52, v52
	v_cndmask_b32_e64 v12, 0, v12, s[6:7]
	v_sub_f32_e32 v50, v50, v53
	v_sub_f32_e32 v9, v9, v10
	v_rcp_iflag_f32_e32 v52, v52
	v_lshlrev_b32_e32 v10, 16, v12
	v_add_f32_e32 v50, v50, v10
	v_and_b32_e32 v12, 0xffff0000, v12
	v_fma_f32 v53, v52, v50, -v10
	v_sub_f32_e32 v50, v50, v51
	v_add_u32_e32 v51, s95, v129
	v_min_i32_e32 v51, 1, v51
	v_add_u32_e32 v51, 1, v51
	v_cvt_f32_i32_e32 v51, v51
	v_cndmask_b32_e64 v13, 0, v13, s[8:9]
	v_add_f32_e32 v9, v9, v12
	v_fma_f32 v52, v52, v9, -v12
	v_rcp_iflag_f32_e32 v51, v51
	v_sub_f32_e32 v9, v9, v11
	v_lshlrev_b32_e32 v11, 16, v13
	v_cvt_pk_bf16_f32 v52, v53, v52
	v_add_u32_e32 v170, 0, v147
	v_add_f32_e32 v50, v50, v11
	ds_write_b32 v170, v52 offset:34816
	v_fma_f32 v52, v51, v50, -v11
	v_sub_f32_e32 v10, v50, v10
	v_add_u32_e32 v50, s95, v130
	v_min_i32_e32 v50, 1, v50
	v_add_u32_e32 v50, 1, v50
	v_cvt_f32_i32_e32 v50, v50
	v_and_b32_e32 v13, 0xffff0000, v13
	v_cndmask_b32_e64 v14, 0, v14, s[10:11]
	v_add_f32_e32 v9, v9, v13
	v_rcp_iflag_f32_e32 v50, v50
	v_fma_f32 v51, v51, v9, -v13
	v_sub_f32_e32 v9, v9, v12
	v_lshlrev_b32_e32 v12, 16, v14
	v_and_b32_e32 v14, 0xffff0000, v14
	v_cndmask_b32_e64 v15, 0, v15, s[12:13]
	v_cvt_pk_bf16_f32 v51, v52, v51
	v_add_u32_e32 v171, 0, v148
	v_add_f32_e32 v10, v10, v12
	v_add_f32_e32 v9, v9, v14
	ds_write_b32 v171, v51 offset:34816
	v_fma_f32 v51, v50, v10, -v12
	v_fma_f32 v50, v50, v9, -v14
	v_sub_f32_e32 v10, v10, v11
	v_sub_f32_e32 v9, v9, v13
	v_lshlrev_b32_e32 v11, 16, v15
	v_and_b32_e32 v13, 0xffff0000, v15
	v_add_u32_e32 v15, s95, v131
	v_min_i32_e32 v15, 1, v15
	v_add_u32_e32 v15, 1, v15
	v_cvt_f32_i32_e32 v15, v15
	v_cvt_pk_bf16_f32 v50, v51, v50
	v_add_u32_e32 v172, 0, v149
	v_add_f32_e32 v10, v10, v11
	v_rcp_iflag_f32_e32 v15, v15
	v_add_f32_e32 v9, v9, v13
	ds_write_b32 v172, v50 offset:34816
	v_add_u32_e32 v173, 0, v150
	v_fma_f32 v50, v15, v10, -v11
	v_fma_f32 v15, v15, v9, -v13
	v_cvt_pk_bf16_f32 v15, v50, v15
	ds_write_b32 v173, v15 offset:34816
	v_add_u32_e32 v15, s95, v132
	v_min_i32_e32 v15, 1, v15
	v_add_u32_e32 v15, 1, v15
	v_cvt_f32_i32_e32 v15, v15
	v_cndmask_b32_e64 v16, 0, v16, s[14:15]
	v_sub_f32_e32 v10, v10, v12
	v_sub_f32_e32 v9, v9, v14
	v_rcp_iflag_f32_e32 v15, v15
	v_lshlrev_b32_e32 v12, 16, v16
	v_and_b32_e32 v14, 0xffff0000, v16
	v_add_f32_e32 v10, v10, v12
	v_add_f32_e32 v9, v9, v14
	v_fma_f32 v16, v15, v10, -v12
	v_fma_f32 v15, v15, v9, -v14
	v_cvt_pk_bf16_f32 v15, v16, v15
	v_add_u32_e32 v174, 0, v151
	ds_write_b32 v174, v15 offset:34816
	v_add_u32_e32 v15, s95, v133
	v_min_i32_e32 v15, 1, v15
	v_add_u32_e32 v15, 1, v15
	v_cvt_f32_i32_e32 v15, v15
	v_cndmask_b32_e64 v17, 0, v17, s[16:17]
	v_sub_f32_e32 v10, v10, v11
	v_sub_f32_e32 v9, v9, v13
	v_rcp_iflag_f32_e32 v15, v15
	v_lshlrev_b32_e32 v11, 16, v17
	v_and_b32_e32 v13, 0xffff0000, v17
	v_add_f32_e32 v10, v10, v11
	v_add_f32_e32 v9, v9, v13
	v_fma_f32 v16, v15, v10, -v11
	v_fma_f32 v15, v15, v9, -v13
	v_sub_f32_e32 v9, v9, v14
	v_add_u32_e32 v14, s95, v134
	v_min_i32_e32 v14, 1, v14
	v_add_u32_e32 v14, 1, v14
	v_cvt_f32_i32_e32 v14, v14
	v_cndmask_b32_e64 v8, 0, v8, s[18:19]
	v_sub_f32_e32 v10, v10, v12
	v_lshlrev_b32_e32 v12, 16, v8
	v_rcp_iflag_f32_e32 v14, v14
	v_and_b32_e32 v8, 0xffff0000, v8
	v_cvt_pk_bf16_f32 v15, v16, v15
	v_add_u32_e32 v175, 0, v152
	v_add_f32_e32 v10, v10, v12
	v_add_f32_e32 v9, v9, v8
	ds_write_b32 v175, v15 offset:34816
	v_fma_f32 v15, v14, v10, -v12
	v_fma_f32 v14, v14, v9, -v8
	v_sub_f32_e32 v9, v9, v13
	v_add_u32_e32 v13, s95, v135
	v_min_i32_e32 v13, 1, v13
	v_add_u32_e32 v13, 1, v13
	v_cvt_f32_i32_e32 v13, v13
	v_cndmask_b32_e64 v7, 0, v7, s[20:21]
	v_sub_f32_e32 v10, v10, v11
	v_lshlrev_b32_e32 v11, 16, v7
	v_rcp_iflag_f32_e32 v13, v13
	v_cvt_pk_bf16_f32 v14, v15, v14
	v_add_u32_e32 v176, 0, v153
	v_add_f32_e32 v10, v10, v11
	ds_write_b32 v176, v14 offset:34816
	v_fma_f32 v14, v13, v10, -v11
	v_sub_f32_e32 v10, v10, v12
	v_add_u32_e32 v12, s95, v136
	v_min_i32_e32 v12, 1, v12
	v_add_u32_e32 v12, 1, v12
	v_cvt_f32_i32_e32 v12, v12
	v_and_b32_e32 v7, 0xffff0000, v7
	v_cndmask_b32_e64 v6, 0, v6, s[22:23]
	v_add_f32_e32 v9, v9, v7
	v_rcp_iflag_f32_e32 v12, v12
	v_fma_f32 v13, v13, v9, -v7
	v_sub_f32_e32 v8, v9, v8
	v_lshlrev_b32_e32 v9, 16, v6
	v_cvt_pk_bf16_f32 v13, v14, v13
	v_add_u32_e32 v177, 0, v154
	v_add_f32_e32 v10, v10, v9
	ds_write_b32 v177, v13 offset:34816
	v_fma_f32 v13, v12, v10, -v9
	v_sub_f32_e32 v10, v10, v11
	v_add_u32_e32 v11, s95, v137
	v_min_i32_e32 v11, 1, v11
	v_add_u32_e32 v11, 1, v11
	v_cvt_f32_i32_e32 v11, v11
	v_and_b32_e32 v6, 0xffff0000, v6
	v_cndmask_b32_e64 v5, 0, v5, s[24:25]
	v_add_f32_e32 v8, v8, v6
	v_rcp_iflag_f32_e32 v11, v11
	v_fma_f32 v12, v12, v8, -v6
	v_sub_f32_e32 v7, v8, v7
	v_lshlrev_b32_e32 v8, 16, v5
	v_cvt_pk_bf16_f32 v12, v13, v12
	v_add_u32_e32 v178, 0, v155
	v_add_f32_e32 v10, v10, v8
	ds_write_b32 v178, v12 offset:34816
	v_fma_f32 v12, v11, v10, -v8
	v_sub_f32_e32 v9, v10, v9
	v_add_u32_e32 v10, s95, v138
	v_min_i32_e32 v10, 1, v10
	v_add_u32_e32 v10, 1, v10
	v_cvt_f32_i32_e32 v10, v10
	v_and_b32_e32 v5, 0xffff0000, v5
	v_cndmask_b32_e64 v4, 0, v4, s[26:27]
	v_add_f32_e32 v7, v7, v5
	v_rcp_iflag_f32_e32 v10, v10
	v_fma_f32 v11, v11, v7, -v5
	v_sub_f32_e32 v6, v7, v6
	v_lshlrev_b32_e32 v7, 16, v4
	v_cvt_pk_bf16_f32 v11, v12, v11
	v_add_u32_e32 v179, 0, v156
	v_add_f32_e32 v9, v9, v7
	ds_write_b32 v179, v11 offset:34816
	v_fma_f32 v11, v10, v9, -v7
	v_sub_f32_e32 v8, v9, v8
	v_add_u32_e32 v9, s95, v139
	v_min_i32_e32 v9, 1, v9
	v_add_u32_e32 v9, 1, v9
	v_cvt_f32_i32_e32 v9, v9
	v_and_b32_e32 v4, 0xffff0000, v4
	v_cndmask_b32_e64 v3, 0, v3, s[28:29]
	v_add_f32_e32 v6, v6, v4
	v_rcp_iflag_f32_e32 v9, v9
	v_fma_f32 v10, v10, v6, -v4
	v_sub_f32_e32 v5, v6, v5
	v_lshlrev_b32_e32 v6, 16, v3
	v_cvt_pk_bf16_f32 v10, v11, v10
	v_add_u32_e32 v180, 0, v157
	v_add_f32_e32 v8, v8, v6
	ds_write_b32 v180, v10 offset:34816
	v_fma_f32 v10, v9, v8, -v6
	v_sub_f32_e32 v7, v8, v7
	v_add_u32_e32 v8, s95, v140
	v_min_i32_e32 v8, 1, v8
	v_add_u32_e32 v8, 1, v8
	v_cvt_f32_i32_e32 v8, v8
	v_and_b32_e32 v3, 0xffff0000, v3
	v_cndmask_b32_e64 v2, 0, v2, s[38:39]
	v_add_f32_e32 v5, v5, v3
	v_rcp_iflag_f32_e32 v8, v8
	v_fma_f32 v9, v9, v5, -v3
	v_sub_f32_e32 v4, v5, v4
	v_lshlrev_b32_e32 v5, 16, v2
	v_and_b32_e32 v2, 0xffff0000, v2
	v_add_f32_e32 v7, v7, v5
	v_add_f32_e32 v4, v4, v2
	v_fma_f32 v5, v8, v7, -v5
	v_fma_f32 v2, v8, v4, -v2
	v_cvt_pk_bf16_f32 v2, v5, v2
	v_add_u32_e32 v5, s95, v141
	v_min_i32_e32 v5, 1, v5
	v_add_u32_e32 v5, 1, v5
	v_cvt_f32_i32_e32 v5, v5
	v_add_u32_e32 v181, 0, v158
	v_add_u32_e32 v182, 0, v159
	s_or_b32 s0, s94, 0x80
	v_rcp_iflag_f32_e32 v5, v5
	v_cvt_pk_bf16_f32 v9, v10, v9
	ds_write_b32 v181, v9 offset:34816
	ds_write_b32 v182, v2 offset:34816
	v_sub_f32_e32 v2, v7, v6
	v_sub_f32_e32 v3, v4, v3
	v_lshlrev_b32_e32 v4, 16, v0
	v_and_b32_e32 v0, 0xffff0000, v0
	s_xor_b32 s1, s95, 0xffffff7f
	s_mul_i32 s2, s0, 0x1e00
	v_add_f32_e32 v2, v2, v4
	v_add_f32_e32 v3, v3, v0
	s_mul_hi_i32 s3, s0, 0x1e00
	s_add_u32 s2, s91, s2
	v_fma_f32 v2, v5, v2, -v4
	v_fma_f32 v0, v5, v3, -v0
	s_addc_u32 s3, s92, s3
	v_mov_b32_e32 v105, v1
	v_cvt_pk_bf16_f32 v0, v2, v0
	v_add_u32_e32 v183, 0, v160
	v_cmp_lt_i32_e32 vcc, s1, v141
	v_lshl_add_u64 v[2:3], s[2:3], 0, v[104:105]
	s_mov_b64 s[2:3], 0x1420
	ds_write_b32 v183, v0 offset:34816
	v_lshl_add_u64 v[2:3], v[2:3], 0, s[2:3]
	v_cndmask_b32_e32 v0, 0, v141, vcc
	s_movk_i32 s6, 0x1e00
	v_mad_i64_i32 v[4:5], s[2:3], v0, s6, v[2:3]
	global_load_dword v0, v[4:5], off
	v_add_u32_e32 v186, v144, v143
	v_add_u32_e32 v185, v144, v161
	v_mov_b32_e32 v103, v1
	v_add_u32_e32 v184, v144, v163
	v_lshlrev_b32_e32 v116, 1, v98
	v_mov_b32_e32 v117, v1
	s_mov_b64 s[36:37], 0
	s_waitcnt vmcnt(0)
	v_cndmask_b32_e32 v105, 0, v0, vcc
	v_cmp_lt_i32_e32 vcc, s1, v126
	v_mov_b32_e32 v212, 0
	s_nop 0
	v_cndmask_b32_e32 v0, 0, v126, vcc
	v_mad_i64_i32 v[4:5], s[2:3], v0, s6, v[2:3]
	s_and_saveexec_b64 s[98:99], vcc
	global_load_dword v212, v[4:5], off
	s_mov_b64 exec, s[98:99]
	v_cmp_lt_i32_e32 vcc, s1, v83
	v_mov_b32_e32 v213, 0
	s_nop 0
	v_cndmask_b32_e32 v0, 0, v83, vcc
	v_mad_i64_i32 v[4:5], s[2:3], v0, s6, v[2:3]
	s_and_saveexec_b64 s[98:99], vcc
	global_load_dword v213, v[4:5], off
	s_mov_b64 exec, s[98:99]
	v_cmp_gt_i32_e32 vcc, s1, v83
	s_nop 1
	v_cndmask_b32_e64 v0, v127, 0, vcc
	v_mad_i64_i32 v[4:5], s[2:3], v0, s6, v[2:3]
	global_load_dword v0, v[4:5], off
	s_waitcnt vmcnt(0)
	v_cndmask_b32_e64 v191, v0, 0, vcc
	v_cmp_lt_i32_e32 vcc, s1, v128
	v_mov_b32_e32 v211, 0
	s_nop 0
	v_cndmask_b32_e32 v0, 0, v128, vcc
	v_mad_i64_i32 v[4:5], s[2:3], v0, s6, v[2:3]
	s_and_saveexec_b64 s[98:99], vcc
	global_load_dword v211, v[4:5], off
	s_mov_b64 exec, s[98:99]
	v_cmp_lt_i32_e32 vcc, s1, v129
	v_mov_b32_e32 v210, 0
	s_nop 0
	v_cndmask_b32_e32 v0, 0, v129, vcc
	v_mad_i64_i32 v[4:5], s[2:3], v0, s6, v[2:3]
	s_and_saveexec_b64 s[98:99], vcc
	global_load_dword v210, v[4:5], off
	s_mov_b64 exec, s[98:99]
	v_cmp_lt_i32_e32 vcc, s1, v130
	v_mov_b32_e32 v209, 0
	s_nop 0
	v_cndmask_b32_e32 v0, 0, v130, vcc
	v_mad_i64_i32 v[4:5], s[2:3], v0, s6, v[2:3]
	s_and_saveexec_b64 s[98:99], vcc
	global_load_dword v209, v[4:5], off
	s_mov_b64 exec, s[98:99]
	v_cmp_lt_i32_e32 vcc, s1, v131
	v_mov_b32_e32 v208, 0
	s_nop 0
	v_cndmask_b32_e32 v0, 0, v131, vcc
	v_mad_i64_i32 v[4:5], s[2:3], v0, s6, v[2:3]
	s_and_saveexec_b64 s[98:99], vcc
	global_load_dword v208, v[4:5], off
	s_mov_b64 exec, s[98:99]
	v_cmp_lt_i32_e32 vcc, s1, v132
	v_mov_b32_e32 v207, 0
	s_nop 0
	v_cndmask_b32_e32 v0, 0, v132, vcc
	v_mad_i64_i32 v[4:5], s[2:3], v0, s6, v[2:3]
	s_and_saveexec_b64 s[98:99], vcc
	global_load_dword v207, v[4:5], off
	s_mov_b64 exec, s[98:99]
	v_cmp_lt_i32_e32 vcc, s1, v133
	v_mov_b32_e32 v206, 0
	s_nop 0
	v_cndmask_b32_e32 v0, 0, v133, vcc
	v_mad_i64_i32 v[4:5], s[2:3], v0, s6, v[2:3]
	s_and_saveexec_b64 s[98:99], vcc
	global_load_dword v206, v[4:5], off
	s_mov_b64 exec, s[98:99]
	v_cmp_lt_i32_e32 vcc, s1, v134
	v_mov_b32_e32 v205, 0
	s_nop 0
	v_cndmask_b32_e32 v0, 0, v134, vcc
	v_mad_i64_i32 v[4:5], s[2:3], v0, s6, v[2:3]
	s_and_saveexec_b64 s[98:99], vcc
	global_load_dword v205, v[4:5], off
	s_mov_b64 exec, s[98:99]
	v_cmp_lt_i32_e32 vcc, s1, v135
	v_mov_b32_e32 v204, 0
	s_nop 0
	v_cndmask_b32_e32 v0, 0, v135, vcc
	v_mad_i64_i32 v[4:5], s[2:3], v0, s6, v[2:3]
	s_and_saveexec_b64 s[98:99], vcc
	global_load_dword v204, v[4:5], off
	s_mov_b64 exec, s[98:99]
	v_cmp_lt_i32_e32 vcc, s1, v136
	v_mov_b32_e32 v192, 0
	s_nop 0
	v_cndmask_b32_e32 v0, 0, v136, vcc
	v_mad_i64_i32 v[4:5], s[2:3], v0, s6, v[2:3]
	s_and_saveexec_b64 s[98:99], vcc
	global_load_dword v192, v[4:5], off
	s_mov_b64 exec, s[98:99]
	v_cmp_lt_i32_e32 vcc, s1, v137
	v_mov_b32_e32 v190, 0
	s_nop 0
	v_cndmask_b32_e32 v0, 0, v137, vcc
	v_mad_i64_i32 v[4:5], s[2:3], v0, s6, v[2:3]
	s_and_saveexec_b64 s[98:99], vcc
	global_load_dword v190, v[4:5], off
	s_mov_b64 exec, s[98:99]
	v_cmp_lt_i32_e32 vcc, s1, v138
	v_mov_b32_e32 v189, 0
	s_nop 0
	v_cndmask_b32_e32 v0, 0, v138, vcc
	v_mad_i64_i32 v[4:5], s[2:3], v0, s6, v[2:3]
	s_and_saveexec_b64 s[98:99], vcc
	global_load_dword v189, v[4:5], off
	s_mov_b64 exec, s[98:99]
	v_cmp_lt_i32_e32 vcc, s1, v139
	v_mov_b32_e32 v188, 0
	s_nop 0
	v_cndmask_b32_e32 v0, 0, v139, vcc
	v_mad_i64_i32 v[4:5], s[2:3], v0, s6, v[2:3]
	s_and_saveexec_b64 s[98:99], vcc
	global_load_dword v188, v[4:5], off
	s_mov_b64 exec, s[98:99]
	v_cmp_lt_i32_e32 vcc, s1, v140
	s_and_b32 s1, s0, 0xf80
	s_nop 0
	v_cndmask_b32_e32 v0, 0, v140, vcc
	v_mad_i64_i32 v[2:3], s[2:3], v0, s6, v[2:3]
	global_load_dword v0, v[2:3], off
	v_add_u32_e32 v2, s94, v142
	v_ashrrev_i32_e32 v3, 31, v2
	v_lshlrev_b64 v[2:3], 12, v[2:3]
	s_waitcnt lgkmcnt(0)
	s_barrier
	v_lshl_add_u64 v[2:3], s[70:71], 0, v[2:3]
	s_mov_b64 s[2:3], 0x26000800
	ds_read_b128 v[74:77], v186 offset:34816
	ds_read_b128 v[78:81], v186 offset:34848
	ds_read_b128 v[70:73], v186 offset:34880
	ds_read_b128 v[66:69], v186 offset:34912
	ds_read_b128 v[62:65], v186 offset:34944
	ds_read_b128 v[58:61], v186 offset:34976
	ds_read_b128 v[54:57], v186 offset:35008
	ds_read_b128 v[50:53], v186 offset:35040
	v_lshl_add_u64 v[106:107], v[2:3], 0, s[2:3]
	ds_read_b128 v[2:5], v185
	ds_read_b128 v[108:111], v185 offset:32
	ds_read_b128 v[228:231], v185 offset:64
	ds_read_b128 v[242:245], v185 offset:96
	s_waitcnt lgkmcnt(3)
	v_mfma_f32_32x32x16_bf16 v[2:17], v[2:5], v[74:77], 0
	s_waitcnt vmcnt(0)
	v_cndmask_b32_e32 v187, 0, v0, vcc
	s_waitcnt lgkmcnt(2)
	v_mfma_f32_32x32x16_bf16 v[2:17], v[108:111], v[78:81], v[2:17]
	ds_read_b128 v[108:111], v185 offset:128
	s_waitcnt lgkmcnt(2)
	v_mfma_f32_32x32x16_bf16 v[2:17], v[228:231], v[70:73], v[2:17]
	ds_read_b128 v[228:231], v185 offset:160
	s_waitcnt lgkmcnt(2)
	v_mfma_f32_32x32x16_bf16 v[2:17], v[242:245], v[66:69], v[2:17]
	ds_read_b128 v[242:245], v185 offset:192
	s_waitcnt lgkmcnt(2)
	v_mfma_f32_32x32x16_bf16 v[2:17], v[108:111], v[62:65], v[2:17]
	ds_read_b128 v[108:111], v185 offset:224
	s_waitcnt lgkmcnt(2)
	v_mfma_f32_32x32x16_bf16 v[2:17], v[228:231], v[58:61], v[2:17]
	s_waitcnt lgkmcnt(1)
	v_mfma_f32_32x32x16_bf16 v[2:17], v[242:245], v[54:57], v[2:17]
	s_waitcnt lgkmcnt(0)
	v_mfma_f32_32x32x16_bf16 v[2:17], v[108:111], v[50:53], v[2:17]
	v_lshlrev_b32_e32 v108, 1, v90
	v_mov_b32_e32 v109, v1
	v_lshlrev_b32_e32 v110, 1, v92
	v_mov_b32_e32 v111, v1
	s_nop 7
	v_mul_f32_e32 v0, v46, v2
	v_mul_f32_e32 v2, v47, v3
	v_cvt_pk_bf16_f32 v2, v0, v2
	v_mul_f32_e32 v0, v48, v4
	v_mul_f32_e32 v3, v49, v5
	v_cvt_pk_bf16_f32 v3, v0, v3
	v_lshlrev_b32_e32 v0, 1, v88
	v_lshl_add_u64 v[4:5], v[106:107], 0, v[0:1]
	global_store_dwordx2 v[4:5], v[2:3], off
	v_mul_f32_e32 v2, v42, v6
	v_mul_f32_e32 v3, v43, v7
	v_cvt_pk_bf16_f32 v2, v2, v3
	v_mul_f32_e32 v3, v44, v8
	v_mul_f32_e32 v4, v45, v9
	v_cvt_pk_bf16_f32 v3, v3, v4
	v_lshl_add_u64 v[4:5], v[106:107], 0, v[108:109]
	global_store_dwordx2 v[4:5], v[2:3], off
	v_mul_f32_e32 v2, v38, v10
	v_mul_f32_e32 v3, v39, v11
	v_cvt_pk_bf16_f32 v2, v2, v3
	v_mul_f32_e32 v3, v40, v12
	v_mul_f32_e32 v4, v41, v13
	v_cvt_pk_bf16_f32 v3, v3, v4
	v_lshl_add_u64 v[4:5], v[106:107], 0, v[110:111]
	global_store_dwordx2 v[4:5], v[2:3], off
	v_mul_f32_e32 v2, v34, v14
	v_mul_f32_e32 v3, v35, v15
	v_cvt_pk_bf16_f32 v2, v2, v3
	v_mul_f32_e32 v3, v36, v16
	v_mul_f32_e32 v4, v37, v17
	v_cvt_pk_bf16_f32 v3, v3, v4
	v_lshl_add_u64 v[4:5], v[106:107], 0, v[102:103]
	global_store_dwordx2 v[4:5], v[2:3], off
	ds_read_b128 v[2:5], v184
	ds_read_b128 v[112:115], v184 offset:32
	s_waitcnt lgkmcnt(1)
	v_mfma_f32_32x32x16_bf16 v[2:17], v[2:5], v[74:77], 0
	ds_read_b128 v[74:77], v184 offset:64
	s_waitcnt lgkmcnt(1)
	v_mfma_f32_32x32x16_bf16 v[2:17], v[112:115], v[78:81], v[2:17]
	v_lshlrev_b32_e32 v112, 1, v94
	v_mov_b32_e32 v113, v1
	v_lshlrev_b32_e32 v114, 1, v96
	v_mov_b32_e32 v115, v1
	s_waitcnt lgkmcnt(0)
	v_mfma_f32_32x32x16_bf16 v[2:17], v[74:77], v[70:73], v[2:17]
	ds_read_b128 v[70:73], v184 offset:96
	s_waitcnt lgkmcnt(0)
	v_mfma_f32_32x32x16_bf16 v[2:17], v[70:73], v[66:69], v[2:17]
	ds_read_b128 v[66:69], v184 offset:128
	s_waitcnt lgkmcnt(0)
	v_mfma_f32_32x32x16_bf16 v[2:17], v[66:69], v[62:65], v[2:17]
	ds_read_b128 v[62:65], v184 offset:160
	s_waitcnt lgkmcnt(0)
	v_mfma_f32_32x32x16_bf16 v[2:17], v[62:65], v[58:61], v[2:17]
	ds_read_b128 v[58:61], v184 offset:192
	s_waitcnt lgkmcnt(0)
	v_mfma_f32_32x32x16_bf16 v[2:17], v[58:61], v[54:57], v[2:17]
	ds_read_b128 v[54:57], v184 offset:224
	s_waitcnt lgkmcnt(0)
	v_mfma_f32_32x32x16_bf16 v[2:17], v[54:57], v[50:53], v[2:17]
	s_nop 11
	v_mul_f32_e32 v2, v30, v2
	v_mul_f32_e32 v3, v31, v3
	v_cvt_pk_bf16_f32 v2, v2, v3
	v_mul_f32_e32 v3, v32, v4
	v_mul_f32_e32 v4, v33, v5
	v_cvt_pk_bf16_f32 v3, v3, v4
	v_lshl_add_u64 v[4:5], v[106:107], 0, v[112:113]
	global_store_dwordx2 v[4:5], v[2:3], off
	v_mul_f32_e32 v2, v26, v6
	v_mul_f32_e32 v3, v27, v7
	v_cvt_pk_bf16_f32 v2, v2, v3
	v_mul_f32_e32 v3, v28, v8
	v_mul_f32_e32 v4, v29, v9
	v_cvt_pk_bf16_f32 v3, v3, v4
	v_lshl_add_u64 v[4:5], v[106:107], 0, v[114:115]
	v_add_u32_e32 v8, s1, v83
	global_store_dwordx2 v[4:5], v[2:3], off
	v_mul_f32_e32 v2, v22, v10
	v_mul_f32_e32 v3, v23, v11
	v_min_i32_e32 v8, 1, v8
	v_cvt_pk_bf16_f32 v2, v2, v3
	v_mul_f32_e32 v3, v24, v12
	v_mul_f32_e32 v4, v25, v13
	v_add_u32_e32 v8, 1, v8
	v_cvt_pk_bf16_f32 v3, v3, v4
	v_lshl_add_u64 v[4:5], v[106:107], 0, v[116:117]
	v_cvt_f32_i32_e32 v8, v8
	global_store_dwordx2 v[4:5], v[2:3], off
	v_mul_f32_e32 v2, v18, v14
	v_mul_f32_e32 v3, v19, v15
	v_cvt_pk_bf16_f32 v2, v2, v3
	v_mul_f32_e32 v3, v20, v16
	v_mul_f32_e32 v4, v21, v17
	v_cvt_pk_bf16_f32 v3, v3, v4
	v_lshlrev_b32_e32 v4, 1, v100
	v_mov_b32_e32 v5, v1
	v_lshl_add_u64 v[4:5], v[106:107], 0, v[4:5]
	v_rcp_iflag_f32_e32 v8, v8
	global_store_dwordx2 v[4:5], v[2:3], off
	v_lshlrev_b32_e32 v2, 16, v212
	v_and_b32_e32 v3, 0xffff0000, v212
	v_add_f32_e32 v4, 0, v2
	v_add_f32_e32 v5, 0, v3
	v_lshlrev_b32_e32 v6, 16, v213
	v_and_b32_e32 v7, 0xffff0000, v213
	v_add_f32_e32 v4, v4, v6
	v_add_f32_e32 v5, v5, v7
	v_fma_f32 v9, v8, v4, -v6
	v_fma_f32 v8, v8, v5, -v7
	v_cvt_pk_bf16_f32 v8, v9, v8
	s_waitcnt lgkmcnt(0)
	s_barrier
	ds_write_b32 v168, v8 offset:34816
	v_add_u32_e32 v8, s1, v127
	v_min_i32_e32 v8, 1, v8
	v_add_u32_e32 v8, 1, v8
	v_cvt_f32_i32_e32 v8, v8
	v_sub_f32_e32 v2, v4, v2
	v_sub_f32_e32 v3, v5, v3
	v_lshlrev_b32_e32 v4, 16, v191
	v_rcp_iflag_f32_e32 v8, v8
	v_and_b32_e32 v5, 0xffff0000, v191
	v_add_f32_e32 v2, v2, v4
	v_add_f32_e32 v3, v3, v5
	v_fma_f32 v9, v8, v2, -v4
	v_fma_f32 v8, v8, v3, -v5
	v_cvt_pk_bf16_f32 v8, v9, v8
	ds_write_b32 v169, v8 offset:34816
	v_add_u32_e32 v8, s1, v128
	v_min_i32_e32 v8, 1, v8
	v_add_u32_e32 v8, 1, v8
	v_cvt_f32_i32_e32 v8, v8
	v_sub_f32_e32 v2, v2, v6
	v_sub_f32_e32 v3, v3, v7
	v_lshlrev_b32_e32 v6, 16, v211
	v_rcp_iflag_f32_e32 v8, v8
	v_and_b32_e32 v7, 0xffff0000, v211
	v_add_f32_e32 v2, v2, v6
	v_add_f32_e32 v3, v3, v7
	v_fma_f32 v9, v8, v2, -v6
	v_fma_f32 v8, v8, v3, -v7
	v_cvt_pk_bf16_f32 v8, v9, v8
	ds_write_b32 v170, v8 offset:34816
	v_add_u32_e32 v8, s1, v129
	v_min_i32_e32 v8, 1, v8
	v_add_u32_e32 v8, 1, v8
	v_cvt_f32_i32_e32 v8, v8
	v_sub_f32_e32 v2, v2, v4
	v_sub_f32_e32 v3, v3, v5
	v_lshlrev_b32_e32 v4, 16, v210
	v_rcp_iflag_f32_e32 v8, v8
	v_and_b32_e32 v5, 0xffff0000, v210
	v_add_f32_e32 v2, v2, v4
	v_add_f32_e32 v3, v3, v5
	v_fma_f32 v9, v8, v2, -v4
	v_fma_f32 v8, v8, v3, -v5
	v_cvt_pk_bf16_f32 v8, v9, v8
	ds_write_b32 v171, v8 offset:34816
	v_add_u32_e32 v8, s1, v130
	v_min_i32_e32 v8, 1, v8
	v_add_u32_e32 v8, 1, v8
	v_cvt_f32_i32_e32 v8, v8
	v_sub_f32_e32 v2, v2, v6
	v_sub_f32_e32 v3, v3, v7
	v_lshlrev_b32_e32 v6, 16, v209
	v_rcp_iflag_f32_e32 v8, v8
	v_and_b32_e32 v7, 0xffff0000, v209
	v_add_f32_e32 v2, v2, v6
	v_add_f32_e32 v3, v3, v7
	v_fma_f32 v9, v8, v2, -v6
	v_fma_f32 v8, v8, v3, -v7
	v_cvt_pk_bf16_f32 v8, v9, v8
	ds_write_b32 v172, v8 offset:34816
	v_add_u32_e32 v8, s1, v131
	v_min_i32_e32 v8, 1, v8
	v_add_u32_e32 v8, 1, v8
	v_cvt_f32_i32_e32 v8, v8
	v_sub_f32_e32 v2, v2, v4
	v_sub_f32_e32 v3, v3, v5
	v_lshlrev_b32_e32 v4, 16, v208
	v_rcp_iflag_f32_e32 v8, v8
	v_and_b32_e32 v5, 0xffff0000, v208
	v_add_f32_e32 v2, v2, v4
	v_add_f32_e32 v3, v3, v5
	v_fma_f32 v9, v8, v2, -v4
	v_fma_f32 v8, v8, v3, -v5
	v_cvt_pk_bf16_f32 v8, v9, v8
	ds_write_b32 v173, v8 offset:34816
	v_add_u32_e32 v8, s1, v132
	v_min_i32_e32 v8, 1, v8
	v_add_u32_e32 v8, 1, v8
	v_cvt_f32_i32_e32 v8, v8
	v_sub_f32_e32 v2, v2, v6
	v_sub_f32_e32 v3, v3, v7
	v_lshlrev_b32_e32 v6, 16, v207
	v_rcp_iflag_f32_e32 v8, v8
	v_and_b32_e32 v7, 0xffff0000, v207
	v_add_f32_e32 v2, v2, v6
	v_add_f32_e32 v3, v3, v7
	v_fma_f32 v9, v8, v2, -v6
	v_fma_f32 v8, v8, v3, -v7
	v_cvt_pk_bf16_f32 v8, v9, v8
	ds_write_b32 v174, v8 offset:34816
	v_add_u32_e32 v8, s1, v133
	v_min_i32_e32 v8, 1, v8
	v_add_u32_e32 v8, 1, v8
	v_cvt_f32_i32_e32 v8, v8
	v_sub_f32_e32 v2, v2, v4
	v_sub_f32_e32 v3, v3, v5
	v_lshlrev_b32_e32 v4, 16, v206
	v_rcp_iflag_f32_e32 v8, v8
	v_and_b32_e32 v5, 0xffff0000, v206
	v_add_f32_e32 v2, v2, v4
	v_add_f32_e32 v3, v3, v5
	v_fma_f32 v9, v8, v2, -v4
	v_fma_f32 v8, v8, v3, -v5
	v_cvt_pk_bf16_f32 v8, v9, v8
	ds_write_b32 v175, v8 offset:34816
	v_add_u32_e32 v8, s1, v134
	v_min_i32_e32 v8, 1, v8
	v_add_u32_e32 v8, 1, v8
	v_cvt_f32_i32_e32 v8, v8
	v_sub_f32_e32 v2, v2, v6
	v_sub_f32_e32 v3, v3, v7
	v_lshlrev_b32_e32 v6, 16, v205
	v_rcp_iflag_f32_e32 v8, v8
	v_and_b32_e32 v7, 0xffff0000, v205
	v_add_f32_e32 v2, v2, v6
	v_add_f32_e32 v3, v3, v7
	v_fma_f32 v9, v8, v2, -v6
	v_fma_f32 v8, v8, v3, -v7
	v_cvt_pk_bf16_f32 v8, v9, v8
	ds_write_b32 v176, v8 offset:34816
	v_add_u32_e32 v8, s1, v135
	v_min_i32_e32 v8, 1, v8
	v_add_u32_e32 v8, 1, v8
	v_cvt_f32_i32_e32 v8, v8
	v_sub_f32_e32 v2, v2, v4
	v_sub_f32_e32 v3, v3, v5
	v_lshlrev_b32_e32 v4, 16, v204
	v_rcp_iflag_f32_e32 v8, v8
	v_and_b32_e32 v5, 0xffff0000, v204
	v_add_f32_e32 v2, v2, v4
	v_add_f32_e32 v3, v3, v5
	v_fma_f32 v9, v8, v2, -v4
	v_fma_f32 v8, v8, v3, -v5
	v_cvt_pk_bf16_f32 v8, v9, v8
	ds_write_b32 v177, v8 offset:34816
	v_add_u32_e32 v8, s1, v136
	v_min_i32_e32 v8, 1, v8
	v_add_u32_e32 v8, 1, v8
	v_cvt_f32_i32_e32 v8, v8
	v_sub_f32_e32 v2, v2, v6
	v_sub_f32_e32 v3, v3, v7
	v_lshlrev_b32_e32 v6, 16, v192
	v_rcp_iflag_f32_e32 v8, v8
	v_and_b32_e32 v7, 0xffff0000, v192
	v_add_f32_e32 v2, v2, v6
	v_add_f32_e32 v3, v3, v7
	v_fma_f32 v9, v8, v2, -v6
	v_fma_f32 v8, v8, v3, -v7
	v_cvt_pk_bf16_f32 v8, v9, v8
	ds_write_b32 v178, v8 offset:34816
	v_add_u32_e32 v8, s1, v137
	v_min_i32_e32 v8, 1, v8
	v_add_u32_e32 v8, 1, v8
	v_cvt_f32_i32_e32 v8, v8
	v_sub_f32_e32 v2, v2, v4
	v_sub_f32_e32 v3, v3, v5
	v_lshlrev_b32_e32 v4, 16, v190
	v_rcp_iflag_f32_e32 v8, v8
	v_and_b32_e32 v5, 0xffff0000, v190
	v_add_f32_e32 v2, v2, v4
	v_add_f32_e32 v3, v3, v5
	v_fma_f32 v9, v8, v2, -v4
	v_fma_f32 v8, v8, v3, -v5
	v_cvt_pk_bf16_f32 v8, v9, v8
	ds_write_b32 v179, v8 offset:34816
	v_add_u32_e32 v8, s1, v138
	v_min_i32_e32 v8, 1, v8
	v_add_u32_e32 v8, 1, v8
	v_cvt_f32_i32_e32 v8, v8
	v_sub_f32_e32 v2, v2, v6
	v_sub_f32_e32 v3, v3, v7
	v_lshlrev_b32_e32 v6, 16, v189
	v_rcp_iflag_f32_e32 v8, v8
	v_and_b32_e32 v7, 0xffff0000, v189
	v_add_f32_e32 v2, v2, v6
	v_add_f32_e32 v3, v3, v7
	v_fma_f32 v9, v8, v2, -v6
	v_fma_f32 v8, v8, v3, -v7
	v_cvt_pk_bf16_f32 v8, v9, v8
	ds_write_b32 v180, v8 offset:34816
	v_add_u32_e32 v8, s1, v139
	v_min_i32_e32 v8, 1, v8
	v_add_u32_e32 v8, 1, v8
	v_cvt_f32_i32_e32 v8, v8
	v_sub_f32_e32 v2, v2, v4
	v_sub_f32_e32 v3, v3, v5
	v_lshlrev_b32_e32 v4, 16, v188
	v_rcp_iflag_f32_e32 v8, v8
	v_and_b32_e32 v5, 0xffff0000, v188
	v_add_f32_e32 v2, v2, v4
	v_add_f32_e32 v3, v3, v5
	v_fma_f32 v9, v8, v2, -v4
	v_fma_f32 v8, v8, v3, -v5
	v_cvt_pk_bf16_f32 v8, v9, v8
	ds_write_b32 v181, v8 offset:34816
	v_add_u32_e32 v8, s1, v140
	v_min_i32_e32 v8, 1, v8
	v_add_u32_e32 v8, 1, v8
	v_cvt_f32_i32_e32 v8, v8
	v_sub_f32_e32 v2, v2, v6
	v_lshlrev_b32_e32 v6, 16, v187
	v_sub_f32_e32 v3, v3, v7
	v_rcp_iflag_f32_e32 v8, v8
	v_and_b32_e32 v7, 0xffff0000, v187
	v_add_f32_e32 v2, v2, v6
	v_add_f32_e32 v3, v3, v7
	v_fma_f32 v6, v8, v2, -v6
	v_fma_f32 v7, v8, v3, -v7
	v_cvt_pk_bf16_f32 v6, v6, v7
	ds_write_b32 v182, v6 offset:34816
	v_add_u32_e32 v6, s1, v141
	v_min_i32_e32 v6, 1, v6
	v_add_u32_e32 v6, 1, v6
	v_cvt_f32_i32_e32 v6, v6
	v_sub_f32_e32 v2, v2, v4
	v_lshlrev_b32_e32 v4, 16, v105
	v_sub_f32_e32 v3, v3, v5
	v_rcp_iflag_f32_e32 v6, v6
	v_and_b32_e32 v5, 0xffff0000, v105
	v_add_f32_e32 v2, v2, v4
	v_add_f32_e32 v3, v3, v5
	v_fma_f32 v2, v6, v2, -v4
	v_fma_f32 v3, v6, v3, -v5
	v_cvt_pk_bf16_f32 v2, v2, v3
	ds_write_b32 v183, v2 offset:34816
	v_add_u32_e32 v2, s0, v142
	v_ashrrev_i32_e32 v3, 31, v2
	v_lshlrev_b64 v[2:3], 12, v[2:3]
	s_waitcnt lgkmcnt(0)
	s_barrier
	v_lshl_add_u64 v[2:3], s[70:71], 0, v[2:3]
	ds_read_b128 v[74:77], v186 offset:34816
	ds_read_b128 v[78:81], v186 offset:34848
	ds_read_b128 v[70:73], v186 offset:34880
	ds_read_b128 v[66:69], v186 offset:34912
	ds_read_b128 v[62:65], v186 offset:34944
	ds_read_b128 v[58:61], v186 offset:34976
	ds_read_b128 v[54:57], v186 offset:35008
	ds_read_b128 v[50:53], v186 offset:35040
	v_lshl_add_u64 v[106:107], v[2:3], 0, s[2:3]
	ds_read_b128 v[2:5], v185
	ds_read_b128 v[168:171], v185 offset:32
	ds_read_b128 v[228:231], v185 offset:64
	ds_read_b128 v[242:245], v185 offset:96
	s_waitcnt lgkmcnt(3)
	v_mfma_f32_32x32x16_bf16 v[2:17], v[2:5], v[74:77], 0
	s_waitcnt lgkmcnt(2)
	v_mfma_f32_32x32x16_bf16 v[2:17], v[168:171], v[78:81], v[2:17]
	ds_read_b128 v[168:171], v185 offset:128
	s_waitcnt lgkmcnt(2)
	v_mfma_f32_32x32x16_bf16 v[2:17], v[228:231], v[70:73], v[2:17]
	ds_read_b128 v[228:231], v185 offset:160
	s_waitcnt lgkmcnt(2)
	v_mfma_f32_32x32x16_bf16 v[2:17], v[242:245], v[66:69], v[2:17]
	ds_read_b128 v[242:245], v185 offset:192
	s_waitcnt lgkmcnt(2)
	v_mfma_f32_32x32x16_bf16 v[2:17], v[168:171], v[62:65], v[2:17]
	ds_read_b128 v[168:171], v185 offset:224
	s_waitcnt lgkmcnt(2)
	v_mfma_f32_32x32x16_bf16 v[2:17], v[228:231], v[58:61], v[2:17]
	s_waitcnt lgkmcnt(1)
	v_mfma_f32_32x32x16_bf16 v[2:17], v[242:245], v[54:57], v[2:17]
	s_waitcnt lgkmcnt(0)
	v_mfma_f32_32x32x16_bf16 v[2:17], v[168:171], v[50:53], v[2:17]
	s_nop 11
	v_mul_f32_e32 v2, v46, v2
	v_mul_f32_e32 v3, v47, v3
	v_cvt_pk_bf16_f32 v2, v2, v3
	v_mul_f32_e32 v3, v48, v4
	v_mul_f32_e32 v4, v49, v5
	v_cvt_pk_bf16_f32 v3, v3, v4
	v_lshl_add_u64 v[4:5], v[106:107], 0, v[0:1]
	global_store_dwordx2 v[4:5], v[2:3], off
	v_mul_f32_e32 v0, v42, v6
	v_mul_f32_e32 v2, v43, v7
	v_mul_f32_e32 v3, v45, v9
	v_cvt_pk_bf16_f32 v2, v0, v2
	v_mul_f32_e32 v0, v44, v8
	v_cvt_pk_bf16_f32 v3, v0, v3
	v_lshl_add_u64 v[4:5], v[106:107], 0, v[108:109]
	global_store_dwordx2 v[4:5], v[2:3], off
	v_mul_f32_e32 v0, v38, v10
	v_mul_f32_e32 v2, v39, v11
	v_mul_f32_e32 v3, v41, v13
	v_cvt_pk_bf16_f32 v2, v0, v2
	v_mul_f32_e32 v0, v40, v12
	v_cvt_pk_bf16_f32 v3, v0, v3
	v_lshl_add_u64 v[4:5], v[106:107], 0, v[110:111]
	global_store_dwordx2 v[4:5], v[2:3], off
	v_mul_f32_e32 v0, v34, v14
	v_mul_f32_e32 v2, v35, v15
	v_mul_f32_e32 v3, v37, v17
	v_lshl_add_u64 v[4:5], v[106:107], 0, v[102:103]
	v_cvt_pk_bf16_f32 v2, v0, v2
	v_mul_f32_e32 v0, v36, v16
	v_cvt_pk_bf16_f32 v3, v0, v3
	global_store_dwordx2 v[4:5], v[2:3], off
	ds_read_b128 v[2:5], v184
	ds_read_b128 v[34:37], v184 offset:32
	ds_read_b128 v[228:231], v184 offset:64
	ds_read_b128 v[242:245], v184 offset:96
	s_waitcnt lgkmcnt(3)
	v_mfma_f32_32x32x16_bf16 v[2:17], v[2:5], v[74:77], 0
	s_waitcnt lgkmcnt(2)
	v_mfma_f32_32x32x16_bf16 v[2:17], v[34:37], v[78:81], v[2:17]
	ds_read_b128 v[34:37], v184 offset:128
	s_waitcnt lgkmcnt(2)
	v_mfma_f32_32x32x16_bf16 v[2:17], v[228:231], v[70:73], v[2:17]
	ds_read_b128 v[228:231], v184 offset:160
	s_waitcnt lgkmcnt(2)
	v_mfma_f32_32x32x16_bf16 v[2:17], v[242:245], v[66:69], v[2:17]
	ds_read_b128 v[242:245], v184 offset:192
	s_waitcnt lgkmcnt(2)
	v_mfma_f32_32x32x16_bf16 v[2:17], v[34:37], v[62:65], v[2:17]
	ds_read_b128 v[34:37], v184 offset:224
	s_waitcnt lgkmcnt(2)
	v_mfma_f32_32x32x16_bf16 v[2:17], v[228:231], v[58:61], v[2:17]
	s_waitcnt lgkmcnt(1)
	v_mfma_f32_32x32x16_bf16 v[2:17], v[242:245], v[54:57], v[2:17]
	s_waitcnt lgkmcnt(0)
	v_mfma_f32_32x32x16_bf16 v[2:17], v[34:37], v[50:53], v[2:17]
	s_nop 11
	v_mul_f32_e32 v0, v30, v2
	v_mul_f32_e32 v2, v31, v3
	v_mul_f32_e32 v3, v33, v5
	v_cvt_pk_bf16_f32 v2, v0, v2
	v_mul_f32_e32 v0, v32, v4
	v_cvt_pk_bf16_f32 v3, v0, v3
	v_lshl_add_u64 v[4:5], v[106:107], 0, v[112:113]
	global_store_dwordx2 v[4:5], v[2:3], off
	v_mul_f32_e32 v0, v26, v6
	v_mul_f32_e32 v2, v27, v7
	v_mul_f32_e32 v3, v29, v9
	v_cvt_pk_bf16_f32 v2, v0, v2
	v_mul_f32_e32 v0, v28, v8
	v_cvt_pk_bf16_f32 v3, v0, v3
	v_lshl_add_u64 v[4:5], v[106:107], 0, v[114:115]
	global_store_dwordx2 v[4:5], v[2:3], off
	v_mul_f32_e32 v0, v22, v10
	v_mul_f32_e32 v2, v23, v11
	v_mul_f32_e32 v3, v25, v13
	v_cvt_pk_bf16_f32 v2, v0, v2
	v_mul_f32_e32 v0, v24, v12
	v_cvt_pk_bf16_f32 v3, v0, v3
	v_lshl_add_u64 v[4:5], v[106:107], 0, v[116:117]
	global_store_dwordx2 v[4:5], v[2:3], off
	v_mul_f32_e32 v0, v18, v14
	v_mul_f32_e32 v2, v19, v15
	v_mul_f32_e32 v3, v21, v17
	v_cvt_pk_bf16_f32 v2, v0, v2
	v_mul_f32_e32 v0, v20, v16
	v_cvt_pk_bf16_f32 v3, v0, v3

.LBB0_235:
	s_add_i32 s40, s33, s4
	s_ashr_i32 s41, s40, 31
	s_mul_i32 s2, s40, 0x1e00
	s_mul_hi_i32 s3, s40, 0x1e00
	s_add_u32 s2, s91, s2
	v_lshl_add_u64 v[32:33], s[70:71], 0, v[28:29]
	s_addc_u32 s3, s92, s3
	v_add_co_u32_e32 v36, vcc, 0x8001000, v32
	s_add_u32 s10, s2, 0x1820
	s_nop 0
	v_addc_co_u32_e32 v37, vcc, 0, v33, vcc
	s_addc_u32 s11, s3, 0
	global_load_dword v32, v[36:37], off offset:2080
	global_load_dword v34, v[36:37], off offset:2336
	global_load_dword v39, v[36:37], off offset:2592
	global_load_dword v38, v[36:37], off offset:2848
	s_nop 0
	global_load_dword v37, v[36:37], off offset:3104
	s_nop 0
	global_load_dword v75, v47, s[10:11]
	global_load_dword v73, v48, s[10:11]
	global_load_dword v72, v49, s[10:11]
	s_add_u32 s10, s2, 0x1b20
	s_addc_u32 s11, s3, 0
	v_lshlrev_b32_e32 v0, 1, v4
	s_add_i32 s34, s53, s4
	v_lshl_add_u64 v[40:41], s[2:3], 0, v[0:1]
	s_lshl_b64 s[38:39], s[40:41], 6
	s_ashr_i32 s35, s34, 31
	s_mul_i32 s2, s34, 0x1e00
	v_add_co_u32_e32 v40, vcc, s60, v40
	s_mul_hi_i32 s3, s34, 0x1e00
	s_add_u32 s2, s91, s2
	v_addc_co_u32_e32 v41, vcc, 0, v41, vcc
	v_lshlrev_b32_e32 v33, 2, v4
	s_addc_u32 s3, s92, s3
	global_load_dword v77, v47, s[10:11]
	global_load_dword v74, v48, s[10:11]
	global_load_ushort v83, v[40:41], off offset:3360
	global_load_ushort v84, v[40:41], off offset:3392
	v_or_b32_e32 v40, s38, v33
	v_mov_b32_e32 v41, s39
	s_add_u32 s10, s2, 0x1820
	v_lshl_add_u64 v[50:51], s[6:7], 0, v[40:41]
	v_lshl_add_u64 v[40:41], s[8:9], 0, v[40:41]
	s_addc_u32 s11, s3, 0
	global_load_dword v85, v[50:51], off
	global_load_dword v86, v[40:41], off
	global_load_dword v79, v47, s[10:11]
	global_load_dword v82, v48, s[10:11]
	global_load_dword v81, v49, s[10:11]
	s_add_u32 s10, s2, 0x1b20
	s_addc_u32 s11, s3, 0
	s_add_i32 s28, s44, s4
	v_lshl_add_u64 v[40:41], s[2:3], 0, v[0:1]
	s_lshl_b64 s[36:37], s[34:35], 6
	s_ashr_i32 s29, s28, 31
	s_mul_i32 s2, s28, 0x1e00
	v_add_co_u32_e32 v40, vcc, s60, v40
	s_mul_hi_i32 s3, s28, 0x1e00
	s_add_u32 s2, s91, s2
	v_addc_co_u32_e32 v41, vcc, 0, v41, vcc
	s_addc_u32 s3, s92, s3
	global_load_dword v80, v47, s[10:11]
	global_load_dword v78, v48, s[10:11]
	global_load_ushort v69, v[40:41], off offset:3360
	global_load_ushort v70, v[40:41], off offset:3392
	v_or_b32_e32 v40, s36, v33
	v_mov_b32_e32 v41, s37
	s_add_u32 s10, s2, 0x1820
	v_lshl_add_u64 v[50:51], s[6:7], 0, v[40:41]
	v_lshl_add_u64 v[40:41], s[8:9], 0, v[40:41]
	s_addc_u32 s11, s3, 0
	global_load_dword v71, v[50:51], off
	global_load_dword v76, v[40:41], off
	global_load_dword v90, v47, s[10:11]
	global_load_dword v91, v48, s[10:11]
	global_load_dword v87, v49, s[10:11]
	s_add_u32 s10, s2, 0x1b20
	s_addc_u32 s11, s3, 0
	s_add_i32 s24, s58, s4
	v_lshl_add_u64 v[40:41], s[2:3], 0, v[0:1]
	s_lshl_b64 s[26:27], s[28:29], 6
	s_ashr_i32 s25, s24, 31
	s_mul_i32 s2, s24, 0x1e00
	v_add_co_u32_e32 v40, vcc, s60, v40
	s_mul_hi_i32 s3, s24, 0x1e00
	s_add_u32 s2, s91, s2
	v_addc_co_u32_e32 v41, vcc, 0, v41, vcc
	s_addc_u32 s3, s92, s3
	global_load_dword v92, v47, s[10:11]
	global_load_dword v93, v48, s[10:11]
	global_load_ushort v65, v[40:41], off offset:3360
	global_load_ushort v66, v[40:41], off offset:3392
	v_or_b32_e32 v40, s26, v33
	v_mov_b32_e32 v41, s27
	s_add_u32 s10, s2, 0x1820
	v_lshl_add_u64 v[50:51], s[6:7], 0, v[40:41]
	v_lshl_add_u64 v[40:41], s[8:9], 0, v[40:41]
	s_addc_u32 s11, s3, 0
	global_load_dword v67, v[50:51], off
	global_load_dword v68, v[40:41], off
	global_load_dword v94, v47, s[10:11]
	global_load_dword v95, v48, s[10:11]
	global_load_dword v96, v49, s[10:11]
	s_add_u32 s10, s2, 0x1b20
	s_addc_u32 s11, s3, 0
	s_add_i32 s20, s45, s4
	v_lshl_add_u64 v[40:41], s[2:3], 0, v[0:1]
	s_lshl_b64 s[22:23], s[24:25], 6
	s_ashr_i32 s21, s20, 31
	s_mul_i32 s2, s20, 0x1e00
	v_add_co_u32_e32 v40, vcc, s60, v40
	s_mul_hi_i32 s3, s20, 0x1e00
	s_add_u32 s2, s91, s2
	v_addc_co_u32_e32 v41, vcc, 0, v41, vcc
	s_addc_u32 s3, s92, s3
	global_load_dword v97, v47, s[10:11]
	global_load_dword v98, v48, s[10:11]
	global_load_ushort v61, v[40:41], off offset:3360
	global_load_ushort v62, v[40:41], off offset:3392
	v_or_b32_e32 v40, s22, v33
	v_mov_b32_e32 v41, s23
	s_add_u32 s10, s2, 0x1820
	v_lshl_add_u64 v[50:51], s[6:7], 0, v[40:41]
	v_lshl_add_u64 v[40:41], s[8:9], 0, v[40:41]
	s_addc_u32 s11, s3, 0
	global_load_dword v63, v[50:51], off
	global_load_dword v64, v[40:41], off
	global_load_dword v99, v47, s[10:11]
	global_load_dword v100, v48, s[10:11]
	global_load_dword v101, v49, s[10:11]
	s_add_u32 s10, s2, 0x1b20
	s_addc_u32 s11, s3, 0
	s_add_i32 s12, s46, s4
	v_lshl_add_u64 v[40:41], s[2:3], 0, v[0:1]
	s_lshl_b64 s[18:19], s[20:21], 6
	s_ashr_i32 s13, s12, 31
	s_mul_i32 s2, s12, 0x1e00
	v_add_co_u32_e32 v40, vcc, s60, v40
	s_mul_hi_i32 s3, s12, 0x1e00
	s_add_u32 s2, s91, s2
	v_addc_co_u32_e32 v41, vcc, 0, v41, vcc
	s_addc_u32 s3, s92, s3
	global_load_dword v147, v47, s[10:11]
	global_load_dword v148, v48, s[10:11]
	global_load_ushort v57, v[40:41], off offset:3360
	global_load_ushort v58, v[40:41], off offset:3392
	v_or_b32_e32 v40, s18, v33
	v_mov_b32_e32 v41, s19
	s_add_u32 s10, s2, 0x1820
	v_lshl_add_u64 v[50:51], s[6:7], 0, v[40:41]
	v_lshl_add_u64 v[40:41], s[8:9], 0, v[40:41]
	s_addc_u32 s11, s3, 0
	global_load_dword v59, v[50:51], off
	global_load_dword v60, v[40:41], off
	global_load_dword v149, v47, s[10:11]
	global_load_dword v150, v48, s[10:11]
	global_load_dword v152, v49, s[10:11]
	s_add_u32 s10, s2, 0x1b20
	s_addc_u32 s11, s3, 0
	global_load_dword v153, v47, s[10:11]
	global_load_dword v154, v48, s[10:11]
	s_add_i32 s10, s47, s4
	v_lshl_add_u64 v[40:41], s[2:3], 0, v[0:1]
	s_lshl_b64 s[16:17], s[12:13], 6
	s_ashr_i32 s11, s10, 31
	s_mul_i32 s2, s10, 0x1e00
	v_add_co_u32_e32 v40, vcc, s60, v40
	s_mul_hi_i32 s3, s10, 0x1e00
	s_add_u32 s2, s91, s2
	v_addc_co_u32_e32 v41, vcc, 0, v41, vcc
	s_addc_u32 s3, s92, s3
	global_load_ushort v52, v[40:41], off offset:3360
	global_load_ushort v53, v[40:41], off offset:3392
	v_or_b32_e32 v40, s16, v33
	v_mov_b32_e32 v41, s17
	s_add_u32 s14, s2, 0x1820
	v_lshl_add_u64 v[50:51], s[6:7], 0, v[40:41]
	v_lshl_add_u64 v[40:41], s[8:9], 0, v[40:41]
	s_addc_u32 s15, s3, 0
	global_load_dword v55, v[50:51], off
	global_load_dword v56, v[40:41], off
	global_load_dword v155, v47, s[14:15]
	global_load_dword v156, v48, s[14:15]
	global_load_dword v157, v49, s[14:15]
	s_add_u32 s14, s2, 0x1b20
	s_addc_u32 s15, s3, 0
	global_load_dword v158, v47, s[14:15]
	global_load_dword v159, v48, s[14:15]
	s_waitcnt vmcnt(58)
	v_and_b32_e32 v145, 0xffff0000, v75
	s_waitcnt vmcnt(57)
	v_and_b32_e32 v142, 0xffff0000, v73
	v_lshlrev_b32_e32 v146, 16, v75
	v_mul_f32_e32 v75, v145, v145
	v_lshlrev_b32_e32 v144, 16, v73
	v_mul_f32_e32 v73, v142, v142
	s_waitcnt vmcnt(56)
	v_and_b32_e32 v141, 0xffff0000, v72
	v_fmac_f32_e32 v73, v144, v144
	v_lshlrev_b32_e32 v143, 16, v72
	v_mul_f32_e32 v72, v141, v141
	s_waitcnt vmcnt(55)
	v_and_b32_e32 v139, 0xffff0000, v77
	s_waitcnt vmcnt(54)
	v_and_b32_e32 v137, 0xffff0000, v74
	v_fmac_f32_e32 v75, v146, v146
	v_fmac_f32_e32 v72, v143, v143
	v_lshlrev_b32_e32 v140, 16, v77
	v_mul_f32_e32 v77, v139, v139
	v_lshlrev_b32_e32 v138, 16, v74
	v_mul_f32_e32 v74, v137, v137
	v_add_f32_e32 v73, v75, v73
	s_waitcnt vmcnt(49)
	v_and_b32_e32 v135, 0xffff0000, v79
	s_waitcnt vmcnt(48)
	v_and_b32_e32 v132, 0xffff0000, v82
	v_lshl_add_u64 v[40:41], s[2:3], 0, v[0:1]
	v_fmac_f32_e32 v77, v140, v140
	v_fmac_f32_e32 v74, v138, v138
	v_add_f32_e32 v163, v73, v72
	v_lshlrev_b32_e32 v136, 16, v79
	v_mul_f32_e32 v72, v135, v135
	v_lshlrev_b32_e32 v134, 16, v82
	v_mul_f32_e32 v73, v132, v132
	s_waitcnt vmcnt(47)
	v_and_b32_e32 v131, 0xffff0000, v81
	v_add_co_u32_e32 v40, vcc, s60, v40
	v_add_f32_e32 v161, v77, v74
	v_fmac_f32_e32 v73, v134, v134
	v_lshlrev_b32_e32 v133, 16, v81
	v_mul_f32_e32 v74, v131, v131
	v_fmac_f32_e32 v72, v136, v136
	v_addc_co_u32_e32 v41, vcc, 0, v41, vcc
	s_lshl_b64 s[14:15], s[10:11], 6
	v_fmac_f32_e32 v74, v133, v133
	v_add_f32_e32 v72, v72, v73
	s_waitcnt vmcnt(40)
	v_and_b32_e32 v125, 0xffff0000, v90
	s_waitcnt vmcnt(39)
	v_and_b32_e32 v122, 0xffff0000, v91
	global_load_ushort v0, v[40:41], off offset:3360
	global_load_ushort v50, v[40:41], off offset:3392
	v_or_b32_e32 v40, s14, v33
	v_mov_b32_e32 v41, s15
	v_add_f32_e32 v165, v72, v74
	v_lshlrev_b32_e32 v126, 16, v90
	v_mul_f32_e32 v72, v125, v125
	v_lshlrev_b32_e32 v124, 16, v91
	v_mul_f32_e32 v73, v122, v122
	s_waitcnt vmcnt(40)
	v_and_b32_e32 v121, 0xffff0000, v87
	v_lshl_add_u64 v[88:89], s[6:7], 0, v[40:41]
	v_lshl_add_u64 v[40:41], s[8:9], 0, v[40:41]
	v_lshlrev_b32_e32 v36, 16, v32
	v_and_b32_e32 v33, 0xffff0000, v32
	v_lshlrev_b32_e32 v32, 16, v34
	v_and_b32_e32 v34, 0xffff0000, v34
	v_and_b32_e32 v129, 0xffff0000, v80
	v_and_b32_e32 v127, 0xffff0000, v78
	v_fmac_f32_e32 v73, v124, v124
	v_lshlrev_b32_e32 v123, 16, v87
	v_mul_f32_e32 v74, v121, v121
	v_fmac_f32_e32 v72, v126, v126
	global_load_dword v51, v[88:89], off
	global_load_dword v54, v[40:41], off
	v_mul_f32_e32 v88, v33, v33
	v_mul_f32_e32 v89, v34, v34
	v_and_b32_e32 v41, 0xffff0000, v39
	v_lshlrev_b32_e32 v130, 16, v80
	v_mul_f32_e32 v75, v129, v129
	v_lshlrev_b32_e32 v128, 16, v78
	v_mul_f32_e32 v77, v127, v127
	v_fmac_f32_e32 v74, v123, v123
	v_add_f32_e32 v72, v72, v73
	s_waitcnt vmcnt(35)
	v_and_b32_e32 v115, 0xffff0000, v94
	s_waitcnt vmcnt(34)
	v_and_b32_e32 v112, 0xffff0000, v95
	v_fmac_f32_e32 v89, v32, v32
	v_lshlrev_b32_e32 v35, 16, v39
	v_mul_f32_e32 v102, v41, v41
	v_and_b32_e32 v39, 0xffff0000, v38
	v_and_b32_e32 v151, 0xffff0000, v37
	v_fmac_f32_e32 v88, v36, v36
	v_fmac_f32_e32 v75, v130, v130
	v_fmac_f32_e32 v77, v128, v128
	v_and_b32_e32 v119, 0xffff0000, v92
	v_and_b32_e32 v117, 0xffff0000, v93
	v_add_f32_e32 v167, v72, v74
	v_lshlrev_b32_e32 v116, 16, v94
	v_mul_f32_e32 v72, v115, v115
	v_lshlrev_b32_e32 v114, 16, v95
	v_mul_f32_e32 v73, v112, v112
	s_waitcnt vmcnt(33)
	v_and_b32_e32 v111, 0xffff0000, v96
	v_fmac_f32_e32 v102, v35, v35
	v_lshlrev_b32_e32 v40, 16, v38
	v_mul_f32_e32 v103, v39, v39
	v_lshlrev_b32_e32 v38, 16, v37
	v_mul_f32_e32 v37, v151, v151
	v_add_f32_e32 v88, v88, v89
	v_add_f32_e32 v164, v75, v77
	v_lshlrev_b32_e32 v120, 16, v92
	v_mul_f32_e32 v75, v119, v119
	v_lshlrev_b32_e32 v118, 16, v93
	v_mul_f32_e32 v77, v117, v117
	v_fmac_f32_e32 v73, v114, v114
	v_lshlrev_b32_e32 v113, 16, v96
	v_mul_f32_e32 v74, v111, v111
	v_fmac_f32_e32 v72, v116, v116
	v_fmac_f32_e32 v103, v40, v40
	v_fmac_f32_e32 v37, v38, v38
	v_add_f32_e32 v160, v88, v102
	v_fmac_f32_e32 v75, v120, v120
	v_fmac_f32_e32 v77, v118, v118
	v_fmac_f32_e32 v74, v113, v113
	s_waitcnt vmcnt(32)
	v_and_b32_e32 v109, 0xffff0000, v97
	s_waitcnt vmcnt(31)
	v_and_b32_e32 v107, 0xffff0000, v98
	v_add_f32_e32 v72, v72, v73
	s_waitcnt vmcnt(26)
	v_and_b32_e32 v105, 0xffff0000, v99
	s_waitcnt vmcnt(25)
	v_and_b32_e32 v102, 0xffff0000, v100
	v_add_f32_e32 v37, v103, v37
	v_add_f32_e32 v166, v75, v77
	v_lshlrev_b32_e32 v110, 16, v97
	v_mul_f32_e32 v75, v109, v109
	v_lshlrev_b32_e32 v108, 16, v98
	v_mul_f32_e32 v77, v107, v107
	v_add_f32_e32 v169, v72, v74
	v_lshlrev_b32_e32 v106, 16, v99
	v_mul_f32_e32 v72, v105, v105
	v_lshlrev_b32_e32 v104, 16, v100
	v_mul_f32_e32 v73, v102, v102
	s_waitcnt vmcnt(24)
	v_lshlrev_b32_e32 v103, 16, v101
	v_and_b32_e32 v101, 0xffff0000, v101
	v_fmac_f32_e32 v75, v110, v110
	v_fmac_f32_e32 v77, v108, v108
	v_fmac_f32_e32 v73, v104, v104
	v_mul_f32_e32 v74, v101, v101
	s_waitcnt vmcnt(23)
	v_and_b32_e32 v99, 0xffff0000, v147
	s_waitcnt vmcnt(22)
	v_and_b32_e32 v97, 0xffff0000, v148
	v_fmac_f32_e32 v72, v106, v106
	v_add_f32_e32 v168, v75, v77
	v_fmac_f32_e32 v74, v103, v103
	v_lshlrev_b32_e32 v100, 16, v147
	v_mul_f32_e32 v75, v99, v99
	v_lshlrev_b32_e32 v98, 16, v148
	v_mul_f32_e32 v77, v97, v97
	v_add_f32_e32 v72, v72, v73
	s_waitcnt vmcnt(17)
	v_and_b32_e32 v95, 0xffff0000, v149
	s_waitcnt vmcnt(16)
	v_and_b32_e32 v92, 0xffff0000, v150
	v_fmac_f32_e32 v75, v100, v100
	v_fmac_f32_e32 v77, v98, v98
	v_add_f32_e32 v148, v72, v74
	v_lshlrev_b32_e32 v96, 16, v149
	v_mul_f32_e32 v72, v95, v95
	v_lshlrev_b32_e32 v94, 16, v150
	v_mul_f32_e32 v73, v92, v92
	s_waitcnt vmcnt(15)
	v_and_b32_e32 v91, 0xffff0000, v152
	s_waitcnt vmcnt(14)
	v_and_b32_e32 v89, 0xffff0000, v153
	s_waitcnt vmcnt(13)
	v_and_b32_e32 v87, 0xffff0000, v154
	v_add_f32_e32 v147, v75, v77
	v_fmac_f32_e32 v73, v94, v94
	v_lshlrev_b32_e32 v93, 16, v152
	v_mul_f32_e32 v74, v91, v91
	v_lshlrev_b32_e32 v90, 16, v153
	v_mul_f32_e32 v75, v89, v89
	v_lshlrev_b32_e32 v88, 16, v154
	v_mul_f32_e32 v77, v87, v87
	v_fmac_f32_e32 v72, v96, v96
	v_fmac_f32_e32 v74, v93, v93
	v_fmac_f32_e32 v75, v90, v90
	v_fmac_f32_e32 v77, v88, v88
	v_add_f32_e32 v72, v72, v73
	v_add_f32_e32 v149, v75, v77
	v_add_f32_e32 v150, v72, v74
	s_waitcnt vmcnt(5)
	v_lshlrev_b32_e32 v75, 16, v158
	v_and_b32_e32 v74, 0xffff0000, v158
	ds_bpermute_b32 v158, v5, v164
	v_and_b32_e32 v81, 0xffff0000, v155
	v_and_b32_e32 v78, 0xffff0000, v156
	v_lshlrev_b32_e32 v82, 16, v155
	v_mul_f32_e32 v152, v81, v81
	s_waitcnt lgkmcnt(0)
	v_add_f32_e32 v158, v164, v158
	ds_bpermute_b32 v164, v5, v148
	v_lshlrev_b32_e32 v80, 16, v156
	v_mul_f32_e32 v153, v78, v78
	v_and_b32_e32 v77, 0xffff0000, v157
	v_fmac_f32_e32 v153, v80, v80
	s_waitcnt lgkmcnt(0)
	v_add_f32_e32 v148, v148, v164
	ds_bpermute_b32 v164, v5, v147
	v_lshlrev_b32_e32 v79, 16, v157
	v_mul_f32_e32 v154, v77, v77
	v_fmac_f32_e32 v152, v82, v82
	v_fmac_f32_e32 v154, v79, v79
	s_waitcnt lgkmcnt(0)
	v_add_f32_e32 v147, v147, v164
	ds_bpermute_b32 v164, v5, v150
	v_add_f32_e32 v152, v152, v153
	v_add_f32_e32 v152, v152, v154
	s_waitcnt vmcnt(4)
	v_and_b32_e32 v72, 0xffff0000, v159
	v_mul_f32_e32 v155, v74, v74
	s_waitcnt lgkmcnt(0)
	v_add_f32_e32 v150, v150, v164
	ds_bpermute_b32 v164, v5, v149
	v_lshlrev_b32_e32 v73, 16, v159
	v_mul_f32_e32 v156, v72, v72
	v_fmac_f32_e32 v155, v75, v75
	v_fmac_f32_e32 v156, v73, v73
	s_waitcnt lgkmcnt(0)
	v_add_f32_e32 v149, v149, v164
	ds_bpermute_b32 v164, v5, v152
	v_add_f32_e32 v155, v155, v156
	ds_bpermute_b32 v153, v5, v160
	ds_bpermute_b32 v154, v5, v37
	ds_bpermute_b32 v156, v5, v161
	s_waitcnt lgkmcnt(3)
	v_add_f32_e32 v152, v152, v164
	ds_bpermute_b32 v164, v5, v155
	s_waitcnt lgkmcnt(3)
	v_add_f32_e32 v153, v160, v153
	s_waitcnt lgkmcnt(2)
	v_add_f32_e32 v37, v37, v154
	ds_bpermute_b32 v154, v5, v163
	s_waitcnt lgkmcnt(2)
	v_add_f32_e32 v156, v161, v156
	s_waitcnt lgkmcnt(1)
	v_add_f32_e32 v155, v155, v164
	ds_bpermute_b32 v164, v42, v153
	ds_bpermute_b32 v157, v5, v165
	s_waitcnt lgkmcnt(2)
	v_add_f32_e32 v154, v163, v154
	ds_bpermute_b32 v159, v5, v167
	ds_bpermute_b32 v160, v5, v166
	s_waitcnt lgkmcnt(3)
	v_add_f32_e32 v153, v153, v164
	ds_bpermute_b32 v164, v42, v37
	s_waitcnt lgkmcnt(3)
	v_add_f32_e32 v157, v165, v157
	s_waitcnt lgkmcnt(2)
	v_add_f32_e32 v159, v167, v159
	s_waitcnt lgkmcnt(1)
	v_add_f32_e32 v160, v166, v160
	ds_bpermute_b32 v161, v5, v169
	s_waitcnt lgkmcnt(1)
	v_add_f32_e32 v37, v37, v164
	ds_bpermute_b32 v164, v42, v154
	ds_bpermute_b32 v163, v5, v168
	s_waitcnt lgkmcnt(2)
	v_add_f32_e32 v161, v169, v161
	s_waitcnt lgkmcnt(1)
	v_add_f32_e32 v154, v154, v164
	ds_bpermute_b32 v164, v42, v156
	s_waitcnt lgkmcnt(1)
	v_add_f32_e32 v163, v168, v163
	s_waitcnt lgkmcnt(0)
	v_add_f32_e32 v156, v156, v164
	ds_bpermute_b32 v164, v42, v157
	ds_bpermute_b32 v200, v42, v158
	ds_bpermute_b32 v201, v42, v159
	ds_bpermute_b32 v202, v42, v160
	ds_bpermute_b32 v196, v42, v161
	ds_bpermute_b32 v162, v42, v163
	s_waitcnt lgkmcnt(0)
	v_add_f32_e32 v157, v157, v164
	v_add_f32_e32 v158, v158, v200
	v_add_f32_e32 v159, v159, v201
	v_add_f32_e32 v160, v160, v202
	v_add_f32_e32 v161, v161, v196
	v_add_f32_e32 v163, v163, v162
	ds_bpermute_b32 v164, v42, v148
	ds_bpermute_b32 v200, v42, v147
	ds_bpermute_b32 v201, v42, v150
	ds_bpermute_b32 v202, v42, v149
	ds_bpermute_b32 v196, v42, v152
	ds_bpermute_b32 v162, v42, v155
	s_waitcnt lgkmcnt(0)
	v_add_f32_e32 v148, v148, v164
	v_add_f32_e32 v147, v147, v200
	v_add_f32_e32 v150, v150, v201
	v_add_f32_e32 v149, v149, v202
	v_add_f32_e32 v152, v152, v196
	v_add_f32_e32 v155, v155, v162
	ds_bpermute_b32 v164, v43, v153
	ds_bpermute_b32 v200, v43, v37
	ds_bpermute_b32 v201, v43, v154
	ds_bpermute_b32 v202, v43, v156
	ds_bpermute_b32 v196, v43, v157
	ds_bpermute_b32 v162, v43, v158
	s_waitcnt lgkmcnt(0)
	v_add_f32_e32 v153, v153, v164
	v_add_f32_e32 v37, v37, v200
	v_add_f32_e32 v154, v154, v201
	v_add_f32_e32 v156, v156, v202
	v_add_f32_e32 v157, v157, v196
	v_add_f32_e32 v158, v158, v162
	ds_bpermute_b32 v164, v43, v159
	ds_bpermute_b32 v200, v43, v160
	ds_bpermute_b32 v201, v43, v161
	ds_bpermute_b32 v202, v43, v163
	ds_bpermute_b32 v196, v43, v148
	ds_bpermute_b32 v162, v43, v147
	s_waitcnt lgkmcnt(0)
	v_add_f32_e32 v159, v159, v164
	v_add_f32_e32 v160, v160, v200
	v_add_f32_e32 v161, v161, v201
	v_add_f32_e32 v163, v163, v202
	v_add_f32_e32 v148, v148, v196
	v_add_f32_e32 v147, v147, v162
	ds_bpermute_b32 v164, v43, v150
	ds_bpermute_b32 v200, v43, v149
	ds_bpermute_b32 v201, v43, v152
	ds_bpermute_b32 v202, v43, v155
	s_waitcnt lgkmcnt(0)
	v_add_f32_e32 v150, v150, v164
	v_add_f32_e32 v149, v149, v200
	v_add_f32_e32 v152, v152, v201
	v_add_f32_e32 v155, v155, v202
	ds_bpermute_b32 v164, v44, v153
	ds_bpermute_b32 v200, v44, v37
	ds_bpermute_b32 v201, v44, v154
	ds_bpermute_b32 v202, v44, v156
	ds_bpermute_b32 v196, v44, v157
	ds_bpermute_b32 v162, v44, v158
	s_waitcnt lgkmcnt(0)
	v_add_f32_e32 v153, v153, v164
	v_add_f32_e32 v37, v37, v200
	v_add_f32_e32 v154, v154, v201
	v_add_f32_e32 v156, v156, v202
	v_add_f32_e32 v157, v157, v196
	v_add_f32_e32 v158, v158, v162
	ds_bpermute_b32 v164, v44, v159
	ds_bpermute_b32 v200, v44, v160
	ds_bpermute_b32 v201, v44, v161
	ds_bpermute_b32 v202, v44, v163
	ds_bpermute_b32 v196, v44, v148
	ds_bpermute_b32 v162, v44, v147
	s_waitcnt lgkmcnt(0)
	v_add_f32_e32 v159, v159, v164
	v_add_f32_e32 v160, v160, v200
	v_add_f32_e32 v161, v161, v201
	v_add_f32_e32 v163, v163, v202
	v_add_f32_e32 v148, v148, v196
	v_add_f32_e32 v147, v147, v162
	ds_bpermute_b32 v164, v44, v150
	ds_bpermute_b32 v200, v44, v149
	s_waitcnt lgkmcnt(0)
	v_add_f32_e32 v150, v150, v164
	v_add_f32_e32 v149, v149, v200
	ds_bpermute_b32 v164, v44, v152
	s_waitcnt lgkmcnt(0)
	v_add_f32_e32 v164, v152, v164
	ds_bpermute_b32 v152, v44, v155
	s_waitcnt lgkmcnt(0)
	v_add_f32_e32 v155, v155, v152
	ds_bpermute_b32 v152, v45, v153
	s_waitcnt lgkmcnt(0)
	v_add_f32_e32 v165, v153, v152
	ds_bpermute_b32 v152, v45, v37
	s_waitcnt lgkmcnt(0)
	v_add_f32_e32 v37, v37, v152
	ds_bpermute_b32 v152, v45, v154
	s_waitcnt lgkmcnt(0)
	v_add_f32_e32 v178, v154, v152
	ds_bpermute_b32 v152, v45, v156
	ds_bpermute_b32 v180, v46, v178
	s_waitcnt lgkmcnt(1)
	v_add_f32_e32 v177, v156, v152
	ds_bpermute_b32 v152, v45, v157
	ds_bpermute_b32 v179, v46, v177
	s_waitcnt lgkmcnt(1)
	v_add_f32_e32 v174, v157, v152
	ds_bpermute_b32 v152, v45, v158
	ds_bpermute_b32 v176, v46, v174
	s_waitcnt lgkmcnt(1)
	v_add_f32_e32 v173, v158, v152
	ds_bpermute_b32 v152, v45, v159
	ds_bpermute_b32 v175, v46, v173
	s_waitcnt lgkmcnt(1)
	v_add_f32_e32 v170, v159, v152
	ds_bpermute_b32 v152, v45, v160
	ds_bpermute_b32 v172, v46, v170
	s_waitcnt lgkmcnt(1)
	v_add_f32_e32 v169, v160, v152
	ds_bpermute_b32 v152, v45, v161
	ds_bpermute_b32 v171, v46, v169
	s_waitcnt lgkmcnt(1)
	v_add_f32_e32 v161, v161, v152
	ds_bpermute_b32 v152, v45, v163
	ds_bpermute_b32 v168, v46, v161
	s_waitcnt lgkmcnt(1)
	v_add_f32_e32 v160, v163, v152
	ds_bpermute_b32 v152, v45, v148
	ds_bpermute_b32 v163, v46, v160
	s_waitcnt lgkmcnt(1)
	v_add_f32_e32 v157, v148, v152
	ds_bpermute_b32 v148, v45, v147
	ds_bpermute_b32 v159, v46, v157
	s_waitcnt lgkmcnt(1)
	v_add_f32_e32 v156, v147, v148
	ds_bpermute_b32 v147, v45, v150
	ds_bpermute_b32 v148, v46, v165
	ds_bpermute_b32 v158, v46, v156
	s_waitcnt lgkmcnt(2)
	v_add_f32_e32 v153, v150, v147
	ds_bpermute_b32 v147, v45, v149
	s_waitcnt lgkmcnt(0)
	v_add_f32_e32 v152, v149, v147
	ds_bpermute_b32 v147, v45, v164
	ds_bpermute_b32 v154, v46, v152
	s_waitcnt lgkmcnt(1)
	v_add_f32_e32 v149, v164, v147
	v_add_f32_e32 v164, v165, v148
	v_fmamk_f32 v164, v164, 0x3b2aaaab, v194
	v_cmp_gt_f32_e32 vcc, s61, v164
	v_mul_f32_e32 v165, 0x4f800000, v164
	ds_bpermute_b32 v148, v46, v37
	v_cndmask_b32_e32 v164, v164, v165, vcc
	v_sqrt_f32_e32 v165, v164
	ds_bpermute_b32 v147, v45, v155
	ds_bpermute_b32 v150, v46, v149
	s_waitcnt lgkmcnt(2)
	v_add_f32_e32 v37, v37, v148
	v_add_u32_e32 v166, -1, v165
	v_fma_f32 v167, -v166, v165, v164
	v_cmp_ge_f32_e64 s[2:3], 0, v167
	v_add_u32_e32 v167, 1, v165
	v_fmamk_f32 v37, v37, 0x3b800000, v194
	v_cndmask_b32_e64 v166, v165, v166, s[2:3]
	v_fma_f32 v165, -v167, v165, v164
	v_cmp_lt_f32_e64 s[2:3], 0, v165
	s_waitcnt lgkmcnt(1)
	v_add_f32_e32 v147, v155, v147
	ds_bpermute_b32 v155, v46, v153
	v_cndmask_b32_e64 v165, v166, v167, s[2:3]
	v_mul_f32_e32 v166, 0x37800000, v165
	v_cndmask_b32_e32 v165, v165, v166, vcc
	v_cmp_class_f32_e32 vcc, v164, v195
	ds_bpermute_b32 v148, v46, v147
	s_nop 0
	v_cndmask_b32_e32 v164, v165, v164, vcc
	v_div_scale_f32 v165, s[2:3], v164, v164, 1.0
	v_rcp_f32_e32 v166, v165
	s_nop 0
	v_fma_f32 v167, -v165, v166, 1.0
	v_fmac_f32_e32 v166, v167, v166
	v_div_scale_f32 v167, vcc, 1.0, v164, 1.0
	v_mul_f32_e32 v181, v167, v166
	v_fma_f32 v182, -v165, v181, v167
	v_fmac_f32_e32 v181, v182, v166
	v_fma_f32 v165, -v165, v181, v167
	v_div_fmas_f32 v165, v165, v166, v181
	v_div_fixup_f32 v164, v165, v164, 1.0
	v_cmp_gt_f32_e32 vcc, s61, v37
	v_mul_f32_e32 v165, 0x4f800000, v37
	v_mul_f32_e32 v36, v164, v36
	v_cndmask_b32_e32 v37, v37, v165, vcc
	v_sqrt_f32_e32 v165, v37
	v_mul_f32_e32 v33, v164, v33
	v_mul_f32_e32 v36, v36, v2
	v_mul_f32_e32 v33, v33, v3
	v_add_u32_e32 v166, -1, v165
	v_fma_f32 v167, -v166, v165, v37
	v_cmp_ge_f32_e64 s[2:3], 0, v167
	v_add_u32_e32 v167, 1, v165
	v_cvt_pk_bf16_f32 v33, v36, v33
	v_mul_f32_e32 v34, v164, v34
	v_cndmask_b32_e64 v166, v165, v166, s[2:3]
	v_fma_f32 v165, -v167, v165, v37
	v_cmp_lt_f32_e64 s[2:3], 0, v165
	v_mul_f32_e32 v41, v164, v41
	s_nop 0
	v_cndmask_b32_e64 v165, v166, v167, s[2:3]
	v_mul_f32_e32 v166, 0x37800000, v165
	v_cndmask_b32_e32 v165, v165, v166, vcc
	v_cmp_class_f32_e32 vcc, v37, v195
	v_mul_f32_e32 v166, v164, v32
	s_nop 0
	v_cndmask_b32_e32 v165, v165, v37, vcc
	v_lshl_add_u64 v[36:37], s[70:71], 0, v[24:25]
	global_store_dword v[36:37], v33, off
	global_load_dwordx2 v[32:33], v[8:9], off
	s_waitcnt vmcnt(0)
	v_mul_f32_e32 v34, v34, v33
	v_mul_f32_e32 v166, v166, v32
	v_cvt_pk_bf16_f32 v34, v166, v34
	global_store_dword v[36:37], v34, off offset:256
	v_mul_f32_e32 v166, v164, v35
	global_load_dwordx2 v[34:35], v[10:11], off
	s_waitcnt vmcnt(0)
	v_mul_f32_e32 v41, v41, v35
	v_mul_f32_e32 v166, v166, v34
	v_cvt_pk_bf16_f32 v41, v166, v41
	global_store_dword v[36:37], v41, off offset:512
	v_div_scale_f32 v36, s[2:3], v165, v165, 1.0
	v_rcp_f32_e32 v37, v36
	s_mov_b32 s2, 0x3000000
	v_fma_f32 v41, -v36, v37, 1.0
	v_fmac_f32_e32 v37, v41, v37
	v_div_scale_f32 v41, vcc, 1.0, v165, 1.0
	v_mul_f32_e32 v164, v41, v37
	v_fma_f32 v166, -v36, v164, v41
	v_fmac_f32_e32 v164, v166, v37
	v_fma_f32 v36, -v36, v164, v41
	v_div_fmas_f32 v36, v36, v37, v164
	v_div_fixup_f32 v181, v36, v165, 1.0
	global_load_dwordx2 v[36:37], v[12:13], off
	v_mul_f32_e32 v40, v181, v40
	v_mul_f32_e32 v39, v181, v39
	v_mul_f32_e32 v164, v181, v38
	v_mul_f32_e32 v151, v181, v151
	s_waitcnt vmcnt(0)
	v_mul_f32_e32 v40, v40, v36
	v_mul_f32_e32 v39, v39, v37
	v_cvt_pk_bf16_f32 v39, v40, v39
	v_lshl_add_u64 v[40:41], s[70:71], 0, v[22:23]
	v_add_co_u32_e32 v40, vcc, s2, v40
	s_nop 1
	v_addc_co_u32_e32 v41, vcc, 0, v41, vcc
	global_store_dword v[40:41], v39, off
	global_load_dwordx2 v[38:39], v[14:15], off
	s_waitcnt vmcnt(0)
	v_mul_f32_e32 v151, v151, v39
	v_mul_f32_e32 v164, v164, v38
	v_cvt_pk_bf16_f32 v151, v164, v151
	global_store_dword v[40:41], v151, off offset:256
	s_and_saveexec_b64 s[2:3], s[0:1]
	s_cbranch_execz .LBB0_237
	v_lshl_add_u64 v[40:41], s[70:71], 0, v[30:31]
	v_add_co_u32_e32 v40, vcc, 0x8001000, v40
	s_movk_i32 s5, 0x7fff
	s_nop 0
	v_addc_co_u32_e32 v41, vcc, 0, v41, vcc
	global_load_ushort v151, v[40:41], off offset:3360
	global_load_ushort v166, v[40:41], off offset:3392
	v_lshl_add_u64 v[40:41], s[70:71], 0, v[26:27]
	v_add_co_u32_e32 v164, vcc, 0x39e00000, v40
	s_waitcnt vmcnt(1)
	v_lshlrev_b32_e32 v151, 16, v151
	v_addc_co_u32_e32 v165, vcc, 0, v41, vcc
	v_add_co_u32_e32 v40, vcc, 0x3a200000, v40
	global_load_dword v164, v[164:165], off
	s_nop 0
	v_addc_co_u32_e32 v41, vcc, 0, v41, vcc
	global_load_dword v165, v[40:41], off
	s_waitcnt vmcnt(2)
	v_lshlrev_b32_e32 v166, 16, v166
	s_waitcnt vmcnt(0)
	v_mul_f32_e32 v40, v165, v166
	v_fma_f32 v40, v164, v151, -v40
	v_bfe_u32 v41, v40, 16, 1
	v_mul_f32_e32 v164, v164, v166
	v_add3_u32 v167, v40, v41, s5
	v_lshl_add_u64 v[40:41], s[70:71], 0, v[20:21]
	v_fmac_f32_e32 v164, v165, v151
	v_add_co_u32_e32 v40, vcc, 0x5000000, v40
	v_bfe_u32 v151, v164, 16, 1
	s_nop 0
	v_addc_co_u32_e32 v41, vcc, 0, v41, vcc
	v_add3_u32 v151, v164, v151, s5
	global_store_short_d16_hi v[40:41], v167, off
	global_store_short_d16_hi v[40:41], v151, off offset:32

.LBB0_463:
	s_ashr_i32 s1, s0, 31
	s_lshl_b64 s[2:3], s[0:1], 12
	v_lshl_add_u64 v[84:85], v[66:67], 0, s[2:3]
	global_load_dwordx4 v[62:65], v[84:85], off
	global_load_dwordx4 v[58:61], v[84:85], off offset:1024
	s_add_i32 s2, s0, s97
	s_ashr_i32 s3, s2, 31
	s_lshl_b64 s[4:5], s[2:3], 12
	v_lshl_add_u64 v[82:83], v[66:67], 0, s[4:5]
	global_load_dwordx4 v[46:49], v[82:83], off
	global_load_dwordx4 v[42:45], v[82:83], off offset:1024
	s_add_i32 s1, s2, s97
	s_add_i32 s2, s88, s0
	s_ashr_i32 s3, s2, 31
	s_lshl_b64 s[2:3], s[2:3], 12
	v_lshl_add_u64 v[80:81], v[66:67], 0, s[2:3]
	global_load_dwordx4 v[38:41], v[80:81], off
	global_load_dwordx4 v[34:37], v[80:81], off offset:1024
	s_add_i32 s2, s75, s0
	s_ashr_i32 s3, s2, 31
	s_lshl_b64 s[2:3], s[2:3], 12
	v_lshl_add_u64 v[78:79], v[66:67], 0, s[2:3]
	global_load_dwordx4 v[30:33], v[78:79], off
	global_load_dwordx4 v[26:29], v[78:79], off offset:1024
	s_add_i32 s2, s89, s0
	s_ashr_i32 s3, s2, 31
	s_lshl_b64 s[2:3], s[2:3], 12
	v_lshl_add_u64 v[76:77], v[66:67], 0, s[2:3]
	global_load_dwordx4 v[22:25], v[76:77], off
	global_load_dwordx4 v[18:21], v[76:77], off offset:1024
	s_add_i32 s2, s77, s0
	s_ashr_i32 s3, s2, 31
	s_lshl_b64 s[2:3], s[2:3], 12
	v_lshl_add_u64 v[74:75], v[66:67], 0, s[2:3]
	global_load_dwordx4 v[14:17], v[74:75], off
	global_load_dwordx4 v[10:13], v[74:75], off offset:1024
	s_add_i32 s2, s78, s0
	s_ashr_i32 s3, s2, 31
	s_lshl_b64 s[2:3], s[2:3], 12
	v_lshl_add_u64 v[72:73], v[66:67], 0, s[2:3]
	global_load_dwordx4 v[6:9], v[72:73], off
	global_load_dwordx4 v[2:5], v[72:73], off offset:1024
	s_add_i32 s1, s1, s97
	s_add_i32 s1, s1, s97
	s_add_i32 s1, s1, s97
	s_add_i32 s1, s1, s97
	s_add_i32 s0, s79, s0
	s_add_i32 s2, s1, s97
	s_ashr_i32 s1, s0, 31
	s_lshl_b64 s[0:1], s[0:1], 12
	v_lshl_add_u64 v[70:71], v[66:67], 0, s[0:1]
	global_load_dwordx4 v[54:57], v[70:71], off
	global_load_dwordx4 v[50:53], v[70:71], off offset:1024
	s_waitcnt vmcnt(0)
	v_and_b32_e32 v152, 0xffff0000, v62
	v_and_b32_e32 v156, 0xffff0000, v63
	v_lshlrev_b32_e32 v154, 16, v62
	v_lshlrev_b32_e32 v145, 16, v58
	v_and_b32_e32 v144, 0xffff0000, v58
	v_mul_f32_e32 v0, v152, v152
	v_lshlrev_b32_e32 v157, 16, v63
	v_mul_f32_e32 v58, v156, v156
	v_fmac_f32_e32 v0, v154, v154
	v_lshlrev_b32_e32 v155, 16, v59
	v_fmac_f32_e32 v58, v157, v157
	v_fmac_f32_e32 v0, v145, v145
	v_and_b32_e32 v153, 0xffff0000, v59
	v_fmac_f32_e32 v58, v155, v155
	v_fmac_f32_e32 v0, v144, v144
	v_fmac_f32_e32 v58, v153, v153
	v_and_b32_e32 v170, 0xffff0000, v64
	v_add_f32_e32 v0, v0, v58
	v_lshlrev_b32_e32 v171, 16, v64
	v_mul_f32_e32 v58, v170, v170
	v_lshlrev_b32_e32 v159, 16, v60
	v_fmac_f32_e32 v58, v171, v171
	v_and_b32_e32 v158, 0xffff0000, v60
	v_fmac_f32_e32 v58, v159, v159
	v_fmac_f32_e32 v58, v158, v158
	v_and_b32_e32 v180, 0xffff0000, v65
	v_add_f32_e32 v0, v58, v0
	v_lshlrev_b32_e32 v182, 16, v65
	v_mul_f32_e32 v58, v180, v180
	v_lshlrev_b32_e32 v174, 16, v61
	v_fmac_f32_e32 v58, v182, v182
	v_and_b32_e32 v172, 0xffff0000, v61
	v_fmac_f32_e32 v58, v174, v174
	v_fmac_f32_e32 v58, v172, v172
	v_and_b32_e32 v150, 0xffff0000, v46
	v_and_b32_e32 v176, 0xffff0000, v47
	v_add_f32_e32 v164, v58, v0
	v_lshlrev_b32_e32 v151, 16, v46
	v_lshlrev_b32_e32 v142, 16, v42
	v_and_b32_e32 v160, 0xffff0000, v42
	v_mul_f32_e32 v0, v150, v150
	v_lshlrev_b32_e32 v177, 16, v47
	v_mul_f32_e32 v42, v176, v176
	v_fmac_f32_e32 v0, v151, v151
	v_lshlrev_b32_e32 v163, 16, v43
	v_fmac_f32_e32 v42, v177, v177
	v_fmac_f32_e32 v0, v142, v142
	v_and_b32_e32 v161, 0xffff0000, v43
	v_fmac_f32_e32 v42, v163, v163
	v_fmac_f32_e32 v0, v160, v160
	v_fmac_f32_e32 v42, v161, v161
	v_and_b32_e32 v178, 0xffff0000, v48
	v_add_f32_e32 v0, v0, v42
	v_lshlrev_b32_e32 v179, 16, v48
	v_mul_f32_e32 v42, v178, v178
	v_lshlrev_b32_e32 v169, 16, v44
	v_fmac_f32_e32 v42, v179, v179
	v_and_b32_e32 v168, 0xffff0000, v44
	v_fmac_f32_e32 v42, v169, v169
	v_fmac_f32_e32 v42, v168, v168
	v_and_b32_e32 v181, 0xffff0000, v49
	v_add_f32_e32 v0, v42, v0
	v_lshlrev_b32_e32 v183, 16, v49
	v_mul_f32_e32 v42, v181, v181
	v_lshlrev_b32_e32 v175, 16, v45
	v_fmac_f32_e32 v42, v183, v183
	v_and_b32_e32 v173, 0xffff0000, v45
	v_fmac_f32_e32 v42, v175, v175
	v_fmac_f32_e32 v42, v173, v173
	v_and_b32_e32 v139, 0xffff0000, v38
	v_and_b32_e32 v141, 0xffff0000, v39
	v_add_f32_e32 v165, v42, v0
	v_lshlrev_b32_e32 v140, 16, v38
	v_lshlrev_b32_e32 v132, 16, v34
	v_and_b32_e32 v131, 0xffff0000, v34
	v_mul_f32_e32 v0, v139, v139
	v_lshlrev_b32_e32 v143, 16, v39
	v_mul_f32_e32 v34, v141, v141
	v_fmac_f32_e32 v0, v140, v140
	v_lshlrev_b32_e32 v134, 16, v35
	v_fmac_f32_e32 v34, v143, v143
	v_fmac_f32_e32 v0, v132, v132
	v_and_b32_e32 v133, 0xffff0000, v35
	v_fmac_f32_e32 v34, v134, v134
	v_fmac_f32_e32 v0, v131, v131
	v_fmac_f32_e32 v34, v133, v133
	v_and_b32_e32 v146, 0xffff0000, v40
	v_add_f32_e32 v0, v0, v34
	v_lshlrev_b32_e32 v147, 16, v40
	v_mul_f32_e32 v34, v146, v146
	v_lshlrev_b32_e32 v136, 16, v36
	v_fmac_f32_e32 v34, v147, v147
	v_and_b32_e32 v135, 0xffff0000, v36
	v_fmac_f32_e32 v34, v136, v136
	v_fmac_f32_e32 v34, v135, v135
	v_and_b32_e32 v148, 0xffff0000, v41
	v_add_f32_e32 v0, v34, v0
	v_lshlrev_b32_e32 v149, 16, v41
	v_mul_f32_e32 v34, v148, v148
	v_lshlrev_b32_e32 v138, 16, v37
	v_fmac_f32_e32 v34, v149, v149
	v_and_b32_e32 v137, 0xffff0000, v37
	v_fmac_f32_e32 v34, v138, v138
	v_fmac_f32_e32 v34, v137, v137
	v_and_b32_e32 v123, 0xffff0000, v30
	v_and_b32_e32 v125, 0xffff0000, v31
	v_add_f32_e32 v166, v34, v0
	v_lshlrev_b32_e32 v124, 16, v30
	v_lshlrev_b32_e32 v116, 16, v26
	v_and_b32_e32 v115, 0xffff0000, v26
	v_mul_f32_e32 v0, v123, v123
	v_lshlrev_b32_e32 v126, 16, v31
	v_mul_f32_e32 v26, v125, v125
	v_fmac_f32_e32 v0, v124, v124
	v_lshlrev_b32_e32 v118, 16, v27
	v_fmac_f32_e32 v26, v126, v126
	v_fmac_f32_e32 v0, v116, v116
	v_and_b32_e32 v117, 0xffff0000, v27
	v_fmac_f32_e32 v26, v118, v118
	v_fmac_f32_e32 v0, v115, v115
	v_fmac_f32_e32 v26, v117, v117
	v_and_b32_e32 v127, 0xffff0000, v32
	v_add_f32_e32 v0, v0, v26
	v_lshlrev_b32_e32 v128, 16, v32
	v_mul_f32_e32 v26, v127, v127
	v_lshlrev_b32_e32 v120, 16, v28
	v_fmac_f32_e32 v26, v128, v128
	v_and_b32_e32 v119, 0xffff0000, v28
	v_fmac_f32_e32 v26, v120, v120
	v_fmac_f32_e32 v26, v119, v119
	v_and_b32_e32 v129, 0xffff0000, v33
	v_add_f32_e32 v0, v26, v0
	v_lshlrev_b32_e32 v130, 16, v33
	v_mul_f32_e32 v26, v129, v129
	v_lshlrev_b32_e32 v122, 16, v29
	v_fmac_f32_e32 v26, v130, v130
	v_and_b32_e32 v121, 0xffff0000, v29
	v_fmac_f32_e32 v26, v122, v122
	v_fmac_f32_e32 v26, v121, v121
	v_and_b32_e32 v107, 0xffff0000, v22
	v_and_b32_e32 v109, 0xffff0000, v23
	v_add_f32_e32 v167, v26, v0
	v_lshlrev_b32_e32 v108, 16, v22
	v_lshlrev_b32_e32 v100, 16, v18
	v_and_b32_e32 v99, 0xffff0000, v18
	v_mul_f32_e32 v0, v107, v107
	v_lshlrev_b32_e32 v110, 16, v23
	v_mul_f32_e32 v18, v109, v109
	v_fmac_f32_e32 v0, v108, v108
	v_lshlrev_b32_e32 v102, 16, v19
	v_fmac_f32_e32 v18, v110, v110
	v_fmac_f32_e32 v0, v100, v100
	v_and_b32_e32 v101, 0xffff0000, v19
	v_fmac_f32_e32 v18, v102, v102
	v_fmac_f32_e32 v0, v99, v99
	v_fmac_f32_e32 v18, v101, v101
	v_and_b32_e32 v111, 0xffff0000, v24
	v_add_f32_e32 v0, v0, v18
	v_lshlrev_b32_e32 v112, 16, v24
	v_mul_f32_e32 v18, v111, v111
	v_lshlrev_b32_e32 v104, 16, v20
	v_fmac_f32_e32 v18, v112, v112
	v_and_b32_e32 v103, 0xffff0000, v20
	v_fmac_f32_e32 v18, v104, v104
	v_fmac_f32_e32 v18, v103, v103
	v_and_b32_e32 v113, 0xffff0000, v25
	v_add_f32_e32 v0, v18, v0
	v_lshlrev_b32_e32 v114, 16, v25
	v_mul_f32_e32 v18, v113, v113
	v_lshlrev_b32_e32 v106, 16, v21
	v_fmac_f32_e32 v18, v114, v114
	v_and_b32_e32 v105, 0xffff0000, v21
	v_fmac_f32_e32 v18, v106, v106
	v_fmac_f32_e32 v18, v105, v105
	v_and_b32_e32 v65, 0xffff0000, v14
	v_and_b32_e32 v93, 0xffff0000, v15
	v_add_f32_e32 v184, v18, v0
	v_lshlrev_b32_e32 v92, 16, v14
	v_lshlrev_b32_e32 v58, 16, v10
	v_and_b32_e32 v49, 0xffff0000, v10
	v_mul_f32_e32 v0, v65, v65
	v_lshlrev_b32_e32 v94, 16, v15
	v_mul_f32_e32 v10, v93, v93
	v_fmac_f32_e32 v0, v92, v92
	v_lshlrev_b32_e32 v60, 16, v11
	v_fmac_f32_e32 v10, v94, v94
	v_fmac_f32_e32 v0, v58, v58
	v_and_b32_e32 v59, 0xffff0000, v11
	v_fmac_f32_e32 v10, v60, v60
	v_fmac_f32_e32 v0, v49, v49
	v_fmac_f32_e32 v10, v59, v59
	v_and_b32_e32 v95, 0xffff0000, v16
	v_add_f32_e32 v0, v0, v10
	v_lshlrev_b32_e32 v96, 16, v16
	v_mul_f32_e32 v10, v95, v95
	v_lshlrev_b32_e32 v62, 16, v12
	v_fmac_f32_e32 v10, v96, v96
	v_and_b32_e32 v61, 0xffff0000, v12
	v_fmac_f32_e32 v10, v62, v62
	v_fmac_f32_e32 v10, v61, v61
	v_and_b32_e32 v97, 0xffff0000, v17
	v_add_f32_e32 v0, v10, v0
	v_lshlrev_b32_e32 v98, 16, v17
	v_mul_f32_e32 v10, v97, v97
	v_lshlrev_b32_e32 v64, 16, v13
	v_fmac_f32_e32 v10, v98, v98
	v_and_b32_e32 v63, 0xffff0000, v13
	v_fmac_f32_e32 v10, v64, v64
	v_fmac_f32_e32 v10, v63, v63
	v_and_b32_e32 v41, 0xffff0000, v6
	v_and_b32_e32 v43, 0xffff0000, v7
	v_add_f32_e32 v10, v10, v0
	v_lshlrev_b32_e32 v42, 16, v6
	v_lshlrev_b32_e32 v34, 16, v2
	v_and_b32_e32 v33, 0xffff0000, v2
	v_mul_f32_e32 v0, v41, v41
	v_lshlrev_b32_e32 v44, 16, v7
	v_mul_f32_e32 v2, v43, v43
	v_fmac_f32_e32 v0, v42, v42
	v_lshlrev_b32_e32 v36, 16, v3
	v_fmac_f32_e32 v2, v44, v44
	v_fmac_f32_e32 v0, v34, v34
	v_and_b32_e32 v35, 0xffff0000, v3
	v_fmac_f32_e32 v2, v36, v36
	v_fmac_f32_e32 v0, v33, v33
	v_fmac_f32_e32 v2, v35, v35
	v_and_b32_e32 v45, 0xffff0000, v8
	v_add_f32_e32 v0, v0, v2
	v_lshlrev_b32_e32 v46, 16, v8
	v_mul_f32_e32 v2, v45, v45
	v_lshlrev_b32_e32 v38, 16, v4
	v_fmac_f32_e32 v2, v46, v46
	v_and_b32_e32 v37, 0xffff0000, v4
	v_fmac_f32_e32 v2, v38, v38
	v_fmac_f32_e32 v2, v37, v37
	v_and_b32_e32 v47, 0xffff0000, v9
	v_add_f32_e32 v0, v2, v0
	v_lshlrev_b32_e32 v48, 16, v9
	v_mul_f32_e32 v2, v47, v47
	v_lshlrev_b32_e32 v40, 16, v5
	v_fmac_f32_e32 v2, v48, v48
	v_and_b32_e32 v25, 0xffff0000, v54
	v_and_b32_e32 v27, 0xffff0000, v55
	v_and_b32_e32 v39, 0xffff0000, v5
	v_fmac_f32_e32 v2, v40, v40
	v_lshlrev_b32_e32 v26, 16, v54
	v_mul_f32_e32 v3, v25, v25
	v_lshlrev_b32_e32 v28, 16, v55
	v_mul_f32_e32 v4, v27, v27
	v_fmac_f32_e32 v2, v39, v39
	v_lshlrev_b32_e32 v18, 16, v50
	v_fmac_f32_e32 v3, v26, v26
	v_lshlrev_b32_e32 v20, 16, v51
	v_fmac_f32_e32 v4, v28, v28
	v_add_f32_e32 v2, v2, v0
	v_and_b32_e32 v0, 0xffff0000, v50
	v_fmac_f32_e32 v3, v18, v18
	v_and_b32_e32 v19, 0xffff0000, v51
	v_fmac_f32_e32 v4, v20, v20
	v_fmac_f32_e32 v3, v0, v0
	v_fmac_f32_e32 v4, v19, v19
	v_and_b32_e32 v29, 0xffff0000, v56
	ds_bpermute_b32 v9, v86, v10
	v_add_f32_e32 v3, v3, v4
	v_lshlrev_b32_e32 v30, 16, v56
	v_mul_f32_e32 v4, v29, v29
	v_lshlrev_b32_e32 v22, 16, v52
	v_fmac_f32_e32 v4, v30, v30
	v_and_b32_e32 v21, 0xffff0000, v52
	v_fmac_f32_e32 v4, v22, v22
	v_fmac_f32_e32 v4, v21, v21
	v_and_b32_e32 v31, 0xffff0000, v57
	v_add_f32_e32 v3, v4, v3
	v_lshlrev_b32_e32 v32, 16, v57
	v_mul_f32_e32 v4, v31, v31
	s_waitcnt lgkmcnt(0)
	v_add_f32_e32 v9, v10, v9
	ds_bpermute_b32 v10, v86, v2
	v_lshlrev_b32_e32 v24, 16, v53
	v_fmac_f32_e32 v4, v32, v32
	v_and_b32_e32 v23, 0xffff0000, v53
	v_fmac_f32_e32 v4, v24, v24
	v_fmac_f32_e32 v4, v23, v23
	v_add_f32_e32 v3, v4, v3
	ds_bpermute_b32 v4, v86, v164
	s_waitcnt lgkmcnt(1)
	v_add_f32_e32 v2, v2, v10
	ds_bpermute_b32 v10, v86, v3
	ds_bpermute_b32 v5, v86, v165
	ds_bpermute_b32 v6, v86, v166
	s_waitcnt lgkmcnt(3)
	v_add_f32_e32 v4, v164, v4
	ds_bpermute_b32 v7, v86, v167
	s_waitcnt lgkmcnt(3)
	v_add_f32_e32 v3, v3, v10
	ds_bpermute_b32 v10, v87, v4
	s_waitcnt lgkmcnt(3)
	v_add_f32_e32 v5, v165, v5
	s_waitcnt lgkmcnt(2)
	v_add_f32_e32 v6, v166, v6
	s_waitcnt lgkmcnt(1)
	v_add_f32_e32 v7, v167, v7
	ds_bpermute_b32 v8, v86, v184
	s_waitcnt lgkmcnt(1)
	v_add_f32_e32 v4, v4, v10
	ds_bpermute_b32 v10, v87, v5
	s_waitcnt lgkmcnt(1)
	v_add_f32_e32 v8, v184, v8
	s_waitcnt lgkmcnt(0)
	v_add_f32_e32 v5, v5, v10
	ds_bpermute_b32 v10, v87, v6
	ds_bpermute_b32 v200, v87, v7
	ds_bpermute_b32 v201, v87, v8
	ds_bpermute_b32 v202, v87, v9
	ds_bpermute_b32 v196, v87, v2
	ds_bpermute_b32 v162, v87, v3
	s_waitcnt lgkmcnt(0)
	v_add_f32_e32 v6, v6, v10
	v_add_f32_e32 v7, v7, v200
	v_add_f32_e32 v8, v8, v201
	v_add_f32_e32 v9, v9, v202
	v_add_f32_e32 v2, v2, v196
	v_add_f32_e32 v3, v3, v162
	ds_bpermute_b32 v10, v88, v4
	ds_bpermute_b32 v200, v88, v5
	ds_bpermute_b32 v201, v88, v6
	ds_bpermute_b32 v202, v88, v7
	ds_bpermute_b32 v196, v88, v8
	ds_bpermute_b32 v162, v88, v9
	ds_bpermute_b32 v250, v88, v2
	ds_bpermute_b32 v251, v88, v3
	s_waitcnt lgkmcnt(0)
	v_add_f32_e32 v4, v4, v10
	v_add_f32_e32 v5, v5, v200
	v_add_f32_e32 v6, v6, v201
	v_add_f32_e32 v7, v7, v202
	v_add_f32_e32 v8, v8, v196
	v_add_f32_e32 v9, v9, v162
	v_add_f32_e32 v2, v2, v250
	v_add_f32_e32 v3, v3, v251
	ds_bpermute_b32 v10, v89, v4
	ds_bpermute_b32 v200, v89, v5
	ds_bpermute_b32 v201, v89, v6
	ds_bpermute_b32 v202, v89, v7
	ds_bpermute_b32 v196, v89, v8
	ds_bpermute_b32 v162, v89, v9
	ds_bpermute_b32 v250, v89, v2
	ds_bpermute_b32 v251, v89, v3
	s_waitcnt lgkmcnt(0)
	v_add_f32_e32 v4, v4, v10
	v_add_f32_e32 v5, v5, v200
	v_add_f32_e32 v6, v6, v201
	v_add_f32_e32 v7, v7, v202
	v_add_f32_e32 v8, v8, v196
	v_add_f32_e32 v9, v9, v162
	v_add_f32_e32 v2, v2, v250
	v_add_f32_e32 v3, v3, v251
	ds_bpermute_b32 v10, v90, v4
	ds_bpermute_b32 v200, v90, v5
	ds_bpermute_b32 v201, v90, v6
	ds_bpermute_b32 v202, v90, v7
	ds_bpermute_b32 v196, v90, v8
	ds_bpermute_b32 v162, v90, v9
	ds_bpermute_b32 v250, v90, v2
	ds_bpermute_b32 v251, v90, v3
	s_waitcnt lgkmcnt(0)
	v_add_f32_e32 v4, v4, v10
	v_add_f32_e32 v5, v5, v200
	v_add_f32_e32 v6, v6, v201
	v_add_f32_e32 v7, v7, v202
	v_add_f32_e32 v8, v8, v196
	v_add_f32_e32 v9, v9, v162
	v_add_f32_e32 v2, v2, v250
	v_add_f32_e32 v3, v3, v251
	ds_bpermute_b32 v10, v91, v4
	s_waitcnt lgkmcnt(0)
	v_add_f32_e32 v56, v4, v10
	ds_bpermute_b32 v4, v91, v5
	v_fmamk_f32 v56, v56, 0x3a800000, v194
	v_cmp_gt_f32_e32 vcc, s61, v56
	v_mul_f32_e32 v164, 0x4f800000, v56
	s_waitcnt lgkmcnt(0)
	v_add_f32_e32 v57, v5, v4
	ds_bpermute_b32 v4, v91, v6
	v_cndmask_b32_e32 v56, v56, v164, vcc
	v_sqrt_f32_e32 v164, v56
	s_waitcnt lgkmcnt(0)
	v_add_f32_e32 v55, v6, v4
	ds_bpermute_b32 v4, v91, v7
	v_add_u32_e32 v165, -1, v164
	v_fma_f32 v166, -v165, v164, v56
	v_cmp_ge_f32_e64 s[0:1], 0, v166
	v_add_u32_e32 v166, 1, v164
	s_waitcnt lgkmcnt(0)
	v_add_f32_e32 v54, v7, v4
	ds_bpermute_b32 v4, v91, v8
	v_cndmask_b32_e64 v165, v164, v165, s[0:1]
	v_fma_f32 v164, -v166, v164, v56
	v_cmp_lt_f32_e64 s[0:1], 0, v164
	v_fmamk_f32 v55, v55, 0x3a800000, v194
	s_waitcnt lgkmcnt(0)
	v_add_f32_e32 v53, v8, v4
	ds_bpermute_b32 v4, v91, v9
	v_cndmask_b32_e64 v164, v165, v166, s[0:1]
	v_mul_f32_e32 v165, 0x37800000, v164
	v_cndmask_b32_e32 v164, v164, v165, vcc
	v_cmp_class_f32_e32 vcc, v56, v195
	s_waitcnt lgkmcnt(0)
	v_add_f32_e32 v52, v9, v4
	ds_bpermute_b32 v4, v91, v2
	v_cndmask_b32_e32 v56, v164, v56, vcc
	v_div_scale_f32 v164, s[0:1], v56, v56, 1.0
	v_rcp_f32_e32 v165, v164
	s_waitcnt lgkmcnt(0)
	v_add_f32_e32 v51, v2, v4
	ds_bpermute_b32 v2, v91, v3
	v_fmamk_f32 v54, v54, 0x3a800000, v194
	v_fma_f32 v166, -v164, v165, 1.0
	v_fmac_f32_e32 v165, v166, v165
	v_div_scale_f32 v166, vcc, 1.0, v56, 1.0
	s_waitcnt lgkmcnt(0)
	v_add_f32_e32 v50, v3, v2
	global_load_dwordx4 v[2:5], v[68:69], off offset:16
	global_load_dwordx4 v[6:9], v[68:69], off
	global_load_dwordx4 v[10:13], v[68:69], off offset:2064
	global_load_dwordx4 v[14:17], v[68:69], off offset:2048
	v_mul_f32_e32 v167, v166, v165
	v_fma_f32 v184, -v164, v167, v166
	v_fmac_f32_e32 v167, v184, v165
	v_fma_f32 v164, -v164, v167, v166
	v_div_fmas_f32 v164, v164, v165, v167
	v_div_fixup_f32 v56, v164, v56, 1.0
	v_mul_f32_e32 v152, v56, v152
	v_mul_f32_e32 v154, v56, v154
	v_mul_f32_e32 v144, v56, v144
	v_mul_f32_e32 v145, v56, v145
	v_fmamk_f32 v53, v53, 0x3a800000, v194
	v_fmamk_f32 v52, v52, 0x3a800000, v194
	s_waitcnt vmcnt(2)
	v_mul_f32_e32 v152, v152, v7
	v_mul_f32_e32 v154, v154, v6
	v_cvt_pk_bf16_f32 v164, v154, v152
	v_mul_f32_e32 v152, v56, v157
	v_mul_f32_e32 v152, v152, v8
	v_mul_f32_e32 v154, v56, v156
	v_mul_f32_e32 v154, v154, v9
	v_cvt_pk_bf16_f32 v165, v152, v154
	v_mul_f32_e32 v152, v56, v171
	v_mul_f32_e32 v152, v152, v2
	v_mul_f32_e32 v154, v56, v170
	v_mul_f32_e32 v154, v154, v3
	v_cvt_pk_bf16_f32 v166, v152, v154
	v_mul_f32_e32 v152, v56, v182
	v_mul_f32_e32 v152, v152, v4
	v_mul_f32_e32 v154, v56, v180
	s_waitcnt vmcnt(0)
	v_mul_f32_e32 v144, v144, v15
	v_mul_f32_e32 v154, v154, v5
	v_cvt_pk_bf16_f32 v167, v152, v154
	v_mul_f32_e32 v145, v145, v14
	v_cvt_pk_bf16_f32 v152, v145, v144
	v_mul_f32_e32 v144, v56, v155
	v_mul_f32_e32 v144, v144, v16
	v_mul_f32_e32 v145, v56, v153
	v_mul_f32_e32 v145, v145, v17
	v_cvt_pk_bf16_f32 v153, v144, v145
	v_mul_f32_e32 v144, v56, v159
	v_mul_f32_e32 v144, v144, v10
	v_mul_f32_e32 v145, v56, v158
	v_mul_f32_e32 v145, v145, v11
	v_cvt_pk_bf16_f32 v154, v144, v145
	v_mul_f32_e32 v144, v56, v174
	v_mul_f32_e32 v56, v56, v172
	v_mul_f32_e32 v56, v56, v13
	v_mul_f32_e32 v144, v144, v12
	v_cvt_pk_bf16_f32 v155, v144, v56
	v_fmamk_f32 v56, v57, 0x3a800000, v194
	v_cmp_gt_f32_e32 vcc, s61, v56
	v_mul_f32_e32 v57, 0x4f800000, v56
	global_store_dwordx4 v[84:85], v[164:167], off
	global_store_dwordx4 v[84:85], v[152:155], off offset:1024
	v_cndmask_b32_e32 v56, v56, v57, vcc
	v_sqrt_f32_e32 v57, v56
	s_nop 0
	v_add_u32_e32 v84, -1, v57
	v_fma_f32 v85, -v84, v57, v56
	v_cmp_ge_f32_e64 s[0:1], 0, v85
	v_add_u32_e32 v85, 1, v57
	s_nop 0
	v_cndmask_b32_e64 v84, v57, v84, s[0:1]
	v_fma_f32 v57, -v85, v57, v56
	v_cmp_lt_f32_e64 s[0:1], 0, v57
	s_nop 1
	v_cndmask_b32_e64 v57, v84, v85, s[0:1]
	v_mul_f32_e32 v84, 0x37800000, v57
	v_cndmask_b32_e32 v57, v57, v84, vcc
	v_cmp_class_f32_e32 vcc, v56, v195
	s_nop 1
	v_cndmask_b32_e32 v56, v57, v56, vcc
	v_div_scale_f32 v57, s[0:1], v56, v56, 1.0
	v_rcp_f32_e32 v84, v57
	s_nop 0
	v_fma_f32 v85, -v57, v84, 1.0
	v_fmac_f32_e32 v84, v85, v84
	v_div_scale_f32 v85, vcc, 1.0, v56, 1.0
	v_mul_f32_e32 v144, v85, v84
	v_fma_f32 v145, -v57, v144, v85
	v_fmac_f32_e32 v144, v145, v84
	v_fma_f32 v57, -v57, v144, v85
	v_div_fmas_f32 v57, v57, v84, v144
	v_div_fixup_f32 v56, v57, v56, 1.0
	v_mul_f32_e32 v57, v56, v151
	v_mul_f32_e32 v57, v57, v6
	v_mul_f32_e32 v84, v56, v150
	v_mul_f32_e32 v84, v84, v7
	v_cvt_pk_bf16_f32 v150, v57, v84
	v_mul_f32_e32 v57, v56, v177
	v_mul_f32_e32 v57, v57, v8
	v_mul_f32_e32 v84, v56, v176
	v_mul_f32_e32 v84, v84, v9
	v_cvt_pk_bf16_f32 v151, v57, v84
	v_mul_f32_e32 v57, v56, v179
	v_mul_f32_e32 v57, v57, v2
	v_mul_f32_e32 v84, v56, v178
	v_mul_f32_e32 v84, v84, v3
	v_cvt_pk_bf16_f32 v152, v57, v84
	v_mul_f32_e32 v57, v56, v183
	v_mul_f32_e32 v57, v57, v4
	v_mul_f32_e32 v84, v56, v181
	v_mul_f32_e32 v84, v84, v5
	v_cvt_pk_bf16_f32 v153, v57, v84
	v_mul_f32_e32 v57, v56, v142
	v_mul_f32_e32 v57, v57, v14
	v_mul_f32_e32 v84, v56, v160
	v_mul_f32_e32 v84, v84, v15
	v_cvt_pk_bf16_f32 v154, v57, v84
	v_mul_f32_e32 v57, v56, v163
	v_mul_f32_e32 v57, v57, v16
	v_mul_f32_e32 v84, v56, v161
	v_mul_f32_e32 v84, v84, v17
	v_cvt_pk_bf16_f32 v155, v57, v84
	v_mul_f32_e32 v57, v56, v169
	v_mul_f32_e32 v57, v57, v10
	v_mul_f32_e32 v84, v56, v168
	v_mul_f32_e32 v84, v84, v11
	v_cvt_pk_bf16_f32 v156, v57, v84
	v_mul_f32_e32 v57, v56, v175
	v_mul_f32_e32 v56, v56, v173
	v_mul_f32_e32 v56, v56, v13
	v_mul_f32_e32 v57, v57, v12
	v_cvt_pk_bf16_f32 v157, v57, v56
	v_cmp_gt_f32_e32 vcc, s61, v55
	v_mul_f32_e32 v56, 0x4f800000, v55
	global_store_dwordx4 v[82:83], v[150:153], off
	global_store_dwordx4 v[82:83], v[154:157], off offset:1024
	v_cndmask_b32_e32 v55, v55, v56, vcc
	v_sqrt_f32_e32 v56, v55
	s_nop 0
	v_add_u32_e32 v57, -1, v56
	v_fma_f32 v82, -v57, v56, v55
	v_cmp_ge_f32_e64 s[0:1], 0, v82
	v_add_u32_e32 v82, 1, v56
	s_nop 0
	v_cndmask_b32_e64 v57, v56, v57, s[0:1]
	v_fma_f32 v56, -v82, v56, v55
	v_cmp_lt_f32_e64 s[0:1], 0, v56
	s_nop 1
	v_cndmask_b32_e64 v56, v57, v82, s[0:1]
	v_mul_f32_e32 v57, 0x37800000, v56
	v_cndmask_b32_e32 v56, v56, v57, vcc
	v_cmp_class_f32_e32 vcc, v55, v195
	s_nop 1
	v_cndmask_b32_e32 v55, v56, v55, vcc
	v_div_scale_f32 v56, s[0:1], v55, v55, 1.0
	v_rcp_f32_e32 v57, v56
	s_nop 0
	v_fma_f32 v82, -v56, v57, 1.0
	v_fmac_f32_e32 v57, v82, v57
	v_div_scale_f32 v82, vcc, 1.0, v55, 1.0
	v_mul_f32_e32 v83, v82, v57
	v_fma_f32 v84, -v56, v83, v82
	v_fmac_f32_e32 v83, v84, v57
	v_fma_f32 v56, -v56, v83, v82
	v_div_fmas_f32 v56, v56, v57, v83
	v_div_fixup_f32 v55, v56, v55, 1.0
	v_mul_f32_e32 v56, v55, v140
	v_mul_f32_e32 v56, v6, v56
	v_mul_f32_e32 v57, v55, v139
	v_mul_f32_e32 v57, v7, v57
	v_cvt_pk_bf16_f32 v82, v56, v57
	v_mul_f32_e32 v56, v55, v143
	v_mul_f32_e32 v56, v8, v56
	v_mul_f32_e32 v57, v55, v141
	v_mul_f32_e32 v57, v9, v57
	v_cvt_pk_bf16_f32 v83, v56, v57
	v_mul_f32_e32 v56, v55, v147
	v_mul_f32_e32 v56, v56, v2
	v_mul_f32_e32 v57, v55, v146
	v_mul_f32_e32 v57, v57, v3
	v_cvt_pk_bf16_f32 v84, v56, v57
	v_mul_f32_e32 v56, v55, v149
	v_mul_f32_e32 v56, v56, v4
	v_mul_f32_e32 v57, v55, v148
	v_mul_f32_e32 v57, v57, v5
	v_cvt_pk_bf16_f32 v85, v56, v57
	v_mul_f32_e32 v56, v55, v132
	v_mul_f32_e32 v56, v56, v14
	v_mul_f32_e32 v57, v55, v131
	v_mul_f32_e32 v57, v57, v15
	v_cvt_pk_bf16_f32 v132, v56, v57
	v_mul_f32_e32 v56, v55, v134
	v_mul_f32_e32 v56, v56, v16
	v_mul_f32_e32 v57, v55, v133
	v_mul_f32_e32 v57, v57, v17
	v_cvt_pk_bf16_f32 v133, v56, v57
	v_mul_f32_e32 v56, v55, v136
	v_mul_f32_e32 v56, v56, v10
	v_mul_f32_e32 v57, v55, v135
	v_mul_f32_e32 v57, v57, v11
	v_cvt_pk_bf16_f32 v134, v56, v57
	v_mul_f32_e32 v56, v55, v138
	v_mul_f32_e32 v55, v55, v137
	v_mul_f32_e32 v55, v55, v13
	v_mul_f32_e32 v56, v56, v12
	v_cvt_pk_bf16_f32 v135, v56, v55
	v_cmp_gt_f32_e32 vcc, s61, v54
	v_mul_f32_e32 v55, 0x4f800000, v54
	global_store_dwordx4 v[80:81], v[82:85], off
	global_store_dwordx4 v[80:81], v[132:135], off offset:1024
	v_cndmask_b32_e32 v54, v54, v55, vcc
	v_sqrt_f32_e32 v55, v54
	s_nop 0
	v_add_u32_e32 v56, -1, v55
	v_fma_f32 v57, -v56, v55, v54
	v_cmp_ge_f32_e64 s[0:1], 0, v57
	v_add_u32_e32 v57, 1, v55
	s_nop 0
	v_cndmask_b32_e64 v56, v55, v56, s[0:1]
	v_fma_f32 v55, -v57, v55, v54
	v_cmp_lt_f32_e64 s[0:1], 0, v55
	s_nop 1
	v_cndmask_b32_e64 v55, v56, v57, s[0:1]
	v_mul_f32_e32 v56, 0x37800000, v55
	v_cndmask_b32_e32 v55, v55, v56, vcc
	v_cmp_class_f32_e32 vcc, v54, v195
	s_nop 1
	v_cndmask_b32_e32 v54, v55, v54, vcc
	v_div_scale_f32 v55, s[0:1], v54, v54, 1.0
	v_rcp_f32_e32 v56, v55
	s_nop 0
	v_fma_f32 v57, -v55, v56, 1.0
	v_fmac_f32_e32 v56, v57, v56
	v_div_scale_f32 v57, vcc, 1.0, v54, 1.0
	v_mul_f32_e32 v80, v57, v56
	v_fma_f32 v81, -v55, v80, v57
	v_fmac_f32_e32 v80, v81, v56
	v_fma_f32 v55, -v55, v80, v57
	v_div_fmas_f32 v55, v55, v56, v80
	v_div_fixup_f32 v83, v55, v54, 1.0
	v_mul_f32_e32 v54, v83, v124
	v_mul_f32_e32 v55, v83, v123
	v_mul_f32_e32 v54, v6, v54
	v_mul_f32_e32 v55, v7, v55
	v_cvt_pk_bf16_f32 v54, v54, v55
	v_mul_f32_e32 v55, v83, v126
	v_mul_f32_e32 v56, v83, v125
	v_mul_f32_e32 v55, v8, v55
	v_mul_f32_e32 v56, v9, v56
	v_cvt_pk_bf16_f32 v55, v55, v56
	v_mul_f32_e32 v56, v83, v128
	v_mul_f32_e32 v57, v83, v127
	v_mul_f32_e32 v56, v2, v56
	v_mul_f32_e32 v57, v3, v57
	v_cvt_pk_bf16_f32 v56, v56, v57
	v_mul_f32_e32 v57, v83, v130
	v_mul_f32_e32 v80, v83, v129
	v_mul_f32_e32 v57, v4, v57
	v_mul_f32_e32 v80, v5, v80
	v_cvt_pk_bf16_f32 v57, v57, v80
	v_mul_f32_e32 v80, v83, v116
	v_mul_f32_e32 v81, v83, v115
	v_mul_f32_e32 v80, v80, v14
	v_mul_f32_e32 v81, v81, v15
	v_cvt_pk_bf16_f32 v80, v80, v81
	v_mul_f32_e32 v81, v83, v118
	v_mul_f32_e32 v82, v83, v117
	v_mul_f32_e32 v81, v81, v16
	v_mul_f32_e32 v82, v82, v17
	v_cvt_pk_bf16_f32 v81, v81, v82
	v_mul_f32_e32 v82, v83, v120
	v_mul_f32_e32 v84, v83, v119
	v_mul_f32_e32 v82, v82, v10
	v_mul_f32_e32 v84, v84, v11
	v_cvt_pk_bf16_f32 v82, v82, v84
	v_mul_f32_e32 v84, v83, v122
	v_mul_f32_e32 v83, v83, v121
	v_mul_f32_e32 v83, v83, v13
	v_mul_f32_e32 v84, v84, v12
	v_cvt_pk_bf16_f32 v83, v84, v83
	global_store_dwordx4 v[78:79], v[54:57], off
	global_store_dwordx4 v[78:79], v[80:83], off offset:1024
	v_cmp_gt_f32_e32 vcc, s61, v53
	v_mul_f32_e32 v54, 0x4f800000, v53
	s_nop 0
	v_cndmask_b32_e32 v53, v53, v54, vcc
	v_sqrt_f32_e32 v54, v53
	s_nop 0
	v_add_u32_e32 v55, -1, v54
	v_fma_f32 v56, -v55, v54, v53
	v_cmp_ge_f32_e64 s[0:1], 0, v56
	v_add_u32_e32 v56, 1, v54
	s_nop 0
	v_cndmask_b32_e64 v55, v54, v55, s[0:1]
	v_fma_f32 v54, -v56, v54, v53
	v_cmp_lt_f32_e64 s[0:1], 0, v54
	s_nop 1
	v_cndmask_b32_e64 v54, v55, v56, s[0:1]
	v_mul_f32_e32 v55, 0x37800000, v54
	v_cndmask_b32_e32 v54, v54, v55, vcc
	v_cmp_class_f32_e32 vcc, v53, v195
	s_nop 1
	v_cndmask_b32_e32 v53, v54, v53, vcc
	v_div_scale_f32 v54, s[0:1], v53, v53, 1.0
	v_rcp_f32_e32 v55, v54
	s_nop 0
	v_fma_f32 v56, -v54, v55, 1.0
	v_fmac_f32_e32 v55, v56, v55
	v_div_scale_f32 v56, vcc, 1.0, v53, 1.0
	v_mul_f32_e32 v57, v56, v55
	v_fma_f32 v78, -v54, v57, v56
	v_fmac_f32_e32 v57, v78, v55
	v_fma_f32 v54, -v54, v57, v56
	v_div_fmas_f32 v54, v54, v55, v57
	v_div_fixup_f32 v53, v54, v53, 1.0
	v_mul_f32_e32 v54, v53, v108
	v_mul_f32_e32 v55, v53, v107
	v_mul_f32_e32 v54, v6, v54
	v_mul_f32_e32 v55, v7, v55
	v_cvt_pk_bf16_f32 v54, v54, v55
	v_mul_f32_e32 v55, v53, v110
	v_mul_f32_e32 v56, v53, v109
	v_mul_f32_e32 v55, v8, v55
	v_mul_f32_e32 v56, v9, v56
	v_cvt_pk_bf16_f32 v55, v55, v56
	v_mul_f32_e32 v56, v53, v112
	v_mul_f32_e32 v57, v53, v111
	v_mul_f32_e32 v56, v2, v56
	v_mul_f32_e32 v57, v3, v57
	v_cvt_pk_bf16_f32 v56, v56, v57
	v_mul_f32_e32 v57, v53, v114
	v_mul_f32_e32 v78, v53, v113
	v_mul_f32_e32 v57, v4, v57
	v_mul_f32_e32 v78, v5, v78
	v_cvt_pk_bf16_f32 v57, v57, v78
	v_mul_f32_e32 v78, v53, v100
	v_mul_f32_e32 v79, v53, v99
	v_mul_f32_e32 v78, v14, v78
	v_mul_f32_e32 v79, v15, v79
	v_cvt_pk_bf16_f32 v78, v78, v79
	v_mul_f32_e32 v79, v53, v102
	v_mul_f32_e32 v80, v53, v101
	v_mul_f32_e32 v79, v16, v79
	v_mul_f32_e32 v80, v17, v80
	v_cvt_pk_bf16_f32 v79, v79, v80
	v_mul_f32_e32 v80, v53, v104
	v_mul_f32_e32 v81, v53, v103
	v_mul_f32_e32 v80, v80, v10
	v_mul_f32_e32 v81, v81, v11
	v_cvt_pk_bf16_f32 v80, v80, v81
	v_mul_f32_e32 v81, v53, v106
	v_mul_f32_e32 v53, v53, v105
	v_mul_f32_e32 v81, v81, v12
	v_mul_f32_e32 v53, v53, v13
	v_cvt_pk_bf16_f32 v81, v81, v53
	v_cmp_gt_f32_e32 vcc, s61, v52
	v_mul_f32_e32 v53, 0x4f800000, v52
	global_store_dwordx4 v[76:77], v[54:57], off
	global_store_dwordx4 v[76:77], v[78:81], off offset:1024
	v_cndmask_b32_e32 v52, v52, v53, vcc
	v_sqrt_f32_e32 v53, v52
	s_nop 0
	v_add_u32_e32 v54, -1, v53
	v_fma_f32 v55, -v54, v53, v52
	v_cmp_ge_f32_e64 s[0:1], 0, v55
	v_add_u32_e32 v55, 1, v53
	s_nop 0
	v_cndmask_b32_e64 v54, v53, v54, s[0:1]
	v_fma_f32 v53, -v55, v53, v52
	v_cmp_lt_f32_e64 s[0:1], 0, v53
	s_nop 1
	v_cndmask_b32_e64 v53, v54, v55, s[0:1]
	v_mul_f32_e32 v54, 0x37800000, v53
	v_cndmask_b32_e32 v53, v53, v54, vcc
	v_cmp_class_f32_e32 vcc, v52, v195
	s_nop 1
	v_cndmask_b32_e32 v52, v53, v52, vcc
	v_div_scale_f32 v53, s[0:1], v52, v52, 1.0
	v_rcp_f32_e32 v54, v53
	s_nop 0
	v_fma_f32 v55, -v53, v54, 1.0
	v_fmac_f32_e32 v54, v55, v54
	v_div_scale_f32 v55, vcc, 1.0, v52, 1.0
	v_mul_f32_e32 v56, v55, v54
	v_fma_f32 v57, -v53, v56, v55
	v_fmac_f32_e32 v56, v57, v54
	v_fma_f32 v53, -v53, v56, v55
	v_div_fmas_f32 v53, v53, v54, v56
	v_div_fixup_f32 v76, v53, v52, 1.0
	v_mul_f32_e32 v52, v76, v92
	v_mul_f32_e32 v53, v76, v65
	v_mul_f32_e32 v52, v6, v52
	v_mul_f32_e32 v53, v7, v53
	v_cvt_pk_bf16_f32 v52, v52, v53
	v_mul_f32_e32 v53, v76, v94
	v_mul_f32_e32 v54, v76, v93
	v_mul_f32_e32 v53, v8, v53
	v_mul_f32_e32 v54, v9, v54
	v_cvt_pk_bf16_f32 v53, v53, v54
	v_mul_f32_e32 v54, v76, v96
	v_mul_f32_e32 v55, v76, v95
	v_mul_f32_e32 v54, v2, v54
	v_mul_f32_e32 v55, v3, v55
	v_cvt_pk_bf16_f32 v54, v54, v55
	v_mul_f32_e32 v55, v76, v98
	v_mul_f32_e32 v56, v76, v97
	v_mul_f32_e32 v55, v4, v55
	v_mul_f32_e32 v56, v5, v56
	v_cvt_pk_bf16_f32 v55, v55, v56
	v_mul_f32_e32 v56, v76, v58
	v_mul_f32_e32 v49, v76, v49
	v_mul_f32_e32 v56, v14, v56
	v_mul_f32_e32 v49, v15, v49
	v_cvt_pk_bf16_f32 v56, v56, v49
	v_mul_f32_e32 v49, v76, v60
	v_mul_f32_e32 v57, v76, v59
	v_mul_f32_e32 v49, v16, v49
	v_mul_f32_e32 v57, v17, v57
	v_cvt_pk_bf16_f32 v57, v49, v57
	v_mul_f32_e32 v49, v76, v62
	v_mul_f32_e32 v58, v76, v61
	v_mul_f32_e32 v49, v10, v49
	v_mul_f32_e32 v58, v11, v58
	v_cvt_pk_bf16_f32 v58, v49, v58
	v_mul_f32_e32 v49, v76, v64
	v_mul_f32_e32 v59, v76, v63
	v_mul_f32_e32 v49, v12, v49
	v_mul_f32_e32 v59, v13, v59
	v_cvt_pk_bf16_f32 v59, v49, v59
	v_fmamk_f32 v49, v51, 0x3a800000, v194
	v_cmp_gt_f32_e32 vcc, s61, v49
	v_mul_f32_e32 v51, 0x4f800000, v49
	global_store_dwordx4 v[74:75], v[52:55], off
	global_store_dwordx4 v[74:75], v[56:59], off offset:1024
	v_cndmask_b32_e32 v49, v49, v51, vcc
	v_sqrt_f32_e32 v51, v49
	s_nop 0
	v_add_u32_e32 v52, -1, v51
	v_fma_f32 v53, -v52, v51, v49
	v_cmp_ge_f32_e64 s[0:1], 0, v53
	v_add_u32_e32 v53, 1, v51
	s_nop 0
	v_cndmask_b32_e64 v52, v51, v52, s[0:1]
	v_fma_f32 v51, -v53, v51, v49
	v_cmp_lt_f32_e64 s[0:1], 0, v51
	s_nop 1
	v_cndmask_b32_e64 v51, v52, v53, s[0:1]
	v_mul_f32_e32 v52, 0x37800000, v51
	v_cndmask_b32_e32 v51, v51, v52, vcc
	v_cmp_class_f32_e32 vcc, v49, v195
	s_nop 1
	v_cndmask_b32_e32 v49, v51, v49, vcc
	v_div_scale_f32 v51, s[0:1], v49, v49, 1.0
	v_rcp_f32_e32 v52, v51
	s_nop 0
	v_fma_f32 v53, -v51, v52, 1.0
	v_fmac_f32_e32 v52, v53, v52
	v_div_scale_f32 v53, vcc, 1.0, v49, 1.0
	v_mul_f32_e32 v54, v53, v52
	v_fma_f32 v55, -v51, v54, v53
	v_fmac_f32_e32 v54, v55, v52
	v_fma_f32 v51, -v51, v54, v53
	v_div_fmas_f32 v51, v51, v52, v54
	v_div_fixup_f32 v49, v51, v49, 1.0
	v_mul_f32_e32 v34, v49, v34
	v_mul_f32_e32 v33, v49, v33
	v_mul_f32_e32 v42, v49, v42
	v_mul_f32_e32 v41, v49, v41
	v_mul_f32_e32 v34, v14, v34
	v_mul_f32_e32 v33, v15, v33
	v_mul_f32_e32 v42, v6, v42
	v_mul_f32_e32 v41, v7, v41
	v_cvt_pk_bf16_f32 v34, v34, v33
	v_mul_f32_e32 v33, v49, v36
	v_mul_f32_e32 v35, v49, v35
	v_cvt_pk_bf16_f32 v42, v42, v41
	v_mul_f32_e32 v41, v49, v44
	v_mul_f32_e32 v43, v49, v43
	v_mul_f32_e32 v33, v16, v33
	v_mul_f32_e32 v35, v17, v35
	v_mul_f32_e32 v41, v8, v41
	v_mul_f32_e32 v43, v9, v43
	v_cvt_pk_bf16_f32 v35, v33, v35
	v_mul_f32_e32 v33, v49, v38
	v_mul_f32_e32 v36, v49, v37
	v_cvt_pk_bf16_f32 v43, v41, v43
	v_mul_f32_e32 v41, v49, v46
	v_mul_f32_e32 v44, v49, v45
	v_mul_f32_e32 v33, v10, v33
	v_mul_f32_e32 v36, v11, v36
	v_mul_f32_e32 v41, v2, v41
	v_mul_f32_e32 v44, v3, v44
	v_mul_f32_e32 v45, v49, v47
	v_cvt_pk_bf16_f32 v36, v33, v36
	v_mul_f32_e32 v33, v49, v40
	v_mul_f32_e32 v37, v49, v39
	v_cvt_pk_bf16_f32 v44, v41, v44
	v_mul_f32_e32 v41, v49, v48
	v_mul_f32_e32 v45, v5, v45
	v_mul_f32_e32 v33, v12, v33
	v_mul_f32_e32 v37, v13, v37
	v_mul_f32_e32 v41, v4, v41
	v_cvt_pk_bf16_f32 v45, v41, v45
	v_cvt_pk_bf16_f32 v37, v33, v37
	v_fmamk_f32 v33, v50, 0x3a800000, v194
	global_store_dwordx4 v[72:73], v[42:45], off
	global_store_dwordx4 v[72:73], v[34:37], off offset:1024
	v_cmp_gt_f32_e32 vcc, s61, v33
	s_nop 0
	v_mul_f32_e32 v34, 0x4f800000, v33
	v_cndmask_b32_e32 v33, v33, v34, vcc
	v_sqrt_f32_e32 v34, v33
	s_nop 0
	v_add_u32_e32 v35, -1, v34
	v_fma_f32 v36, -v35, v34, v33
	v_cmp_ge_f32_e64 s[0:1], 0, v36
	v_add_u32_e32 v36, 1, v34
	s_nop 0
	v_cndmask_b32_e64 v35, v34, v35, s[0:1]
	v_fma_f32 v34, -v36, v34, v33
	v_cmp_lt_f32_e64 s[0:1], 0, v34
	s_nop 1
	v_cndmask_b32_e64 v34, v35, v36, s[0:1]
	v_mul_f32_e32 v35, 0x37800000, v34
	v_cndmask_b32_e32 v34, v34, v35, vcc
	v_cmp_class_f32_e32 vcc, v33, v195
	s_nop 1
	v_cndmask_b32_e32 v33, v34, v33, vcc
	v_div_scale_f32 v34, s[0:1], v33, v33, 1.0
	v_rcp_f32_e32 v35, v34
	s_add_i32 s0, s2, s97
	s_cmp_gt_i32 s0, 0xffff
	v_fma_f32 v36, -v34, v35, 1.0
	v_fmac_f32_e32 v35, v36, v35
	v_div_scale_f32 v36, vcc, 1.0, v33, 1.0
	v_mul_f32_e32 v37, v36, v35
	v_fma_f32 v38, -v34, v37, v36
	v_fmac_f32_e32 v37, v38, v35
	v_fma_f32 v34, -v34, v37, v36
	v_div_fmas_f32 v34, v34, v35, v37
	v_div_fixup_f32 v33, v34, v33, 1.0
	v_mul_f32_e32 v26, v33, v26
	v_mul_f32_e32 v25, v33, v25
	v_mul_f32_e32 v6, v6, v26
	v_mul_f32_e32 v7, v7, v25
	v_cvt_pk_bf16_f32 v6, v6, v7
	v_mul_f32_e32 v7, v33, v28
	v_mul_f32_e32 v7, v8, v7
	v_mul_f32_e32 v8, v33, v27
	v_mul_f32_e32 v8, v9, v8
	v_cvt_pk_bf16_f32 v7, v7, v8
	v_mul_f32_e32 v8, v33, v30
	v_mul_f32_e32 v2, v2, v8
	v_mul_f32_e32 v8, v33, v29
	v_mul_f32_e32 v3, v3, v8
	v_cvt_pk_bf16_f32 v8, v2, v3
	v_mul_f32_e32 v2, v33, v32
	v_mul_f32_e32 v2, v4, v2
	v_mul_f32_e32 v3, v33, v31
	v_mul_f32_e32 v3, v5, v3
	v_cvt_pk_bf16_f32 v9, v2, v3
	v_mul_f32_e32 v2, v33, v18
	v_mul_f32_e32 v0, v33, v0
	v_mul_f32_e32 v2, v14, v2
	v_mul_f32_e32 v0, v15, v0
	v_cvt_pk_bf16_f32 v2, v2, v0
	v_mul_f32_e32 v0, v33, v20
	v_mul_f32_e32 v3, v33, v19
	v_mul_f32_e32 v0, v16, v0
	v_mul_f32_e32 v3, v17, v3
	v_cvt_pk_bf16_f32 v3, v0, v3
	v_mul_f32_e32 v0, v33, v22
	v_mul_f32_e32 v4, v33, v21
	v_mul_f32_e32 v0, v10, v0
	v_mul_f32_e32 v4, v11, v4
	v_mul_f32_e32 v5, v33, v23
	v_cvt_pk_bf16_f32 v4, v0, v4
	v_mul_f32_e32 v0, v33, v24
	v_mul_f32_e32 v5, v13, v5
	v_mul_f32_e32 v0, v12, v0
	v_cvt_pk_bf16_f32 v5, v0, v5
	global_store_dwordx4 v[70:71], v[6:9], off
	global_store_dwordx4 v[70:71], v[2:5], off offset:1024
	s_cbranch_scc0 .LBB0_463

.LBB0_672:
	s_ashr_i32 s17, s16, 31
	s_lshl_b64 s[0:1], s[16:17], 12
	v_lshl_add_u64 v[2:3], v[146:147], 0, s[0:1]
	global_load_dwordx4 v[126:129], v[2:3], off
	global_load_dwordx4 v[122:125], v[2:3], off offset:1024
	global_load_dwordx4 v[118:121], v[2:3], off offset:2048
	global_load_dwordx4 v[114:117], v[2:3], off offset:3072
	s_add_i32 s14, s16, s97
	s_ashr_i32 s15, s14, 31
	s_lshl_b64 s[0:1], s[14:15], 12
	v_lshl_add_u64 v[2:3], v[146:147], 0, s[0:1]
	global_load_dwordx4 v[110:113], v[2:3], off
	global_load_dwordx4 v[106:109], v[2:3], off offset:1024
	global_load_dwordx4 v[102:105], v[2:3], off offset:2048
	global_load_dwordx4 v[98:101], v[2:3], off offset:3072
	s_add_i32 s12, s88, s16
	s_ashr_i32 s13, s12, 31
	s_lshl_b64 s[0:1], s[12:13], 12
	v_lshl_add_u64 v[2:3], v[146:147], 0, s[0:1]
	global_load_dwordx4 v[94:97], v[2:3], off
	global_load_dwordx4 v[90:93], v[2:3], off offset:1024
	global_load_dwordx4 v[86:89], v[2:3], off offset:2048
	global_load_dwordx4 v[82:85], v[2:3], off offset:3072
	s_add_i32 s10, s75, s16
	s_ashr_i32 s11, s10, 31
	s_lshl_b64 s[0:1], s[10:11], 12
	v_lshl_add_u64 v[2:3], v[146:147], 0, s[0:1]
	global_load_dwordx4 v[78:81], v[2:3], off
	global_load_dwordx4 v[74:77], v[2:3], off offset:1024
	global_load_dwordx4 v[70:73], v[2:3], off offset:2048
	global_load_dwordx4 v[66:69], v[2:3], off offset:3072
	s_add_i32 s8, s89, s16
	s_ashr_i32 s9, s8, 31
	s_lshl_b64 s[0:1], s[8:9], 12
	v_lshl_add_u64 v[2:3], v[146:147], 0, s[0:1]
	global_load_dwordx4 v[62:65], v[2:3], off
	global_load_dwordx4 v[58:61], v[2:3], off offset:1024
	global_load_dwordx4 v[54:57], v[2:3], off offset:2048
	global_load_dwordx4 v[50:53], v[2:3], off offset:3072
	s_add_i32 s6, s77, s16
	s_ashr_i32 s7, s6, 31
	s_lshl_b64 s[0:1], s[6:7], 12
	v_lshl_add_u64 v[2:3], v[146:147], 0, s[0:1]
	global_load_dwordx4 v[46:49], v[2:3], off
	global_load_dwordx4 v[42:45], v[2:3], off offset:1024
	global_load_dwordx4 v[34:37], v[2:3], off offset:2048
	global_load_dwordx4 v[26:29], v[2:3], off offset:3072
	s_add_i32 s4, s78, s16
	s_ashr_i32 s5, s4, 31
	s_lshl_b64 s[0:1], s[4:5], 12
	v_lshl_add_u64 v[2:3], v[146:147], 0, s[0:1]
	global_load_dwordx4 v[14:17], v[2:3], off
	global_load_dwordx4 v[10:13], v[2:3], off offset:1024
	global_load_dwordx4 v[6:9], v[2:3], off offset:2048
	s_nop 0
	global_load_dwordx4 v[2:5], v[2:3], off offset:3072
	s_add_i32 s2, s14, s97
	s_add_i32 s2, s2, s97
	s_add_i32 s2, s2, s97
	s_add_i32 s2, s2, s97
	s_add_i32 s18, s2, s97
	s_add_i32 s2, s79, s16
	s_ashr_i32 s3, s2, 31
	s_lshl_b64 s[0:1], s[2:3], 12
	v_lshl_add_u64 v[18:19], v[146:147], 0, s[0:1]
	global_load_dwordx4 v[38:41], v[18:19], off
	global_load_dwordx4 v[30:33], v[18:19], off offset:1024
	global_load_dwordx4 v[22:25], v[18:19], off offset:2048
	s_nop 0
	global_load_dwordx4 v[18:21], v[18:19], off offset:3072
	s_add_i32 s18, s18, s97
	s_waitcnt vmcnt(31)
	v_mul_f32_e32 v0, v127, v127
	v_mul_f32_e32 v130, v129, v129
	v_fmac_f32_e32 v0, v126, v126
	v_fmac_f32_e32 v130, v128, v128
	v_add_f32_e32 v0, v0, v130
	s_waitcnt vmcnt(30)
	v_mul_f32_e32 v130, v123, v123
	v_mul_f32_e32 v131, v125, v125
	v_fmac_f32_e32 v130, v122, v122
	v_fmac_f32_e32 v131, v124, v124
	v_add_f32_e32 v130, v130, v131
	v_add_f32_e32 v0, v0, v130
	s_waitcnt vmcnt(29)
	v_mul_f32_e32 v130, v119, v119
	v_mul_f32_e32 v131, v121, v121
	v_fmac_f32_e32 v130, v118, v118
	v_fmac_f32_e32 v131, v120, v120
	v_add_f32_e32 v130, v130, v131
	v_add_f32_e32 v0, v0, v130
	s_waitcnt vmcnt(28)
	v_mul_f32_e32 v130, v115, v115
	v_mul_f32_e32 v131, v117, v117
	v_fmac_f32_e32 v130, v114, v114
	v_fmac_f32_e32 v131, v116, v116
	v_add_f32_e32 v130, v130, v131
	v_add_f32_e32 v0, v0, v130
	s_waitcnt vmcnt(27)
	v_mul_f32_e32 v130, v111, v111
	v_mul_f32_e32 v131, v113, v113
	v_fmac_f32_e32 v130, v110, v110
	v_fmac_f32_e32 v131, v112, v112
	v_add_f32_e32 v130, v130, v131
	s_waitcnt vmcnt(26)
	v_mul_f32_e32 v131, v107, v107
	v_mul_f32_e32 v132, v109, v109
	v_fmac_f32_e32 v131, v106, v106
	v_fmac_f32_e32 v132, v108, v108
	v_add_f32_e32 v131, v131, v132
	v_add_f32_e32 v130, v130, v131
	s_waitcnt vmcnt(25)
	v_mul_f32_e32 v131, v103, v103
	v_mul_f32_e32 v132, v105, v105
	v_fmac_f32_e32 v131, v102, v102
	v_fmac_f32_e32 v132, v104, v104
	v_add_f32_e32 v131, v131, v132
	v_add_f32_e32 v130, v130, v131
	s_waitcnt vmcnt(24)
	v_mul_f32_e32 v131, v99, v99
	v_mul_f32_e32 v132, v101, v101
	v_fmac_f32_e32 v131, v98, v98
	v_fmac_f32_e32 v132, v100, v100
	v_add_f32_e32 v131, v131, v132
	v_add_f32_e32 v130, v130, v131
	s_waitcnt vmcnt(23)
	v_mul_f32_e32 v131, v95, v95
	v_mul_f32_e32 v132, v97, v97
	v_fmac_f32_e32 v131, v94, v94
	v_fmac_f32_e32 v132, v96, v96
	v_add_f32_e32 v131, v131, v132
	s_waitcnt vmcnt(22)
	v_mul_f32_e32 v132, v91, v91
	v_mul_f32_e32 v133, v93, v93
	v_fmac_f32_e32 v132, v90, v90
	v_fmac_f32_e32 v133, v92, v92
	v_add_f32_e32 v132, v132, v133
	v_add_f32_e32 v131, v131, v132
	s_waitcnt vmcnt(21)
	v_mul_f32_e32 v132, v87, v87
	v_mul_f32_e32 v133, v89, v89
	v_fmac_f32_e32 v132, v86, v86
	v_fmac_f32_e32 v133, v88, v88
	v_add_f32_e32 v132, v132, v133
	v_add_f32_e32 v131, v131, v132
	s_waitcnt vmcnt(20)
	v_mul_f32_e32 v132, v83, v83
	v_mul_f32_e32 v133, v85, v85
	v_fmac_f32_e32 v132, v82, v82
	v_fmac_f32_e32 v133, v84, v84
	v_add_f32_e32 v132, v132, v133
	v_add_f32_e32 v131, v131, v132
	s_waitcnt vmcnt(19)
	v_mul_f32_e32 v132, v79, v79
	v_mul_f32_e32 v133, v81, v81
	v_fmac_f32_e32 v132, v78, v78
	v_fmac_f32_e32 v133, v80, v80
	v_add_f32_e32 v132, v132, v133
	s_waitcnt vmcnt(18)
	v_mul_f32_e32 v133, v75, v75
	v_mul_f32_e32 v134, v77, v77
	v_fmac_f32_e32 v133, v74, v74
	v_fmac_f32_e32 v134, v76, v76
	v_add_f32_e32 v133, v133, v134
	v_add_f32_e32 v132, v132, v133
	s_waitcnt vmcnt(17)
	v_mul_f32_e32 v133, v71, v71
	v_mul_f32_e32 v134, v73, v73
	v_fmac_f32_e32 v133, v70, v70
	v_fmac_f32_e32 v134, v72, v72
	v_add_f32_e32 v133, v133, v134
	v_add_f32_e32 v132, v132, v133
	s_waitcnt vmcnt(16)
	v_mul_f32_e32 v133, v67, v67
	v_mul_f32_e32 v134, v69, v69
	v_fmac_f32_e32 v133, v66, v66
	v_fmac_f32_e32 v134, v68, v68
	v_add_f32_e32 v133, v133, v134
	v_add_f32_e32 v132, v132, v133
	s_waitcnt vmcnt(15)
	v_mul_f32_e32 v133, v63, v63
	v_mul_f32_e32 v134, v65, v65
	v_fmac_f32_e32 v133, v62, v62
	v_fmac_f32_e32 v134, v64, v64
	v_add_f32_e32 v133, v133, v134
	s_waitcnt vmcnt(14)
	v_mul_f32_e32 v134, v59, v59
	v_mul_f32_e32 v135, v61, v61
	v_fmac_f32_e32 v134, v58, v58
	v_fmac_f32_e32 v135, v60, v60
	v_add_f32_e32 v134, v134, v135
	v_add_f32_e32 v133, v133, v134
	s_waitcnt vmcnt(13)
	v_mul_f32_e32 v134, v55, v55
	v_mul_f32_e32 v135, v57, v57
	v_fmac_f32_e32 v134, v54, v54
	v_fmac_f32_e32 v135, v56, v56
	v_add_f32_e32 v134, v134, v135
	v_add_f32_e32 v133, v133, v134
	s_waitcnt vmcnt(12)
	v_mul_f32_e32 v134, v51, v51
	v_mul_f32_e32 v135, v53, v53
	v_fmac_f32_e32 v134, v50, v50
	v_fmac_f32_e32 v135, v52, v52
	v_add_f32_e32 v134, v134, v135
	v_add_f32_e32 v133, v133, v134
	s_waitcnt vmcnt(11)
	v_mul_f32_e32 v134, v47, v47
	v_mul_f32_e32 v135, v49, v49
	v_fmac_f32_e32 v134, v46, v46
	v_fmac_f32_e32 v135, v48, v48
	v_add_f32_e32 v134, v134, v135
	s_waitcnt vmcnt(10)
	v_mul_f32_e32 v135, v43, v43
	v_mul_f32_e32 v136, v45, v45
	v_fmac_f32_e32 v135, v42, v42
	v_fmac_f32_e32 v136, v44, v44
	v_add_f32_e32 v135, v135, v136
	v_add_f32_e32 v134, v134, v135
	s_waitcnt vmcnt(9)
	v_mul_f32_e32 v135, v35, v35
	v_mul_f32_e32 v136, v37, v37
	v_fmac_f32_e32 v135, v34, v34
	v_fmac_f32_e32 v136, v36, v36
	v_add_f32_e32 v135, v135, v136
	v_add_f32_e32 v134, v134, v135
	s_waitcnt vmcnt(8)
	v_mul_f32_e32 v135, v27, v27
	v_mul_f32_e32 v136, v29, v29
	v_fmac_f32_e32 v135, v26, v26
	v_fmac_f32_e32 v136, v28, v28
	v_add_f32_e32 v135, v135, v136
	v_add_f32_e32 v134, v134, v135
	s_waitcnt vmcnt(7)
	v_mul_f32_e32 v135, v15, v15
	v_mul_f32_e32 v136, v17, v17
	v_fmac_f32_e32 v135, v14, v14
	v_fmac_f32_e32 v136, v16, v16
	v_add_f32_e32 v135, v135, v136
	s_waitcnt vmcnt(6)
	v_mul_f32_e32 v136, v11, v11
	v_mul_f32_e32 v137, v13, v13
	v_fmac_f32_e32 v136, v10, v10
	v_fmac_f32_e32 v137, v12, v12
	v_add_f32_e32 v136, v136, v137
	v_add_f32_e32 v135, v135, v136
	s_waitcnt vmcnt(5)
	v_mul_f32_e32 v136, v7, v7
	v_mul_f32_e32 v137, v9, v9
	v_fmac_f32_e32 v136, v6, v6
	v_fmac_f32_e32 v137, v8, v8
	v_add_f32_e32 v136, v136, v137
	v_add_f32_e32 v135, v135, v136
	s_waitcnt vmcnt(4)
	v_mul_f32_e32 v136, v3, v3
	v_mul_f32_e32 v137, v5, v5
	v_fmac_f32_e32 v136, v2, v2
	v_fmac_f32_e32 v137, v4, v4
	v_add_f32_e32 v136, v136, v137
	v_add_f32_e32 v135, v135, v136
	s_waitcnt vmcnt(3)
	v_mul_f32_e32 v136, v39, v39
	v_mul_f32_e32 v137, v41, v41
	v_fmac_f32_e32 v136, v38, v38
	v_fmac_f32_e32 v137, v40, v40
	v_add_f32_e32 v136, v136, v137
	s_waitcnt vmcnt(2)
	v_mul_f32_e32 v137, v31, v31
	v_mul_f32_e32 v138, v33, v33
	v_fmac_f32_e32 v137, v30, v30
	v_fmac_f32_e32 v138, v32, v32
	v_add_f32_e32 v137, v137, v138
	v_add_f32_e32 v136, v136, v137
	s_waitcnt vmcnt(1)
	v_mul_f32_e32 v137, v23, v23
	v_mul_f32_e32 v138, v25, v25
	v_fmac_f32_e32 v137, v22, v22
	v_fmac_f32_e32 v138, v24, v24
	v_add_f32_e32 v137, v137, v138
	v_add_f32_e32 v136, v136, v137
	s_waitcnt vmcnt(0)
	v_mul_f32_e32 v137, v19, v19
	v_mul_f32_e32 v138, v21, v21
	v_fmac_f32_e32 v137, v18, v18
	v_fmac_f32_e32 v138, v20, v20
	v_add_f32_e32 v137, v137, v138
	v_add_f32_e32 v136, v136, v137
	ds_bpermute_b32 v137, v152, v0
	ds_bpermute_b32 v200, v152, v130
	ds_bpermute_b32 v201, v152, v131
	ds_bpermute_b32 v202, v152, v132
	ds_bpermute_b32 v196, v152, v133
	ds_bpermute_b32 v162, v152, v134
	ds_bpermute_b32 v250, v152, v135
	ds_bpermute_b32 v251, v152, v136
	s_waitcnt lgkmcnt(0)
	v_add_f32_e32 v0, v0, v137
	v_add_f32_e32 v130, v130, v200
	v_add_f32_e32 v131, v131, v201
	v_add_f32_e32 v132, v132, v202
	v_add_f32_e32 v133, v133, v196
	v_add_f32_e32 v134, v134, v162
	v_add_f32_e32 v135, v135, v250
	v_add_f32_e32 v136, v136, v251
	ds_bpermute_b32 v137, v153, v0
	ds_bpermute_b32 v200, v153, v130
	ds_bpermute_b32 v201, v153, v131
	ds_bpermute_b32 v202, v153, v132
	ds_bpermute_b32 v196, v153, v133
	ds_bpermute_b32 v162, v153, v134
	ds_bpermute_b32 v250, v153, v135
	ds_bpermute_b32 v251, v153, v136
	s_waitcnt lgkmcnt(0)
	v_add_f32_e32 v0, v0, v137
	v_add_f32_e32 v130, v130, v200
	v_add_f32_e32 v131, v131, v201
	v_add_f32_e32 v132, v132, v202
	v_add_f32_e32 v133, v133, v196
	v_add_f32_e32 v134, v134, v162
	v_add_f32_e32 v135, v135, v250
	v_add_f32_e32 v136, v136, v251
	ds_bpermute_b32 v137, v154, v0
	ds_bpermute_b32 v200, v154, v130
	ds_bpermute_b32 v201, v154, v131
	ds_bpermute_b32 v202, v154, v132
	ds_bpermute_b32 v196, v154, v133
	ds_bpermute_b32 v162, v154, v134
	ds_bpermute_b32 v250, v154, v135
	ds_bpermute_b32 v251, v154, v136
	s_waitcnt lgkmcnt(0)
	v_add_f32_e32 v0, v0, v137
	v_add_f32_e32 v130, v130, v200
	v_add_f32_e32 v131, v131, v201
	v_add_f32_e32 v132, v132, v202
	v_add_f32_e32 v133, v133, v196
	v_add_f32_e32 v134, v134, v162
	v_add_f32_e32 v135, v135, v250
	v_add_f32_e32 v136, v136, v251
	ds_bpermute_b32 v137, v155, v0
	ds_bpermute_b32 v200, v155, v130
	ds_bpermute_b32 v201, v155, v131
	ds_bpermute_b32 v202, v155, v132
	ds_bpermute_b32 v196, v155, v133
	ds_bpermute_b32 v162, v155, v134
	ds_bpermute_b32 v250, v155, v135
	ds_bpermute_b32 v251, v155, v136
	s_waitcnt lgkmcnt(0)
	v_add_f32_e32 v0, v0, v137
	v_add_f32_e32 v130, v130, v200
	v_add_f32_e32 v131, v131, v201
	v_add_f32_e32 v132, v132, v202
	v_add_f32_e32 v133, v133, v196
	v_add_f32_e32 v134, v134, v162
	v_add_f32_e32 v135, v135, v250
	v_add_f32_e32 v136, v136, v251
	ds_bpermute_b32 v137, v156, v0
	ds_bpermute_b32 v200, v156, v130
	ds_bpermute_b32 v201, v156, v131
	ds_bpermute_b32 v202, v156, v132
	ds_bpermute_b32 v196, v156, v133
	ds_bpermute_b32 v162, v156, v134
	ds_bpermute_b32 v250, v156, v135
	ds_bpermute_b32 v251, v156, v136
	s_waitcnt lgkmcnt(0)
	v_add_f32_e32 v0, v0, v137
	v_add_f32_e32 v130, v130, v200
	v_add_f32_e32 v131, v131, v201
	v_add_f32_e32 v132, v132, v202
	v_add_f32_e32 v133, v133, v196
	v_add_f32_e32 v134, v134, v162
	v_add_f32_e32 v135, v135, v250
	v_add_f32_e32 v136, v136, v251
	ds_bpermute_b32 v137, v157, v0
	s_waitcnt lgkmcnt(0)
	v_add_f32_e32 v164, v0, v137
	ds_bpermute_b32 v0, v157, v130
	v_fmamk_f32 v164, v164, 0x3a800000, v194
	v_cmp_gt_f32_e32 vcc, s61, v164
	v_mul_f32_e32 v165, 0x4f800000, v164
	s_waitcnt lgkmcnt(0)
	v_add_f32_e32 v166, v130, v0
	ds_bpermute_b32 v0, v157, v131
	v_cndmask_b32_e32 v164, v164, v165, vcc
	v_sqrt_f32_e32 v165, v164
	s_waitcnt lgkmcnt(0)
	v_add_f32_e32 v163, v131, v0
	ds_bpermute_b32 v0, v157, v132
	v_add_u32_e32 v167, -1, v165
	v_fma_f32 v168, -v167, v165, v164
	v_cmp_ge_f32_e64 s[0:1], 0, v168
	v_add_u32_e32 v168, 1, v165
	s_waitcnt lgkmcnt(0)
	v_add_f32_e32 v161, v132, v0
	ds_bpermute_b32 v0, v157, v133
	v_cndmask_b32_e64 v167, v165, v167, s[0:1]
	v_fma_f32 v165, -v168, v165, v164
	v_cmp_lt_f32_e64 s[0:1], 0, v165
	s_waitcnt lgkmcnt(0)
	v_add_f32_e32 v160, v133, v0
	ds_bpermute_b32 v0, v157, v134
	v_cndmask_b32_e64 v165, v167, v168, s[0:1]
	v_mul_f32_e32 v167, 0x37800000, v165
	v_cndmask_b32_e32 v165, v165, v167, vcc
	v_cmp_class_f32_e32 vcc, v164, v195
	s_waitcnt lgkmcnt(0)
	v_add_f32_e32 v159, v134, v0
	ds_bpermute_b32 v0, v157, v135
	v_cndmask_b32_e32 v164, v165, v164, vcc
	v_div_scale_f32 v165, s[0:1], v164, v164, 1.0
	v_rcp_f32_e32 v167, v165
	s_waitcnt lgkmcnt(0)
	v_add_f32_e32 v158, v135, v0
	ds_bpermute_b32 v0, v157, v136
	s_lshl_b64 s[0:1], s[16:17], 11
	v_fma_f32 v168, -v165, v167, 1.0
	v_fmac_f32_e32 v167, v168, v167
	v_div_scale_f32 v168, vcc, 1.0, v164, 1.0
	s_waitcnt lgkmcnt(0)
	v_add_f32_e32 v0, v136, v0
	global_load_dwordx4 v[130:133], v[148:149], off
	global_load_dwordx4 v[134:137], v[148:149], off offset:1024
	global_load_dwordx4 v[138:141], v[148:149], off offset:2048
	global_load_dwordx4 v[142:145], v[148:149], off offset:3072
	v_mul_f32_e32 v169, v168, v167
	v_fma_f32 v170, -v165, v169, v168
	v_fmac_f32_e32 v169, v170, v167
	v_fma_f32 v165, -v165, v169, v168
	v_div_fmas_f32 v165, v165, v167, v169
	v_div_fixup_f32 v167, v165, v164, 1.0
	v_mul_f32_e32 v114, v114, v167
	v_mul_f32_e32 v115, v115, v167
	v_lshl_add_u64 v[164:165], v[150:151], 0, s[0:1]
	v_mul_f32_e32 v118, v118, v167
	v_mul_f32_e32 v119, v119, v167
	v_fmamk_f32 v0, v0, 0x3a800000, v194
	v_mul_f32_e32 v126, v126, v167
	v_mul_f32_e32 v127, v127, v167
	v_mul_f32_e32 v122, v122, v167
	v_mul_f32_e32 v123, v123, v167
	s_add_i32 s16, s18, s97
	s_waitcnt vmcnt(3)
	v_mul_f32_e32 v126, v126, v130
	v_mul_f32_e32 v127, v127, v131
	s_waitcnt vmcnt(1)
	v_mul_f32_e32 v118, v118, v138
	s_waitcnt vmcnt(0)
	v_mul_f32_e32 v114, v114, v142
	v_mul_f32_e32 v115, v115, v143
	v_cvt_pk_bf16_f32 v114, v114, v115
	v_mul_f32_e32 v115, v116, v167
	v_mul_f32_e32 v115, v115, v144
	v_mul_f32_e32 v116, v117, v167
	v_mul_f32_e32 v116, v116, v145
	v_cvt_pk_bf16_f32 v115, v115, v116
	global_store_dwordx2 v[164:165], v[114:115], off offset:1536
	v_fmamk_f32 v114, v166, 0x3a800000, v194
	v_cmp_gt_f32_e32 vcc, s61, v114
	v_mul_f32_e32 v115, 0x4f800000, v114
	v_mul_f32_e32 v119, v119, v139
	v_cndmask_b32_e32 v114, v114, v115, vcc
	v_sqrt_f32_e32 v115, v114
	v_cvt_pk_bf16_f32 v118, v118, v119
	v_mul_f32_e32 v119, v120, v167
	v_mul_f32_e32 v119, v119, v140
	v_add_u32_e32 v116, -1, v115
	v_fma_f32 v117, -v116, v115, v114
	v_cmp_ge_f32_e64 s[0:1], 0, v117
	v_add_u32_e32 v117, 1, v115
	v_mul_f32_e32 v120, v121, v167
	v_cndmask_b32_e64 v116, v115, v116, s[0:1]
	v_fma_f32 v115, -v117, v115, v114
	v_cmp_lt_f32_e64 s[0:1], 0, v115
	v_mul_f32_e32 v120, v120, v141
	v_cvt_pk_bf16_f32 v119, v119, v120
	global_store_dwordx2 v[164:165], v[118:119], off offset:1024
	v_cndmask_b32_e64 v115, v116, v117, s[0:1]
	v_mul_f32_e32 v116, 0x37800000, v115
	v_cndmask_b32_e32 v115, v115, v116, vcc
	v_cmp_class_f32_e32 vcc, v114, v195
	v_cvt_pk_bf16_f32 v126, v126, v127
	v_mul_f32_e32 v127, v128, v167
	v_mul_f32_e32 v127, v127, v132
	v_cndmask_b32_e32 v114, v115, v114, vcc
	v_div_scale_f32 v115, s[0:1], v114, v114, 1.0
	v_rcp_f32_e32 v116, v115
	s_lshl_b64 s[0:1], s[14:15], 11
	v_mul_f32_e32 v128, v129, v167
	v_mul_f32_e32 v128, v128, v133
	v_fma_f32 v117, -v115, v116, 1.0
	v_fmac_f32_e32 v116, v117, v116
	v_div_scale_f32 v117, vcc, 1.0, v114, 1.0
	v_mul_f32_e32 v118, v117, v116
	v_fma_f32 v119, -v115, v118, v117
	v_fmac_f32_e32 v118, v119, v116
	v_fma_f32 v115, -v115, v118, v117
	v_div_fmas_f32 v115, v115, v116, v118
	v_div_fixup_f32 v116, v115, v114, 1.0
	v_mul_f32_e32 v98, v98, v116
	v_mul_f32_e32 v99, v99, v116
	v_mul_f32_e32 v98, v98, v142
	v_mul_f32_e32 v99, v99, v143
	v_cvt_pk_bf16_f32 v98, v98, v99
	v_mul_f32_e32 v99, v100, v116
	v_lshl_add_u64 v[114:115], v[150:151], 0, s[0:1]
	v_mul_f32_e32 v99, v99, v144
	v_mul_f32_e32 v100, v101, v116
	v_mul_f32_e32 v100, v100, v145
	v_cvt_pk_bf16_f32 v99, v99, v100
	global_store_dwordx2 v[114:115], v[98:99], off offset:1536
	v_fmamk_f32 v98, v163, 0x3a800000, v194
	v_cmp_gt_f32_e32 vcc, s61, v98
	v_mul_f32_e32 v99, 0x4f800000, v98
	v_mul_f32_e32 v102, v102, v116
	v_cndmask_b32_e32 v98, v98, v99, vcc
	v_sqrt_f32_e32 v99, v98
	v_mul_f32_e32 v103, v103, v116
	v_mul_f32_e32 v102, v102, v138
	v_mul_f32_e32 v103, v103, v139
	v_add_u32_e32 v100, -1, v99
	v_fma_f32 v101, -v100, v99, v98
	v_cmp_ge_f32_e64 s[0:1], 0, v101
	v_add_u32_e32 v101, 1, v99
	v_cvt_pk_bf16_f32 v102, v102, v103
	v_mul_f32_e32 v103, v104, v116
	v_cndmask_b32_e64 v100, v99, v100, s[0:1]
	v_fma_f32 v99, -v101, v99, v98
	v_cmp_lt_f32_e64 s[0:1], 0, v99
	v_mul_f32_e32 v103, v103, v140
	v_mul_f32_e32 v104, v105, v116
	v_cndmask_b32_e64 v99, v100, v101, s[0:1]
	v_mul_f32_e32 v100, 0x37800000, v99
	v_cndmask_b32_e32 v99, v99, v100, vcc
	v_cmp_class_f32_e32 vcc, v98, v195
	v_mul_f32_e32 v104, v104, v141
	v_cvt_pk_bf16_f32 v103, v103, v104
	global_store_dwordx2 v[114:115], v[102:103], off offset:1024
	v_cndmask_b32_e32 v98, v99, v98, vcc
	v_div_scale_f32 v99, s[0:1], v98, v98, 1.0
	v_rcp_f32_e32 v100, v99
	s_lshl_b64 s[0:1], s[12:13], 11
	v_mul_f32_e32 v110, v110, v116
	v_mul_f32_e32 v111, v111, v116
	v_fma_f32 v101, -v99, v100, 1.0
	v_fmac_f32_e32 v100, v101, v100
	v_div_scale_f32 v101, vcc, 1.0, v98, 1.0
	v_mul_f32_e32 v102, v101, v100
	v_fma_f32 v103, -v99, v102, v101
	v_fmac_f32_e32 v102, v103, v100
	v_fma_f32 v99, -v99, v102, v101
	v_div_fmas_f32 v99, v99, v100, v102
	v_div_fixup_f32 v100, v99, v98, 1.0
	v_mul_f32_e32 v82, v82, v100
	v_mul_f32_e32 v83, v83, v100
	v_mul_f32_e32 v82, v82, v142
	v_mul_f32_e32 v83, v83, v143
	v_cvt_pk_bf16_f32 v82, v82, v83
	v_mul_f32_e32 v83, v84, v100
	v_lshl_add_u64 v[98:99], v[150:151], 0, s[0:1]
	v_mul_f32_e32 v83, v83, v144
	v_mul_f32_e32 v84, v85, v100
	v_mul_f32_e32 v84, v84, v145
	v_cvt_pk_bf16_f32 v83, v83, v84
	global_store_dwordx2 v[98:99], v[82:83], off offset:1536
	v_fmamk_f32 v82, v161, 0x3a800000, v194
	v_cmp_gt_f32_e32 vcc, s61, v82
	v_mul_f32_e32 v83, 0x4f800000, v82
	v_mul_f32_e32 v86, v86, v100
	v_cndmask_b32_e32 v82, v82, v83, vcc
	v_sqrt_f32_e32 v83, v82
	v_mul_f32_e32 v87, v87, v100
	v_mul_f32_e32 v86, v86, v138
	v_mul_f32_e32 v87, v87, v139
	v_add_u32_e32 v84, -1, v83
	v_fma_f32 v85, -v84, v83, v82
	v_cmp_ge_f32_e64 s[0:1], 0, v85
	v_add_u32_e32 v85, 1, v83
	v_cvt_pk_bf16_f32 v86, v86, v87
	v_mul_f32_e32 v87, v88, v100
	v_cndmask_b32_e64 v84, v83, v84, s[0:1]
	v_fma_f32 v83, -v85, v83, v82
	v_cmp_lt_f32_e64 s[0:1], 0, v83
	v_mul_f32_e32 v87, v87, v140
	v_mul_f32_e32 v88, v89, v100
	v_cndmask_b32_e64 v83, v84, v85, s[0:1]
	v_mul_f32_e32 v84, 0x37800000, v83
	v_cndmask_b32_e32 v83, v83, v84, vcc
	v_cmp_class_f32_e32 vcc, v82, v195
	v_mul_f32_e32 v88, v88, v141
	v_cvt_pk_bf16_f32 v87, v87, v88
	global_store_dwordx2 v[98:99], v[86:87], off offset:1024
	v_cndmask_b32_e32 v82, v83, v82, vcc
	v_div_scale_f32 v83, s[0:1], v82, v82, 1.0
	v_rcp_f32_e32 v84, v83
	s_lshl_b64 s[0:1], s[10:11], 11
	v_mul_f32_e32 v94, v94, v100
	v_mul_f32_e32 v95, v95, v100
	v_fma_f32 v85, -v83, v84, 1.0
	v_fmac_f32_e32 v84, v85, v84
	v_div_scale_f32 v85, vcc, 1.0, v82, 1.0
	v_mul_f32_e32 v86, v85, v84
	v_fma_f32 v87, -v83, v86, v85
	v_fmac_f32_e32 v86, v87, v84
	v_fma_f32 v83, -v83, v86, v85
	v_div_fmas_f32 v83, v83, v84, v86
	v_div_fixup_f32 v84, v83, v82, 1.0
	v_mul_f32_e32 v66, v66, v84
	v_mul_f32_e32 v67, v67, v84
	v_mul_f32_e32 v66, v66, v142
	v_mul_f32_e32 v67, v67, v143
	v_cvt_pk_bf16_f32 v66, v66, v67
	v_mul_f32_e32 v67, v68, v84
	v_lshl_add_u64 v[82:83], v[150:151], 0, s[0:1]
	v_mul_f32_e32 v67, v67, v144
	v_mul_f32_e32 v68, v69, v84
	v_mul_f32_e32 v68, v68, v145
	v_cvt_pk_bf16_f32 v67, v67, v68
	global_store_dwordx2 v[82:83], v[66:67], off offset:1536
	v_fmamk_f32 v66, v160, 0x3a800000, v194
	v_cmp_gt_f32_e32 vcc, s61, v66
	v_mul_f32_e32 v67, 0x4f800000, v66
	v_mul_f32_e32 v70, v70, v84
	v_cndmask_b32_e32 v66, v66, v67, vcc
	v_sqrt_f32_e32 v67, v66
	v_mul_f32_e32 v71, v71, v84
	v_mul_f32_e32 v70, v70, v138
	v_mul_f32_e32 v71, v71, v139
	v_add_u32_e32 v68, -1, v67
	v_fma_f32 v69, -v68, v67, v66
	v_cmp_ge_f32_e64 s[0:1], 0, v69
	v_add_u32_e32 v69, 1, v67
	v_cvt_pk_bf16_f32 v70, v70, v71
	v_mul_f32_e32 v71, v72, v84
	v_cndmask_b32_e64 v68, v67, v68, s[0:1]
	v_fma_f32 v67, -v69, v67, v66
	v_cmp_lt_f32_e64 s[0:1], 0, v67
	v_mul_f32_e32 v71, v71, v140
	v_mul_f32_e32 v72, v73, v84
	v_cndmask_b32_e64 v67, v68, v69, s[0:1]
	v_mul_f32_e32 v68, 0x37800000, v67
	v_cndmask_b32_e32 v67, v67, v68, vcc
	v_cmp_class_f32_e32 vcc, v66, v195
	v_mul_f32_e32 v72, v72, v141
	v_cvt_pk_bf16_f32 v71, v71, v72
	global_store_dwordx2 v[82:83], v[70:71], off offset:1024
	v_cndmask_b32_e32 v66, v67, v66, vcc
	v_div_scale_f32 v67, s[0:1], v66, v66, 1.0
	v_rcp_f32_e32 v68, v67
	s_lshl_b64 s[0:1], s[8:9], 11
	v_mul_f32_e32 v78, v78, v84
	v_mul_f32_e32 v79, v79, v84
	v_fma_f32 v69, -v67, v68, 1.0
	v_fmac_f32_e32 v68, v69, v68
	v_div_scale_f32 v69, vcc, 1.0, v66, 1.0
	v_mul_f32_e32 v70, v69, v68
	v_fma_f32 v71, -v67, v70, v69
	v_fmac_f32_e32 v70, v71, v68
	v_fma_f32 v67, -v67, v70, v69
	v_div_fmas_f32 v67, v67, v68, v70
	v_div_fixup_f32 v68, v67, v66, 1.0
	v_mul_f32_e32 v50, v50, v68
	v_mul_f32_e32 v51, v51, v68
	v_mul_f32_e32 v50, v50, v142
	v_mul_f32_e32 v51, v51, v143
	v_cvt_pk_bf16_f32 v50, v50, v51
	v_mul_f32_e32 v51, v52, v68
	v_lshl_add_u64 v[66:67], v[150:151], 0, s[0:1]
	v_mul_f32_e32 v51, v51, v144
	v_mul_f32_e32 v52, v53, v68
	v_mul_f32_e32 v52, v52, v145
	v_cvt_pk_bf16_f32 v51, v51, v52
	global_store_dwordx2 v[66:67], v[50:51], off offset:1536
	v_fmamk_f32 v50, v159, 0x3a800000, v194
	v_cmp_gt_f32_e32 vcc, s61, v50
	v_mul_f32_e32 v51, 0x4f800000, v50
	v_mul_f32_e32 v54, v54, v68
	v_cndmask_b32_e32 v50, v50, v51, vcc
	v_sqrt_f32_e32 v51, v50
	v_mul_f32_e32 v55, v55, v68
	v_mul_f32_e32 v54, v54, v138
	v_mul_f32_e32 v55, v55, v139
	v_add_u32_e32 v52, -1, v51
	v_fma_f32 v53, -v52, v51, v50
	v_cmp_ge_f32_e64 s[0:1], 0, v53
	v_add_u32_e32 v53, 1, v51
	v_cvt_pk_bf16_f32 v54, v54, v55
	v_mul_f32_e32 v55, v56, v68
	v_cndmask_b32_e64 v52, v51, v52, s[0:1]
	v_fma_f32 v51, -v53, v51, v50
	v_cmp_lt_f32_e64 s[0:1], 0, v51
	v_mul_f32_e32 v55, v55, v140
	v_mul_f32_e32 v56, v57, v68
	v_cndmask_b32_e64 v51, v52, v53, s[0:1]
	v_mul_f32_e32 v52, 0x37800000, v51
	v_cndmask_b32_e32 v51, v51, v52, vcc
	v_cmp_class_f32_e32 vcc, v50, v195
	v_mul_f32_e32 v56, v56, v141
	v_cvt_pk_bf16_f32 v55, v55, v56
	global_store_dwordx2 v[66:67], v[54:55], off offset:1024
	v_cndmask_b32_e32 v50, v51, v50, vcc
	v_div_scale_f32 v51, s[0:1], v50, v50, 1.0
	v_rcp_f32_e32 v52, v51
	s_lshl_b64 s[0:1], s[6:7], 11
	v_mul_f32_e32 v62, v62, v68
	v_mul_f32_e32 v63, v63, v68
	v_fma_f32 v53, -v51, v52, 1.0
	v_fmac_f32_e32 v52, v53, v52
	v_div_scale_f32 v53, vcc, 1.0, v50, 1.0
	v_mul_f32_e32 v54, v53, v52
	v_fma_f32 v55, -v51, v54, v53
	v_fmac_f32_e32 v54, v55, v52
	v_fma_f32 v51, -v51, v54, v53
	v_div_fmas_f32 v51, v51, v52, v54
	v_div_fixup_f32 v52, v51, v50, 1.0
	v_mul_f32_e32 v26, v26, v52
	v_mul_f32_e32 v27, v27, v52
	v_mul_f32_e32 v26, v26, v142
	v_mul_f32_e32 v27, v27, v143
	v_cvt_pk_bf16_f32 v26, v26, v27
	v_mul_f32_e32 v27, v28, v52
	v_lshl_add_u64 v[50:51], v[150:151], 0, s[0:1]
	v_mul_f32_e32 v27, v27, v144
	v_mul_f32_e32 v28, v29, v52
	v_mul_f32_e32 v28, v28, v145
	v_cvt_pk_bf16_f32 v27, v27, v28
	global_store_dwordx2 v[50:51], v[26:27], off offset:1536
	v_fmamk_f32 v26, v158, 0x3a800000, v194
	v_cmp_gt_f32_e32 vcc, s61, v26
	v_mul_f32_e32 v27, 0x4f800000, v26
	v_mul_f32_e32 v34, v34, v52
	v_cndmask_b32_e32 v26, v26, v27, vcc
	v_sqrt_f32_e32 v27, v26
	v_mul_f32_e32 v35, v35, v52
	v_mul_f32_e32 v34, v138, v34
	v_mul_f32_e32 v35, v139, v35
	v_add_u32_e32 v28, -1, v27
	v_fma_f32 v29, -v28, v27, v26
	v_cmp_ge_f32_e64 s[0:1], 0, v29
	v_add_u32_e32 v29, 1, v27
	v_cvt_pk_bf16_f32 v34, v34, v35
	v_mul_f32_e32 v35, v36, v52
	v_cndmask_b32_e64 v28, v27, v28, s[0:1]
	v_fma_f32 v27, -v29, v27, v26
	v_cmp_lt_f32_e64 s[0:1], 0, v27
	v_mul_f32_e32 v35, v140, v35
	v_mul_f32_e32 v36, v37, v52
	v_cndmask_b32_e64 v27, v28, v29, s[0:1]
	v_mul_f32_e32 v28, 0x37800000, v27
	v_cndmask_b32_e32 v27, v27, v28, vcc
	v_cmp_class_f32_e32 vcc, v26, v195
	v_mul_f32_e32 v36, v141, v36
	v_cvt_pk_bf16_f32 v35, v35, v36
	global_store_dwordx2 v[50:51], v[34:35], off offset:1024
	v_cndmask_b32_e32 v26, v27, v26, vcc
	v_div_scale_f32 v27, s[0:1], v26, v26, 1.0
	v_rcp_f32_e32 v28, v27
	s_lshl_b64 s[0:1], s[4:5], 11
	v_mul_f32_e32 v46, v46, v52
	v_mul_f32_e32 v47, v47, v52
	v_fma_f32 v29, -v27, v28, 1.0
	v_fmac_f32_e32 v28, v29, v28
	v_div_scale_f32 v29, vcc, 1.0, v26, 1.0
	v_mul_f32_e32 v34, v29, v28
	v_fma_f32 v35, -v27, v34, v29
	v_fmac_f32_e32 v34, v35, v28
	v_fma_f32 v27, -v27, v34, v29
	v_div_fmas_f32 v27, v27, v28, v34
	v_div_fixup_f32 v28, v27, v26, 1.0
	v_mul_f32_e32 v2, v2, v28
	v_mul_f32_e32 v3, v3, v28
	v_mul_f32_e32 v2, v142, v2
	v_mul_f32_e32 v3, v143, v3
	v_cvt_pk_bf16_f32 v2, v2, v3
	v_mul_f32_e32 v3, v4, v28
	v_lshl_add_u64 v[26:27], v[150:151], 0, s[0:1]
	v_mul_f32_e32 v3, v144, v3
	v_mul_f32_e32 v4, v5, v28
	v_mul_f32_e32 v4, v145, v4
	v_cvt_pk_bf16_f32 v3, v3, v4
	global_store_dwordx2 v[26:27], v[2:3], off offset:1536
	v_cmp_gt_f32_e32 vcc, s61, v0
	v_mul_f32_e32 v2, 0x4f800000, v0
	v_mul_f32_e32 v6, v6, v28
	v_cndmask_b32_e32 v0, v0, v2, vcc
	v_sqrt_f32_e32 v2, v0
	v_mul_f32_e32 v7, v7, v28
	v_mul_f32_e32 v6, v138, v6
	v_mul_f32_e32 v7, v139, v7
	v_add_u32_e32 v3, -1, v2
	v_fma_f32 v4, -v3, v2, v0
	v_cmp_ge_f32_e64 s[0:1], 0, v4
	v_add_u32_e32 v4, 1, v2
	v_cvt_pk_bf16_f32 v6, v6, v7
	v_mul_f32_e32 v7, v8, v28
	v_cndmask_b32_e64 v3, v2, v3, s[0:1]
	v_fma_f32 v2, -v4, v2, v0
	v_cmp_lt_f32_e64 s[0:1], 0, v2
	v_mul_f32_e32 v7, v140, v7
	v_mul_f32_e32 v8, v9, v28
	v_cndmask_b32_e64 v2, v3, v4, s[0:1]
	v_mul_f32_e32 v3, 0x37800000, v2
	v_cndmask_b32_e32 v2, v2, v3, vcc
	v_cmp_class_f32_e32 vcc, v0, v195
	v_mul_f32_e32 v8, v141, v8
	v_cvt_pk_bf16_f32 v7, v7, v8
	global_store_dwordx2 v[26:27], v[6:7], off offset:1024
	v_cndmask_b32_e32 v0, v2, v0, vcc
	v_div_scale_f32 v2, s[0:1], v0, v0, 1.0
	v_rcp_f32_e32 v3, v2
	v_mul_f32_e32 v14, v14, v28
	v_mul_f32_e32 v15, v15, v28
	v_mul_f32_e32 v110, v110, v130
	v_fma_f32 v4, -v2, v3, 1.0
	v_fmac_f32_e32 v3, v4, v3
	v_div_scale_f32 v4, vcc, 1.0, v0, 1.0
	v_mul_f32_e32 v5, v4, v3
	v_fma_f32 v6, -v2, v5, v4
	v_fmac_f32_e32 v5, v6, v3
	v_fma_f32 v2, -v2, v5, v4
	v_div_fmas_f32 v2, v2, v3, v5
	v_div_fixup_f32 v0, v2, v0, 1.0
	v_mul_f32_e32 v4, v38, v0
	v_mul_f32_e32 v5, v39, v0
	v_mul_f32_e32 v4, v130, v4
	v_mul_f32_e32 v5, v131, v5
	v_mul_f32_e32 v111, v111, v131
	v_mul_f32_e32 v94, v94, v130
	v_mul_f32_e32 v95, v95, v131
	v_mul_f32_e32 v78, v130, v78
	v_mul_f32_e32 v79, v131, v79
	v_mul_f32_e32 v62, v130, v62
	v_mul_f32_e32 v63, v131, v63
	v_mul_f32_e32 v46, v130, v46
	v_mul_f32_e32 v47, v131, v47
	v_mul_f32_e32 v14, v130, v14
	v_mul_f32_e32 v15, v131, v15
	v_cvt_pk_bf16_f32 v4, v4, v5
	v_mul_f32_e32 v5, v40, v0
	v_cvt_pk_bf16_f32 v110, v110, v111
	v_mul_f32_e32 v111, v112, v116
	v_cvt_pk_bf16_f32 v94, v94, v95
	v_mul_f32_e32 v95, v96, v100
	v_cvt_pk_bf16_f32 v78, v78, v79
	v_mul_f32_e32 v79, v80, v84
	v_cvt_pk_bf16_f32 v62, v62, v63
	v_mul_f32_e32 v63, v64, v68
	v_cvt_pk_bf16_f32 v46, v46, v47
	v_mul_f32_e32 v47, v48, v52
	v_cvt_pk_bf16_f32 v14, v14, v15
	v_mul_f32_e32 v15, v16, v28
	s_lshl_b64 s[0:1], s[2:3], 11
	v_mul_f32_e32 v5, v132, v5
	v_mul_f32_e32 v6, v41, v0
	v_mul_f32_e32 v111, v111, v132
	v_mul_f32_e32 v112, v113, v116
	v_mul_f32_e32 v95, v95, v132
	v_mul_f32_e32 v96, v97, v100
	v_mul_f32_e32 v79, v132, v79
	v_mul_f32_e32 v80, v81, v84
	v_mul_f32_e32 v63, v132, v63
	v_mul_f32_e32 v64, v65, v68
	v_mul_f32_e32 v47, v132, v47
	v_mul_f32_e32 v48, v49, v52
	v_mul_f32_e32 v15, v132, v15
	v_mul_f32_e32 v16, v17, v28
	v_lshl_add_u64 v[2:3], v[150:151], 0, s[0:1]
	v_mul_f32_e32 v6, v133, v6
	v_cvt_pk_bf16_f32 v5, v5, v6
	v_cvt_pk_bf16_f32 v127, v127, v128
	global_store_dwordx2 v[164:165], v[126:127], off
	v_mul_f32_e32 v112, v112, v133
	v_cvt_pk_bf16_f32 v111, v111, v112
	global_store_dwordx2 v[114:115], v[110:111], off
	v_mul_f32_e32 v96, v96, v133
	v_cvt_pk_bf16_f32 v95, v95, v96
	global_store_dwordx2 v[98:99], v[94:95], off
	v_mul_f32_e32 v80, v133, v80
	v_cvt_pk_bf16_f32 v79, v79, v80
	global_store_dwordx2 v[82:83], v[78:79], off
	v_mul_f32_e32 v64, v133, v64
	v_cvt_pk_bf16_f32 v63, v63, v64
	global_store_dwordx2 v[66:67], v[62:63], off
	v_mul_f32_e32 v48, v133, v48
	v_cvt_pk_bf16_f32 v47, v47, v48
	global_store_dwordx2 v[50:51], v[46:47], off
	v_mul_f32_e32 v16, v133, v16
	v_cvt_pk_bf16_f32 v15, v15, v16
	global_store_dwordx2 v[26:27], v[14:15], off
	global_store_dwordx2 v[2:3], v[4:5], off
	v_mul_f32_e32 v4, v30, v0
	v_mul_f32_e32 v5, v31, v0
	v_mul_f32_e32 v106, v106, v116
	v_mul_f32_e32 v107, v107, v116
	v_mul_f32_e32 v90, v90, v100
	v_mul_f32_e32 v91, v91, v100
	v_mul_f32_e32 v74, v74, v84
	v_mul_f32_e32 v75, v75, v84
	v_mul_f32_e32 v58, v58, v68
	v_mul_f32_e32 v59, v59, v68
	v_mul_f32_e32 v42, v42, v52
	v_mul_f32_e32 v43, v43, v52
	v_mul_f32_e32 v10, v10, v28
	v_mul_f32_e32 v11, v11, v28
	v_mul_f32_e32 v4, v134, v4
	v_mul_f32_e32 v5, v135, v5
	v_mul_f32_e32 v122, v122, v134
	v_mul_f32_e32 v123, v123, v135
	v_mul_f32_e32 v106, v106, v134
	v_mul_f32_e32 v107, v107, v135
	v_mul_f32_e32 v90, v90, v134
	v_mul_f32_e32 v91, v91, v135
	v_mul_f32_e32 v74, v74, v134
	v_mul_f32_e32 v75, v75, v135
	v_mul_f32_e32 v58, v134, v58
	v_mul_f32_e32 v59, v135, v59
	v_mul_f32_e32 v42, v134, v42
	v_mul_f32_e32 v43, v135, v43
	v_mul_f32_e32 v10, v134, v10
	v_mul_f32_e32 v11, v135, v11
	v_cvt_pk_bf16_f32 v4, v4, v5
	v_mul_f32_e32 v5, v32, v0
	v_cvt_pk_bf16_f32 v122, v122, v123
	v_mul_f32_e32 v123, v124, v167
	v_cvt_pk_bf16_f32 v106, v106, v107
	v_mul_f32_e32 v107, v108, v116
	v_cvt_pk_bf16_f32 v90, v90, v91
	v_mul_f32_e32 v91, v92, v100
	v_cvt_pk_bf16_f32 v74, v74, v75
	v_mul_f32_e32 v75, v76, v84
	v_cvt_pk_bf16_f32 v58, v58, v59
	v_mul_f32_e32 v59, v60, v68
	v_cvt_pk_bf16_f32 v42, v42, v43
	v_mul_f32_e32 v43, v44, v52
	v_cvt_pk_bf16_f32 v10, v10, v11
	v_mul_f32_e32 v11, v12, v28
	v_mul_f32_e32 v5, v136, v5
	v_mul_f32_e32 v6, v33, v0
	v_mul_f32_e32 v123, v123, v136
	v_mul_f32_e32 v124, v125, v167
	v_mul_f32_e32 v107, v107, v136
	v_mul_f32_e32 v108, v109, v116
	v_mul_f32_e32 v91, v91, v136
	v_mul_f32_e32 v92, v93, v100
	v_mul_f32_e32 v75, v75, v136
	v_mul_f32_e32 v76, v77, v84
	v_mul_f32_e32 v59, v136, v59
	v_mul_f32_e32 v60, v61, v68
	v_mul_f32_e32 v43, v136, v43
	v_mul_f32_e32 v44, v45, v52
	v_mul_f32_e32 v11, v136, v11
	v_mul_f32_e32 v12, v13, v28
	v_mul_f32_e32 v6, v137, v6
	v_cvt_pk_bf16_f32 v5, v5, v6
	v_mul_f32_e32 v124, v124, v137
	v_cvt_pk_bf16_f32 v123, v123, v124
	global_store_dwordx2 v[164:165], v[122:123], off offset:512
	v_mul_f32_e32 v108, v108, v137
	v_cvt_pk_bf16_f32 v107, v107, v108
	global_store_dwordx2 v[114:115], v[106:107], off offset:512
	v_mul_f32_e32 v92, v92, v137
	v_cvt_pk_bf16_f32 v91, v91, v92
	global_store_dwordx2 v[98:99], v[90:91], off offset:512
	v_mul_f32_e32 v76, v76, v137
	v_cvt_pk_bf16_f32 v75, v75, v76
	global_store_dwordx2 v[82:83], v[74:75], off offset:512
	v_mul_f32_e32 v60, v137, v60
	v_cvt_pk_bf16_f32 v59, v59, v60
	global_store_dwordx2 v[66:67], v[58:59], off offset:512
	v_mul_f32_e32 v44, v137, v44
	v_cvt_pk_bf16_f32 v43, v43, v44
	global_store_dwordx2 v[50:51], v[42:43], off offset:512
	v_mul_f32_e32 v12, v137, v12
	v_cvt_pk_bf16_f32 v11, v11, v12
	global_store_dwordx2 v[26:27], v[10:11], off offset:512
	global_store_dwordx2 v[2:3], v[4:5], off offset:512
	v_mul_f32_e32 v4, v22, v0
	v_mul_f32_e32 v5, v23, v0
	v_mul_f32_e32 v4, v138, v4
	v_mul_f32_e32 v5, v139, v5
	v_cvt_pk_bf16_f32 v4, v4, v5
	v_mul_f32_e32 v5, v24, v0
	v_mul_f32_e32 v5, v140, v5
	v_mul_f32_e32 v6, v25, v0
	v_mul_f32_e32 v6, v141, v6
	v_cvt_pk_bf16_f32 v5, v5, v6
	global_store_dwordx2 v[2:3], v[4:5], off offset:1024
	v_mul_f32_e32 v4, v18, v0
	v_mul_f32_e32 v5, v19, v0
	v_mul_f32_e32 v4, v142, v4
	v_mul_f32_e32 v5, v143, v5
	v_cvt_pk_bf16_f32 v4, v4, v5
	v_mul_f32_e32 v5, v20, v0
	v_mul_f32_e32 v5, v144, v5
	v_mul_f32_e32 v0, v21, v0
	s_cmp_gt_i32 s16, 0xffff
	v_mul_f32_e32 v0, v145, v0
	v_cvt_pk_bf16_f32 v5, v5, v0
	global_store_dwordx2 v[2:3], v[4:5], off offset:1536
	s_cbranch_scc0 .LBB0_672

.LBB0_951:
	s_ashr_i32 s3, s2, 31
	s_lshl_b64 s[4:5], s[2:3], 12
	v_lshl_add_u64 v[170:171], v[146:147], 0, s[4:5]
	global_load_dwordx4 v[126:129], v[170:171], off
	global_load_dwordx4 v[122:125], v[170:171], off offset:1024
	global_load_dwordx4 v[118:121], v[170:171], off offset:2048
	global_load_dwordx4 v[114:117], v[170:171], off offset:3072
	s_add_i32 s4, s2, s97
	s_ashr_i32 s5, s4, 31
	s_lshl_b64 s[14:15], s[4:5], 12
	v_lshl_add_u64 v[168:169], v[146:147], 0, s[14:15]
	global_load_dwordx4 v[110:113], v[168:169], off
	global_load_dwordx4 v[106:109], v[168:169], off offset:1024
	global_load_dwordx4 v[102:105], v[168:169], off offset:2048
	global_load_dwordx4 v[98:101], v[168:169], off offset:3072
	s_add_i32 s3, s4, s97
	s_add_i32 s4, s88, s2
	s_ashr_i32 s5, s4, 31
	s_lshl_b64 s[4:5], s[4:5], 12
	v_lshl_add_u64 v[160:161], v[146:147], 0, s[4:5]
	global_load_dwordx4 v[94:97], v[160:161], off
	global_load_dwordx4 v[90:93], v[160:161], off offset:1024
	global_load_dwordx4 v[86:89], v[160:161], off offset:2048
	global_load_dwordx4 v[82:85], v[160:161], off offset:3072
	s_add_i32 s4, s75, s2
	s_ashr_i32 s5, s4, 31
	s_lshl_b64 s[4:5], s[4:5], 12
	v_lshl_add_u64 v[158:159], v[146:147], 0, s[4:5]
	global_load_dwordx4 v[78:81], v[158:159], off
	global_load_dwordx4 v[74:77], v[158:159], off offset:1024
	global_load_dwordx4 v[70:73], v[158:159], off offset:2048
	global_load_dwordx4 v[66:69], v[158:159], off offset:3072
	s_add_i32 s4, s89, s2
	s_ashr_i32 s5, s4, 31
	s_lshl_b64 s[4:5], s[4:5], 12
	v_lshl_add_u64 v[156:157], v[146:147], 0, s[4:5]
	global_load_dwordx4 v[62:65], v[156:157], off
	global_load_dwordx4 v[58:61], v[156:157], off offset:1024
	global_load_dwordx4 v[54:57], v[156:157], off offset:2048
	global_load_dwordx4 v[50:53], v[156:157], off offset:3072
	s_add_i32 s4, s77, s2
	s_ashr_i32 s5, s4, 31
	s_lshl_b64 s[4:5], s[4:5], 12
	v_lshl_add_u64 v[154:155], v[146:147], 0, s[4:5]
	global_load_dwordx4 v[34:37], v[154:155], off
	global_load_dwordx4 v[26:29], v[154:155], off offset:1024
	global_load_dwordx4 v[22:25], v[154:155], off offset:2048
	global_load_dwordx4 v[18:21], v[154:155], off offset:3072
	s_add_i32 s4, s78, s2
	s_ashr_i32 s5, s4, 31
	s_lshl_b64 s[4:5], s[4:5], 12
	v_lshl_add_u64 v[150:151], v[146:147], 0, s[4:5]
	global_load_dwordx4 v[14:17], v[150:151], off
	global_load_dwordx4 v[10:13], v[150:151], off offset:1024
	global_load_dwordx4 v[6:9], v[150:151], off offset:2048
	global_load_dwordx4 v[2:5], v[150:151], off offset:3072
	s_add_i32 s3, s3, s97
	s_add_i32 s3, s3, s97
	s_add_i32 s3, s3, s97
	s_add_i32 s3, s3, s97
	s_add_i32 s2, s79, s2
	s_add_i32 s4, s3, s97
	s_ashr_i32 s3, s2, 31
	s_lshl_b64 s[2:3], s[2:3], 12
	v_lshl_add_u64 v[152:153], v[146:147], 0, s[2:3]
	global_load_dwordx4 v[46:49], v[152:153], off
	global_load_dwordx4 v[42:45], v[152:153], off offset:1024
	global_load_dwordx4 v[38:41], v[152:153], off offset:2048
	global_load_dwordx4 v[30:33], v[152:153], off offset:3072
	s_waitcnt vmcnt(31)
	v_pk_mul_f32 v[130:131], v[128:129], v[128:129]
	v_pk_mul_f32 v[132:133], v[126:127], v[126:127]
	s_waitcnt vmcnt(28)
	v_mul_f32_e32 v0, v114, v114
	v_pk_mov_b32 v[134:135], v[132:133], v[130:131] op_sel:[1,0]
	v_mov_b32_e32 v133, v131
	v_pk_add_f32 v[130:131], v[134:135], v[132:133]
	v_pk_mul_f32 v[132:133], v[124:125], v[124:125]
	v_pk_mul_f32 v[134:135], v[122:123], v[122:123]
	v_pk_add_f32 v[130:131], v[130:131], v[130:131] op_sel:[0,1] op_sel_hi:[1,0]
	v_pk_mov_b32 v[136:137], v[134:135], v[132:133] op_sel:[1,0]
	v_mov_b32_e32 v135, v133
	v_pk_add_f32 v[132:133], v[136:137], v[134:135]
	v_mul_f32_e32 v134, v115, v115
	v_pk_add_f32 v[132:133], v[132:133], v[132:133] op_sel:[0,1] op_sel_hi:[1,0]
	v_mov_b32_e32 v131, v0
	v_mov_b32_e32 v133, v134
	v_mul_f32_e32 v0, v119, v119
	v_mul_f32_e32 v135, v116, v116
	v_pk_add_f32 v[130:131], v[130:131], v[132:133]
	v_pk_fma_f32 v[132:133], v[118:119], v[118:119], v[0:1] op_sel_hi:[1,1,0]
	v_mul_f32_e32 v0, v121, v121
	v_mul_f32_e32 v136, v117, v117
	v_mov_b32_e32 v133, v135
	v_pk_fma_f32 v[134:135], v[120:121], v[120:121], v[0:1] op_sel_hi:[1,1,0]
	s_waitcnt vmcnt(24)
	v_mul_f32_e32 v0, v98, v98
	v_mov_b32_e32 v135, v136
	v_pk_add_f32 v[132:133], v[132:133], v[134:135]
	s_nop 0
	v_pk_add_f32 v[130:131], v[130:131], v[132:133]
	v_pk_mul_f32 v[132:133], v[110:111], v[110:111]
	v_add_f32_e32 v138, v130, v131
	v_pk_mul_f32 v[130:131], v[112:113], v[112:113]
	s_nop 0
	v_pk_mov_b32 v[134:135], v[132:133], v[130:131] op_sel:[1,0]
	v_mov_b32_e32 v133, v131
	v_pk_add_f32 v[130:131], v[134:135], v[132:133]
	v_pk_mul_f32 v[132:133], v[108:109], v[108:109]
	v_pk_mul_f32 v[134:135], v[106:107], v[106:107]
	v_pk_add_f32 v[130:131], v[130:131], v[130:131] op_sel:[0,1] op_sel_hi:[1,0]
	v_pk_mov_b32 v[136:137], v[134:135], v[132:133] op_sel:[1,0]
	v_mov_b32_e32 v135, v133
	v_pk_add_f32 v[132:133], v[136:137], v[134:135]
	v_mul_f32_e32 v134, v99, v99
	v_pk_add_f32 v[132:133], v[132:133], v[132:133] op_sel:[0,1] op_sel_hi:[1,0]
	v_mov_b32_e32 v131, v0
	v_mov_b32_e32 v133, v134
	v_mul_f32_e32 v0, v103, v103
	v_mul_f32_e32 v135, v100, v100
	v_pk_add_f32 v[130:131], v[130:131], v[132:133]
	v_pk_fma_f32 v[132:133], v[102:103], v[102:103], v[0:1] op_sel_hi:[1,1,0]
	v_mul_f32_e32 v0, v105, v105
	v_mul_f32_e32 v136, v101, v101
	v_mov_b32_e32 v133, v135
	v_pk_fma_f32 v[134:135], v[104:105], v[104:105], v[0:1] op_sel_hi:[1,1,0]
	s_waitcnt vmcnt(20)
	v_mul_f32_e32 v0, v82, v82
	v_mov_b32_e32 v135, v136
	v_pk_add_f32 v[132:133], v[132:133], v[134:135]
	s_nop 0
	v_pk_add_f32 v[130:131], v[130:131], v[132:133]
	v_pk_mul_f32 v[132:133], v[94:95], v[94:95]
	v_add_f32_e32 v139, v130, v131
	v_pk_mul_f32 v[130:131], v[96:97], v[96:97]
	s_nop 0
	v_pk_mov_b32 v[134:135], v[132:133], v[130:131] op_sel:[1,0]
	v_mov_b32_e32 v133, v131
	v_pk_add_f32 v[130:131], v[134:135], v[132:133]
	v_pk_mul_f32 v[132:133], v[92:93], v[92:93]
	v_pk_mul_f32 v[134:135], v[90:91], v[90:91]
	v_pk_add_f32 v[130:131], v[130:131], v[130:131] op_sel:[0,1] op_sel_hi:[1,0]
	v_pk_mov_b32 v[136:137], v[134:135], v[132:133] op_sel:[1,0]
	v_mov_b32_e32 v135, v133
	v_pk_add_f32 v[132:133], v[136:137], v[134:135]
	v_mul_f32_e32 v134, v83, v83
	v_pk_add_f32 v[132:133], v[132:133], v[132:133] op_sel:[0,1] op_sel_hi:[1,0]
	v_mov_b32_e32 v131, v0
	v_mov_b32_e32 v133, v134
	v_mul_f32_e32 v0, v87, v87
	v_mul_f32_e32 v135, v84, v84
	v_pk_add_f32 v[130:131], v[130:131], v[132:133]
	v_pk_fma_f32 v[132:133], v[86:87], v[86:87], v[0:1] op_sel_hi:[1,1,0]
	v_mul_f32_e32 v0, v89, v89
	v_mul_f32_e32 v136, v85, v85
	v_mov_b32_e32 v133, v135
	v_pk_fma_f32 v[134:135], v[88:89], v[88:89], v[0:1] op_sel_hi:[1,1,0]
	s_waitcnt vmcnt(16)
	v_mul_f32_e32 v0, v66, v66
	v_mov_b32_e32 v135, v136
	v_pk_add_f32 v[132:133], v[132:133], v[134:135]
	s_nop 0
	v_pk_add_f32 v[130:131], v[130:131], v[132:133]
	v_pk_mul_f32 v[132:133], v[78:79], v[78:79]
	v_add_f32_e32 v140, v130, v131
	v_pk_mul_f32 v[130:131], v[80:81], v[80:81]
	s_nop 0
	v_pk_mov_b32 v[134:135], v[132:133], v[130:131] op_sel:[1,0]
	v_mov_b32_e32 v133, v131
	v_pk_add_f32 v[130:131], v[134:135], v[132:133]
	v_pk_mul_f32 v[132:133], v[76:77], v[76:77]
	v_pk_mul_f32 v[134:135], v[74:75], v[74:75]
	v_pk_add_f32 v[130:131], v[130:131], v[130:131] op_sel:[0,1] op_sel_hi:[1,0]
	v_pk_mov_b32 v[136:137], v[134:135], v[132:133] op_sel:[1,0]
	v_mov_b32_e32 v135, v133
	v_pk_add_f32 v[132:133], v[136:137], v[134:135]
	v_mul_f32_e32 v134, v67, v67
	v_pk_add_f32 v[132:133], v[132:133], v[132:133] op_sel:[0,1] op_sel_hi:[1,0]
	v_mov_b32_e32 v131, v0
	v_mov_b32_e32 v133, v134
	v_mul_f32_e32 v0, v71, v71
	v_mul_f32_e32 v135, v68, v68
	v_pk_add_f32 v[130:131], v[130:131], v[132:133]
	v_pk_fma_f32 v[132:133], v[70:71], v[70:71], v[0:1] op_sel_hi:[1,1,0]
	v_mul_f32_e32 v0, v73, v73
	v_mul_f32_e32 v136, v69, v69
	v_mov_b32_e32 v133, v135
	v_pk_fma_f32 v[134:135], v[72:73], v[72:73], v[0:1] op_sel_hi:[1,1,0]
	s_waitcnt vmcnt(12)
	v_mul_f32_e32 v0, v50, v50
	v_mov_b32_e32 v135, v136
	v_pk_add_f32 v[132:133], v[132:133], v[134:135]
	s_nop 0
	v_pk_add_f32 v[130:131], v[130:131], v[132:133]
	v_pk_mul_f32 v[132:133], v[62:63], v[62:63]
	v_add_f32_e32 v141, v130, v131
	v_pk_mul_f32 v[130:131], v[64:65], v[64:65]
	s_nop 0
	v_pk_mov_b32 v[134:135], v[132:133], v[130:131] op_sel:[1,0]
	v_mov_b32_e32 v133, v131
	v_pk_add_f32 v[130:131], v[134:135], v[132:133]
	v_pk_mul_f32 v[132:133], v[60:61], v[60:61]
	v_pk_mul_f32 v[134:135], v[58:59], v[58:59]
	v_pk_add_f32 v[130:131], v[130:131], v[130:131] op_sel:[0,1] op_sel_hi:[1,0]
	v_pk_mov_b32 v[136:137], v[134:135], v[132:133] op_sel:[1,0]
	v_mov_b32_e32 v135, v133
	v_pk_add_f32 v[132:133], v[136:137], v[134:135]
	v_mul_f32_e32 v134, v51, v51
	v_pk_add_f32 v[132:133], v[132:133], v[132:133] op_sel:[0,1] op_sel_hi:[1,0]
	v_mov_b32_e32 v131, v0
	v_mov_b32_e32 v133, v134
	v_mul_f32_e32 v0, v55, v55
	v_mul_f32_e32 v135, v52, v52
	v_pk_add_f32 v[130:131], v[130:131], v[132:133]
	v_pk_fma_f32 v[132:133], v[54:55], v[54:55], v[0:1] op_sel_hi:[1,1,0]
	v_mul_f32_e32 v0, v57, v57
	v_mul_f32_e32 v136, v53, v53
	v_mov_b32_e32 v133, v135
	v_pk_fma_f32 v[134:135], v[56:57], v[56:57], v[0:1] op_sel_hi:[1,1,0]
	s_waitcnt vmcnt(8)
	v_mul_f32_e32 v0, v18, v18
	v_mov_b32_e32 v135, v136
	v_pk_add_f32 v[132:133], v[132:133], v[134:135]
	s_nop 0
	v_pk_add_f32 v[130:131], v[130:131], v[132:133]
	v_pk_mul_f32 v[132:133], v[34:35], v[34:35]
	v_add_f32_e32 v142, v130, v131
	v_pk_mul_f32 v[130:131], v[36:37], v[36:37]
	s_nop 0
	v_pk_mov_b32 v[134:135], v[132:133], v[130:131] op_sel:[1,0]
	v_mov_b32_e32 v133, v131
	v_pk_add_f32 v[130:131], v[134:135], v[132:133]
	v_pk_mul_f32 v[132:133], v[28:29], v[28:29]
	v_pk_mul_f32 v[134:135], v[26:27], v[26:27]
	v_pk_add_f32 v[130:131], v[130:131], v[130:131] op_sel:[0,1] op_sel_hi:[1,0]
	v_pk_mov_b32 v[136:137], v[134:135], v[132:133] op_sel:[1,0]
	v_mov_b32_e32 v135, v133
	v_pk_add_f32 v[132:133], v[136:137], v[134:135]
	v_mul_f32_e32 v134, v19, v19
	v_pk_add_f32 v[132:133], v[132:133], v[132:133] op_sel:[0,1] op_sel_hi:[1,0]
	v_mov_b32_e32 v131, v0
	v_mov_b32_e32 v133, v134
	v_mul_f32_e32 v0, v23, v23
	v_mul_f32_e32 v135, v20, v20
	v_pk_add_f32 v[130:131], v[130:131], v[132:133]
	v_pk_fma_f32 v[132:133], v[22:23], v[22:23], v[0:1] op_sel_hi:[1,1,0]
	v_mul_f32_e32 v0, v25, v25
	v_mul_f32_e32 v136, v21, v21
	v_mov_b32_e32 v133, v135
	v_pk_fma_f32 v[134:135], v[24:25], v[24:25], v[0:1] op_sel_hi:[1,1,0]
	s_waitcnt vmcnt(4)
	v_mul_f32_e32 v0, v2, v2
	v_mov_b32_e32 v135, v136
	v_pk_add_f32 v[132:133], v[132:133], v[134:135]
	s_nop 0
	v_pk_add_f32 v[130:131], v[130:131], v[132:133]
	v_pk_mul_f32 v[132:133], v[14:15], v[14:15]
	v_add_f32_e32 v143, v130, v131
	v_pk_mul_f32 v[130:131], v[16:17], v[16:17]
	s_nop 0
	v_pk_mov_b32 v[134:135], v[132:133], v[130:131] op_sel:[1,0]
	v_mov_b32_e32 v133, v131
	v_pk_add_f32 v[130:131], v[134:135], v[132:133]
	v_pk_mul_f32 v[132:133], v[12:13], v[12:13]
	v_pk_mul_f32 v[134:135], v[10:11], v[10:11]
	v_pk_add_f32 v[130:131], v[130:131], v[130:131] op_sel:[0,1] op_sel_hi:[1,0]
	v_pk_mov_b32 v[136:137], v[134:135], v[132:133] op_sel:[1,0]
	v_mov_b32_e32 v135, v133
	v_pk_add_f32 v[132:133], v[136:137], v[134:135]
	v_mul_f32_e32 v134, v3, v3
	v_pk_add_f32 v[132:133], v[132:133], v[132:133] op_sel:[0,1] op_sel_hi:[1,0]
	v_mov_b32_e32 v131, v0
	v_mov_b32_e32 v133, v134
	v_mul_f32_e32 v0, v7, v7
	v_mul_f32_e32 v135, v4, v4
	v_pk_add_f32 v[130:131], v[130:131], v[132:133]
	v_pk_fma_f32 v[132:133], v[6:7], v[6:7], v[0:1] op_sel_hi:[1,1,0]
	v_mul_f32_e32 v0, v9, v9
	v_mul_f32_e32 v136, v5, v5
	v_mov_b32_e32 v133, v135
	v_pk_fma_f32 v[134:135], v[8:9], v[8:9], v[0:1] op_sel_hi:[1,1,0]
	s_waitcnt vmcnt(0)
	v_mul_f32_e32 v0, v30, v30
	v_mov_b32_e32 v135, v136
	v_pk_add_f32 v[132:133], v[132:133], v[134:135]
	s_nop 0
	v_pk_add_f32 v[130:131], v[130:131], v[132:133]
	v_pk_mul_f32 v[132:133], v[46:47], v[46:47]
	v_add_f32_e32 v144, v130, v131
	v_pk_mul_f32 v[130:131], v[48:49], v[48:49]
	s_nop 0
	v_pk_mov_b32 v[134:135], v[132:133], v[130:131] op_sel:[1,0]
	v_mov_b32_e32 v133, v131
	v_pk_add_f32 v[130:131], v[134:135], v[132:133]
	v_pk_mul_f32 v[132:133], v[44:45], v[44:45]
	v_pk_mul_f32 v[134:135], v[42:43], v[42:43]
	v_pk_add_f32 v[130:131], v[130:131], v[130:131] op_sel:[0,1] op_sel_hi:[1,0]
	v_pk_mov_b32 v[136:137], v[134:135], v[132:133] op_sel:[1,0]
	v_mov_b32_e32 v135, v133
	v_pk_add_f32 v[132:133], v[136:137], v[134:135]
	v_mul_f32_e32 v134, v31, v31
	v_pk_add_f32 v[132:133], v[132:133], v[132:133] op_sel:[0,1] op_sel_hi:[1,0]
	v_mov_b32_e32 v131, v0
	v_mov_b32_e32 v133, v134
	v_mul_f32_e32 v0, v39, v39
	v_mul_f32_e32 v135, v32, v32
	v_pk_add_f32 v[130:131], v[130:131], v[132:133]
	v_pk_fma_f32 v[132:133], v[38:39], v[38:39], v[0:1] op_sel_hi:[1,1,0]
	v_mul_f32_e32 v0, v41, v41
	v_mul_f32_e32 v136, v33, v33
	v_mov_b32_e32 v133, v135
	v_pk_fma_f32 v[134:135], v[40:41], v[40:41], v[0:1] op_sel_hi:[1,1,0]
	s_nop 0
	v_mov_b32_e32 v135, v136
	v_pk_add_f32 v[132:133], v[132:133], v[134:135]
	ds_bpermute_b32 v134, v172, v142
	v_pk_add_f32 v[130:131], v[130:131], v[132:133]
	ds_bpermute_b32 v132, v172, v140
	v_add_f32_e32 v0, v130, v131
	ds_bpermute_b32 v130, v172, v138
	ds_bpermute_b32 v137, v172, v0
	ds_bpermute_b32 v131, v172, v139
	s_waitcnt lgkmcnt(3)
	v_add_f32_e32 v132, v140, v132
	ds_bpermute_b32 v133, v172, v141
	s_waitcnt lgkmcnt(3)
	v_add_f32_e32 v130, v138, v130
	s_waitcnt lgkmcnt(2)
	v_add_f32_e32 v0, v0, v137
	ds_bpermute_b32 v137, v173, v130
	s_waitcnt lgkmcnt(2)
	v_add_f32_e32 v131, v139, v131
	s_waitcnt lgkmcnt(1)
	v_add_f32_e32 v133, v141, v133
	v_add_f32_e32 v134, v142, v134
	ds_bpermute_b32 v135, v172, v143
	s_waitcnt lgkmcnt(1)
	v_add_f32_e32 v130, v130, v137
	ds_bpermute_b32 v137, v173, v131
	ds_bpermute_b32 v136, v172, v144
	s_waitcnt lgkmcnt(2)
	v_add_f32_e32 v135, v143, v135
	s_waitcnt lgkmcnt(1)
	v_add_f32_e32 v131, v131, v137
	ds_bpermute_b32 v137, v173, v132
	s_waitcnt lgkmcnt(1)
	v_add_f32_e32 v136, v144, v136
	s_waitcnt lgkmcnt(0)
	v_add_f32_e32 v132, v132, v137
	ds_bpermute_b32 v137, v173, v133
	ds_bpermute_b32 v200, v173, v134
	ds_bpermute_b32 v201, v173, v135
	ds_bpermute_b32 v202, v173, v136
	ds_bpermute_b32 v196, v173, v0
	s_waitcnt lgkmcnt(0)
	v_add_f32_e32 v133, v133, v137
	v_add_f32_e32 v134, v134, v200
	v_add_f32_e32 v135, v135, v201
	v_add_f32_e32 v136, v136, v202
	v_add_f32_e32 v0, v0, v196
	ds_bpermute_b32 v137, v174, v130
	ds_bpermute_b32 v200, v174, v131
	ds_bpermute_b32 v201, v174, v132
	ds_bpermute_b32 v202, v174, v133
	ds_bpermute_b32 v196, v174, v134
	ds_bpermute_b32 v162, v174, v135
	ds_bpermute_b32 v250, v174, v136
	ds_bpermute_b32 v251, v174, v0
	s_waitcnt lgkmcnt(0)
	v_add_f32_e32 v130, v130, v137
	v_add_f32_e32 v131, v131, v200
	v_add_f32_e32 v132, v132, v201
	v_add_f32_e32 v133, v133, v202
	v_add_f32_e32 v134, v134, v196
	v_add_f32_e32 v135, v135, v162
	v_add_f32_e32 v136, v136, v250
	v_add_f32_e32 v0, v0, v251
	ds_bpermute_b32 v137, v175, v130
	ds_bpermute_b32 v200, v175, v131
	ds_bpermute_b32 v201, v175, v132
	ds_bpermute_b32 v202, v175, v133
	ds_bpermute_b32 v196, v175, v134
	ds_bpermute_b32 v162, v175, v135
	ds_bpermute_b32 v250, v175, v136
	ds_bpermute_b32 v251, v175, v0
	s_waitcnt lgkmcnt(0)
	v_add_f32_e32 v130, v130, v137
	v_add_f32_e32 v131, v131, v200
	v_add_f32_e32 v132, v132, v201
	v_add_f32_e32 v133, v133, v202
	v_add_f32_e32 v134, v134, v196
	v_add_f32_e32 v135, v135, v162
	v_add_f32_e32 v136, v136, v250
	v_add_f32_e32 v0, v0, v251
	ds_bpermute_b32 v137, v176, v130
	ds_bpermute_b32 v200, v176, v131
	ds_bpermute_b32 v201, v176, v132
	ds_bpermute_b32 v202, v176, v133
	ds_bpermute_b32 v196, v176, v134
	ds_bpermute_b32 v162, v176, v135
	ds_bpermute_b32 v250, v176, v136
	ds_bpermute_b32 v251, v176, v0
	s_waitcnt lgkmcnt(0)
	v_add_f32_e32 v130, v130, v137
	v_add_f32_e32 v131, v131, v200
	v_add_f32_e32 v132, v132, v201
	v_add_f32_e32 v133, v133, v202
	v_add_f32_e32 v134, v134, v196
	v_add_f32_e32 v135, v135, v162
	v_add_f32_e32 v136, v136, v250
	v_add_f32_e32 v0, v0, v251
	ds_bpermute_b32 v137, v177, v130
	s_waitcnt lgkmcnt(0)
	v_add_f32_e32 v164, v130, v137
	ds_bpermute_b32 v130, v177, v131
	v_fmamk_f32 v164, v164, 0x3a800000, v194
	v_cmp_gt_f32_e32 vcc, s61, v164
	v_mul_f32_e32 v166, 0x4f800000, v164
	s_waitcnt lgkmcnt(0)
	v_add_f32_e32 v165, v131, v130
	ds_bpermute_b32 v130, v177, v132
	v_cndmask_b32_e32 v164, v164, v166, vcc
	v_sqrt_f32_e32 v166, v164
	s_waitcnt lgkmcnt(0)
	v_add_f32_e32 v182, v132, v130
	ds_bpermute_b32 v130, v177, v133
	v_add_u32_e32 v167, -1, v166
	v_fma_f32 v183, -v167, v166, v164
	v_cmp_ge_f32_e64 s[2:3], 0, v183
	v_add_u32_e32 v183, 1, v166
	s_waitcnt lgkmcnt(0)
	v_add_f32_e32 v181, v133, v130
	ds_bpermute_b32 v130, v177, v134
	v_cndmask_b32_e64 v167, v166, v167, s[2:3]
	v_fma_f32 v166, -v183, v166, v164
	v_cmp_lt_f32_e64 s[2:3], 0, v166
	s_waitcnt lgkmcnt(0)
	v_add_f32_e32 v180, v134, v130
	ds_bpermute_b32 v130, v177, v135
	v_cndmask_b32_e64 v166, v167, v183, s[2:3]
	v_mul_f32_e32 v167, 0x37800000, v166
	v_cndmask_b32_e32 v166, v166, v167, vcc
	v_cmp_class_f32_e32 vcc, v164, v195
	s_waitcnt lgkmcnt(0)
	v_add_f32_e32 v179, v135, v130
	ds_bpermute_b32 v130, v177, v136
	v_cndmask_b32_e32 v164, v166, v164, vcc
	v_div_scale_f32 v166, s[2:3], v164, v164, 1.0
	v_rcp_f32_e32 v167, v166
	s_waitcnt lgkmcnt(0)
	v_add_f32_e32 v178, v136, v130
	ds_bpermute_b32 v130, v177, v0
	v_fma_f32 v183, -v166, v167, 1.0
	v_fmac_f32_e32 v167, v183, v167
	v_div_scale_f32 v183, vcc, 1.0, v164, 1.0
	s_waitcnt lgkmcnt(0)
	v_add_f32_e32 v0, v0, v130
	global_load_dwordx4 v[130:133], v[148:149], off
	global_load_dwordx4 v[134:137], v[148:149], off offset:1024
	global_load_dwordx4 v[138:141], v[148:149], off offset:2048
	global_load_dwordx4 v[142:145], v[148:149], off offset:3072
	v_mul_f32_e32 v184, v183, v167
	v_fma_f32 v185, -v166, v184, v183
	v_fmac_f32_e32 v184, v185, v167
	v_fma_f32 v166, -v166, v184, v183
	v_div_fmas_f32 v166, v166, v167, v184
	v_div_fixup_f32 v164, v166, v164, 1.0
	v_pk_mul_f32 v[114:115], v[114:115], v[164:165] op_sel_hi:[1,0]
	v_pk_mul_f32 v[116:117], v[116:117], v[164:165] op_sel_hi:[1,0]
	v_pk_mul_f32 v[118:119], v[118:119], v[164:165] op_sel_hi:[1,0]
	v_pk_mul_f32 v[120:121], v[120:121], v[164:165] op_sel_hi:[1,0]
	v_fmamk_f32 v0, v0, 0x3a800000, v194
	v_pk_mul_f32 v[126:127], v[126:127], v[164:165] op_sel_hi:[1,0]
	v_pk_mul_f32 v[128:129], v[128:129], v[164:165] op_sel_hi:[1,0]
	v_pk_mul_f32 v[122:123], v[122:123], v[164:165] op_sel_hi:[1,0]
	v_pk_mul_f32 v[124:125], v[124:125], v[164:165] op_sel_hi:[1,0]
	s_waitcnt vmcnt(3)
	v_pk_mul_f32 v[128:129], v[132:133], v[128:129]
	v_pk_mul_f32 v[126:127], v[130:131], v[126:127]
	s_waitcnt vmcnt(1)
	v_pk_mul_f32 v[120:121], v[120:121], v[140:141]
	s_waitcnt vmcnt(0)
	v_pk_mul_f32 v[116:117], v[116:117], v[144:145]
	v_pk_mul_f32 v[114:115], v[114:115], v[142:143]
	global_store_dwordx4 v[170:171], v[114:117], off offset:3072
	v_pk_mul_f32 v[118:119], v[118:119], v[138:139]
	global_store_dwordx4 v[170:171], v[118:121], off offset:2048
	v_fmamk_f32 v114, v165, 0x3a800000, v194
	v_cmp_gt_f32_e32 vcc, s61, v114
	v_mul_f32_e32 v115, 0x4f800000, v114
	global_store_dwordx4 v[170:171], v[126:129], off
	v_cndmask_b32_e32 v114, v114, v115, vcc
	v_sqrt_f32_e32 v115, v114
	v_pk_mul_f32 v[124:125], v[124:125], v[136:137]
	v_pk_mul_f32 v[122:123], v[122:123], v[134:135]
	global_store_dwordx4 v[170:171], v[122:125], off offset:1024
	v_add_u32_e32 v116, -1, v115
	v_fma_f32 v117, -v116, v115, v114
	v_cmp_ge_f32_e64 s[2:3], 0, v117
	v_add_u32_e32 v117, 1, v115
	s_nop 0
	v_cndmask_b32_e64 v116, v115, v116, s[2:3]
	v_fma_f32 v115, -v117, v115, v114
	v_cmp_lt_f32_e64 s[2:3], 0, v115
	s_nop 1
	v_cndmask_b32_e64 v115, v116, v117, s[2:3]
	v_mul_f32_e32 v116, 0x37800000, v115
	v_cndmask_b32_e32 v115, v115, v116, vcc
	v_cmp_class_f32_e32 vcc, v114, v195
	s_nop 1
	v_cndmask_b32_e32 v114, v115, v114, vcc
	v_div_scale_f32 v115, s[2:3], v114, v114, 1.0
	v_rcp_f32_e32 v116, v115
	s_nop 0
	v_fma_f32 v117, -v115, v116, 1.0
	v_fmac_f32_e32 v116, v117, v116
	v_div_scale_f32 v117, vcc, 1.0, v114, 1.0
	v_mul_f32_e32 v118, v117, v116
	v_fma_f32 v119, -v115, v118, v117
	v_fmac_f32_e32 v118, v119, v116
	v_fma_f32 v115, -v115, v118, v117
	v_div_fmas_f32 v115, v115, v116, v118
	v_div_fixup_f32 v114, v115, v114, 1.0
	v_pk_mul_f32 v[98:99], v[98:99], v[114:115] op_sel_hi:[1,0]
	v_pk_mul_f32 v[100:101], v[100:101], v[114:115] op_sel_hi:[1,0]
	v_pk_mul_f32 v[98:99], v[98:99], v[142:143]
	v_pk_mul_f32 v[100:101], v[100:101], v[144:145]
	global_store_dwordx4 v[168:169], v[98:101], off offset:3072
	v_pk_mul_f32 v[102:103], v[102:103], v[114:115] op_sel_hi:[1,0]
	v_pk_mul_f32 v[104:105], v[104:105], v[114:115] op_sel_hi:[1,0]
	v_fmamk_f32 v98, v182, 0x3a800000, v194
	v_cmp_gt_f32_e32 vcc, s61, v98
	v_mul_f32_e32 v99, 0x4f800000, v98
	v_pk_mul_f32 v[104:105], v[104:105], v[140:141]
	v_cndmask_b32_e32 v98, v98, v99, vcc
	v_sqrt_f32_e32 v99, v98
	v_pk_mul_f32 v[102:103], v[102:103], v[138:139]
	global_store_dwordx4 v[168:169], v[102:105], off offset:2048
	v_pk_mul_f32 v[110:111], v[110:111], v[114:115] op_sel_hi:[1,0]
	v_add_u32_e32 v100, -1, v99
	v_fma_f32 v101, -v100, v99, v98
	v_cmp_ge_f32_e64 s[2:3], 0, v101
	v_add_u32_e32 v101, 1, v99
	v_pk_mul_f32 v[112:113], v[112:113], v[114:115] op_sel_hi:[1,0]
	v_cndmask_b32_e64 v100, v99, v100, s[2:3]
	v_fma_f32 v99, -v101, v99, v98
	v_cmp_lt_f32_e64 s[2:3], 0, v99
	v_pk_mul_f32 v[112:113], v[132:133], v[112:113]
	v_pk_mul_f32 v[110:111], v[130:131], v[110:111]
	v_cndmask_b32_e64 v99, v100, v101, s[2:3]
	v_mul_f32_e32 v100, 0x37800000, v99
	v_cndmask_b32_e32 v99, v99, v100, vcc
	v_cmp_class_f32_e32 vcc, v98, v195
	global_store_dwordx4 v[168:169], v[110:113], off
	v_pk_mul_f32 v[106:107], v[106:107], v[114:115] op_sel_hi:[1,0]
	v_cndmask_b32_e32 v98, v99, v98, vcc
	v_div_scale_f32 v99, s[2:3], v98, v98, 1.0
	v_rcp_f32_e32 v100, v99
	v_pk_mul_f32 v[108:109], v[108:109], v[114:115] op_sel_hi:[1,0]
	v_pk_mul_f32 v[106:107], v[134:135], v[106:107]
	v_pk_mul_f32 v[108:109], v[136:137], v[108:109]
	v_fma_f32 v101, -v99, v100, 1.0
	v_fmac_f32_e32 v100, v101, v100
	v_div_scale_f32 v101, vcc, 1.0, v98, 1.0
	v_mul_f32_e32 v102, v101, v100
	v_fma_f32 v103, -v99, v102, v101
	v_fmac_f32_e32 v102, v103, v100
	v_fma_f32 v99, -v99, v102, v101
	v_div_fmas_f32 v99, v99, v100, v102
	v_div_fixup_f32 v98, v99, v98, 1.0
	v_pk_mul_f32 v[82:83], v[82:83], v[98:99] op_sel_hi:[1,0]
	v_pk_mul_f32 v[84:85], v[84:85], v[98:99] op_sel_hi:[1,0]
	v_pk_mul_f32 v[82:83], v[82:83], v[142:143]
	v_pk_mul_f32 v[84:85], v[84:85], v[144:145]
	global_store_dwordx4 v[160:161], v[82:85], off offset:3072
	v_pk_mul_f32 v[86:87], v[86:87], v[98:99] op_sel_hi:[1,0]
	v_pk_mul_f32 v[88:89], v[88:89], v[98:99] op_sel_hi:[1,0]
	v_fmamk_f32 v82, v181, 0x3a800000, v194
	v_cmp_gt_f32_e32 vcc, s61, v82
	v_mul_f32_e32 v83, 0x4f800000, v82
	v_pk_mul_f32 v[88:89], v[140:141], v[88:89]
	v_cndmask_b32_e32 v82, v82, v83, vcc
	v_sqrt_f32_e32 v83, v82
	v_pk_mul_f32 v[86:87], v[138:139], v[86:87]
	global_store_dwordx4 v[160:161], v[86:89], off offset:2048
	v_pk_mul_f32 v[94:95], v[94:95], v[98:99] op_sel_hi:[1,0]
	v_add_u32_e32 v84, -1, v83
	v_fma_f32 v85, -v84, v83, v82
	v_cmp_ge_f32_e64 s[2:3], 0, v85
	v_add_u32_e32 v85, 1, v83
	v_pk_mul_f32 v[96:97], v[96:97], v[98:99] op_sel_hi:[1,0]
	v_cndmask_b32_e64 v84, v83, v84, s[2:3]
	v_fma_f32 v83, -v85, v83, v82
	v_cmp_lt_f32_e64 s[2:3], 0, v83
	v_pk_mul_f32 v[96:97], v[132:133], v[96:97]
	v_pk_mul_f32 v[94:95], v[130:131], v[94:95]
	v_cndmask_b32_e64 v83, v84, v85, s[2:3]
	v_mul_f32_e32 v84, 0x37800000, v83
	v_cndmask_b32_e32 v83, v83, v84, vcc
	v_cmp_class_f32_e32 vcc, v82, v195
	global_store_dwordx4 v[160:161], v[94:97], off
	v_pk_mul_f32 v[90:91], v[90:91], v[98:99] op_sel_hi:[1,0]
	v_cndmask_b32_e32 v82, v83, v82, vcc
	v_div_scale_f32 v83, s[2:3], v82, v82, 1.0
	v_rcp_f32_e32 v84, v83
	v_pk_mul_f32 v[92:93], v[92:93], v[98:99] op_sel_hi:[1,0]
	v_pk_mul_f32 v[90:91], v[134:135], v[90:91]
	v_pk_mul_f32 v[92:93], v[136:137], v[92:93]
	v_fma_f32 v85, -v83, v84, 1.0
	v_fmac_f32_e32 v84, v85, v84
	v_div_scale_f32 v85, vcc, 1.0, v82, 1.0
	v_mul_f32_e32 v86, v85, v84
	v_fma_f32 v87, -v83, v86, v85
	v_fmac_f32_e32 v86, v87, v84
	v_fma_f32 v83, -v83, v86, v85
	v_div_fmas_f32 v83, v83, v84, v86
	v_div_fixup_f32 v82, v83, v82, 1.0
	v_pk_mul_f32 v[66:67], v[66:67], v[82:83] op_sel_hi:[1,0]
	v_pk_mul_f32 v[68:69], v[68:69], v[82:83] op_sel_hi:[1,0]
	v_pk_mul_f32 v[66:67], v[142:143], v[66:67]
	v_pk_mul_f32 v[68:69], v[144:145], v[68:69]
	global_store_dwordx4 v[158:159], v[66:69], off offset:3072
	v_pk_mul_f32 v[70:71], v[70:71], v[82:83] op_sel_hi:[1,0]
	v_pk_mul_f32 v[72:73], v[72:73], v[82:83] op_sel_hi:[1,0]
	v_fmamk_f32 v66, v180, 0x3a800000, v194
	v_cmp_gt_f32_e32 vcc, s61, v66
	v_mul_f32_e32 v67, 0x4f800000, v66
	v_pk_mul_f32 v[72:73], v[140:141], v[72:73]
	v_cndmask_b32_e32 v66, v66, v67, vcc
	v_sqrt_f32_e32 v67, v66
	v_pk_mul_f32 v[70:71], v[138:139], v[70:71]
	global_store_dwordx4 v[158:159], v[70:73], off offset:2048
	v_pk_mul_f32 v[78:79], v[78:79], v[82:83] op_sel_hi:[1,0]
	v_add_u32_e32 v68, -1, v67
	v_fma_f32 v69, -v68, v67, v66
	v_cmp_ge_f32_e64 s[2:3], 0, v69
	v_add_u32_e32 v69, 1, v67
	v_pk_mul_f32 v[80:81], v[80:81], v[82:83] op_sel_hi:[1,0]
	v_cndmask_b32_e64 v68, v67, v68, s[2:3]
	v_fma_f32 v67, -v69, v67, v66
	v_cmp_lt_f32_e64 s[2:3], 0, v67
	v_pk_mul_f32 v[80:81], v[132:133], v[80:81]
	v_pk_mul_f32 v[78:79], v[130:131], v[78:79]
	v_cndmask_b32_e64 v67, v68, v69, s[2:3]
	v_mul_f32_e32 v68, 0x37800000, v67
	v_cndmask_b32_e32 v67, v67, v68, vcc
	v_cmp_class_f32_e32 vcc, v66, v195
	global_store_dwordx4 v[158:159], v[78:81], off
	v_pk_mul_f32 v[74:75], v[74:75], v[82:83] op_sel_hi:[1,0]
	v_cndmask_b32_e32 v66, v67, v66, vcc
	v_div_scale_f32 v67, s[2:3], v66, v66, 1.0
	v_rcp_f32_e32 v68, v67
	v_pk_mul_f32 v[76:77], v[76:77], v[82:83] op_sel_hi:[1,0]
	v_pk_mul_f32 v[74:75], v[134:135], v[74:75]
	v_pk_mul_f32 v[76:77], v[136:137], v[76:77]
	v_fma_f32 v69, -v67, v68, 1.0
	v_fmac_f32_e32 v68, v69, v68
	v_div_scale_f32 v69, vcc, 1.0, v66, 1.0
	v_mul_f32_e32 v70, v69, v68
	v_fma_f32 v71, -v67, v70, v69
	v_fmac_f32_e32 v70, v71, v68
	v_fma_f32 v67, -v67, v70, v69
	v_div_fmas_f32 v67, v67, v68, v70
	v_div_fixup_f32 v66, v67, v66, 1.0
	v_pk_mul_f32 v[50:51], v[50:51], v[66:67] op_sel_hi:[1,0]
	v_pk_mul_f32 v[52:53], v[52:53], v[66:67] op_sel_hi:[1,0]
	v_pk_mul_f32 v[50:51], v[142:143], v[50:51]
	v_pk_mul_f32 v[52:53], v[144:145], v[52:53]
	global_store_dwordx4 v[156:157], v[50:53], off offset:3072
	v_pk_mul_f32 v[54:55], v[54:55], v[66:67] op_sel_hi:[1,0]
	v_pk_mul_f32 v[56:57], v[56:57], v[66:67] op_sel_hi:[1,0]
	v_fmamk_f32 v50, v179, 0x3a800000, v194
	v_cmp_gt_f32_e32 vcc, s61, v50
	v_mul_f32_e32 v51, 0x4f800000, v50
	v_pk_mul_f32 v[56:57], v[140:141], v[56:57]
	v_cndmask_b32_e32 v50, v50, v51, vcc
	v_sqrt_f32_e32 v51, v50
	v_pk_mul_f32 v[54:55], v[138:139], v[54:55]
	global_store_dwordx4 v[156:157], v[54:57], off offset:2048
	v_pk_mul_f32 v[62:63], v[62:63], v[66:67] op_sel_hi:[1,0]
	v_add_u32_e32 v52, -1, v51
	v_fma_f32 v53, -v52, v51, v50
	v_cmp_ge_f32_e64 s[2:3], 0, v53
	v_add_u32_e32 v53, 1, v51
	v_pk_mul_f32 v[64:65], v[64:65], v[66:67] op_sel_hi:[1,0]
	v_cndmask_b32_e64 v52, v51, v52, s[2:3]
	v_fma_f32 v51, -v53, v51, v50
	v_cmp_lt_f32_e64 s[2:3], 0, v51
	v_pk_mul_f32 v[64:65], v[132:133], v[64:65]
	v_pk_mul_f32 v[62:63], v[130:131], v[62:63]
	v_cndmask_b32_e64 v51, v52, v53, s[2:3]
	v_mul_f32_e32 v52, 0x37800000, v51
	v_cndmask_b32_e32 v51, v51, v52, vcc
	v_cmp_class_f32_e32 vcc, v50, v195
	global_store_dwordx4 v[156:157], v[62:65], off
	v_pk_mul_f32 v[58:59], v[58:59], v[66:67] op_sel_hi:[1,0]
	v_cndmask_b32_e32 v50, v51, v50, vcc
	v_div_scale_f32 v51, s[2:3], v50, v50, 1.0
	v_rcp_f32_e32 v52, v51
	v_pk_mul_f32 v[60:61], v[60:61], v[66:67] op_sel_hi:[1,0]
	v_pk_mul_f32 v[58:59], v[134:135], v[58:59]
	v_pk_mul_f32 v[60:61], v[136:137], v[60:61]
	v_fma_f32 v53, -v51, v52, 1.0
	v_fmac_f32_e32 v52, v53, v52
	v_div_scale_f32 v53, vcc, 1.0, v50, 1.0
	v_mul_f32_e32 v54, v53, v52
	v_fma_f32 v55, -v51, v54, v53
	v_fmac_f32_e32 v54, v55, v52
	v_fma_f32 v51, -v51, v54, v53
	v_div_fmas_f32 v51, v51, v52, v54
	v_div_fixup_f32 v50, v51, v50, 1.0
	v_pk_mul_f32 v[18:19], v[18:19], v[50:51] op_sel_hi:[1,0]
	v_pk_mul_f32 v[20:21], v[20:21], v[50:51] op_sel_hi:[1,0]
	v_pk_mul_f32 v[18:19], v[142:143], v[18:19]
	v_pk_mul_f32 v[20:21], v[144:145], v[20:21]
	global_store_dwordx4 v[154:155], v[18:21], off offset:3072
	v_pk_mul_f32 v[22:23], v[22:23], v[50:51] op_sel_hi:[1,0]
	v_pk_mul_f32 v[24:25], v[24:25], v[50:51] op_sel_hi:[1,0]
	v_fmamk_f32 v18, v178, 0x3a800000, v194
	v_cmp_gt_f32_e32 vcc, s61, v18
	v_mul_f32_e32 v19, 0x4f800000, v18
	v_pk_mul_f32 v[24:25], v[140:141], v[24:25]
	v_cndmask_b32_e32 v18, v18, v19, vcc
	v_sqrt_f32_e32 v19, v18
	v_pk_mul_f32 v[22:23], v[138:139], v[22:23]
	global_store_dwordx4 v[154:155], v[22:25], off offset:2048
	v_pk_mul_f32 v[34:35], v[34:35], v[50:51] op_sel_hi:[1,0]
	v_add_u32_e32 v20, -1, v19
	v_fma_f32 v21, -v20, v19, v18
	v_cmp_ge_f32_e64 s[2:3], 0, v21
	v_add_u32_e32 v21, 1, v19
	v_pk_mul_f32 v[36:37], v[36:37], v[50:51] op_sel_hi:[1,0]
	v_cndmask_b32_e64 v20, v19, v20, s[2:3]
	v_fma_f32 v19, -v21, v19, v18
	v_cmp_lt_f32_e64 s[2:3], 0, v19
	v_pk_mul_f32 v[36:37], v[132:133], v[36:37]
	v_pk_mul_f32 v[34:35], v[130:131], v[34:35]
	v_cndmask_b32_e64 v19, v20, v21, s[2:3]
	v_mul_f32_e32 v20, 0x37800000, v19
	v_cndmask_b32_e32 v19, v19, v20, vcc
	v_cmp_class_f32_e32 vcc, v18, v195
	global_store_dwordx4 v[154:155], v[34:37], off
	v_pk_mul_f32 v[26:27], v[26:27], v[50:51] op_sel_hi:[1,0]
	v_cndmask_b32_e32 v18, v19, v18, vcc
	v_div_scale_f32 v19, s[2:3], v18, v18, 1.0
	v_rcp_f32_e32 v20, v19
	v_pk_mul_f32 v[28:29], v[28:29], v[50:51] op_sel_hi:[1,0]
	v_pk_mul_f32 v[26:27], v[134:135], v[26:27]
	v_pk_mul_f32 v[28:29], v[136:137], v[28:29]
	v_fma_f32 v21, -v19, v20, 1.0
	v_fmac_f32_e32 v20, v21, v20
	v_div_scale_f32 v21, vcc, 1.0, v18, 1.0
	v_mul_f32_e32 v22, v21, v20
	v_fma_f32 v23, -v19, v22, v21
	v_fmac_f32_e32 v22, v23, v20
	v_fma_f32 v19, -v19, v22, v21
	v_div_fmas_f32 v19, v19, v20, v22
	v_div_fixup_f32 v18, v19, v18, 1.0
	v_pk_mul_f32 v[2:3], v[2:3], v[18:19] op_sel_hi:[1,0]
	v_pk_mul_f32 v[4:5], v[4:5], v[18:19] op_sel_hi:[1,0]
	v_pk_mul_f32 v[2:3], v[142:143], v[2:3]
	v_pk_mul_f32 v[4:5], v[144:145], v[4:5]
	global_store_dwordx4 v[150:151], v[2:5], off offset:3072
	v_cmp_gt_f32_e32 vcc, s61, v0
	v_pk_mul_f32 v[6:7], v[6:7], v[18:19] op_sel_hi:[1,0]
	v_mul_f32_e32 v2, 0x4f800000, v0
	v_cndmask_b32_e32 v0, v0, v2, vcc
	v_sqrt_f32_e32 v2, v0
	v_pk_mul_f32 v[8:9], v[8:9], v[18:19] op_sel_hi:[1,0]
	v_pk_mul_f32 v[6:7], v[138:139], v[6:7]
	v_pk_mul_f32 v[8:9], v[140:141], v[8:9]
	v_add_u32_e32 v3, -1, v2
	v_fma_f32 v4, -v3, v2, v0
	v_cmp_ge_f32_e64 s[2:3], 0, v4
	v_add_u32_e32 v4, 1, v2
	global_store_dwordx4 v[150:151], v[6:9], off offset:2048
	v_cndmask_b32_e64 v3, v2, v3, s[2:3]
	v_fma_f32 v2, -v4, v2, v0
	v_cmp_lt_f32_e64 s[2:3], 0, v2
	v_pk_mul_f32 v[14:15], v[14:15], v[18:19] op_sel_hi:[1,0]
	v_pk_mul_f32 v[16:17], v[16:17], v[18:19] op_sel_hi:[1,0]
	v_cndmask_b32_e64 v2, v3, v4, s[2:3]
	v_mul_f32_e32 v3, 0x37800000, v2
	v_cndmask_b32_e32 v2, v2, v3, vcc
	v_cmp_class_f32_e32 vcc, v0, v195
	v_pk_mul_f32 v[16:17], v[132:133], v[16:17]
	v_pk_mul_f32 v[14:15], v[130:131], v[14:15]
	v_cndmask_b32_e32 v0, v2, v0, vcc
	v_div_scale_f32 v2, s[2:3], v0, v0, 1.0
	v_rcp_f32_e32 v3, v2
	global_store_dwordx4 v[150:151], v[14:17], off
	v_pk_mul_f32 v[10:11], v[10:11], v[18:19] op_sel_hi:[1,0]
	v_pk_mul_f32 v[12:13], v[12:13], v[18:19] op_sel_hi:[1,0]
	v_fma_f32 v4, -v2, v3, 1.0
	v_fmac_f32_e32 v3, v4, v3
	v_div_scale_f32 v4, vcc, 1.0, v0, 1.0
	v_mul_f32_e32 v5, v4, v3
	v_fma_f32 v6, -v2, v5, v4
	v_fmac_f32_e32 v5, v6, v3
	v_fma_f32 v2, -v2, v5, v4
	v_div_fmas_f32 v2, v2, v3, v5
	v_div_fixup_f32 v0, v2, v0, 1.0
	v_pk_mul_f32 v[2:3], v[46:47], v[0:1] op_sel_hi:[1,0]
	v_pk_mul_f32 v[4:5], v[48:49], v[0:1] op_sel_hi:[1,0]
	v_pk_mul_f32 v[2:3], v[130:131], v[2:3]
	v_pk_mul_f32 v[4:5], v[132:133], v[4:5]
	global_store_dwordx4 v[152:153], v[2:5], off
	v_pk_mul_f32 v[12:13], v[136:137], v[12:13]
	v_pk_mul_f32 v[10:11], v[134:135], v[10:11]
	v_pk_mul_f32 v[2:3], v[42:43], v[0:1] op_sel_hi:[1,0]
	v_pk_mul_f32 v[4:5], v[44:45], v[0:1] op_sel_hi:[1,0]
	v_pk_mul_f32 v[2:3], v[134:135], v[2:3]
	v_pk_mul_f32 v[4:5], v[136:137], v[4:5]
	global_store_dwordx4 v[168:169], v[106:109], off offset:1024
	global_store_dwordx4 v[160:161], v[90:93], off offset:1024
	global_store_dwordx4 v[158:159], v[74:77], off offset:1024
	global_store_dwordx4 v[156:157], v[58:61], off offset:1024
	global_store_dwordx4 v[154:155], v[26:29], off offset:1024
	global_store_dwordx4 v[150:151], v[10:13], off offset:1024
	global_store_dwordx4 v[152:153], v[2:5], off offset:1024
	s_add_i32 s2, s4, s97
	s_cmp_lt_i32 s2, 0x10000
	v_pk_mul_f32 v[2:3], v[38:39], v[0:1] op_sel_hi:[1,0]
	v_pk_mul_f32 v[4:5], v[40:41], v[0:1] op_sel_hi:[1,0]
	v_pk_mul_f32 v[2:3], v[138:139], v[2:3]
	v_pk_mul_f32 v[4:5], v[140:141], v[4:5]
	global_store_dwordx4 v[152:153], v[2:5], off offset:2048
	s_nop 1
	v_pk_mul_f32 v[2:3], v[30:31], v[0:1] op_sel_hi:[1,0]
	v_pk_mul_f32 v[4:5], v[32:33], v[0:1] op_sel_hi:[1,0]
	v_pk_mul_f32 v[2:3], v[142:143], v[2:3]
	v_pk_mul_f32 v[4:5], v[144:145], v[4:5]
	global_store_dwordx4 v[152:153], v[2:5], off offset:3072
	s_cbranch_scc1 .LBB0_951

.LBB0_956:
	s_ashr_i32 s9, s8, 31
	s_lshl_b64 s[0:1], s[8:9], 12
	v_lshl_add_u64 v[2:3], v[146:147], 0, s[0:1]
	global_load_dwordx4 v[126:129], v[2:3], off
	global_load_dwordx4 v[122:125], v[2:3], off offset:1024
	global_load_dwordx4 v[118:121], v[2:3], off offset:2048
	global_load_dwordx4 v[114:117], v[2:3], off offset:3072
	s_add_i32 s16, s8, s97
	s_ashr_i32 s17, s16, 31
	s_lshl_b64 s[0:1], s[16:17], 12
	v_lshl_add_u64 v[2:3], v[146:147], 0, s[0:1]
	global_load_dwordx4 v[110:113], v[2:3], off
	global_load_dwordx4 v[106:109], v[2:3], off offset:1024
	global_load_dwordx4 v[102:105], v[2:3], off offset:2048
	global_load_dwordx4 v[98:101], v[2:3], off offset:3072
	s_add_i32 s14, s88, s8
	s_ashr_i32 s15, s14, 31
	s_lshl_b64 s[0:1], s[14:15], 12
	v_lshl_add_u64 v[2:3], v[146:147], 0, s[0:1]
	global_load_dwordx4 v[94:97], v[2:3], off
	global_load_dwordx4 v[90:93], v[2:3], off offset:1024
	global_load_dwordx4 v[86:89], v[2:3], off offset:2048
	global_load_dwordx4 v[82:85], v[2:3], off offset:3072
	s_add_i32 s12, s75, s8
	s_ashr_i32 s13, s12, 31
	s_lshl_b64 s[0:1], s[12:13], 12
	v_lshl_add_u64 v[2:3], v[146:147], 0, s[0:1]
	global_load_dwordx4 v[78:81], v[2:3], off
	global_load_dwordx4 v[74:77], v[2:3], off offset:1024
	global_load_dwordx4 v[70:73], v[2:3], off offset:2048
	global_load_dwordx4 v[66:69], v[2:3], off offset:3072
	s_add_i32 s10, s89, s8
	s_ashr_i32 s11, s10, 31
	s_lshl_b64 s[0:1], s[10:11], 12
	v_lshl_add_u64 v[2:3], v[146:147], 0, s[0:1]
	global_load_dwordx4 v[62:65], v[2:3], off
	global_load_dwordx4 v[58:61], v[2:3], off offset:1024
	global_load_dwordx4 v[54:57], v[2:3], off offset:2048
	global_load_dwordx4 v[50:53], v[2:3], off offset:3072
	s_add_i32 s6, s77, s8
	s_ashr_i32 s7, s6, 31
	s_lshl_b64 s[0:1], s[6:7], 12
	v_lshl_add_u64 v[2:3], v[146:147], 0, s[0:1]
	global_load_dwordx4 v[46:49], v[2:3], off
	global_load_dwordx4 v[42:45], v[2:3], off offset:1024
	global_load_dwordx4 v[34:37], v[2:3], off offset:2048
	global_load_dwordx4 v[26:29], v[2:3], off offset:3072
	s_add_i32 s4, s78, s8
	s_ashr_i32 s5, s4, 31
	s_lshl_b64 s[0:1], s[4:5], 12
	v_lshl_add_u64 v[2:3], v[146:147], 0, s[0:1]
	global_load_dwordx4 v[14:17], v[2:3], off
	global_load_dwordx4 v[10:13], v[2:3], off offset:1024
	global_load_dwordx4 v[6:9], v[2:3], off offset:2048
	s_nop 0
	global_load_dwordx4 v[2:5], v[2:3], off offset:3072
	s_add_i32 s2, s16, s97
	s_add_i32 s2, s2, s97
	s_add_i32 s2, s2, s97
	s_add_i32 s2, s2, s97
	s_add_i32 s18, s2, s97
	s_add_i32 s2, s79, s8
	s_ashr_i32 s3, s2, 31
	s_lshl_b64 s[0:1], s[2:3], 12
	v_lshl_add_u64 v[18:19], v[146:147], 0, s[0:1]
	global_load_dwordx4 v[38:41], v[18:19], off
	global_load_dwordx4 v[30:33], v[18:19], off offset:1024
	global_load_dwordx4 v[22:25], v[18:19], off offset:2048
	s_nop 0
	global_load_dwordx4 v[18:21], v[18:19], off offset:3072
	s_add_i32 s18, s18, s97
	s_waitcnt vmcnt(31)
	v_mul_f32_e32 v0, v127, v127
	v_mul_f32_e32 v130, v129, v129
	v_fmac_f32_e32 v0, v126, v126
	v_fmac_f32_e32 v130, v128, v128
	v_add_f32_e32 v0, v0, v130
	s_waitcnt vmcnt(30)
	v_mul_f32_e32 v130, v123, v123
	v_mul_f32_e32 v131, v125, v125
	v_fmac_f32_e32 v130, v122, v122
	v_fmac_f32_e32 v131, v124, v124
	v_add_f32_e32 v130, v130, v131
	v_add_f32_e32 v0, v0, v130
	s_waitcnt vmcnt(29)
	v_mul_f32_e32 v130, v119, v119
	v_mul_f32_e32 v131, v121, v121
	v_fmac_f32_e32 v130, v118, v118
	v_fmac_f32_e32 v131, v120, v120
	v_add_f32_e32 v130, v130, v131
	v_add_f32_e32 v0, v0, v130
	s_waitcnt vmcnt(28)
	v_mul_f32_e32 v130, v115, v115
	v_mul_f32_e32 v131, v117, v117
	v_fmac_f32_e32 v130, v114, v114
	v_fmac_f32_e32 v131, v116, v116
	v_add_f32_e32 v130, v130, v131
	v_add_f32_e32 v0, v0, v130
	s_waitcnt vmcnt(27)
	v_mul_f32_e32 v130, v111, v111
	v_mul_f32_e32 v131, v113, v113
	v_fmac_f32_e32 v130, v110, v110
	v_fmac_f32_e32 v131, v112, v112
	v_add_f32_e32 v130, v130, v131
	s_waitcnt vmcnt(26)
	v_mul_f32_e32 v131, v107, v107
	v_mul_f32_e32 v132, v109, v109
	v_fmac_f32_e32 v131, v106, v106
	v_fmac_f32_e32 v132, v108, v108
	v_add_f32_e32 v131, v131, v132
	v_add_f32_e32 v130, v130, v131
	s_waitcnt vmcnt(25)
	v_mul_f32_e32 v131, v103, v103
	v_mul_f32_e32 v132, v105, v105
	v_fmac_f32_e32 v131, v102, v102
	v_fmac_f32_e32 v132, v104, v104
	v_add_f32_e32 v131, v131, v132
	v_add_f32_e32 v130, v130, v131
	s_waitcnt vmcnt(24)
	v_mul_f32_e32 v131, v99, v99
	v_mul_f32_e32 v132, v101, v101
	v_fmac_f32_e32 v131, v98, v98
	v_fmac_f32_e32 v132, v100, v100
	v_add_f32_e32 v131, v131, v132
	v_add_f32_e32 v130, v130, v131
	s_waitcnt vmcnt(23)
	v_mul_f32_e32 v131, v95, v95
	v_mul_f32_e32 v132, v97, v97
	v_fmac_f32_e32 v131, v94, v94
	v_fmac_f32_e32 v132, v96, v96
	v_add_f32_e32 v131, v131, v132
	s_waitcnt vmcnt(22)
	v_mul_f32_e32 v132, v91, v91
	v_mul_f32_e32 v133, v93, v93
	v_fmac_f32_e32 v132, v90, v90
	v_fmac_f32_e32 v133, v92, v92
	v_add_f32_e32 v132, v132, v133
	v_add_f32_e32 v131, v131, v132
	s_waitcnt vmcnt(21)
	v_mul_f32_e32 v132, v87, v87
	v_mul_f32_e32 v133, v89, v89
	v_fmac_f32_e32 v132, v86, v86
	v_fmac_f32_e32 v133, v88, v88
	v_add_f32_e32 v132, v132, v133
	v_add_f32_e32 v131, v131, v132
	s_waitcnt vmcnt(20)
	v_mul_f32_e32 v132, v83, v83
	v_mul_f32_e32 v133, v85, v85
	v_fmac_f32_e32 v132, v82, v82
	v_fmac_f32_e32 v133, v84, v84
	v_add_f32_e32 v132, v132, v133
	v_add_f32_e32 v131, v131, v132
	s_waitcnt vmcnt(19)
	v_mul_f32_e32 v132, v79, v79
	v_mul_f32_e32 v133, v81, v81
	v_fmac_f32_e32 v132, v78, v78
	v_fmac_f32_e32 v133, v80, v80
	v_add_f32_e32 v132, v132, v133
	s_waitcnt vmcnt(18)
	v_mul_f32_e32 v133, v75, v75
	v_mul_f32_e32 v134, v77, v77
	v_fmac_f32_e32 v133, v74, v74
	v_fmac_f32_e32 v134, v76, v76
	v_add_f32_e32 v133, v133, v134
	v_add_f32_e32 v132, v132, v133
	s_waitcnt vmcnt(17)
	v_mul_f32_e32 v133, v71, v71
	v_mul_f32_e32 v134, v73, v73
	v_fmac_f32_e32 v133, v70, v70
	v_fmac_f32_e32 v134, v72, v72
	v_add_f32_e32 v133, v133, v134
	v_add_f32_e32 v132, v132, v133
	s_waitcnt vmcnt(16)
	v_mul_f32_e32 v133, v67, v67
	v_mul_f32_e32 v134, v69, v69
	v_fmac_f32_e32 v133, v66, v66
	v_fmac_f32_e32 v134, v68, v68
	v_add_f32_e32 v133, v133, v134
	v_add_f32_e32 v132, v132, v133
	s_waitcnt vmcnt(15)
	v_mul_f32_e32 v133, v63, v63
	v_mul_f32_e32 v134, v65, v65
	v_fmac_f32_e32 v133, v62, v62
	v_fmac_f32_e32 v134, v64, v64
	v_add_f32_e32 v133, v133, v134
	s_waitcnt vmcnt(14)
	v_mul_f32_e32 v134, v59, v59
	v_mul_f32_e32 v135, v61, v61
	v_fmac_f32_e32 v134, v58, v58
	v_fmac_f32_e32 v135, v60, v60
	v_add_f32_e32 v134, v134, v135
	v_add_f32_e32 v133, v133, v134
	s_waitcnt vmcnt(13)
	v_mul_f32_e32 v134, v55, v55
	v_mul_f32_e32 v135, v57, v57
	v_fmac_f32_e32 v134, v54, v54
	v_fmac_f32_e32 v135, v56, v56
	v_add_f32_e32 v134, v134, v135
	v_add_f32_e32 v133, v133, v134
	s_waitcnt vmcnt(12)
	v_mul_f32_e32 v134, v51, v51
	v_mul_f32_e32 v135, v53, v53
	v_fmac_f32_e32 v134, v50, v50
	v_fmac_f32_e32 v135, v52, v52
	v_add_f32_e32 v134, v134, v135
	v_add_f32_e32 v133, v133, v134
	s_waitcnt vmcnt(11)
	v_mul_f32_e32 v134, v47, v47
	v_mul_f32_e32 v135, v49, v49
	v_fmac_f32_e32 v134, v46, v46
	v_fmac_f32_e32 v135, v48, v48
	v_add_f32_e32 v134, v134, v135
	s_waitcnt vmcnt(10)
	v_mul_f32_e32 v135, v43, v43
	v_mul_f32_e32 v136, v45, v45
	v_fmac_f32_e32 v135, v42, v42
	v_fmac_f32_e32 v136, v44, v44
	v_add_f32_e32 v135, v135, v136
	v_add_f32_e32 v134, v134, v135
	s_waitcnt vmcnt(9)
	v_mul_f32_e32 v135, v35, v35
	v_mul_f32_e32 v136, v37, v37
	v_fmac_f32_e32 v135, v34, v34
	v_fmac_f32_e32 v136, v36, v36
	v_add_f32_e32 v135, v135, v136
	v_add_f32_e32 v134, v134, v135
	s_waitcnt vmcnt(8)
	v_mul_f32_e32 v135, v27, v27
	v_mul_f32_e32 v136, v29, v29
	v_fmac_f32_e32 v135, v26, v26
	v_fmac_f32_e32 v136, v28, v28
	v_add_f32_e32 v135, v135, v136
	v_add_f32_e32 v134, v134, v135
	s_waitcnt vmcnt(7)
	v_mul_f32_e32 v135, v15, v15
	v_mul_f32_e32 v136, v17, v17
	v_fmac_f32_e32 v135, v14, v14
	v_fmac_f32_e32 v136, v16, v16
	v_add_f32_e32 v135, v135, v136
	s_waitcnt vmcnt(6)
	v_mul_f32_e32 v136, v11, v11
	v_mul_f32_e32 v137, v13, v13
	v_fmac_f32_e32 v136, v10, v10
	v_fmac_f32_e32 v137, v12, v12
	v_add_f32_e32 v136, v136, v137
	v_add_f32_e32 v135, v135, v136
	s_waitcnt vmcnt(5)
	v_mul_f32_e32 v136, v7, v7
	v_mul_f32_e32 v137, v9, v9
	v_fmac_f32_e32 v136, v6, v6
	v_fmac_f32_e32 v137, v8, v8
	v_add_f32_e32 v136, v136, v137
	v_add_f32_e32 v135, v135, v136
	s_waitcnt vmcnt(4)
	v_mul_f32_e32 v136, v3, v3
	v_mul_f32_e32 v137, v5, v5
	v_fmac_f32_e32 v136, v2, v2
	v_fmac_f32_e32 v137, v4, v4
	v_add_f32_e32 v136, v136, v137
	v_add_f32_e32 v135, v135, v136
	s_waitcnt vmcnt(3)
	v_mul_f32_e32 v136, v39, v39
	v_mul_f32_e32 v137, v41, v41
	v_fmac_f32_e32 v136, v38, v38
	v_fmac_f32_e32 v137, v40, v40
	v_add_f32_e32 v136, v136, v137
	s_waitcnt vmcnt(2)
	v_mul_f32_e32 v137, v31, v31
	v_mul_f32_e32 v138, v33, v33
	v_fmac_f32_e32 v137, v30, v30
	v_fmac_f32_e32 v138, v32, v32
	v_add_f32_e32 v137, v137, v138
	v_add_f32_e32 v136, v136, v137
	s_waitcnt vmcnt(1)
	v_mul_f32_e32 v137, v23, v23
	v_mul_f32_e32 v138, v25, v25
	v_fmac_f32_e32 v137, v22, v22
	v_fmac_f32_e32 v138, v24, v24
	v_add_f32_e32 v137, v137, v138
	v_add_f32_e32 v136, v136, v137
	s_waitcnt vmcnt(0)
	v_mul_f32_e32 v137, v19, v19
	v_mul_f32_e32 v138, v21, v21
	v_fmac_f32_e32 v137, v18, v18
	v_fmac_f32_e32 v138, v20, v20
	v_add_f32_e32 v137, v137, v138
	v_add_f32_e32 v136, v136, v137
	ds_bpermute_b32 v137, v152, v0
	ds_bpermute_b32 v200, v152, v130
	ds_bpermute_b32 v201, v152, v131
	ds_bpermute_b32 v202, v152, v132
	ds_bpermute_b32 v196, v152, v133
	ds_bpermute_b32 v162, v152, v134
	ds_bpermute_b32 v250, v152, v135
	ds_bpermute_b32 v251, v152, v136
	s_waitcnt lgkmcnt(0)
	v_add_f32_e32 v0, v0, v137
	v_add_f32_e32 v130, v130, v200
	v_add_f32_e32 v131, v131, v201
	v_add_f32_e32 v132, v132, v202
	v_add_f32_e32 v133, v133, v196
	v_add_f32_e32 v134, v134, v162
	v_add_f32_e32 v135, v135, v250
	v_add_f32_e32 v136, v136, v251
	ds_bpermute_b32 v137, v153, v0
	ds_bpermute_b32 v200, v153, v130
	ds_bpermute_b32 v201, v153, v131
	ds_bpermute_b32 v202, v153, v132
	ds_bpermute_b32 v196, v153, v133
	ds_bpermute_b32 v162, v153, v134
	ds_bpermute_b32 v250, v153, v135
	ds_bpermute_b32 v251, v153, v136
	s_waitcnt lgkmcnt(0)
	v_add_f32_e32 v0, v0, v137
	v_add_f32_e32 v130, v130, v200
	v_add_f32_e32 v131, v131, v201
	v_add_f32_e32 v132, v132, v202
	v_add_f32_e32 v133, v133, v196
	v_add_f32_e32 v134, v134, v162
	v_add_f32_e32 v135, v135, v250
	v_add_f32_e32 v136, v136, v251
	ds_bpermute_b32 v137, v154, v0
	ds_bpermute_b32 v200, v154, v130
	ds_bpermute_b32 v201, v154, v131
	ds_bpermute_b32 v202, v154, v132
	ds_bpermute_b32 v196, v154, v133
	ds_bpermute_b32 v162, v154, v134
	ds_bpermute_b32 v250, v154, v135
	ds_bpermute_b32 v251, v154, v136
	s_waitcnt lgkmcnt(0)
	v_add_f32_e32 v0, v0, v137
	v_add_f32_e32 v130, v130, v200
	v_add_f32_e32 v131, v131, v201
	v_add_f32_e32 v132, v132, v202
	v_add_f32_e32 v133, v133, v196
	v_add_f32_e32 v134, v134, v162
	v_add_f32_e32 v135, v135, v250
	v_add_f32_e32 v136, v136, v251
	ds_bpermute_b32 v137, v155, v0
	ds_bpermute_b32 v200, v155, v130
	ds_bpermute_b32 v201, v155, v131
	ds_bpermute_b32 v202, v155, v132
	ds_bpermute_b32 v196, v155, v133
	ds_bpermute_b32 v162, v155, v134
	ds_bpermute_b32 v250, v155, v135
	ds_bpermute_b32 v251, v155, v136
	s_waitcnt lgkmcnt(0)
	v_add_f32_e32 v0, v0, v137
	v_add_f32_e32 v130, v130, v200
	v_add_f32_e32 v131, v131, v201
	v_add_f32_e32 v132, v132, v202
	v_add_f32_e32 v133, v133, v196
	v_add_f32_e32 v134, v134, v162
	v_add_f32_e32 v135, v135, v250
	v_add_f32_e32 v136, v136, v251
	ds_bpermute_b32 v137, v156, v0
	ds_bpermute_b32 v200, v156, v130
	ds_bpermute_b32 v201, v156, v131
	ds_bpermute_b32 v202, v156, v132
	ds_bpermute_b32 v196, v156, v133
	ds_bpermute_b32 v162, v156, v134
	ds_bpermute_b32 v250, v156, v135
	ds_bpermute_b32 v251, v156, v136
	s_waitcnt lgkmcnt(0)
	v_add_f32_e32 v0, v0, v137
	v_add_f32_e32 v130, v130, v200
	v_add_f32_e32 v131, v131, v201
	v_add_f32_e32 v132, v132, v202
	v_add_f32_e32 v133, v133, v196
	v_add_f32_e32 v134, v134, v162
	v_add_f32_e32 v135, v135, v250
	v_add_f32_e32 v136, v136, v251
	ds_bpermute_b32 v137, v157, v0
	s_waitcnt lgkmcnt(0)
	v_add_f32_e32 v164, v0, v137
	ds_bpermute_b32 v0, v157, v130
	v_fmamk_f32 v164, v164, 0x3a800000, v194
	v_cmp_gt_f32_e32 vcc, s61, v164
	v_mul_f32_e32 v165, 0x4f800000, v164
	s_waitcnt lgkmcnt(0)
	v_add_f32_e32 v166, v130, v0
	ds_bpermute_b32 v0, v157, v131
	v_cndmask_b32_e32 v164, v164, v165, vcc
	v_sqrt_f32_e32 v165, v164
	s_waitcnt lgkmcnt(0)
	v_add_f32_e32 v163, v131, v0
	ds_bpermute_b32 v0, v157, v132
	v_add_u32_e32 v167, -1, v165
	v_fma_f32 v168, -v167, v165, v164
	v_cmp_ge_f32_e64 s[0:1], 0, v168
	v_add_u32_e32 v168, 1, v165
	s_waitcnt lgkmcnt(0)
	v_add_f32_e32 v161, v132, v0
	ds_bpermute_b32 v0, v157, v133
	v_cndmask_b32_e64 v167, v165, v167, s[0:1]
	v_fma_f32 v165, -v168, v165, v164
	v_cmp_lt_f32_e64 s[0:1], 0, v165
	s_waitcnt lgkmcnt(0)
	v_add_f32_e32 v160, v133, v0
	ds_bpermute_b32 v0, v157, v134
	v_cndmask_b32_e64 v165, v167, v168, s[0:1]
	v_mul_f32_e32 v167, 0x37800000, v165
	v_cndmask_b32_e32 v165, v165, v167, vcc
	v_cmp_class_f32_e32 vcc, v164, v195
	s_waitcnt lgkmcnt(0)
	v_add_f32_e32 v159, v134, v0
	ds_bpermute_b32 v0, v157, v135
	v_cndmask_b32_e32 v164, v165, v164, vcc
	v_div_scale_f32 v165, s[0:1], v164, v164, 1.0
	v_rcp_f32_e32 v167, v165
	s_waitcnt lgkmcnt(0)
	v_add_f32_e32 v158, v135, v0
	ds_bpermute_b32 v0, v157, v136
	s_lshl_b64 s[0:1], s[8:9], 11
	v_fma_f32 v168, -v165, v167, 1.0
	v_fmac_f32_e32 v167, v168, v167
	v_div_scale_f32 v168, vcc, 1.0, v164, 1.0
	s_waitcnt lgkmcnt(0)
	v_add_f32_e32 v0, v136, v0
	global_load_dwordx4 v[130:133], v[148:149], off
	global_load_dwordx4 v[134:137], v[148:149], off offset:1024
	global_load_dwordx4 v[138:141], v[148:149], off offset:2048
	global_load_dwordx4 v[142:145], v[148:149], off offset:3072
	v_mul_f32_e32 v169, v168, v167
	v_fma_f32 v170, -v165, v169, v168
	v_fmac_f32_e32 v169, v170, v167
	v_fma_f32 v165, -v165, v169, v168
	v_div_fmas_f32 v165, v165, v167, v169
	v_div_fixup_f32 v167, v165, v164, 1.0
	v_mul_f32_e32 v114, v114, v167
	v_mul_f32_e32 v115, v115, v167
	v_lshl_add_u64 v[164:165], v[150:151], 0, s[0:1]
	v_mul_f32_e32 v118, v118, v167
	v_mul_f32_e32 v119, v119, v167
	v_fmamk_f32 v0, v0, 0x3a800000, v194
	v_mul_f32_e32 v126, v126, v167
	v_mul_f32_e32 v127, v127, v167
	v_mul_f32_e32 v122, v122, v167
	v_mul_f32_e32 v123, v123, v167
	s_add_i32 s8, s18, s97
	s_waitcnt vmcnt(3)
	v_mul_f32_e32 v126, v126, v130
	v_mul_f32_e32 v127, v127, v131
	s_waitcnt vmcnt(1)
	v_mul_f32_e32 v118, v118, v138
	s_waitcnt vmcnt(0)
	v_mul_f32_e32 v114, v114, v142
	v_mul_f32_e32 v115, v115, v143
	v_cvt_pk_bf16_f32 v114, v114, v115
	v_mul_f32_e32 v115, v116, v167
	v_mul_f32_e32 v115, v115, v144
	v_mul_f32_e32 v116, v117, v167
	v_mul_f32_e32 v116, v116, v145
	v_cvt_pk_bf16_f32 v115, v115, v116
	global_store_dwordx2 v[164:165], v[114:115], off offset:1536
	v_fmamk_f32 v114, v166, 0x3a800000, v194
	v_cmp_gt_f32_e32 vcc, s61, v114
	v_mul_f32_e32 v115, 0x4f800000, v114
	v_mul_f32_e32 v119, v119, v139
	v_cndmask_b32_e32 v114, v114, v115, vcc
	v_sqrt_f32_e32 v115, v114
	v_cvt_pk_bf16_f32 v118, v118, v119
	v_mul_f32_e32 v119, v120, v167
	v_mul_f32_e32 v119, v119, v140
	v_add_u32_e32 v116, -1, v115
	v_fma_f32 v117, -v116, v115, v114
	v_cmp_ge_f32_e64 s[0:1], 0, v117
	v_add_u32_e32 v117, 1, v115
	v_mul_f32_e32 v120, v121, v167
	v_cndmask_b32_e64 v116, v115, v116, s[0:1]
	v_fma_f32 v115, -v117, v115, v114
	v_cmp_lt_f32_e64 s[0:1], 0, v115
	v_mul_f32_e32 v120, v120, v141
	v_cvt_pk_bf16_f32 v119, v119, v120
	global_store_dwordx2 v[164:165], v[118:119], off offset:1024
	v_cndmask_b32_e64 v115, v116, v117, s[0:1]
	v_mul_f32_e32 v116, 0x37800000, v115
	v_cndmask_b32_e32 v115, v115, v116, vcc
	v_cmp_class_f32_e32 vcc, v114, v195
	v_cvt_pk_bf16_f32 v126, v126, v127
	v_mul_f32_e32 v127, v128, v167
	v_mul_f32_e32 v127, v127, v132
	v_cndmask_b32_e32 v114, v115, v114, vcc
	v_div_scale_f32 v115, s[0:1], v114, v114, 1.0
	v_rcp_f32_e32 v116, v115
	s_lshl_b64 s[0:1], s[16:17], 11
	v_mul_f32_e32 v128, v129, v167
	v_mul_f32_e32 v128, v128, v133
	v_fma_f32 v117, -v115, v116, 1.0
	v_fmac_f32_e32 v116, v117, v116
	v_div_scale_f32 v117, vcc, 1.0, v114, 1.0
	v_mul_f32_e32 v118, v117, v116
	v_fma_f32 v119, -v115, v118, v117
	v_fmac_f32_e32 v118, v119, v116
	v_fma_f32 v115, -v115, v118, v117
	v_div_fmas_f32 v115, v115, v116, v118
	v_div_fixup_f32 v116, v115, v114, 1.0
	v_mul_f32_e32 v98, v98, v116
	v_mul_f32_e32 v99, v99, v116
	v_mul_f32_e32 v98, v98, v142
	v_mul_f32_e32 v99, v99, v143
	v_cvt_pk_bf16_f32 v98, v98, v99
	v_mul_f32_e32 v99, v100, v116
	v_lshl_add_u64 v[114:115], v[150:151], 0, s[0:1]
	v_mul_f32_e32 v99, v99, v144
	v_mul_f32_e32 v100, v101, v116
	v_mul_f32_e32 v100, v100, v145
	v_cvt_pk_bf16_f32 v99, v99, v100
	global_store_dwordx2 v[114:115], v[98:99], off offset:1536
	v_fmamk_f32 v98, v163, 0x3a800000, v194
	v_cmp_gt_f32_e32 vcc, s61, v98
	v_mul_f32_e32 v99, 0x4f800000, v98
	v_mul_f32_e32 v102, v102, v116
	v_cndmask_b32_e32 v98, v98, v99, vcc
	v_sqrt_f32_e32 v99, v98
	v_mul_f32_e32 v103, v103, v116
	v_mul_f32_e32 v102, v102, v138
	v_mul_f32_e32 v103, v103, v139
	v_add_u32_e32 v100, -1, v99
	v_fma_f32 v101, -v100, v99, v98
	v_cmp_ge_f32_e64 s[0:1], 0, v101
	v_add_u32_e32 v101, 1, v99
	v_cvt_pk_bf16_f32 v102, v102, v103
	v_mul_f32_e32 v103, v104, v116
	v_cndmask_b32_e64 v100, v99, v100, s[0:1]
	v_fma_f32 v99, -v101, v99, v98
	v_cmp_lt_f32_e64 s[0:1], 0, v99
	v_mul_f32_e32 v103, v103, v140
	v_mul_f32_e32 v104, v105, v116
	v_cndmask_b32_e64 v99, v100, v101, s[0:1]
	v_mul_f32_e32 v100, 0x37800000, v99
	v_cndmask_b32_e32 v99, v99, v100, vcc
	v_cmp_class_f32_e32 vcc, v98, v195
	v_mul_f32_e32 v104, v104, v141
	v_cvt_pk_bf16_f32 v103, v103, v104
	global_store_dwordx2 v[114:115], v[102:103], off offset:1024
	v_cndmask_b32_e32 v98, v99, v98, vcc
	v_div_scale_f32 v99, s[0:1], v98, v98, 1.0
	v_rcp_f32_e32 v100, v99
	s_lshl_b64 s[0:1], s[14:15], 11
	v_mul_f32_e32 v110, v110, v116
	v_mul_f32_e32 v111, v111, v116
	v_fma_f32 v101, -v99, v100, 1.0
	v_fmac_f32_e32 v100, v101, v100
	v_div_scale_f32 v101, vcc, 1.0, v98, 1.0
	v_mul_f32_e32 v102, v101, v100
	v_fma_f32 v103, -v99, v102, v101
	v_fmac_f32_e32 v102, v103, v100
	v_fma_f32 v99, -v99, v102, v101
	v_div_fmas_f32 v99, v99, v100, v102
	v_div_fixup_f32 v100, v99, v98, 1.0
	v_mul_f32_e32 v82, v82, v100
	v_mul_f32_e32 v83, v83, v100
	v_mul_f32_e32 v82, v82, v142
	v_mul_f32_e32 v83, v83, v143
	v_cvt_pk_bf16_f32 v82, v82, v83
	v_mul_f32_e32 v83, v84, v100
	v_lshl_add_u64 v[98:99], v[150:151], 0, s[0:1]
	v_mul_f32_e32 v83, v83, v144
	v_mul_f32_e32 v84, v85, v100
	v_mul_f32_e32 v84, v84, v145
	v_cvt_pk_bf16_f32 v83, v83, v84
	global_store_dwordx2 v[98:99], v[82:83], off offset:1536
	v_fmamk_f32 v82, v161, 0x3a800000, v194
	v_cmp_gt_f32_e32 vcc, s61, v82
	v_mul_f32_e32 v83, 0x4f800000, v82
	v_mul_f32_e32 v86, v86, v100
	v_cndmask_b32_e32 v82, v82, v83, vcc
	v_sqrt_f32_e32 v83, v82
	v_mul_f32_e32 v87, v87, v100
	v_mul_f32_e32 v86, v86, v138
	v_mul_f32_e32 v87, v87, v139
	v_add_u32_e32 v84, -1, v83
	v_fma_f32 v85, -v84, v83, v82
	v_cmp_ge_f32_e64 s[0:1], 0, v85
	v_add_u32_e32 v85, 1, v83
	v_cvt_pk_bf16_f32 v86, v86, v87
	v_mul_f32_e32 v87, v88, v100
	v_cndmask_b32_e64 v84, v83, v84, s[0:1]
	v_fma_f32 v83, -v85, v83, v82
	v_cmp_lt_f32_e64 s[0:1], 0, v83
	v_mul_f32_e32 v87, v87, v140
	v_mul_f32_e32 v88, v89, v100
	v_cndmask_b32_e64 v83, v84, v85, s[0:1]
	v_mul_f32_e32 v84, 0x37800000, v83
	v_cndmask_b32_e32 v83, v83, v84, vcc
	v_cmp_class_f32_e32 vcc, v82, v195
	v_mul_f32_e32 v88, v88, v141
	v_cvt_pk_bf16_f32 v87, v87, v88
	global_store_dwordx2 v[98:99], v[86:87], off offset:1024
	v_cndmask_b32_e32 v82, v83, v82, vcc
	v_div_scale_f32 v83, s[0:1], v82, v82, 1.0
	v_rcp_f32_e32 v84, v83
	s_lshl_b64 s[0:1], s[12:13], 11
	v_mul_f32_e32 v94, v94, v100
	v_mul_f32_e32 v95, v95, v100
	v_fma_f32 v85, -v83, v84, 1.0
	v_fmac_f32_e32 v84, v85, v84
	v_div_scale_f32 v85, vcc, 1.0, v82, 1.0
	v_mul_f32_e32 v86, v85, v84
	v_fma_f32 v87, -v83, v86, v85
	v_fmac_f32_e32 v86, v87, v84
	v_fma_f32 v83, -v83, v86, v85
	v_div_fmas_f32 v83, v83, v84, v86
	v_div_fixup_f32 v84, v83, v82, 1.0
	v_mul_f32_e32 v66, v66, v84
	v_mul_f32_e32 v67, v67, v84
	v_mul_f32_e32 v66, v66, v142
	v_mul_f32_e32 v67, v67, v143
	v_cvt_pk_bf16_f32 v66, v66, v67
	v_mul_f32_e32 v67, v68, v84
	v_lshl_add_u64 v[82:83], v[150:151], 0, s[0:1]
	v_mul_f32_e32 v67, v67, v144
	v_mul_f32_e32 v68, v69, v84
	v_mul_f32_e32 v68, v68, v145
	v_cvt_pk_bf16_f32 v67, v67, v68
	global_store_dwordx2 v[82:83], v[66:67], off offset:1536
	v_fmamk_f32 v66, v160, 0x3a800000, v194
	v_cmp_gt_f32_e32 vcc, s61, v66
	v_mul_f32_e32 v67, 0x4f800000, v66
	v_mul_f32_e32 v70, v70, v84
	v_cndmask_b32_e32 v66, v66, v67, vcc
	v_sqrt_f32_e32 v67, v66
	v_mul_f32_e32 v71, v71, v84
	v_mul_f32_e32 v70, v70, v138
	v_mul_f32_e32 v71, v71, v139
	v_add_u32_e32 v68, -1, v67
	v_fma_f32 v69, -v68, v67, v66
	v_cmp_ge_f32_e64 s[0:1], 0, v69
	v_add_u32_e32 v69, 1, v67
	v_cvt_pk_bf16_f32 v70, v70, v71
	v_mul_f32_e32 v71, v72, v84
	v_cndmask_b32_e64 v68, v67, v68, s[0:1]
	v_fma_f32 v67, -v69, v67, v66
	v_cmp_lt_f32_e64 s[0:1], 0, v67
	v_mul_f32_e32 v71, v71, v140
	v_mul_f32_e32 v72, v73, v84
	v_cndmask_b32_e64 v67, v68, v69, s[0:1]
	v_mul_f32_e32 v68, 0x37800000, v67
	v_cndmask_b32_e32 v67, v67, v68, vcc
	v_cmp_class_f32_e32 vcc, v66, v195
	v_mul_f32_e32 v72, v72, v141
	v_cvt_pk_bf16_f32 v71, v71, v72
	global_store_dwordx2 v[82:83], v[70:71], off offset:1024
	v_cndmask_b32_e32 v66, v67, v66, vcc
	v_div_scale_f32 v67, s[0:1], v66, v66, 1.0
	v_rcp_f32_e32 v68, v67
	s_lshl_b64 s[0:1], s[10:11], 11
	v_mul_f32_e32 v78, v78, v84
	v_mul_f32_e32 v79, v79, v84
	v_fma_f32 v69, -v67, v68, 1.0
	v_fmac_f32_e32 v68, v69, v68
	v_div_scale_f32 v69, vcc, 1.0, v66, 1.0
	v_mul_f32_e32 v70, v69, v68
	v_fma_f32 v71, -v67, v70, v69
	v_fmac_f32_e32 v70, v71, v68
	v_fma_f32 v67, -v67, v70, v69
	v_div_fmas_f32 v67, v67, v68, v70
	v_div_fixup_f32 v68, v67, v66, 1.0
	v_mul_f32_e32 v50, v50, v68
	v_mul_f32_e32 v51, v51, v68
	v_mul_f32_e32 v50, v50, v142
	v_mul_f32_e32 v51, v51, v143
	v_cvt_pk_bf16_f32 v50, v50, v51
	v_mul_f32_e32 v51, v52, v68
	v_lshl_add_u64 v[66:67], v[150:151], 0, s[0:1]
	v_mul_f32_e32 v51, v51, v144
	v_mul_f32_e32 v52, v53, v68
	v_mul_f32_e32 v52, v52, v145
	v_cvt_pk_bf16_f32 v51, v51, v52
	global_store_dwordx2 v[66:67], v[50:51], off offset:1536
	v_fmamk_f32 v50, v159, 0x3a800000, v194
	v_cmp_gt_f32_e32 vcc, s61, v50
	v_mul_f32_e32 v51, 0x4f800000, v50
	v_mul_f32_e32 v54, v54, v68
	v_cndmask_b32_e32 v50, v50, v51, vcc
	v_sqrt_f32_e32 v51, v50
	v_mul_f32_e32 v55, v55, v68
	v_mul_f32_e32 v54, v54, v138
	v_mul_f32_e32 v55, v55, v139
	v_add_u32_e32 v52, -1, v51
	v_fma_f32 v53, -v52, v51, v50
	v_cmp_ge_f32_e64 s[0:1], 0, v53
	v_add_u32_e32 v53, 1, v51
	v_cvt_pk_bf16_f32 v54, v54, v55
	v_mul_f32_e32 v55, v56, v68
	v_cndmask_b32_e64 v52, v51, v52, s[0:1]
	v_fma_f32 v51, -v53, v51, v50
	v_cmp_lt_f32_e64 s[0:1], 0, v51
	v_mul_f32_e32 v55, v55, v140
	v_mul_f32_e32 v56, v57, v68
	v_cndmask_b32_e64 v51, v52, v53, s[0:1]
	v_mul_f32_e32 v52, 0x37800000, v51
	v_cndmask_b32_e32 v51, v51, v52, vcc
	v_cmp_class_f32_e32 vcc, v50, v195
	v_mul_f32_e32 v56, v56, v141
	v_cvt_pk_bf16_f32 v55, v55, v56
	global_store_dwordx2 v[66:67], v[54:55], off offset:1024
	v_cndmask_b32_e32 v50, v51, v50, vcc
	v_div_scale_f32 v51, s[0:1], v50, v50, 1.0
	v_rcp_f32_e32 v52, v51
	s_lshl_b64 s[0:1], s[6:7], 11
	v_mul_f32_e32 v62, v62, v68
	v_mul_f32_e32 v63, v63, v68
	v_fma_f32 v53, -v51, v52, 1.0
	v_fmac_f32_e32 v52, v53, v52
	v_div_scale_f32 v53, vcc, 1.0, v50, 1.0
	v_mul_f32_e32 v54, v53, v52
	v_fma_f32 v55, -v51, v54, v53
	v_fmac_f32_e32 v54, v55, v52
	v_fma_f32 v51, -v51, v54, v53
	v_div_fmas_f32 v51, v51, v52, v54
	v_div_fixup_f32 v52, v51, v50, 1.0
	v_mul_f32_e32 v26, v26, v52
	v_mul_f32_e32 v27, v27, v52
	v_mul_f32_e32 v26, v26, v142
	v_mul_f32_e32 v27, v27, v143
	v_cvt_pk_bf16_f32 v26, v26, v27
	v_mul_f32_e32 v27, v28, v52
	v_lshl_add_u64 v[50:51], v[150:151], 0, s[0:1]
	v_mul_f32_e32 v27, v27, v144
	v_mul_f32_e32 v28, v29, v52
	v_mul_f32_e32 v28, v28, v145
	v_cvt_pk_bf16_f32 v27, v27, v28
	global_store_dwordx2 v[50:51], v[26:27], off offset:1536
	v_fmamk_f32 v26, v158, 0x3a800000, v194
	v_cmp_gt_f32_e32 vcc, s61, v26
	v_mul_f32_e32 v27, 0x4f800000, v26
	v_mul_f32_e32 v34, v34, v52
	v_cndmask_b32_e32 v26, v26, v27, vcc
	v_sqrt_f32_e32 v27, v26
	v_mul_f32_e32 v35, v35, v52
	v_mul_f32_e32 v34, v138, v34
	v_mul_f32_e32 v35, v139, v35
	v_add_u32_e32 v28, -1, v27
	v_fma_f32 v29, -v28, v27, v26
	v_cmp_ge_f32_e64 s[0:1], 0, v29
	v_add_u32_e32 v29, 1, v27
	v_cvt_pk_bf16_f32 v34, v34, v35
	v_mul_f32_e32 v35, v36, v52
	v_cndmask_b32_e64 v28, v27, v28, s[0:1]
	v_fma_f32 v27, -v29, v27, v26
	v_cmp_lt_f32_e64 s[0:1], 0, v27
	v_mul_f32_e32 v35, v140, v35
	v_mul_f32_e32 v36, v37, v52
	v_cndmask_b32_e64 v27, v28, v29, s[0:1]
	v_mul_f32_e32 v28, 0x37800000, v27
	v_cndmask_b32_e32 v27, v27, v28, vcc
	v_cmp_class_f32_e32 vcc, v26, v195
	v_mul_f32_e32 v36, v141, v36
	v_cvt_pk_bf16_f32 v35, v35, v36
	global_store_dwordx2 v[50:51], v[34:35], off offset:1024
	v_cndmask_b32_e32 v26, v27, v26, vcc
	v_div_scale_f32 v27, s[0:1], v26, v26, 1.0
	v_rcp_f32_e32 v28, v27
	s_lshl_b64 s[0:1], s[4:5], 11
	v_mul_f32_e32 v46, v46, v52
	v_mul_f32_e32 v47, v47, v52
	v_fma_f32 v29, -v27, v28, 1.0
	v_fmac_f32_e32 v28, v29, v28
	v_div_scale_f32 v29, vcc, 1.0, v26, 1.0
	v_mul_f32_e32 v34, v29, v28
	v_fma_f32 v35, -v27, v34, v29
	v_fmac_f32_e32 v34, v35, v28
	v_fma_f32 v27, -v27, v34, v29
	v_div_fmas_f32 v27, v27, v28, v34
	v_div_fixup_f32 v28, v27, v26, 1.0
	v_mul_f32_e32 v2, v2, v28
	v_mul_f32_e32 v3, v3, v28
	v_mul_f32_e32 v2, v142, v2
	v_mul_f32_e32 v3, v143, v3
	v_cvt_pk_bf16_f32 v2, v2, v3
	v_mul_f32_e32 v3, v4, v28
	v_lshl_add_u64 v[26:27], v[150:151], 0, s[0:1]
	v_mul_f32_e32 v3, v144, v3
	v_mul_f32_e32 v4, v5, v28
	v_mul_f32_e32 v4, v145, v4
	v_cvt_pk_bf16_f32 v3, v3, v4
	global_store_dwordx2 v[26:27], v[2:3], off offset:1536
	v_cmp_gt_f32_e32 vcc, s61, v0
	v_mul_f32_e32 v2, 0x4f800000, v0
	v_mul_f32_e32 v6, v6, v28
	v_cndmask_b32_e32 v0, v0, v2, vcc
	v_sqrt_f32_e32 v2, v0
	v_mul_f32_e32 v7, v7, v28
	v_mul_f32_e32 v6, v138, v6
	v_mul_f32_e32 v7, v139, v7
	v_add_u32_e32 v3, -1, v2
	v_fma_f32 v4, -v3, v2, v0
	v_cmp_ge_f32_e64 s[0:1], 0, v4
	v_add_u32_e32 v4, 1, v2
	v_cvt_pk_bf16_f32 v6, v6, v7
	v_mul_f32_e32 v7, v8, v28
	v_cndmask_b32_e64 v3, v2, v3, s[0:1]
	v_fma_f32 v2, -v4, v2, v0
	v_cmp_lt_f32_e64 s[0:1], 0, v2
	v_mul_f32_e32 v7, v140, v7
	v_mul_f32_e32 v8, v9, v28
	v_cndmask_b32_e64 v2, v3, v4, s[0:1]
	v_mul_f32_e32 v3, 0x37800000, v2
	v_cndmask_b32_e32 v2, v2, v3, vcc
	v_cmp_class_f32_e32 vcc, v0, v195
	v_mul_f32_e32 v8, v141, v8
	v_cvt_pk_bf16_f32 v7, v7, v8
	global_store_dwordx2 v[26:27], v[6:7], off offset:1024
	v_cndmask_b32_e32 v0, v2, v0, vcc
	v_div_scale_f32 v2, s[0:1], v0, v0, 1.0
	v_rcp_f32_e32 v3, v2
	v_mul_f32_e32 v14, v14, v28
	v_mul_f32_e32 v15, v15, v28
	v_mul_f32_e32 v110, v110, v130
	v_fma_f32 v4, -v2, v3, 1.0
	v_fmac_f32_e32 v3, v4, v3
	v_div_scale_f32 v4, vcc, 1.0, v0, 1.0
	v_mul_f32_e32 v5, v4, v3
	v_fma_f32 v6, -v2, v5, v4
	v_fmac_f32_e32 v5, v6, v3
	v_fma_f32 v2, -v2, v5, v4
	v_div_fmas_f32 v2, v2, v3, v5
	v_div_fixup_f32 v0, v2, v0, 1.0
	v_mul_f32_e32 v4, v38, v0
	v_mul_f32_e32 v5, v39, v0
	v_mul_f32_e32 v4, v130, v4
	v_mul_f32_e32 v5, v131, v5
	v_mul_f32_e32 v111, v111, v131
	v_mul_f32_e32 v94, v94, v130
	v_mul_f32_e32 v95, v95, v131
	v_mul_f32_e32 v78, v130, v78
	v_mul_f32_e32 v79, v131, v79
	v_mul_f32_e32 v62, v130, v62
	v_mul_f32_e32 v63, v131, v63
	v_mul_f32_e32 v46, v130, v46
	v_mul_f32_e32 v47, v131, v47
	v_mul_f32_e32 v14, v130, v14
	v_mul_f32_e32 v15, v131, v15
	v_cvt_pk_bf16_f32 v4, v4, v5
	v_mul_f32_e32 v5, v40, v0
	v_cvt_pk_bf16_f32 v110, v110, v111
	v_mul_f32_e32 v111, v112, v116
	v_cvt_pk_bf16_f32 v94, v94, v95
	v_mul_f32_e32 v95, v96, v100
	v_cvt_pk_bf16_f32 v78, v78, v79
	v_mul_f32_e32 v79, v80, v84
	v_cvt_pk_bf16_f32 v62, v62, v63
	v_mul_f32_e32 v63, v64, v68
	v_cvt_pk_bf16_f32 v46, v46, v47
	v_mul_f32_e32 v47, v48, v52
	v_cvt_pk_bf16_f32 v14, v14, v15
	v_mul_f32_e32 v15, v16, v28
	s_lshl_b64 s[0:1], s[2:3], 11
	v_mul_f32_e32 v5, v132, v5
	v_mul_f32_e32 v6, v41, v0
	v_mul_f32_e32 v111, v111, v132
	v_mul_f32_e32 v112, v113, v116
	v_mul_f32_e32 v95, v95, v132
	v_mul_f32_e32 v96, v97, v100
	v_mul_f32_e32 v79, v132, v79
	v_mul_f32_e32 v80, v81, v84
	v_mul_f32_e32 v63, v132, v63
	v_mul_f32_e32 v64, v65, v68
	v_mul_f32_e32 v47, v132, v47
	v_mul_f32_e32 v48, v49, v52
	v_mul_f32_e32 v15, v132, v15
	v_mul_f32_e32 v16, v17, v28
	v_lshl_add_u64 v[2:3], v[150:151], 0, s[0:1]
	v_mul_f32_e32 v6, v133, v6
	v_cvt_pk_bf16_f32 v5, v5, v6
	v_cvt_pk_bf16_f32 v127, v127, v128
	global_store_dwordx2 v[164:165], v[126:127], off
	v_mul_f32_e32 v112, v112, v133
	v_cvt_pk_bf16_f32 v111, v111, v112
	global_store_dwordx2 v[114:115], v[110:111], off
	v_mul_f32_e32 v96, v96, v133
	v_cvt_pk_bf16_f32 v95, v95, v96
	global_store_dwordx2 v[98:99], v[94:95], off
	v_mul_f32_e32 v80, v133, v80
	v_cvt_pk_bf16_f32 v79, v79, v80
	global_store_dwordx2 v[82:83], v[78:79], off
	v_mul_f32_e32 v64, v133, v64
	v_cvt_pk_bf16_f32 v63, v63, v64
	global_store_dwordx2 v[66:67], v[62:63], off
	v_mul_f32_e32 v48, v133, v48
	v_cvt_pk_bf16_f32 v47, v47, v48
	global_store_dwordx2 v[50:51], v[46:47], off
	v_mul_f32_e32 v16, v133, v16
	v_cvt_pk_bf16_f32 v15, v15, v16
	global_store_dwordx2 v[26:27], v[14:15], off
	global_store_dwordx2 v[2:3], v[4:5], off
	v_mul_f32_e32 v4, v30, v0
	v_mul_f32_e32 v5, v31, v0
	v_mul_f32_e32 v106, v106, v116
	v_mul_f32_e32 v107, v107, v116
	v_mul_f32_e32 v90, v90, v100
	v_mul_f32_e32 v91, v91, v100
	v_mul_f32_e32 v74, v74, v84
	v_mul_f32_e32 v75, v75, v84
	v_mul_f32_e32 v58, v58, v68
	v_mul_f32_e32 v59, v59, v68
	v_mul_f32_e32 v42, v42, v52
	v_mul_f32_e32 v43, v43, v52
	v_mul_f32_e32 v10, v10, v28
	v_mul_f32_e32 v11, v11, v28
	v_mul_f32_e32 v4, v134, v4
	v_mul_f32_e32 v5, v135, v5
	v_mul_f32_e32 v122, v122, v134
	v_mul_f32_e32 v123, v123, v135
	v_mul_f32_e32 v106, v106, v134
	v_mul_f32_e32 v107, v107, v135
	v_mul_f32_e32 v90, v90, v134
	v_mul_f32_e32 v91, v91, v135
	v_mul_f32_e32 v74, v74, v134
	v_mul_f32_e32 v75, v75, v135
	v_mul_f32_e32 v58, v134, v58
	v_mul_f32_e32 v59, v135, v59
	v_mul_f32_e32 v42, v134, v42
	v_mul_f32_e32 v43, v135, v43
	v_mul_f32_e32 v10, v134, v10
	v_mul_f32_e32 v11, v135, v11
	v_cvt_pk_bf16_f32 v4, v4, v5
	v_mul_f32_e32 v5, v32, v0
	v_cvt_pk_bf16_f32 v122, v122, v123
	v_mul_f32_e32 v123, v124, v167
	v_cvt_pk_bf16_f32 v106, v106, v107
	v_mul_f32_e32 v107, v108, v116
	v_cvt_pk_bf16_f32 v90, v90, v91
	v_mul_f32_e32 v91, v92, v100
	v_cvt_pk_bf16_f32 v74, v74, v75
	v_mul_f32_e32 v75, v76, v84
	v_cvt_pk_bf16_f32 v58, v58, v59
	v_mul_f32_e32 v59, v60, v68
	v_cvt_pk_bf16_f32 v42, v42, v43
	v_mul_f32_e32 v43, v44, v52
	v_cvt_pk_bf16_f32 v10, v10, v11
	v_mul_f32_e32 v11, v12, v28
	v_mul_f32_e32 v5, v136, v5
	v_mul_f32_e32 v6, v33, v0
	v_mul_f32_e32 v123, v123, v136
	v_mul_f32_e32 v124, v125, v167
	v_mul_f32_e32 v107, v107, v136
	v_mul_f32_e32 v108, v109, v116
	v_mul_f32_e32 v91, v91, v136
	v_mul_f32_e32 v92, v93, v100
	v_mul_f32_e32 v75, v75, v136
	v_mul_f32_e32 v76, v77, v84
	v_mul_f32_e32 v59, v136, v59
	v_mul_f32_e32 v60, v61, v68
	v_mul_f32_e32 v43, v136, v43
	v_mul_f32_e32 v44, v45, v52
	v_mul_f32_e32 v11, v136, v11
	v_mul_f32_e32 v12, v13, v28
	v_mul_f32_e32 v6, v137, v6
	v_cvt_pk_bf16_f32 v5, v5, v6
	v_mul_f32_e32 v124, v124, v137
	v_cvt_pk_bf16_f32 v123, v123, v124
	global_store_dwordx2 v[164:165], v[122:123], off offset:512
	v_mul_f32_e32 v108, v108, v137
	v_cvt_pk_bf16_f32 v107, v107, v108
	global_store_dwordx2 v[114:115], v[106:107], off offset:512
	v_mul_f32_e32 v92, v92, v137
	v_cvt_pk_bf16_f32 v91, v91, v92
	global_store_dwordx2 v[98:99], v[90:91], off offset:512
	v_mul_f32_e32 v76, v76, v137
	v_cvt_pk_bf16_f32 v75, v75, v76
	global_store_dwordx2 v[82:83], v[74:75], off offset:512
	v_mul_f32_e32 v60, v137, v60
	v_cvt_pk_bf16_f32 v59, v59, v60
	global_store_dwordx2 v[66:67], v[58:59], off offset:512
	v_mul_f32_e32 v44, v137, v44
	v_cvt_pk_bf16_f32 v43, v43, v44
	global_store_dwordx2 v[50:51], v[42:43], off offset:512
	v_mul_f32_e32 v12, v137, v12
	v_cvt_pk_bf16_f32 v11, v11, v12
	global_store_dwordx2 v[26:27], v[10:11], off offset:512
	global_store_dwordx2 v[2:3], v[4:5], off offset:512
	v_mul_f32_e32 v4, v22, v0
	v_mul_f32_e32 v5, v23, v0
	v_mul_f32_e32 v4, v138, v4
	v_mul_f32_e32 v5, v139, v5
	v_cvt_pk_bf16_f32 v4, v4, v5
	v_mul_f32_e32 v5, v24, v0
	v_mul_f32_e32 v5, v140, v5
	v_mul_f32_e32 v6, v25, v0
	v_mul_f32_e32 v6, v141, v6
	v_cvt_pk_bf16_f32 v5, v5, v6
	global_store_dwordx2 v[2:3], v[4:5], off offset:1024
	v_mul_f32_e32 v4, v18, v0
	v_mul_f32_e32 v5, v19, v0
	v_mul_f32_e32 v4, v142, v4
	v_mul_f32_e32 v5, v143, v5
	v_cvt_pk_bf16_f32 v4, v4, v5
	v_mul_f32_e32 v5, v20, v0
	v_mul_f32_e32 v5, v144, v5
	v_mul_f32_e32 v0, v21, v0
	s_cmp_gt_i32 s8, 0xffff
	v_mul_f32_e32 v0, v145, v0
	v_cvt_pk_bf16_f32 v5, v5, v0
	global_store_dwordx2 v[2:3], v[4:5], off offset:1536
	s_cbranch_scc0 .LBB0_956
